# k14 + QK0 / K1 / T1 epilogues: ssq row sums via LDS table (load groups replaced by one ds_read + zeros)
# baseline (speedup 1.0000x reference)
; __device__ __forceinline__ int lane_now() { int l; asm volatile("v_mbcnt_lo_u32_b32 %0, -1, 0\n\tv_mbcnt_hi_u32_b32 %0, -1, %0" : "=v"(l)); return l; }
; __device__ __forceinline__ float ssq_sum(const float* p) {
;     const f32x4 a = *(const f32x4*)p, b = *(const f32x4*)(p + 4), c = *(const f32x4*)(p + 8), d = *(const f32x4*)(p + 12);
;     return (((a[0] + a[1]) + (a[2] + a[3])) + ((b[0] + b[1]) + (b[2] + b[3]))) + (((c[0] + c[1]) + (c[2] + c[3])) + ((d[0] + d[1]) + (d[2] + d[3])));
;     __device__ __forceinline__ void operator()(const f32x4 (&acc)[2][2][4][2], const Unit& u, int wr, int wc, int fr, int fq) const {
;         { const int l_ = lane_now(); fq = l_ >> 4; fr = l_ & 15; }
;         const int row0 = u.pm * BM + wr * 64 + fr;
;         if (u.pn >= 4) {
.LBB0_475:
	s_lshl_b32 s0, s8, 8
	s_add_i32 s0, s0, s54
	v_mbcnt_lo_u32_b32 v128, -1, 0
	v_mbcnt_hi_u32_b32 v128, -1, v128
	s_mov_b64 s[8:9], -1
	v_and_or_b32 v168, v128, 15, s0
	v_readlane_b32 vcc_lo, v254, 7
	v_mbcnt_lo_u32_b32 v218, -1, 0
	v_mbcnt_hi_u32_b32 v218, -1, v218
	v_lshrrev_b32_e32 v219, 1, v218
	v_lshl_add_u32 v219, vcc_lo, 5, v219
	v_and_b32_e32 v220, 1, v218
	v_add_u32_e32 v221, s0, v219
	v_subrev_u32_e32 v221, s54, v221
	v_lshlrev_b32_e32 v221, 6, v221
	v_lshl_add_u32 v221, v220, 5, v221
	global_load_dwordx4 v[222:225], v221, s[18:19]
	global_load_dwordx4 v[226:229], v221, s[18:19] offset:16
	v_and_b32_e32 v253, 0xff, v168
	v_lshlrev_b32_e32 v253, 2, v253
	v_add_u32_e32 v253, 0x20100, v253
	v_lshlrev_b32_e32 v219, 2, v219
	v_add_u32_e32 v219, 0x20100, v219
	s_waitcnt vmcnt(0)
	v_pk_add_f32 v[222:223], v[222:223], v[224:225]
	v_pk_add_f32 v[226:227], v[226:227], v[228:229]
	v_pk_add_f32 v[222:223], v[222:223], v[226:227]
	v_add_f32_e32 v222, v222, v223
	s_nop 1
	v_add_f32_dpp v222, v222, v222 quad_perm:[1,0,3,2] row_mask:0xf bank_mask:0xf
	ds_write_b32 v219, v222
	s_waitcnt lgkmcnt(0)
	s_barrier
	v_or_b32_e32 v170, 16, v168
	v_ashrrev_i32_e32 v206, 4, v128
	s_cmp_lt_i32 s66, 4
	v_ashrrev_i32_e32 v169, 31, v168
	v_ashrrev_i32_e32 v171, 31, v170
	s_cbranch_scc1 .LBB0_478
	s_andn2_b64 vcc, exec, s[8:9]
	s_cbranch_vccz .LBB0_479

; __device__ __forceinline__ unsigned cvtpk(float lo, float hi) { f32x2_t v = {lo, hi}; bf16x2_t b = __builtin_convertvector(v, bf16x2_t); return __builtin_bit_cast(unsigned, b); }
;     __device__ __forceinline__ void operator()(const f32x4 (&acc)[2][2][4][2], const Unit& u, int wr, int wc, int fr, int fq) const {
;     ...
;         const int head = u.pn * 4 + wc;
;         const float* g = (head < 8 ? gq : gk) + 8 * fq;
;         f32x4 gv[2][2];
; #pragma unroll
;         for (int bj = 0; bj < 2; ++bj)
; #pragma unroll
;             for (int n = 0; n < 2; ++n) gv[bj][n] = *(const f32x4*)(g + bj * 32 + 4 * n);
; #pragma unroll
;         for (int ai = 0; ai < 2; ++ai)
; #pragma unroll
;             for (int m = 0; m < 4; ++m) {
;                 const int row = row0 + ai * HALF + m * 16; const int pos = row & (SEQ - 1);
;                 float s = 0.f;
; #pragma unroll
;                 for (int bj = 0; bj < 2; ++bj)
; #pragma unroll
;                     for (int n = 0; n < 2; ++n) { const f32x4 v = acc[ai][bj][m][n]; s += (v[0] * v[0] + v[1] * v[1]) + (v[2] * v[2] + v[3] * v[3]); }
;                 s += __shfl_xor(s, 16); s += __shfl_xor(s, 32);
;                 const float rx = 1.0f / sqrtf(ssq_sum(ssq_in + (size_t)row * 16) * (1.0f / DM) + EPS);
;                 const float rs = (head < 8 ? qscale : 1.0f) * rx / sqrtf(s * rx * rx * (1.0f / 64.0f) + EPS);
;                 float o1[8], o2[8];
; #pragma unroll
;                 for (int n = 0; n < 2; ++n)
; #pragma unroll
;                     for (int e = 0; e < 4; ++e) {
;                         float cs, sn; rope_cs(pos, 8 * fq + 4 * n + e, cs, sn);
;                         const float x1 = acc[ai][0][m][n][e] * rs * gv[0][n][e], x2 = acc[ai][1][m][n][e] * rs * gv[1][n][e];
;                         o1[4 * n + e] = x1 * cs - x2 * sn; o2[4 * n + e] = x1 * sn + x2 * cs;
;                     }
;                 bf16_t* op = O + (size_t)row * 2048 + head * 64 + 8 * fq;
;                 u32x4 w; w.x = cvtpk(o1[0], o1[1]); w.y = cvtpk(o1[2], o1[3]); w.z = cvtpk(o1[4], o1[5]); w.w = cvtpk(o1[6], o1[7]);
;                 *(u32x4*)op = w;
;                 w.x = cvtpk(o2[0], o2[1]); w.y = cvtpk(o2[2], o2[3]); w.z = cvtpk(o2[4], o2[5]); w.w = cvtpk(o2[6], o2[7]);
;                 *(u32x4*)(op + 32) = w;
.LBB0_478:
	v_pk_mul_f32 v[150:151], v[126:127], v[126:127]
	v_pk_mul_f32 v[174:175], v[124:125], v[124:125]
	v_and_b32_e32 v147, 64, v204
	v_pk_mov_b32 v[176:177], v[174:175], v[150:151] op_sel:[1,0]
	v_mov_b32_e32 v175, v151
	v_pk_add_f32 v[150:151], v[176:177], v[174:175]
	v_pk_mul_f32 v[174:175], v[122:123], v[122:123]
	v_pk_mul_f32 v[176:177], v[120:121], v[120:121]
	v_pk_add_f32 v[150:151], v[150:151], v[150:151] op_sel:[0,1] op_sel_hi:[1,0]
	v_pk_mov_b32 v[178:179], v[176:177], v[174:175] op_sel:[1,0]
	v_mov_b32_e32 v177, v175
	v_pk_add_f32 v[174:175], v[178:179], v[176:177]
	v_mul_f32_e32 v176, v112, v112
	v_mul_f32_e32 v177, v113, v113
	v_pk_add_f32 v[174:175], v[174:175], v[174:175] op_sel:[0,1] op_sel_hi:[1,0]
	v_mov_b32_e32 v151, v176
	v_mov_b32_e32 v175, v177
	v_pk_add_f32 v[150:151], v[150:151], v[174:175]
	v_mul_f32_e32 v174, v117, v117
	v_mul_f32_e32 v176, v119, v119
	v_mul_f32_e32 v178, v114, v114
	v_mul_f32_e32 v179, v115, v115
	v_pk_fma_f32 v[174:175], v[116:117], v[116:117], v[174:175] op_sel_hi:[1,1,0]
	v_pk_fma_f32 v[176:177], v[118:119], v[118:119], v[176:177] op_sel_hi:[1,1,0]
	v_xor_b32_e32 v146, 16, v204
	v_add_u32_e32 v147, 64, v147
	v_mov_b32_e32 v175, v178
	v_mov_b32_e32 v177, v179
	v_cmp_lt_i32_e32 vcc, v146, v147
	v_pk_add_f32 v[174:175], v[174:175], v[176:177]
	s_lshl_b32 s0, s66, 2
	v_cndmask_b32_e32 v146, v204, v146, vcc
	v_pk_add_f32 v[150:151], v[150:151], v[174:175]
	v_lshlrev_b32_e32 v208, 2, v146
	v_add_f32_e32 v150, v150, v151
	ds_bpermute_b32 v151, v208, v150
	v_xor_b32_e32 v146, 32, v204
	v_cmp_lt_i32_e32 vcc, v146, v147
	s_or_b32 s2, s0, s53
	s_cmp_lt_i32 s2, 8
	v_cndmask_b32_e32 v146, v204, v146, vcc
	v_lshlrev_b32_e32 v209, 2, v146
	s_waitcnt lgkmcnt(0)
	v_add_f32_e32 v150, v150, v151
	ds_bpermute_b32 v151, v209, v150
	s_cselect_b64 s[8:9], -1, 0
	s_and_b64 s[0:1], s[8:9], exec
	s_cselect_b32 s0, s13, s15
	s_cselect_b32 s1, s12, s14
	v_lshlrev_b32_e32 v144, 3, v206
	v_mov_b32_e32 v128, s1
	v_mov_b32_e32 v129, s0
	v_ashrrev_i32_e32 v145, 31, v144
	s_waitcnt lgkmcnt(0)
	v_add_f32_e32 v191, v150, v151
	v_lshlrev_b64 v[150:151], 6, v[168:169]
	v_lshl_add_u64 v[140:141], v[144:145], 2, v[128:129]
	v_lshl_add_u64 v[150:151], s[18:19], 0, v[150:151]
	global_load_dwordx4 v[132:135], v[140:141], off offset:16
	global_load_dwordx4 v[136:139], v[140:141], off
	global_load_dwordx4 v[128:131], v[140:141], off offset:144
	s_nop 0
	global_load_dwordx4 v[140:143], v[140:141], off offset:128
	s_nop 0
	s_nop 1
	ds_read_b32 v182, v253 offset:0
	v_mov_b32_e32 v183, 0
	v_mov_b32_e32 v184, 0
	v_mov_b32_e32 v185, 0
	v_mov_b32_e32 v174, 0
	v_mov_b32_e32 v175, 0
	v_mov_b32_e32 v176, 0
	v_mov_b32_e32 v177, 0
	v_mov_b32_e32 v186, 0
	v_mov_b32_e32 v187, 0
	v_mov_b32_e32 v188, 0
	v_mov_b32_e32 v189, 0
	v_mov_b32_e32 v178, 0
	v_mov_b32_e32 v179, 0
	v_mov_b32_e32 v180, 0
	v_mov_b32_e32 v181, 0
	s_waitcnt lgkmcnt(0)
	s_lshl_b32 s38, s2, 6
	s_ashr_i32 s39, s38, 31
	v_lshlrev_b64 v[146:147], 3, v[144:145]
	s_getpc_b64 s[0:1]
	s_add_u32 s0, s0, _ZL8ROPE_REV@rel32@lo+4
	s_addc_u32 s1, s1, _ZL8ROPE_REV@rel32@hi+12
	v_lshl_add_u64 v[172:173], s[0:1], 0, v[146:147]
	global_load_dwordx2 v[172:173], v[172:173], off
	s_getpc_b64 s[0:1]
	s_add_u32 s0, s0, _ZL8ROPE_REV@rel32@lo+36
	s_addc_u32 s1, s1, _ZL8ROPE_REV@rel32@hi+44
	v_lshl_add_u64 v[148:149], s[0:1], 0, v[146:147]
	v_cndmask_b32_e64 v207, 1.0, v205, s[8:9]
	v_and_b32_e32 v190, 0xfcf, v168
	s_waitcnt vmcnt(0)
	v_mov_b32_e32 v150, v182
	v_mov_b32_e32 v151, v186
	v_mov_b32_e32 v186, v183
	v_mov_b32_e32 v182, v184
	v_mov_b32_e32 v183, v188
	v_mov_b32_e32 v188, v185
	v_pk_add_f32 v[150:151], v[150:151], v[186:187]
	v_pk_add_f32 v[182:183], v[182:183], v[188:189]
	v_cvt_f64_u32_e32 v[188:189], v190
	v_pk_add_f32 v[150:151], v[150:151], v[182:183]
	v_mov_b32_e32 v182, v174
	v_mov_b32_e32 v183, v178
	v_mov_b32_e32 v178, v175
	v_pk_add_f32 v[174:175], v[182:183], v[178:179]
	v_mov_b32_e32 v178, v176
	v_mov_b32_e32 v179, v180
	v_mov_b32_e32 v180, v177
	v_pk_add_f32 v[176:177], v[178:179], v[180:181]
	s_nop 0
	v_pk_add_f32 v[174:175], v[174:175], v[176:177]
	s_nop 0
	v_pk_add_f32 v[150:151], v[150:151], v[174:175]
	s_nop 0
	v_add_f32_e32 v150, v150, v151
	v_fmamk_f32 v150, v150, 0x3a800000, v202
	v_cmp_gt_f32_e32 vcc, s62, v150
	v_mul_f32_e32 v151, 0x4f800000, v150
	s_nop 0
	v_cndmask_b32_e32 v150, v150, v151, vcc
	v_sqrt_f32_e32 v151, v150
	s_nop 0
	v_add_u32_e32 v174, -1, v151
	v_fma_f32 v175, -v174, v151, v150
	v_cmp_ge_f32_e64 s[10:11], 0, v175
	v_add_u32_e32 v175, 1, v151
	s_nop 0
	v_cndmask_b32_e64 v174, v151, v174, s[10:11]
	v_fma_f32 v151, -v175, v151, v150
	v_cmp_lt_f32_e64 s[10:11], 0, v151
	s_nop 1
	v_cndmask_b32_e64 v151, v174, v175, s[10:11]
	v_mul_f32_e32 v174, 0x37800000, v151
	v_cndmask_b32_e32 v151, v151, v174, vcc
	v_cmp_class_f32_e32 vcc, v150, v203
	s_nop 1
	v_cndmask_b32_e32 v150, v151, v150, vcc
	v_div_scale_f32 v151, s[0:1], v150, v150, 1.0
	v_rcp_f32_e32 v174, v151
	s_nop 0
	v_fma_f32 v175, -v151, v174, 1.0
	v_fmac_f32_e32 v174, v175, v174
	v_div_scale_f32 v175, vcc, 1.0, v150, 1.0
	v_mul_f32_e32 v176, v175, v174
	v_fma_f32 v177, -v151, v176, v175
	v_fmac_f32_e32 v176, v177, v174
	v_fma_f32 v151, -v151, v176, v175
	v_div_fmas_f32 v151, v151, v174, v176
	v_div_fixup_f32 v150, v151, v150, 1.0
	v_mul_f32_e32 v174, v191, v150
	v_mul_f32_e32 v151, v207, v150
	v_mul_f32_e32 v150, v150, v174
	v_fmamk_f32 v150, v150, 0x3c800000, v202
	v_cmp_gt_f32_e32 vcc, s62, v150
	v_mul_f32_e32 v174, 0x4f800000, v150
	s_nop 0
	v_cndmask_b32_e32 v150, v150, v174, vcc
	v_sqrt_f32_e32 v174, v150
	s_nop 0
	v_add_u32_e32 v175, -1, v174
	v_fma_f32 v176, -v175, v174, v150
	v_cmp_ge_f32_e64 s[8:9], 0, v176
	v_add_u32_e32 v176, 1, v174
	s_nop 0
	v_cndmask_b32_e64 v175, v174, v175, s[8:9]
	v_fma_f32 v174, -v176, v174, v150
	v_cmp_lt_f32_e64 s[8:9], 0, v174
	s_nop 1
	v_cndmask_b32_e64 v174, v175, v176, s[8:9]
	v_mul_f32_e32 v175, 0x37800000, v174
	v_cndmask_b32_e32 v174, v174, v175, vcc
	v_cmp_class_f32_e32 vcc, v150, v203
	s_nop 1
	v_cndmask_b32_e32 v150, v174, v150, vcc
	v_div_scale_f32 v174, s[0:1], v150, v150, v151
	v_rcp_f32_e32 v175, v174
	s_getpc_b64 s[0:1]
	s_add_u32 s0, s0, _ZL8ROPE_REV@rel32@lo+12
	s_addc_u32 s1, s1, _ZL8ROPE_REV@rel32@hi+20
	v_fma_f32 v176, -v174, v175, 1.0
	v_fmac_f32_e32 v175, v176, v175
	v_div_scale_f32 v176, vcc, v151, v150, v151
	v_mul_f32_e32 v177, v176, v175
	v_fma_f32 v178, -v174, v177, v176
	v_fmac_f32_e32 v177, v178, v175
	v_fma_f32 v174, -v174, v177, v176
	v_div_fmas_f32 v174, v174, v175, v177
	v_div_fixup_f32 v150, v174, v150, v151
	v_mul_f64 v[174:175], v[172:173], v[188:189]
	v_rndne_f64_e32 v[174:175], v[174:175]
	v_fma_f64 v[174:175], v[172:173], v[188:189], -v[174:175]
	v_cvt_f32_f64_e32 v151, v[174:175]
	v_cos_f32_e32 v176, v151
	v_sin_f32_e32 v178, v151
	v_lshl_add_u64 v[174:175], s[0:1], 0, v[146:147]
	global_load_dwordx2 v[174:175], v[174:175], off
	s_getpc_b64 s[0:1]
	s_add_u32 s0, s0, _ZL8ROPE_REV@rel32@lo+20
	s_addc_u32 s1, s1, _ZL8ROPE_REV@rel32@hi+28
	s_waitcnt vmcnt(0)
; __device__ __forceinline__ unsigned cvtpk(float lo, float hi) { f32x2_t v = {lo, hi}; bf16x2_t b = __builtin_convertvector(v, bf16x2_t); return __builtin_bit_cast(unsigned, b); }
;     __device__ __forceinline__ void operator()(const f32x4 (&acc)[2][2][4][2], const Unit& u, int wr, int wc, int fr, int fq) const {
;     ...
;                 float o1[8], o2[8];
; #pragma unroll
;                 for (int n = 0; n < 2; ++n)
; #pragma unroll
;                     for (int e = 0; e < 4; ++e) {
;                         float cs, sn; rope_cs(pos, 8 * fq + 4 * n + e, cs, sn);
;                         const float x1 = acc[ai][0][m][n][e] * rs * gv[0][n][e], x2 = acc[ai][1][m][n][e] * rs * gv[1][n][e];
;                         o1[4 * n + e] = x1 * cs - x2 * sn; o2[4 * n + e] = x1 * sn + x2 * cs;
;                     }
;                 bf16_t* op = O + (size_t)row * 2048 + head * 64 + 8 * fq;
;                 u32x4 w; w.x = cvtpk(o1[0], o1[1]); w.y = cvtpk(o1[2], o1[3]); w.z = cvtpk(o1[4], o1[5]); w.w = cvtpk(o1[6], o1[7]);
;                 *(u32x4*)op = w;
;                 w.x = cvtpk(o2[0], o2[1]); w.y = cvtpk(o2[2], o2[3]); w.z = cvtpk(o2[4], o2[5]); w.w = cvtpk(o2[6], o2[7]);
;                 *(u32x4*)(op + 32) = w;
	v_mul_f64 v[180:181], v[174:175], v[188:189]
	v_rndne_f64_e32 v[180:181], v[180:181]
	v_fma_f64 v[180:181], v[174:175], v[188:189], -v[180:181]
	v_cvt_f32_f64_e32 v151, v[180:181]
	v_pk_mul_f32 v[182:183], v[116:117], v[150:151] op_sel_hi:[1,0]
	v_cos_f32_e32 v177, v151
	v_sin_f32_e32 v179, v151
	v_pk_mul_f32 v[180:181], v[124:125], v[150:151] op_sel_hi:[1,0]
	v_pk_mul_f32 v[182:183], v[140:141], v[182:183]
	v_pk_mul_f32 v[180:181], v[136:137], v[180:181]
	v_pk_mul_f32 v[184:185], v[176:177], v[182:183]
	s_nop 0
	v_pk_fma_f32 v[190:191], v[178:179], v[180:181], v[184:185]
	v_pk_mul_f32 v[178:179], v[178:179], v[182:183]
	s_nop 0
	v_pk_fma_f32 v[192:193], v[176:177], v[180:181], v[178:179] neg_lo:[0,0,1] neg_hi:[0,0,1]
	v_lshl_add_u64 v[176:177], s[0:1], 0, v[146:147]
	global_load_dwordx2 v[176:177], v[176:177], off
	s_getpc_b64 s[0:1]
	s_add_u32 s0, s0, _ZL8ROPE_REV@rel32@lo+28
	s_addc_u32 s1, s1, _ZL8ROPE_REV@rel32@hi+36
	s_waitcnt vmcnt(0)
	v_mul_f64 v[178:179], v[176:177], v[188:189]
	v_rndne_f64_e32 v[178:179], v[178:179]
	v_fma_f64 v[178:179], v[176:177], v[188:189], -v[178:179]
	v_cvt_f32_f64_e32 v151, v[178:179]
	v_cos_f32_e32 v180, v151
	v_sin_f32_e32 v182, v151
	v_lshl_add_u64 v[178:179], s[0:1], 0, v[146:147]
	global_load_dwordx2 v[178:179], v[178:179], off
	s_getpc_b64 s[0:1]
	s_add_u32 s0, s0, _ZL8ROPE_REV@rel32@lo+44
	s_addc_u32 s1, s1, _ZL8ROPE_REV@rel32@hi+52
	s_waitcnt vmcnt(0)
	v_mul_f64 v[184:185], v[178:179], v[188:189]
	v_rndne_f64_e32 v[184:185], v[184:185]
	v_fma_f64 v[184:185], v[178:179], v[188:189], -v[184:185]
	v_cvt_f32_f64_e32 v151, v[184:185]
	v_pk_mul_f32 v[186:187], v[118:119], v[150:151] op_sel_hi:[1,0]
	v_cos_f32_e32 v181, v151
	v_sin_f32_e32 v183, v151
	v_pk_mul_f32 v[184:185], v[126:127], v[150:151] op_sel_hi:[1,0]
	v_pk_mul_f32 v[186:187], v[142:143], v[186:187]
	v_pk_mul_f32 v[184:185], v[138:139], v[184:185]
	v_pk_mul_f32 v[194:195], v[180:181], v[186:187]
	s_nop 0
	v_pk_fma_f32 v[194:195], v[182:183], v[184:185], v[194:195]
	v_pk_mul_f32 v[182:183], v[182:183], v[186:187]
	s_nop 0
	v_pk_fma_f32 v[196:197], v[180:181], v[184:185], v[182:183] neg_lo:[0,0,1] neg_hi:[0,0,1]
	global_load_dwordx2 v[184:185], v[148:149], off
	v_lshl_add_u64 v[182:183], s[0:1], 0, v[146:147]
	s_getpc_b64 s[0:1]
	s_add_u32 s0, s0, _ZL8ROPE_REV@rel32@lo+52
	s_addc_u32 s1, s1, _ZL8ROPE_REV@rel32@hi+60
	s_waitcnt vmcnt(0)
	v_mul_f64 v[148:149], v[184:185], v[188:189]
	v_rndne_f64_e32 v[148:149], v[148:149]
	v_fma_f64 v[148:149], v[184:185], v[188:189], -v[148:149]
	v_cvt_f32_f64_e32 v149, v[148:149]
	v_cos_f32_e32 v148, v149
	v_sin_f32_e32 v180, v149
	global_load_dwordx2 v[186:187], v[182:183], off
	s_waitcnt vmcnt(0)
	v_mul_f64 v[182:183], v[186:187], v[188:189]
	v_rndne_f64_e32 v[182:183], v[182:183]
	v_fma_f64 v[182:183], v[186:187], v[188:189], -v[182:183]
	v_cvt_f32_f64_e32 v151, v[182:183]
	v_pk_mul_f32 v[210:211], v[112:113], v[150:151] op_sel_hi:[1,0]
	v_cos_f32_e32 v149, v151
	v_sin_f32_e32 v181, v151
	v_pk_mul_f32 v[182:183], v[120:121], v[150:151] op_sel_hi:[1,0]
	v_pk_mul_f32 v[210:211], v[128:129], v[210:211]
	v_pk_mul_f32 v[182:183], v[132:133], v[182:183]
	v_pk_mul_f32 v[212:213], v[148:149], v[210:211]
	s_nop 0
	v_pk_fma_f32 v[212:213], v[180:181], v[182:183], v[212:213]
	v_pk_mul_f32 v[180:181], v[180:181], v[210:211]
	s_nop 0
	v_pk_fma_f32 v[148:149], v[148:149], v[182:183], v[180:181] neg_lo:[0,0,1] neg_hi:[0,0,1]
	v_lshl_add_u64 v[180:181], s[0:1], 0, v[146:147]
	global_load_dwordx2 v[182:183], v[180:181], off
	s_getpc_b64 s[0:1]
	s_add_u32 s0, s0, _ZL8ROPE_REV@rel32@lo+60
	s_addc_u32 s1, s1, _ZL8ROPE_REV@rel32@hi+68
	v_lshl_add_u64 v[146:147], s[0:1], 0, v[146:147]
	s_lshl_b64 s[10:11], s[38:39], 1
	s_waitcnt vmcnt(0)
	v_mul_f64 v[180:181], v[182:183], v[188:189]
	v_rndne_f64_e32 v[180:181], v[180:181]
	v_fma_f64 v[180:181], v[182:183], v[188:189], -v[180:181]
	v_cvt_f32_f64_e32 v151, v[180:181]
	v_cos_f32_e32 v210, v151
	v_sin_f32_e32 v214, v151
	global_load_dwordx2 v[180:181], v[146:147], off
	s_waitcnt vmcnt(0)
	v_mul_f64 v[146:147], v[180:181], v[188:189]
	v_rndne_f64_e32 v[146:147], v[146:147]
	v_fma_f64 v[146:147], v[180:181], v[188:189], -v[146:147]
	v_cvt_f32_f64_e32 v146, v[146:147]
	v_cos_f32_e32 v211, v146
	v_sin_f32_e32 v215, v146
	v_pk_mul_f32 v[146:147], v[122:123], v[150:151] op_sel_hi:[1,0]
	v_pk_mul_f32 v[150:151], v[114:115], v[150:151] op_sel_hi:[1,0]
	v_pk_mul_f32 v[146:147], v[134:135], v[146:147]
	v_pk_mul_f32 v[150:151], v[130:131], v[150:151]
	s_nop 0
	v_pk_mul_f32 v[188:189], v[210:211], v[150:151]
	v_pk_mul_f32 v[150:151], v[214:215], v[150:151]
	v_pk_fma_f32 v[216:217], v[214:215], v[146:147], v[188:189]
	v_pk_fma_f32 v[150:151], v[210:211], v[146:147], v[150:151] neg_lo:[0,0,1] neg_hi:[0,0,1]
	v_lshlrev_b64 v[146:147], 12, v[168:169]
	v_lshl_add_u64 v[146:147], s[22:23], 0, v[146:147]
	v_lshl_add_u64 v[146:147], v[146:147], 0, s[10:11]
	v_lshlrev_b64 v[188:189], 1, v[144:145]
	v_lshl_add_u64 v[210:211], v[146:147], 0, v[188:189]
	v_cvt_pk_bf16_f32 v144, v192, v193
	v_cvt_pk_bf16_f32 v145, v196, v197
	v_cvt_pk_bf16_f32 v146, v148, v149
	v_cvt_pk_bf16_f32 v147, v150, v151
	global_store_dwordx4 v[210:211], v[144:147], off
	s_nop 1
	v_cvt_pk_bf16_f32 v144, v190, v191
	v_cvt_pk_bf16_f32 v145, v194, v195
	v_cvt_pk_bf16_f32 v146, v212, v213
	v_cvt_pk_bf16_f32 v147, v216, v217
	global_store_dwordx4 v[210:211], v[144:147], off offset:64
	v_bitop3_b32 v212, v168, s63, 16 bitop3:0xc8
	s_nop 0
	v_pk_mul_f32 v[144:145], v[110:111], v[110:111]
	v_pk_mul_f32 v[146:147], v[108:109], v[108:109]
	s_nop 0
	v_pk_mov_b32 v[148:149], v[146:147], v[144:145] op_sel:[1,0]
	v_mov_b32_e32 v147, v145
	v_pk_add_f32 v[144:145], v[148:149], v[146:147]
	v_pk_mul_f32 v[146:147], v[106:107], v[106:107]
	v_pk_mul_f32 v[148:149], v[104:105], v[104:105]
	v_pk_add_f32 v[144:145], v[144:145], v[144:145] op_sel:[0,1] op_sel_hi:[1,0]
	v_pk_mov_b32 v[150:151], v[148:149], v[146:147] op_sel:[1,0]
	v_mov_b32_e32 v149, v147
	v_pk_add_f32 v[146:147], v[150:151], v[148:149]
	v_mul_f32_e32 v148, v96, v96
	v_mul_f32_e32 v149, v97, v97
	v_pk_add_f32 v[146:147], v[146:147], v[146:147] op_sel:[0,1] op_sel_hi:[1,0]
	v_mov_b32_e32 v145, v148
	v_mov_b32_e32 v147, v149
	v_pk_add_f32 v[144:145], v[144:145], v[146:147]
	v_mul_f32_e32 v146, v101, v101
	v_mul_f32_e32 v148, v103, v103
	v_mul_f32_e32 v150, v98, v98
	v_mul_f32_e32 v151, v99, v99
	v_pk_fma_f32 v[146:147], v[100:101], v[100:101], v[146:147] op_sel_hi:[1,1,0]
	v_pk_fma_f32 v[148:149], v[102:103], v[102:103], v[148:149] op_sel_hi:[1,1,0]
	v_mov_b32_e32 v147, v150
	v_mov_b32_e32 v149, v151
	v_pk_add_f32 v[146:147], v[146:147], v[148:149]
	s_nop 0
	v_pk_add_f32 v[144:145], v[144:145], v[146:147]
	s_nop 0
	v_add_f32_e32 v144, v144, v145
	ds_bpermute_b32 v145, v208, v144
	s_waitcnt lgkmcnt(0)
; __device__ __forceinline__ unsigned cvtpk(float lo, float hi) { f32x2_t v = {lo, hi}; bf16x2_t b = __builtin_convertvector(v, bf16x2_t); return __builtin_bit_cast(unsigned, b); }
;     __device__ __forceinline__ void operator()(const f32x4 (&acc)[2][2][4][2], const Unit& u, int wr, int wc, int fr, int fq) const {
;     ...
;                 const int row = row0 + ai * HALF + m * 16; const int pos = row & (SEQ - 1);
;                 float s = 0.f;
; #pragma unroll
;                 for (int bj = 0; bj < 2; ++bj)
; #pragma unroll
;                     for (int n = 0; n < 2; ++n) { const f32x4 v = acc[ai][bj][m][n]; s += (v[0] * v[0] + v[1] * v[1]) + (v[2] * v[2] + v[3] * v[3]); }
;                 s += __shfl_xor(s, 16); s += __shfl_xor(s, 32);
;                 const float rx = 1.0f / sqrtf(ssq_sum(ssq_in + (size_t)row * 16) * (1.0f / DM) + EPS);
;                 const float rs = (head < 8 ? qscale : 1.0f) * rx / sqrtf(s * rx * rx * (1.0f / 64.0f) + EPS);
;                 float o1[8], o2[8];
; #pragma unroll
;                 for (int n = 0; n < 2; ++n)
; #pragma unroll
;                     for (int e = 0; e < 4; ++e) {
;                         float cs, sn; rope_cs(pos, 8 * fq + 4 * n + e, cs, sn);
;                         const float x1 = acc[ai][0][m][n][e] * rs * gv[0][n][e], x2 = acc[ai][1][m][n][e] * rs * gv[1][n][e];
;                         o1[4 * n + e] = x1 * cs - x2 * sn; o2[4 * n + e] = x1 * sn + x2 * cs;
;                     }
;                 bf16_t* op = O + (size_t)row * 2048 + head * 64 + 8 * fq;
;                 u32x4 w; w.x = cvtpk(o1[0], o1[1]); w.y = cvtpk(o1[2], o1[3]); w.z = cvtpk(o1[4], o1[5]); w.w = cvtpk(o1[6], o1[7]);
;                 *(u32x4*)op = w;
;                 w.x = cvtpk(o2[0], o2[1]); w.y = cvtpk(o2[2], o2[3]); w.z = cvtpk(o2[4], o2[5]); w.w = cvtpk(o2[6], o2[7]);
;                 *(u32x4*)(op + 32) = w;
	v_add_f32_e32 v144, v144, v145
	ds_bpermute_b32 v145, v209, v144
	s_waitcnt lgkmcnt(0)
	v_add_f32_e32 v213, v144, v145
	v_lshlrev_b64 v[144:145], 6, v[170:171]
	v_lshl_add_u64 v[194:195], s[18:19], 0, v[144:145]
	s_nop 1
	ds_read_b32 v190, v253 offset:64
	v_mov_b32_e32 v191, 0
	v_mov_b32_e32 v192, 0
	v_mov_b32_e32 v193, 0
	v_mov_b32_e32 v144, 0
	v_mov_b32_e32 v145, 0
	v_mov_b32_e32 v146, 0
	v_mov_b32_e32 v147, 0
	v_mov_b32_e32 v194, 0
	v_mov_b32_e32 v195, 0
	v_mov_b32_e32 v196, 0
	v_mov_b32_e32 v197, 0
	v_mov_b32_e32 v148, 0
	v_mov_b32_e32 v149, 0
	v_mov_b32_e32 v150, 0
	v_mov_b32_e32 v151, 0
	s_waitcnt lgkmcnt(0)
	s_waitcnt vmcnt(1)
	v_mov_b32_e32 v210, v190
	s_waitcnt vmcnt(0)
	v_mov_b32_e32 v211, v194
	v_mov_b32_e32 v194, v191
	v_pk_add_f32 v[190:191], v[210:211], v[194:195]
	v_mov_b32_e32 v194, v192
	v_mov_b32_e32 v195, v196
	v_mov_b32_e32 v196, v193
	v_pk_add_f32 v[192:193], v[194:195], v[196:197]
	v_cvt_f64_u32_e32 v[196:197], v212
	v_pk_add_f32 v[190:191], v[190:191], v[192:193]
	v_mov_b32_e32 v192, v144
	v_mov_b32_e32 v193, v148
	v_mov_b32_e32 v148, v145
	v_pk_add_f32 v[144:145], v[192:193], v[148:149]
	v_mov_b32_e32 v148, v146
	v_mov_b32_e32 v149, v150
	v_mov_b32_e32 v150, v147
	v_pk_add_f32 v[146:147], v[148:149], v[150:151]
	s_nop 0
	v_pk_add_f32 v[144:145], v[144:145], v[146:147]
	s_nop 0
	v_pk_add_f32 v[144:145], v[190:191], v[144:145]
	s_nop 0
	v_add_f32_e32 v144, v144, v145
	v_fmamk_f32 v144, v144, 0x3a800000, v202
	v_cmp_gt_f32_e32 vcc, s62, v144
	v_mul_f32_e32 v145, 0x4f800000, v144
	s_nop 0
	v_cndmask_b32_e32 v144, v144, v145, vcc
	v_sqrt_f32_e32 v145, v144
	s_nop 0
	v_add_u32_e32 v146, -1, v145
	v_fma_f32 v147, -v146, v145, v144
	v_cmp_ge_f32_e64 s[8:9], 0, v147
	v_add_u32_e32 v147, 1, v145
	s_nop 0
	v_cndmask_b32_e64 v146, v145, v146, s[8:9]
	v_fma_f32 v145, -v147, v145, v144
	v_cmp_lt_f32_e64 s[8:9], 0, v145
	s_nop 1
	v_cndmask_b32_e64 v145, v146, v147, s[8:9]
	v_mul_f32_e32 v146, 0x37800000, v145
	v_cndmask_b32_e32 v145, v145, v146, vcc
	v_cmp_class_f32_e32 vcc, v144, v203
	s_nop 1
	v_cndmask_b32_e32 v144, v145, v144, vcc
	v_div_scale_f32 v145, s[0:1], v144, v144, 1.0
	v_rcp_f32_e32 v146, v145
	s_nop 0
	v_fma_f32 v147, -v145, v146, 1.0
	v_fmac_f32_e32 v146, v147, v146
	v_div_scale_f32 v147, vcc, 1.0, v144, 1.0
	v_mul_f32_e32 v148, v147, v146
	v_fma_f32 v149, -v145, v148, v147
	v_fmac_f32_e32 v148, v149, v146
	v_fma_f32 v145, -v145, v148, v147
	v_div_fmas_f32 v145, v145, v146, v148
	v_div_fixup_f32 v144, v145, v144, 1.0
	v_mul_f32_e32 v146, v213, v144
	v_mul_f32_e32 v145, v207, v144
	v_mul_f32_e32 v144, v144, v146
	v_fmamk_f32 v144, v144, 0x3c800000, v202
	v_cmp_gt_f32_e32 vcc, s62, v144
	v_mul_f32_e32 v146, 0x4f800000, v144
	s_nop 0
	v_cndmask_b32_e32 v144, v144, v146, vcc
	v_sqrt_f32_e32 v146, v144
	s_nop 0
	v_add_u32_e32 v147, -1, v146
	v_fma_f32 v148, -v147, v146, v144
	v_cmp_ge_f32_e64 s[8:9], 0, v148
	v_add_u32_e32 v148, 1, v146
	s_nop 0
	v_cndmask_b32_e64 v147, v146, v147, s[8:9]
	v_fma_f32 v146, -v148, v146, v144
	v_cmp_lt_f32_e64 s[8:9], 0, v146
	s_nop 1
	v_cndmask_b32_e64 v146, v147, v148, s[8:9]
	v_mul_f32_e32 v147, 0x37800000, v146
	v_cndmask_b32_e32 v146, v146, v147, vcc
	v_cmp_class_f32_e32 vcc, v144, v203
	s_nop 1
	v_cndmask_b32_e32 v144, v146, v144, vcc
	v_div_scale_f32 v146, s[0:1], v144, v144, v145
	v_rcp_f32_e32 v147, v146
	s_nop 0
	v_fma_f32 v148, -v146, v147, 1.0
	v_fmac_f32_e32 v147, v148, v147
	v_div_scale_f32 v148, vcc, v145, v144, v145
	v_mul_f32_e32 v149, v148, v147
	v_fma_f32 v150, -v146, v149, v148
	v_fmac_f32_e32 v149, v150, v147
	v_fma_f32 v146, -v146, v149, v148
	v_div_fmas_f32 v146, v146, v147, v149
	v_div_fixup_f32 v194, v146, v144, v145
	v_mul_f64 v[144:145], v[172:173], v[196:197]
	v_rndne_f64_e32 v[144:145], v[144:145]
	v_fma_f64 v[144:145], v[172:173], v[196:197], -v[144:145]
	v_cvt_f32_f64_e32 v144, v[144:145]
	v_cos_f32_e32 v146, v144
	v_sin_f32_e32 v148, v144
	v_mul_f64 v[144:145], v[174:175], v[196:197]
	v_rndne_f64_e32 v[144:145], v[144:145]
	v_fma_f64 v[144:145], v[174:175], v[196:197], -v[144:145]
	v_cvt_f32_f64_e32 v144, v[144:145]
	v_cos_f32_e32 v147, v144
	v_sin_f32_e32 v149, v144
	v_pk_mul_f32 v[144:145], v[108:109], v[194:195] op_sel_hi:[1,0]
	s_nop 0
	v_pk_mul_f32 v[150:151], v[136:137], v[144:145]
	v_pk_mul_f32 v[144:145], v[100:101], v[194:195] op_sel_hi:[1,0]
	s_nop 0
	v_pk_mul_f32 v[190:191], v[140:141], v[144:145]
	s_nop 0
	v_pk_mul_f32 v[144:145], v[146:147], v[190:191]
	s_nop 0
	v_pk_fma_f32 v[144:145], v[148:149], v[150:151], v[144:145]
	v_pk_mul_f32 v[148:149], v[148:149], v[190:191]
	v_cvt_pk_bf16_f32 v144, v144, v145
	v_pk_fma_f32 v[146:147], v[146:147], v[150:151], v[148:149] neg_lo:[0,0,1] neg_hi:[0,0,1]
	v_mul_f64 v[148:149], v[176:177], v[196:197]
	v_rndne_f64_e32 v[148:149], v[148:149]
	v_fma_f64 v[148:149], v[176:177], v[196:197], -v[148:149]
	v_cvt_f32_f64_e32 v148, v[148:149]
	v_cos_f32_e32 v150, v148
	v_sin_f32_e32 v190, v148
	v_mul_f64 v[148:149], v[178:179], v[196:197]
	v_rndne_f64_e32 v[148:149], v[148:149]
	v_fma_f64 v[148:149], v[178:179], v[196:197], -v[148:149]
	v_cvt_f32_f64_e32 v148, v[148:149]
	v_cos_f32_e32 v151, v148
	v_sin_f32_e32 v191, v148
	v_pk_mul_f32 v[148:149], v[110:111], v[194:195] op_sel_hi:[1,0]
	s_nop 0
	v_pk_mul_f32 v[192:193], v[138:139], v[148:149]
	v_pk_mul_f32 v[148:149], v[102:103], v[194:195] op_sel_hi:[1,0]
	s_nop 0
	v_pk_mul_f32 v[210:211], v[142:143], v[148:149]
	s_nop 0
	v_pk_mul_f32 v[148:149], v[150:151], v[210:211]
	s_nop 0
	v_pk_fma_f32 v[148:149], v[190:191], v[192:193], v[148:149]
	v_pk_mul_f32 v[190:191], v[190:191], v[210:211]
	v_cvt_pk_bf16_f32 v145, v148, v149
; __device__ __forceinline__ unsigned cvtpk(float lo, float hi) { f32x2_t v = {lo, hi}; bf16x2_t b = __builtin_convertvector(v, bf16x2_t); return __builtin_bit_cast(unsigned, b); }
;     __device__ __forceinline__ void operator()(const f32x4 (&acc)[2][2][4][2], const Unit& u, int wr, int wc, int fr, int fq) const {
;     ...
;                 const int row = row0 + ai * HALF + m * 16; const int pos = row & (SEQ - 1);
;                 float s = 0.f;
; #pragma unroll
;                 for (int bj = 0; bj < 2; ++bj)
; #pragma unroll
;                     for (int n = 0; n < 2; ++n) { const f32x4 v = acc[ai][bj][m][n]; s += (v[0] * v[0] + v[1] * v[1]) + (v[2] * v[2] + v[3] * v[3]); }
;                 s += __shfl_xor(s, 16); s += __shfl_xor(s, 32);
;                 const float rx = 1.0f / sqrtf(ssq_sum(ssq_in + (size_t)row * 16) * (1.0f / DM) + EPS);
;                 const float rs = (head < 8 ? qscale : 1.0f) * rx / sqrtf(s * rx * rx * (1.0f / 64.0f) + EPS);
;                 float o1[8], o2[8];
; #pragma unroll
;                 for (int n = 0; n < 2; ++n)
; #pragma unroll
;                     for (int e = 0; e < 4; ++e) {
;                         float cs, sn; rope_cs(pos, 8 * fq + 4 * n + e, cs, sn);
;                         const float x1 = acc[ai][0][m][n][e] * rs * gv[0][n][e], x2 = acc[ai][1][m][n][e] * rs * gv[1][n][e];
;                         o1[4 * n + e] = x1 * cs - x2 * sn; o2[4 * n + e] = x1 * sn + x2 * cs;
;                     }
;                 bf16_t* op = O + (size_t)row * 2048 + head * 64 + 8 * fq;
;                 u32x4 w; w.x = cvtpk(o1[0], o1[1]); w.y = cvtpk(o1[2], o1[3]); w.z = cvtpk(o1[4], o1[5]); w.w = cvtpk(o1[6], o1[7]);
;                 *(u32x4*)op = w;
;                 w.x = cvtpk(o2[0], o2[1]); w.y = cvtpk(o2[2], o2[3]); w.z = cvtpk(o2[4], o2[5]); w.w = cvtpk(o2[6], o2[7]);
;                 *(u32x4*)(op + 32) = w;
	v_pk_fma_f32 v[150:151], v[150:151], v[192:193], v[190:191] neg_lo:[0,0,1] neg_hi:[0,0,1]
	v_mul_f64 v[190:191], v[184:185], v[196:197]
	v_rndne_f64_e32 v[190:191], v[190:191]
	v_fma_f64 v[190:191], v[184:185], v[196:197], -v[190:191]
	v_cvt_f32_f64_e32 v190, v[190:191]
	v_cos_f32_e32 v192, v190
	v_sin_f32_e32 v210, v190
	v_mul_f64 v[190:191], v[186:187], v[196:197]
	v_rndne_f64_e32 v[190:191], v[190:191]
	v_fma_f64 v[190:191], v[186:187], v[196:197], -v[190:191]
	v_cvt_f32_f64_e32 v190, v[190:191]
	v_cos_f32_e32 v193, v190
	v_sin_f32_e32 v211, v190
	v_pk_mul_f32 v[190:191], v[104:105], v[194:195] op_sel_hi:[1,0]
	v_pk_mul_f32 v[148:149], v[92:93], v[92:93]
	v_pk_mul_f32 v[212:213], v[132:133], v[190:191]
	v_pk_mul_f32 v[190:191], v[96:97], v[194:195] op_sel_hi:[1,0]
	s_nop 0
	v_pk_mul_f32 v[214:215], v[128:129], v[190:191]
	s_nop 0
	v_pk_mul_f32 v[190:191], v[192:193], v[214:215]
	s_nop 0
	v_pk_fma_f32 v[190:191], v[210:211], v[212:213], v[190:191]
	v_pk_mul_f32 v[210:211], v[210:211], v[214:215]
	v_mul_f64 v[214:215], v[180:181], v[196:197]
	v_pk_fma_f32 v[192:193], v[192:193], v[212:213], v[210:211] neg_lo:[0,0,1] neg_hi:[0,0,1]
	v_mul_f64 v[210:211], v[182:183], v[196:197]
	v_rndne_f64_e32 v[210:211], v[210:211]
	v_fma_f64 v[210:211], v[182:183], v[196:197], -v[210:211]
	v_rndne_f64_e32 v[214:215], v[214:215]
	v_cvt_f32_f64_e32 v195, v[210:211]
	v_fma_f64 v[196:197], v[180:181], v[196:197], -v[214:215]
	v_cos_f32_e32 v210, v195
	v_sin_f32_e32 v212, v195
	v_cvt_f32_f64_e32 v195, v[196:197]
	v_cos_f32_e32 v211, v195
	v_sin_f32_e32 v213, v195
	v_pk_mul_f32 v[196:197], v[106:107], v[194:195] op_sel_hi:[1,0]
	v_pk_mul_f32 v[194:195], v[98:99], v[194:195] op_sel_hi:[1,0]
	v_pk_mul_f32 v[196:197], v[134:135], v[196:197]
	v_pk_mul_f32 v[214:215], v[130:131], v[194:195]
	s_nop 0
	v_pk_mul_f32 v[194:195], v[210:211], v[214:215]
	s_nop 0
	v_pk_fma_f32 v[194:195], v[212:213], v[196:197], v[194:195]
	v_pk_mul_f32 v[212:213], v[212:213], v[214:215]
	s_nop 0
	v_pk_fma_f32 v[196:197], v[210:211], v[196:197], v[212:213] neg_lo:[0,0,1] neg_hi:[0,0,1]
	v_lshlrev_b64 v[210:211], 12, v[170:171]
	v_lshl_add_u64 v[210:211], s[22:23], 0, v[210:211]
	v_lshl_add_u64 v[210:211], v[210:211], 0, s[10:11]
	v_lshl_add_u64 v[214:215], v[210:211], 0, v[188:189]
	v_cvt_pk_bf16_f32 v210, v146, v147
	v_cvt_pk_bf16_f32 v146, v190, v191
	v_cvt_pk_bf16_f32 v147, v194, v195
	global_store_dwordx4 v[214:215], v[144:147], off offset:64
	v_cvt_pk_bf16_f32 v211, v150, v151
	v_cvt_pk_bf16_f32 v212, v192, v193
	v_pk_mul_f32 v[146:147], v[94:95], v[94:95]
	v_mul_f32_e32 v145, v80, v80
	v_pk_mov_b32 v[150:151], v[148:149], v[146:147] op_sel:[1,0]
	v_mov_b32_e32 v149, v147
	v_pk_add_f32 v[146:147], v[150:151], v[148:149]
	v_pk_mul_f32 v[148:149], v[90:91], v[90:91]
	v_pk_mul_f32 v[150:151], v[88:89], v[88:89]
	v_pk_add_f32 v[146:147], v[146:147], v[146:147] op_sel:[0,1] op_sel_hi:[1,0]
	v_pk_mov_b32 v[190:191], v[150:151], v[148:149] op_sel:[1,0]
	v_mov_b32_e32 v151, v149
	v_pk_add_f32 v[148:149], v[190:191], v[150:151]
	v_mul_f32_e32 v150, v81, v81
	v_pk_add_f32 v[148:149], v[148:149], v[148:149] op_sel:[0,1] op_sel_hi:[1,0]
	v_mov_b32_e32 v147, v145
	v_mov_b32_e32 v149, v150
	v_pk_add_f32 v[146:147], v[146:147], v[148:149]
	v_mul_f32_e32 v148, v85, v85
	v_mul_f32_e32 v151, v82, v82
	v_pk_fma_f32 v[148:149], v[84:85], v[84:85], v[148:149] op_sel_hi:[1,1,0]
	v_mul_f32_e32 v150, v87, v87
	v_mul_f32_e32 v190, v83, v83
	v_mov_b32_e32 v149, v151
	v_pk_fma_f32 v[150:151], v[86:87], v[86:87], v[150:151] op_sel_hi:[1,1,0]
	v_cvt_pk_bf16_f32 v213, v196, v197
	v_mov_b32_e32 v151, v190
	v_pk_add_f32 v[148:149], v[148:149], v[150:151]
	v_or_b32_e32 v144, 32, v168
	v_pk_add_f32 v[146:147], v[146:147], v[148:149]
	global_store_dwordx4 v[214:215], v[210:213], off
	v_add_f32_e32 v145, v146, v147
	ds_bpermute_b32 v146, v208, v145
	v_bitop3_b32 v214, v168, s64, 32 bitop3:0xc8
	s_waitcnt lgkmcnt(0)
	v_add_f32_e32 v145, v145, v146
	ds_bpermute_b32 v146, v209, v145
	s_waitcnt lgkmcnt(0)
	v_add_f32_e32 v215, v145, v146
	v_ashrrev_i32_e32 v145, 31, v144
	v_lshlrev_b64 v[146:147], 6, v[144:145]
	v_lshl_add_u64 v[150:151], s[18:19], 0, v[146:147]
	s_nop 1
	ds_read_b32 v194, v253 offset:128
	v_mov_b32_e32 v195, 0
	v_mov_b32_e32 v196, 0
	v_mov_b32_e32 v197, 0
	v_mov_b32_e32 v146, 0
	v_mov_b32_e32 v147, 0
	v_mov_b32_e32 v148, 0
	v_mov_b32_e32 v149, 0
	v_mov_b32_e32 v210, 0
	v_mov_b32_e32 v211, 0
	v_mov_b32_e32 v212, 0
	v_mov_b32_e32 v213, 0
	v_mov_b32_e32 v190, 0
	v_mov_b32_e32 v191, 0
	v_mov_b32_e32 v192, 0
	v_mov_b32_e32 v193, 0
	s_waitcnt lgkmcnt(0)
	v_lshlrev_b64 v[144:145], 12, v[144:145]
	v_lshl_add_u64 v[144:145], s[22:23], 0, v[144:145]
	v_lshl_add_u64 v[144:145], v[144:145], 0, s[10:11]
	s_waitcnt vmcnt(1)
	v_mov_b32_e32 v150, v194
	s_waitcnt vmcnt(0)
;     __device__ __forceinline__ void operator()(const f32x4 (&acc)[2][2][4][2], const Unit& u, int wr, int wc, int fr, int fq) const {
;     ...
;                 const float rx = 1.0f / sqrtf(ssq_sum(ssq_in + (size_t)row * 16) * (1.0f / DM) + EPS);
;                 const float rs = (head < 8 ? qscale : 1.0f) * rx / sqrtf(s * rx * rx * (1.0f / 64.0f) + EPS);
;                 float o1[8], o2[8];
; #pragma unroll
;                 for (int n = 0; n < 2; ++n)
; #pragma unroll
;                     for (int e = 0; e < 4; ++e) {
;                         float cs, sn; rope_cs(pos, 8 * fq + 4 * n + e, cs, sn);
;                         const float x1 = acc[ai][0][m][n][e] * rs * gv[0][n][e], x2 = acc[ai][1][m][n][e] * rs * gv[1][n][e];
;                         o1[4 * n + e] = x1 * cs - x2 * sn; o2[4 * n + e] = x1 * sn + x2 * cs;
	v_mov_b32_e32 v151, v210
	v_mov_b32_e32 v210, v195
	v_mov_b32_e32 v194, v196
	v_mov_b32_e32 v195, v212
	v_mov_b32_e32 v212, v197
	v_pk_add_f32 v[150:151], v[150:151], v[210:211]
	v_pk_add_f32 v[194:195], v[194:195], v[212:213]
	s_nop 0
	v_pk_add_f32 v[150:151], v[150:151], v[194:195]
	v_mov_b32_e32 v194, v146
	v_mov_b32_e32 v195, v190
	v_mov_b32_e32 v190, v147
	v_pk_add_f32 v[146:147], v[194:195], v[190:191]
	v_mov_b32_e32 v190, v148
	v_mov_b32_e32 v191, v192
	v_mov_b32_e32 v192, v149
	v_pk_add_f32 v[148:149], v[190:191], v[192:193]
	s_nop 0
	v_pk_add_f32 v[146:147], v[146:147], v[148:149]
	s_nop 0
	v_pk_add_f32 v[146:147], v[150:151], v[146:147]
	s_nop 0
	v_add_f32_e32 v146, v146, v147
	v_fmamk_f32 v146, v146, 0x3a800000, v202
	v_cmp_gt_f32_e32 vcc, s62, v146
	v_mul_f32_e32 v147, 0x4f800000, v146
	s_nop 0
	v_cndmask_b32_e32 v146, v146, v147, vcc
	v_sqrt_f32_e32 v147, v146
	s_nop 0
	v_add_u32_e32 v148, -1, v147
	v_fma_f32 v149, -v148, v147, v146
	v_cmp_ge_f32_e64 s[8:9], 0, v149
	v_add_u32_e32 v149, 1, v147
	s_nop 0
	v_cndmask_b32_e64 v148, v147, v148, s[8:9]
	v_fma_f32 v147, -v149, v147, v146
	v_cmp_lt_f32_e64 s[8:9], 0, v147
	s_nop 1
	v_cndmask_b32_e64 v147, v148, v149, s[8:9]
	v_mul_f32_e32 v148, 0x37800000, v147
	v_cndmask_b32_e32 v147, v147, v148, vcc
	v_cmp_class_f32_e32 vcc, v146, v203
	s_nop 1
	v_cndmask_b32_e32 v146, v147, v146, vcc
	v_div_scale_f32 v147, s[0:1], v146, v146, 1.0
	v_rcp_f32_e32 v148, v147
	s_nop 0
	v_fma_f32 v149, -v147, v148, 1.0
	v_fmac_f32_e32 v148, v149, v148
	v_div_scale_f32 v149, vcc, 1.0, v146, 1.0
	v_mul_f32_e32 v150, v149, v148
	v_fma_f32 v151, -v147, v150, v149
	v_fmac_f32_e32 v150, v151, v148
	v_fma_f32 v147, -v147, v150, v149
	v_div_fmas_f32 v147, v147, v148, v150
	v_div_fixup_f32 v146, v147, v146, 1.0
	v_mul_f32_e32 v148, v215, v146
	v_mul_f32_e32 v147, v207, v146
	v_mul_f32_e32 v146, v146, v148
	v_fmamk_f32 v146, v146, 0x3c800000, v202
	v_cmp_gt_f32_e32 vcc, s62, v146
	v_mul_f32_e32 v148, 0x4f800000, v146
	s_nop 0
	v_cndmask_b32_e32 v146, v146, v148, vcc
	v_sqrt_f32_e32 v148, v146
	s_nop 0
	v_add_u32_e32 v149, -1, v148
	v_fma_f32 v150, -v149, v148, v146
	v_cmp_ge_f32_e64 s[8:9], 0, v150
	v_add_u32_e32 v150, 1, v148
	s_nop 0
	v_cndmask_b32_e64 v149, v148, v149, s[8:9]
	v_fma_f32 v148, -v150, v148, v146
	v_cmp_lt_f32_e64 s[8:9], 0, v148
	s_nop 1
	v_cndmask_b32_e64 v148, v149, v150, s[8:9]
	v_mul_f32_e32 v149, 0x37800000, v148
	v_cndmask_b32_e32 v148, v148, v149, vcc
	v_cmp_class_f32_e32 vcc, v146, v203
	s_nop 1
	v_cndmask_b32_e32 v146, v148, v146, vcc
	v_div_scale_f32 v148, s[0:1], v146, v146, v147
	v_rcp_f32_e32 v149, v148
	s_nop 0
	v_fma_f32 v150, -v148, v149, 1.0
	v_fmac_f32_e32 v149, v150, v149
	v_div_scale_f32 v150, vcc, v147, v146, v147
	v_mul_f32_e32 v151, v150, v149
	v_fma_f32 v190, -v148, v151, v150
	v_fmac_f32_e32 v151, v190, v149
	v_fma_f32 v148, -v148, v151, v150
	v_div_fmas_f32 v148, v148, v149, v151
	v_div_fixup_f32 v146, v148, v146, v147
	v_cvt_f64_u32_e32 v[148:149], v214
	v_mul_f64 v[150:151], v[172:173], v[148:149]
	v_rndne_f64_e32 v[150:151], v[150:151]
	v_mul_f64 v[192:193], v[174:175], v[148:149]
	v_fma_f64 v[150:151], v[172:173], v[148:149], -v[150:151]
	v_rndne_f64_e32 v[192:193], v[192:193]
	v_cvt_f32_f64_e32 v147, v[150:151]
	v_fma_f64 v[192:193], v[174:175], v[148:149], -v[192:193]
	v_cos_f32_e32 v150, v147
	v_sin_f32_e32 v190, v147
	v_cvt_f32_f64_e32 v147, v[192:193]
	v_pk_mul_f32 v[194:195], v[84:85], v[146:147] op_sel_hi:[1,0]
	v_cos_f32_e32 v151, v147
	v_sin_f32_e32 v191, v147
	v_pk_mul_f32 v[192:193], v[92:93], v[146:147] op_sel_hi:[1,0]
	v_pk_mul_f32 v[194:195], v[140:141], v[194:195]
	v_pk_mul_f32 v[192:193], v[136:137], v[192:193]
	v_pk_mul_f32 v[196:197], v[150:151], v[194:195]
	s_nop 0
	v_pk_fma_f32 v[196:197], v[190:191], v[192:193], v[196:197]
	v_pk_mul_f32 v[190:191], v[190:191], v[194:195]
	v_mul_f64 v[194:195], v[178:179], v[148:149]
	v_pk_fma_f32 v[150:151], v[150:151], v[192:193], v[190:191] neg_lo:[0,0,1] neg_hi:[0,0,1]
	v_mul_f64 v[190:191], v[176:177], v[148:149]
	v_rndne_f64_e32 v[190:191], v[190:191]
	v_fma_f64 v[190:191], v[176:177], v[148:149], -v[190:191]
	v_rndne_f64_e32 v[194:195], v[194:195]
	v_cvt_f32_f64_e32 v147, v[190:191]
	v_fma_f64 v[194:195], v[178:179], v[148:149], -v[194:195]
	v_cos_f32_e32 v190, v147
	v_sin_f32_e32 v192, v147
	v_cvt_f32_f64_e32 v147, v[194:195]
	v_pk_mul_f32 v[210:211], v[86:87], v[146:147] op_sel_hi:[1,0]
	v_cos_f32_e32 v191, v147
	v_sin_f32_e32 v193, v147
	v_pk_mul_f32 v[194:195], v[94:95], v[146:147] op_sel_hi:[1,0]
	v_pk_mul_f32 v[210:211], v[142:143], v[210:211]
	v_pk_mul_f32 v[194:195], v[138:139], v[194:195]
	v_pk_mul_f32 v[212:213], v[190:191], v[210:211]
	s_nop 0
	v_pk_fma_f32 v[212:213], v[192:193], v[194:195], v[212:213]
	v_pk_mul_f32 v[192:193], v[192:193], v[210:211]
	v_mul_f64 v[210:211], v[186:187], v[148:149]
	v_pk_fma_f32 v[190:191], v[190:191], v[194:195], v[192:193] neg_lo:[0,0,1] neg_hi:[0,0,1]
	v_mul_f64 v[192:193], v[184:185], v[148:149]
	v_rndne_f64_e32 v[192:193], v[192:193]
	v_fma_f64 v[192:193], v[184:185], v[148:149], -v[192:193]
	v_rndne_f64_e32 v[210:211], v[210:211]
	v_cvt_f32_f64_e32 v147, v[192:193]
	v_fma_f64 v[210:211], v[186:187], v[148:149], -v[210:211]
	v_cos_f32_e32 v192, v147
	v_sin_f32_e32 v194, v147
	v_cvt_f32_f64_e32 v147, v[210:211]
	v_pk_mul_f32 v[214:215], v[80:81], v[146:147] op_sel_hi:[1,0]
	v_cos_f32_e32 v193, v147
	v_sin_f32_e32 v195, v147
	v_pk_mul_f32 v[210:211], v[88:89], v[146:147] op_sel_hi:[1,0]
	v_pk_mul_f32 v[214:215], v[128:129], v[214:215]
	v_pk_mul_f32 v[210:211], v[132:133], v[210:211]
	v_pk_mul_f32 v[216:217], v[192:193], v[214:215]
	s_nop 0
; __device__ __forceinline__ unsigned cvtpk(float lo, float hi) { f32x2_t v = {lo, hi}; bf16x2_t b = __builtin_convertvector(v, bf16x2_t); return __builtin_bit_cast(unsigned, b); }
;     __device__ __forceinline__ void operator()(const f32x4 (&acc)[2][2][4][2], const Unit& u, int wr, int wc, int fr, int fq) const {
;     ...
;                 const int row = row0 + ai * HALF + m * 16; const int pos = row & (SEQ - 1);
;                 float s = 0.f;
; #pragma unroll
;                 for (int bj = 0; bj < 2; ++bj)
; #pragma unroll
;                     for (int n = 0; n < 2; ++n) { const f32x4 v = acc[ai][bj][m][n]; s += (v[0] * v[0] + v[1] * v[1]) + (v[2] * v[2] + v[3] * v[3]); }
;                 s += __shfl_xor(s, 16); s += __shfl_xor(s, 32);
;                 const float rx = 1.0f / sqrtf(ssq_sum(ssq_in + (size_t)row * 16) * (1.0f / DM) + EPS);
;                 const float rs = (head < 8 ? qscale : 1.0f) * rx / sqrtf(s * rx * rx * (1.0f / 64.0f) + EPS);
;                 float o1[8], o2[8];
; #pragma unroll
;                 for (int n = 0; n < 2; ++n)
; #pragma unroll
;                     for (int e = 0; e < 4; ++e) {
;                         float cs, sn; rope_cs(pos, 8 * fq + 4 * n + e, cs, sn);
;                         const float x1 = acc[ai][0][m][n][e] * rs * gv[0][n][e], x2 = acc[ai][1][m][n][e] * rs * gv[1][n][e];
;                         o1[4 * n + e] = x1 * cs - x2 * sn; o2[4 * n + e] = x1 * sn + x2 * cs;
;                     }
;                 bf16_t* op = O + (size_t)row * 2048 + head * 64 + 8 * fq;
;                 u32x4 w; w.x = cvtpk(o1[0], o1[1]); w.y = cvtpk(o1[2], o1[3]); w.z = cvtpk(o1[4], o1[5]); w.w = cvtpk(o1[6], o1[7]);
;                 *(u32x4*)op = w;
;                 w.x = cvtpk(o2[0], o2[1]); w.y = cvtpk(o2[2], o2[3]); w.z = cvtpk(o2[4], o2[5]); w.w = cvtpk(o2[6], o2[7]);
;                 *(u32x4*)(op + 32) = w;
	v_pk_fma_f32 v[216:217], v[194:195], v[210:211], v[216:217]
	v_pk_mul_f32 v[194:195], v[194:195], v[214:215]
	v_mul_f64 v[214:215], v[180:181], v[148:149]
	v_pk_fma_f32 v[192:193], v[192:193], v[210:211], v[194:195] neg_lo:[0,0,1] neg_hi:[0,0,1]
	v_mul_f64 v[194:195], v[182:183], v[148:149]
	v_rndne_f64_e32 v[194:195], v[194:195]
	v_fma_f64 v[194:195], v[182:183], v[148:149], -v[194:195]
	v_rndne_f64_e32 v[214:215], v[214:215]
	v_cvt_f32_f64_e32 v147, v[194:195]
	v_fma_f64 v[148:149], v[180:181], v[148:149], -v[214:215]
	v_cos_f32_e32 v194, v147
	v_sin_f32_e32 v210, v147
	v_cvt_f32_f64_e32 v147, v[148:149]
	v_cos_f32_e32 v195, v147
	v_sin_f32_e32 v211, v147
	v_pk_mul_f32 v[148:149], v[90:91], v[146:147] op_sel_hi:[1,0]
	v_pk_mul_f32 v[146:147], v[82:83], v[146:147] op_sel_hi:[1,0]
	v_pk_mul_f32 v[148:149], v[134:135], v[148:149]
	v_pk_mul_f32 v[146:147], v[130:131], v[146:147]
	s_nop 0
	v_pk_mul_f32 v[214:215], v[194:195], v[146:147]
	v_pk_mul_f32 v[146:147], v[210:211], v[146:147]
	v_pk_fma_f32 v[214:215], v[210:211], v[148:149], v[214:215]
	v_pk_fma_f32 v[148:149], v[194:195], v[148:149], v[146:147] neg_lo:[0,0,1] neg_hi:[0,0,1]
	v_lshl_add_u64 v[194:195], v[144:145], 0, v[188:189]
	v_cvt_pk_bf16_f32 v144, v150, v151
	v_cvt_pk_bf16_f32 v145, v190, v191
	v_cvt_pk_bf16_f32 v146, v192, v193
	v_cvt_pk_bf16_f32 v147, v148, v149
	global_store_dwordx4 v[194:195], v[144:147], off
	v_pk_mul_f32 v[148:149], v[76:77], v[76:77]
	s_nop 0
	v_cvt_pk_bf16_f32 v144, v196, v197
	v_cvt_pk_bf16_f32 v145, v212, v213
	v_cvt_pk_bf16_f32 v146, v216, v217
	v_cvt_pk_bf16_f32 v147, v214, v215
	global_store_dwordx4 v[194:195], v[144:147], off offset:64
	v_bitop3_b32 v214, v168, s65, 48 bitop3:0xc8
	s_nop 0
	v_pk_mul_f32 v[146:147], v[78:79], v[78:79]
	v_mul_f32_e32 v145, v64, v64
	v_pk_mov_b32 v[150:151], v[148:149], v[146:147] op_sel:[1,0]
	v_mov_b32_e32 v149, v147
	v_pk_add_f32 v[146:147], v[150:151], v[148:149]
	v_pk_mul_f32 v[148:149], v[74:75], v[74:75]
	v_pk_mul_f32 v[150:151], v[72:73], v[72:73]
	v_pk_add_f32 v[146:147], v[146:147], v[146:147] op_sel:[0,1] op_sel_hi:[1,0]
	v_pk_mov_b32 v[190:191], v[150:151], v[148:149] op_sel:[1,0]
	v_mov_b32_e32 v151, v149
	v_pk_add_f32 v[148:149], v[190:191], v[150:151]
	v_mul_f32_e32 v150, v65, v65
	v_pk_add_f32 v[148:149], v[148:149], v[148:149] op_sel:[0,1] op_sel_hi:[1,0]
	v_mov_b32_e32 v147, v145
	v_mov_b32_e32 v149, v150
	v_pk_add_f32 v[146:147], v[146:147], v[148:149]
	v_mul_f32_e32 v148, v69, v69
	v_mul_f32_e32 v151, v66, v66
	v_pk_fma_f32 v[148:149], v[68:69], v[68:69], v[148:149] op_sel_hi:[1,1,0]
	v_mul_f32_e32 v150, v71, v71
	v_mul_f32_e32 v190, v67, v67
	v_mov_b32_e32 v149, v151
	v_pk_fma_f32 v[150:151], v[70:71], v[70:71], v[150:151] op_sel_hi:[1,1,0]
	v_or_b32_e32 v144, 48, v168
	v_mov_b32_e32 v151, v190
	v_pk_add_f32 v[148:149], v[148:149], v[150:151]
	s_nop 0
	v_pk_add_f32 v[146:147], v[146:147], v[148:149]
	s_nop 0
	v_add_f32_e32 v145, v146, v147
	ds_bpermute_b32 v146, v208, v145
	s_waitcnt lgkmcnt(0)
	v_add_f32_e32 v145, v145, v146
	ds_bpermute_b32 v146, v209, v145
	s_waitcnt lgkmcnt(0)
	v_add_f32_e32 v215, v145, v146
	v_ashrrev_i32_e32 v145, 31, v144
	v_lshlrev_b64 v[146:147], 6, v[144:145]
	v_lshl_add_u64 v[150:151], s[18:19], 0, v[146:147]
	s_nop 1
	ds_read_b32 v194, v253 offset:192
	v_mov_b32_e32 v195, 0
	v_mov_b32_e32 v196, 0
	v_mov_b32_e32 v197, 0
	v_mov_b32_e32 v146, 0
	v_mov_b32_e32 v147, 0
	v_mov_b32_e32 v148, 0
	v_mov_b32_e32 v149, 0
	v_mov_b32_e32 v210, 0
	v_mov_b32_e32 v211, 0
	v_mov_b32_e32 v212, 0
	v_mov_b32_e32 v213, 0
	v_mov_b32_e32 v190, 0
	v_mov_b32_e32 v191, 0
	v_mov_b32_e32 v192, 0
	v_mov_b32_e32 v193, 0
	s_waitcnt lgkmcnt(0)
	v_lshlrev_b64 v[144:145], 12, v[144:145]
	v_lshl_add_u64 v[144:145], s[22:23], 0, v[144:145]
	v_lshl_add_u64 v[144:145], v[144:145], 0, s[10:11]
	s_waitcnt vmcnt(1)
	v_mov_b32_e32 v150, v194
	s_waitcnt vmcnt(0)
	v_mov_b32_e32 v151, v210
	v_mov_b32_e32 v210, v195
	v_mov_b32_e32 v194, v196
	v_mov_b32_e32 v195, v212
	v_mov_b32_e32 v212, v197
	v_pk_add_f32 v[150:151], v[150:151], v[210:211]
	v_pk_add_f32 v[194:195], v[194:195], v[212:213]
	s_nop 0
	v_pk_add_f32 v[150:151], v[150:151], v[194:195]
	v_mov_b32_e32 v194, v146
	v_mov_b32_e32 v195, v190
	v_mov_b32_e32 v190, v147
	v_pk_add_f32 v[146:147], v[194:195], v[190:191]
	v_mov_b32_e32 v190, v148
	v_mov_b32_e32 v191, v192
	v_mov_b32_e32 v192, v149
	v_pk_add_f32 v[148:149], v[190:191], v[192:193]
	s_nop 0
	v_pk_add_f32 v[146:147], v[146:147], v[148:149]
	s_nop 0
	v_pk_add_f32 v[146:147], v[150:151], v[146:147]
	s_nop 0
	v_add_f32_e32 v146, v146, v147
	v_fmamk_f32 v146, v146, 0x3a800000, v202
	v_cmp_gt_f32_e32 vcc, s62, v146
	v_mul_f32_e32 v147, 0x4f800000, v146
	s_nop 0
	v_cndmask_b32_e32 v146, v146, v147, vcc
	v_sqrt_f32_e32 v147, v146
	s_nop 0
	v_add_u32_e32 v148, -1, v147
	v_fma_f32 v149, -v148, v147, v146
	v_cmp_ge_f32_e64 s[8:9], 0, v149
	v_add_u32_e32 v149, 1, v147
	s_nop 0
	v_cndmask_b32_e64 v148, v147, v148, s[8:9]
	v_fma_f32 v147, -v149, v147, v146
	v_cmp_lt_f32_e64 s[8:9], 0, v147
	s_nop 1
	v_cndmask_b32_e64 v147, v148, v149, s[8:9]
	v_mul_f32_e32 v148, 0x37800000, v147
	v_cndmask_b32_e32 v147, v147, v148, vcc
	v_cmp_class_f32_e32 vcc, v146, v203
	s_nop 1
	v_cndmask_b32_e32 v146, v147, v146, vcc
	v_div_scale_f32 v147, s[0:1], v146, v146, 1.0
	v_rcp_f32_e32 v148, v147
	s_nop 0
	v_fma_f32 v149, -v147, v148, 1.0
	v_fmac_f32_e32 v148, v149, v148
	v_div_scale_f32 v149, vcc, 1.0, v146, 1.0
	v_mul_f32_e32 v150, v149, v148
	v_fma_f32 v151, -v147, v150, v149
	v_fmac_f32_e32 v150, v151, v148
	v_fma_f32 v147, -v147, v150, v149
	v_div_fmas_f32 v147, v147, v148, v150
	v_div_fixup_f32 v146, v147, v146, 1.0
; __device__ __forceinline__ unsigned cvtpk(float lo, float hi) { f32x2_t v = {lo, hi}; bf16x2_t b = __builtin_convertvector(v, bf16x2_t); return __builtin_bit_cast(unsigned, b); }
;     __device__ __forceinline__ void operator()(const f32x4 (&acc)[2][2][4][2], const Unit& u, int wr, int wc, int fr, int fq) const {
;     ...
;                 const float rx = 1.0f / sqrtf(ssq_sum(ssq_in + (size_t)row * 16) * (1.0f / DM) + EPS);
;                 const float rs = (head < 8 ? qscale : 1.0f) * rx / sqrtf(s * rx * rx * (1.0f / 64.0f) + EPS);
;                 float o1[8], o2[8];
; #pragma unroll
;                 for (int n = 0; n < 2; ++n)
; #pragma unroll
;                     for (int e = 0; e < 4; ++e) {
;                         float cs, sn; rope_cs(pos, 8 * fq + 4 * n + e, cs, sn);
;                         const float x1 = acc[ai][0][m][n][e] * rs * gv[0][n][e], x2 = acc[ai][1][m][n][e] * rs * gv[1][n][e];
;                         o1[4 * n + e] = x1 * cs - x2 * sn; o2[4 * n + e] = x1 * sn + x2 * cs;
;                     }
;                 bf16_t* op = O + (size_t)row * 2048 + head * 64 + 8 * fq;
;                 u32x4 w; w.x = cvtpk(o1[0], o1[1]); w.y = cvtpk(o1[2], o1[3]); w.z = cvtpk(o1[4], o1[5]); w.w = cvtpk(o1[6], o1[7]);
;                 *(u32x4*)op = w;
;                 w.x = cvtpk(o2[0], o2[1]); w.y = cvtpk(o2[2], o2[3]); w.z = cvtpk(o2[4], o2[5]); w.w = cvtpk(o2[6], o2[7]);
;                 *(u32x4*)(op + 32) = w;
	v_mul_f32_e32 v148, v215, v146
	v_mul_f32_e32 v147, v207, v146
	v_mul_f32_e32 v146, v146, v148
	v_fmamk_f32 v146, v146, 0x3c800000, v202
	v_cmp_gt_f32_e32 vcc, s62, v146
	v_mul_f32_e32 v148, 0x4f800000, v146
	s_nop 0
	v_cndmask_b32_e32 v146, v146, v148, vcc
	v_sqrt_f32_e32 v148, v146
	s_nop 0
	v_add_u32_e32 v149, -1, v148
	v_fma_f32 v150, -v149, v148, v146
	v_cmp_ge_f32_e64 s[8:9], 0, v150
	v_add_u32_e32 v150, 1, v148
	s_nop 0
	v_cndmask_b32_e64 v149, v148, v149, s[8:9]
	v_fma_f32 v148, -v150, v148, v146
	v_cmp_lt_f32_e64 s[8:9], 0, v148
	s_nop 1
	v_cndmask_b32_e64 v148, v149, v150, s[8:9]
	v_mul_f32_e32 v149, 0x37800000, v148
	v_cndmask_b32_e32 v148, v148, v149, vcc
	v_cmp_class_f32_e32 vcc, v146, v203
	s_nop 1
	v_cndmask_b32_e32 v146, v148, v146, vcc
	v_div_scale_f32 v148, s[0:1], v146, v146, v147
	v_rcp_f32_e32 v149, v148
	s_nop 0
	v_fma_f32 v150, -v148, v149, 1.0
	v_fmac_f32_e32 v149, v150, v149
	v_div_scale_f32 v150, vcc, v147, v146, v147
	v_mul_f32_e32 v151, v150, v149
	v_fma_f32 v190, -v148, v151, v150
	v_fmac_f32_e32 v151, v190, v149
	v_fma_f32 v148, -v148, v151, v150
	v_div_fmas_f32 v148, v148, v149, v151
	v_div_fixup_f32 v146, v148, v146, v147
	v_cvt_f64_u32_e32 v[148:149], v214
	v_mul_f64 v[150:151], v[172:173], v[148:149]
	v_rndne_f64_e32 v[150:151], v[150:151]
	v_mul_f64 v[192:193], v[174:175], v[148:149]
	v_fma_f64 v[150:151], v[172:173], v[148:149], -v[150:151]
	v_rndne_f64_e32 v[192:193], v[192:193]
	v_cvt_f32_f64_e32 v147, v[150:151]
	v_fma_f64 v[192:193], v[174:175], v[148:149], -v[192:193]
	v_cos_f32_e32 v150, v147
	v_sin_f32_e32 v190, v147
	v_cvt_f32_f64_e32 v147, v[192:193]
	v_pk_mul_f32 v[194:195], v[68:69], v[146:147] op_sel_hi:[1,0]
	v_cos_f32_e32 v151, v147
	v_sin_f32_e32 v191, v147
	v_pk_mul_f32 v[192:193], v[76:77], v[146:147] op_sel_hi:[1,0]
	v_pk_mul_f32 v[194:195], v[140:141], v[194:195]
	v_pk_mul_f32 v[192:193], v[136:137], v[192:193]
	v_pk_mul_f32 v[196:197], v[150:151], v[194:195]
	s_nop 0
	v_pk_fma_f32 v[196:197], v[190:191], v[192:193], v[196:197]
	v_pk_mul_f32 v[190:191], v[190:191], v[194:195]
	v_mul_f64 v[194:195], v[178:179], v[148:149]
	v_pk_fma_f32 v[150:151], v[150:151], v[192:193], v[190:191] neg_lo:[0,0,1] neg_hi:[0,0,1]
	v_mul_f64 v[190:191], v[176:177], v[148:149]
	v_rndne_f64_e32 v[190:191], v[190:191]
	v_fma_f64 v[190:191], v[176:177], v[148:149], -v[190:191]
	v_rndne_f64_e32 v[194:195], v[194:195]
	v_cvt_f32_f64_e32 v147, v[190:191]
	v_fma_f64 v[194:195], v[178:179], v[148:149], -v[194:195]
	v_cos_f32_e32 v190, v147
	v_sin_f32_e32 v192, v147
	v_cvt_f32_f64_e32 v147, v[194:195]
	v_pk_mul_f32 v[210:211], v[70:71], v[146:147] op_sel_hi:[1,0]
	v_cos_f32_e32 v191, v147
	v_sin_f32_e32 v193, v147
	v_pk_mul_f32 v[194:195], v[78:79], v[146:147] op_sel_hi:[1,0]
	v_pk_mul_f32 v[210:211], v[142:143], v[210:211]
	v_pk_mul_f32 v[194:195], v[138:139], v[194:195]
	v_pk_mul_f32 v[212:213], v[190:191], v[210:211]
	s_nop 0
	v_pk_fma_f32 v[212:213], v[192:193], v[194:195], v[212:213]
	v_pk_mul_f32 v[192:193], v[192:193], v[210:211]
	v_mul_f64 v[210:211], v[186:187], v[148:149]
	v_pk_fma_f32 v[190:191], v[190:191], v[194:195], v[192:193] neg_lo:[0,0,1] neg_hi:[0,0,1]
	v_mul_f64 v[192:193], v[184:185], v[148:149]
	v_rndne_f64_e32 v[192:193], v[192:193]
	v_fma_f64 v[192:193], v[184:185], v[148:149], -v[192:193]
	v_rndne_f64_e32 v[210:211], v[210:211]
	v_cvt_f32_f64_e32 v147, v[192:193]
	v_fma_f64 v[210:211], v[186:187], v[148:149], -v[210:211]
	v_cos_f32_e32 v192, v147
	v_sin_f32_e32 v194, v147
	v_cvt_f32_f64_e32 v147, v[210:211]
	v_pk_mul_f32 v[214:215], v[64:65], v[146:147] op_sel_hi:[1,0]
	v_cos_f32_e32 v193, v147
	v_sin_f32_e32 v195, v147
	v_pk_mul_f32 v[210:211], v[72:73], v[146:147] op_sel_hi:[1,0]
	v_pk_mul_f32 v[214:215], v[128:129], v[214:215]
	v_pk_mul_f32 v[210:211], v[132:133], v[210:211]
	v_pk_mul_f32 v[216:217], v[192:193], v[214:215]
	s_nop 0
	v_pk_fma_f32 v[216:217], v[194:195], v[210:211], v[216:217]
	v_pk_mul_f32 v[194:195], v[194:195], v[214:215]
	v_mul_f64 v[214:215], v[180:181], v[148:149]
	v_pk_fma_f32 v[192:193], v[192:193], v[210:211], v[194:195] neg_lo:[0,0,1] neg_hi:[0,0,1]
	v_mul_f64 v[194:195], v[182:183], v[148:149]
	v_rndne_f64_e32 v[194:195], v[194:195]
	v_fma_f64 v[194:195], v[182:183], v[148:149], -v[194:195]
	v_rndne_f64_e32 v[214:215], v[214:215]
	v_cvt_f32_f64_e32 v147, v[194:195]
	v_fma_f64 v[148:149], v[180:181], v[148:149], -v[214:215]
	v_cos_f32_e32 v194, v147
	v_sin_f32_e32 v210, v147
	v_cvt_f32_f64_e32 v147, v[148:149]
	v_cos_f32_e32 v195, v147
	v_sin_f32_e32 v211, v147
	v_pk_mul_f32 v[148:149], v[74:75], v[146:147] op_sel_hi:[1,0]
	v_pk_mul_f32 v[146:147], v[66:67], v[146:147] op_sel_hi:[1,0]
	v_pk_mul_f32 v[148:149], v[134:135], v[148:149]
	v_pk_mul_f32 v[146:147], v[130:131], v[146:147]
	s_nop 0
	v_pk_mul_f32 v[214:215], v[194:195], v[146:147]
	v_pk_mul_f32 v[146:147], v[210:211], v[146:147]
	v_pk_fma_f32 v[214:215], v[210:211], v[148:149], v[214:215]
	v_pk_fma_f32 v[148:149], v[194:195], v[148:149], v[146:147] neg_lo:[0,0,1] neg_hi:[0,0,1]
	v_lshl_add_u64 v[194:195], v[144:145], 0, v[188:189]
	v_cvt_pk_bf16_f32 v144, v150, v151
	v_cvt_pk_bf16_f32 v145, v190, v191
	v_cvt_pk_bf16_f32 v146, v192, v193
	v_cvt_pk_bf16_f32 v147, v148, v149
	global_store_dwordx4 v[194:195], v[144:147], off
	v_pk_mul_f32 v[148:149], v[60:61], v[60:61]
	s_nop 0
	v_cvt_pk_bf16_f32 v144, v196, v197
	v_cvt_pk_bf16_f32 v145, v212, v213
	v_cvt_pk_bf16_f32 v146, v216, v217
	v_cvt_pk_bf16_f32 v147, v214, v215
	global_store_dwordx4 v[194:195], v[144:147], off offset:64
	s_nop 1
	v_pk_mul_f32 v[146:147], v[62:63], v[62:63]
	v_mul_f32_e32 v145, v48, v48
	v_pk_mov_b32 v[150:151], v[148:149], v[146:147] op_sel:[1,0]
	v_mov_b32_e32 v149, v147
	v_pk_add_f32 v[146:147], v[150:151], v[148:149]
	v_pk_mul_f32 v[148:149], v[58:59], v[58:59]
	v_pk_mul_f32 v[150:151], v[56:57], v[56:57]
	v_pk_add_f32 v[146:147], v[146:147], v[146:147] op_sel:[0,1] op_sel_hi:[1,0]
	v_pk_mov_b32 v[190:191], v[150:151], v[148:149] op_sel:[1,0]
	v_mov_b32_e32 v151, v149
	v_pk_add_f32 v[148:149], v[190:191], v[150:151]
	v_mul_f32_e32 v150, v49, v49
	v_pk_add_f32 v[148:149], v[148:149], v[148:149] op_sel:[0,1] op_sel_hi:[1,0]
	v_mov_b32_e32 v147, v145
	v_mov_b32_e32 v149, v150
	v_pk_add_f32 v[146:147], v[146:147], v[148:149]
	v_mul_f32_e32 v148, v53, v53
	v_mul_f32_e32 v151, v50, v50
	v_pk_fma_f32 v[148:149], v[52:53], v[52:53], v[148:149] op_sel_hi:[1,1,0]
	v_mul_f32_e32 v150, v55, v55
	v_mul_f32_e32 v190, v51, v51
	v_mov_b32_e32 v149, v151
	v_pk_fma_f32 v[150:151], v[54:55], v[54:55], v[150:151] op_sel_hi:[1,1,0]
	v_add_u32_e32 v144, 0x80, v168
	v_mov_b32_e32 v151, v190
	v_pk_add_f32 v[148:149], v[148:149], v[150:151]
	v_and_b32_e32 v214, 0xfcf, v144
	v_pk_add_f32 v[146:147], v[146:147], v[148:149]
	s_nop 0
	v_add_f32_e32 v145, v146, v147
	ds_bpermute_b32 v146, v208, v145
	s_waitcnt lgkmcnt(0)
;     __device__ __forceinline__ void operator()(const f32x4 (&acc)[2][2][4][2], const Unit& u, int wr, int wc, int fr, int fq) const {
;     ...
;                 s += __shfl_xor(s, 16); s += __shfl_xor(s, 32);
;                 const float rx = 1.0f / sqrtf(ssq_sum(ssq_in + (size_t)row * 16) * (1.0f / DM) + EPS);
;                 const float rs = (head < 8 ? qscale : 1.0f) * rx / sqrtf(s * rx * rx * (1.0f / 64.0f) + EPS);
;                 float o1[8], o2[8];
; #pragma unroll
;                 for (int n = 0; n < 2; ++n)
; #pragma unroll
;                     for (int e = 0; e < 4; ++e) {
;                         float cs, sn; rope_cs(pos, 8 * fq + 4 * n + e, cs, sn);
;                         const float x1 = acc[ai][0][m][n][e] * rs * gv[0][n][e], x2 = acc[ai][1][m][n][e] * rs * gv[1][n][e];
;                         o1[4 * n + e] = x1 * cs - x2 * sn; o2[4 * n + e] = x1 * sn + x2 * cs;
	v_add_f32_e32 v145, v145, v146
	ds_bpermute_b32 v146, v209, v145
	s_waitcnt lgkmcnt(0)
	v_add_f32_e32 v215, v145, v146
	v_ashrrev_i32_e32 v145, 31, v144
	v_lshlrev_b64 v[146:147], 6, v[144:145]
	v_lshl_add_u64 v[150:151], s[18:19], 0, v[146:147]
	s_nop 1
	ds_read_b32 v194, v253 offset:512
	v_mov_b32_e32 v195, 0
	v_mov_b32_e32 v196, 0
	v_mov_b32_e32 v197, 0
	v_mov_b32_e32 v146, 0
	v_mov_b32_e32 v147, 0
	v_mov_b32_e32 v148, 0
	v_mov_b32_e32 v149, 0
	v_mov_b32_e32 v210, 0
	v_mov_b32_e32 v211, 0
	v_mov_b32_e32 v212, 0
	v_mov_b32_e32 v213, 0
	v_mov_b32_e32 v190, 0
	v_mov_b32_e32 v191, 0
	v_mov_b32_e32 v192, 0
	v_mov_b32_e32 v193, 0
	s_waitcnt lgkmcnt(0)
	v_lshlrev_b64 v[144:145], 12, v[144:145]
	v_lshl_add_u64 v[144:145], s[22:23], 0, v[144:145]
	v_lshl_add_u64 v[144:145], v[144:145], 0, s[10:11]
	s_waitcnt vmcnt(1)
	v_mov_b32_e32 v150, v194
	s_waitcnt vmcnt(0)
	v_mov_b32_e32 v151, v210
	v_mov_b32_e32 v210, v195
	v_mov_b32_e32 v194, v196
	v_mov_b32_e32 v195, v212
	v_mov_b32_e32 v212, v197
	v_pk_add_f32 v[150:151], v[150:151], v[210:211]
	v_pk_add_f32 v[194:195], v[194:195], v[212:213]
	s_nop 0
	v_pk_add_f32 v[150:151], v[150:151], v[194:195]
	v_mov_b32_e32 v194, v146
	v_mov_b32_e32 v195, v190
	v_mov_b32_e32 v190, v147
	v_pk_add_f32 v[146:147], v[194:195], v[190:191]
	v_mov_b32_e32 v190, v148
	v_mov_b32_e32 v191, v192
	v_mov_b32_e32 v192, v149
	v_pk_add_f32 v[148:149], v[190:191], v[192:193]
	s_nop 0
	v_pk_add_f32 v[146:147], v[146:147], v[148:149]
	s_nop 0
	v_pk_add_f32 v[146:147], v[150:151], v[146:147]
	s_nop 0
	v_add_f32_e32 v146, v146, v147
	v_fmamk_f32 v146, v146, 0x3a800000, v202
	v_cmp_gt_f32_e32 vcc, s62, v146
	v_mul_f32_e32 v147, 0x4f800000, v146
	s_nop 0
	v_cndmask_b32_e32 v146, v146, v147, vcc
	v_sqrt_f32_e32 v147, v146
	s_nop 0
	v_add_u32_e32 v148, -1, v147
	v_fma_f32 v149, -v148, v147, v146
	v_cmp_ge_f32_e64 s[8:9], 0, v149
	v_add_u32_e32 v149, 1, v147
	s_nop 0
	v_cndmask_b32_e64 v148, v147, v148, s[8:9]
	v_fma_f32 v147, -v149, v147, v146
	v_cmp_lt_f32_e64 s[8:9], 0, v147
	s_nop 1
	v_cndmask_b32_e64 v147, v148, v149, s[8:9]
	v_mul_f32_e32 v148, 0x37800000, v147
	v_cndmask_b32_e32 v147, v147, v148, vcc
	v_cmp_class_f32_e32 vcc, v146, v203
	s_nop 1
	v_cndmask_b32_e32 v146, v147, v146, vcc
	v_div_scale_f32 v147, s[0:1], v146, v146, 1.0
	v_rcp_f32_e32 v148, v147
	s_nop 0
	v_fma_f32 v149, -v147, v148, 1.0
	v_fmac_f32_e32 v148, v149, v148
	v_div_scale_f32 v149, vcc, 1.0, v146, 1.0
	v_mul_f32_e32 v150, v149, v148
	v_fma_f32 v151, -v147, v150, v149
	v_fmac_f32_e32 v150, v151, v148
	v_fma_f32 v147, -v147, v150, v149
	v_div_fmas_f32 v147, v147, v148, v150
	v_div_fixup_f32 v146, v147, v146, 1.0
	v_mul_f32_e32 v148, v215, v146
	v_mul_f32_e32 v147, v207, v146
	v_mul_f32_e32 v146, v146, v148
	v_fmamk_f32 v146, v146, 0x3c800000, v202
	v_cmp_gt_f32_e32 vcc, s62, v146
	v_mul_f32_e32 v148, 0x4f800000, v146
	s_nop 0
	v_cndmask_b32_e32 v146, v146, v148, vcc
	v_sqrt_f32_e32 v148, v146
	s_nop 0
	v_add_u32_e32 v149, -1, v148
	v_fma_f32 v150, -v149, v148, v146
	v_cmp_ge_f32_e64 s[8:9], 0, v150
	v_add_u32_e32 v150, 1, v148
	s_nop 0
	v_cndmask_b32_e64 v149, v148, v149, s[8:9]
	v_fma_f32 v148, -v150, v148, v146
	v_cmp_lt_f32_e64 s[8:9], 0, v148
	s_nop 1
	v_cndmask_b32_e64 v148, v149, v150, s[8:9]
	v_mul_f32_e32 v149, 0x37800000, v148
	v_cndmask_b32_e32 v148, v148, v149, vcc
	v_cmp_class_f32_e32 vcc, v146, v203
	s_nop 1
	v_cndmask_b32_e32 v146, v148, v146, vcc
	v_div_scale_f32 v148, s[0:1], v146, v146, v147
	v_rcp_f32_e32 v149, v148
	s_nop 0
	v_fma_f32 v150, -v148, v149, 1.0
	v_fmac_f32_e32 v149, v150, v149
	v_div_scale_f32 v150, vcc, v147, v146, v147
	v_mul_f32_e32 v151, v150, v149
	v_fma_f32 v190, -v148, v151, v150
	v_fmac_f32_e32 v151, v190, v149
	v_fma_f32 v148, -v148, v151, v150
	v_div_fmas_f32 v148, v148, v149, v151
	v_div_fixup_f32 v146, v148, v146, v147
	v_cvt_f64_u32_e32 v[148:149], v214
	v_mul_f64 v[150:151], v[172:173], v[148:149]
	v_rndne_f64_e32 v[150:151], v[150:151]
	v_mul_f64 v[192:193], v[174:175], v[148:149]
	v_fma_f64 v[150:151], v[172:173], v[148:149], -v[150:151]
	v_rndne_f64_e32 v[192:193], v[192:193]
	v_cvt_f32_f64_e32 v147, v[150:151]
	v_fma_f64 v[192:193], v[174:175], v[148:149], -v[192:193]
	v_cos_f32_e32 v150, v147
	v_sin_f32_e32 v190, v147
	v_cvt_f32_f64_e32 v147, v[192:193]
	v_pk_mul_f32 v[194:195], v[52:53], v[146:147] op_sel_hi:[1,0]
	v_cos_f32_e32 v151, v147
	v_sin_f32_e32 v191, v147
	v_pk_mul_f32 v[192:193], v[60:61], v[146:147] op_sel_hi:[1,0]
	v_pk_mul_f32 v[194:195], v[140:141], v[194:195]
	v_pk_mul_f32 v[192:193], v[136:137], v[192:193]
	v_pk_mul_f32 v[196:197], v[150:151], v[194:195]
	s_nop 0
	v_pk_fma_f32 v[196:197], v[190:191], v[192:193], v[196:197]
	v_pk_mul_f32 v[190:191], v[190:191], v[194:195]
	v_mul_f64 v[194:195], v[178:179], v[148:149]
	v_pk_fma_f32 v[150:151], v[150:151], v[192:193], v[190:191] neg_lo:[0,0,1] neg_hi:[0,0,1]
	v_mul_f64 v[190:191], v[176:177], v[148:149]
	v_rndne_f64_e32 v[190:191], v[190:191]
	v_fma_f64 v[190:191], v[176:177], v[148:149], -v[190:191]
	v_rndne_f64_e32 v[194:195], v[194:195]
	v_cvt_f32_f64_e32 v147, v[190:191]
	v_fma_f64 v[194:195], v[178:179], v[148:149], -v[194:195]
	v_cos_f32_e32 v190, v147
	v_sin_f32_e32 v192, v147
	v_cvt_f32_f64_e32 v147, v[194:195]
	v_pk_mul_f32 v[210:211], v[54:55], v[146:147] op_sel_hi:[1,0]
	v_cos_f32_e32 v191, v147
	v_sin_f32_e32 v193, v147
	v_pk_mul_f32 v[194:195], v[62:63], v[146:147] op_sel_hi:[1,0]
	v_pk_mul_f32 v[210:211], v[142:143], v[210:211]
	v_pk_mul_f32 v[194:195], v[138:139], v[194:195]
	v_pk_mul_f32 v[212:213], v[190:191], v[210:211]
	s_nop 0
	v_pk_fma_f32 v[212:213], v[192:193], v[194:195], v[212:213]
	v_pk_mul_f32 v[192:193], v[192:193], v[210:211]
; __device__ __forceinline__ unsigned cvtpk(float lo, float hi) { f32x2_t v = {lo, hi}; bf16x2_t b = __builtin_convertvector(v, bf16x2_t); return __builtin_bit_cast(unsigned, b); }
;     __device__ __forceinline__ void operator()(const f32x4 (&acc)[2][2][4][2], const Unit& u, int wr, int wc, int fr, int fq) const {
;     ...
;                 const int row = row0 + ai * HALF + m * 16; const int pos = row & (SEQ - 1);
;                 float s = 0.f;
; #pragma unroll
;                 for (int bj = 0; bj < 2; ++bj)
; #pragma unroll
;                     for (int n = 0; n < 2; ++n) { const f32x4 v = acc[ai][bj][m][n]; s += (v[0] * v[0] + v[1] * v[1]) + (v[2] * v[2] + v[3] * v[3]); }
;                 s += __shfl_xor(s, 16); s += __shfl_xor(s, 32);
;                 const float rx = 1.0f / sqrtf(ssq_sum(ssq_in + (size_t)row * 16) * (1.0f / DM) + EPS);
;                 const float rs = (head < 8 ? qscale : 1.0f) * rx / sqrtf(s * rx * rx * (1.0f / 64.0f) + EPS);
;     ...
;                         float cs, sn; rope_cs(pos, 8 * fq + 4 * n + e, cs, sn);
;                         const float x1 = acc[ai][0][m][n][e] * rs * gv[0][n][e], x2 = acc[ai][1][m][n][e] * rs * gv[1][n][e];
;                         o1[4 * n + e] = x1 * cs - x2 * sn; o2[4 * n + e] = x1 * sn + x2 * cs;
;                     }
;                 bf16_t* op = O + (size_t)row * 2048 + head * 64 + 8 * fq;
;                 u32x4 w; w.x = cvtpk(o1[0], o1[1]); w.y = cvtpk(o1[2], o1[3]); w.z = cvtpk(o1[4], o1[5]); w.w = cvtpk(o1[6], o1[7]);
;                 *(u32x4*)op = w;
;                 w.x = cvtpk(o2[0], o2[1]); w.y = cvtpk(o2[2], o2[3]); w.z = cvtpk(o2[4], o2[5]); w.w = cvtpk(o2[6], o2[7]);
;                 *(u32x4*)(op + 32) = w;
	v_mul_f64 v[210:211], v[186:187], v[148:149]
	v_pk_fma_f32 v[190:191], v[190:191], v[194:195], v[192:193] neg_lo:[0,0,1] neg_hi:[0,0,1]
	v_mul_f64 v[192:193], v[184:185], v[148:149]
	v_rndne_f64_e32 v[192:193], v[192:193]
	v_fma_f64 v[192:193], v[184:185], v[148:149], -v[192:193]
	v_rndne_f64_e32 v[210:211], v[210:211]
	v_cvt_f32_f64_e32 v147, v[192:193]
	v_fma_f64 v[210:211], v[186:187], v[148:149], -v[210:211]
	v_cos_f32_e32 v192, v147
	v_sin_f32_e32 v194, v147
	v_cvt_f32_f64_e32 v147, v[210:211]
	v_pk_mul_f32 v[214:215], v[48:49], v[146:147] op_sel_hi:[1,0]
	v_cos_f32_e32 v193, v147
	v_sin_f32_e32 v195, v147
	v_pk_mul_f32 v[210:211], v[56:57], v[146:147] op_sel_hi:[1,0]
	v_pk_mul_f32 v[214:215], v[128:129], v[214:215]
	v_pk_mul_f32 v[210:211], v[132:133], v[210:211]
	v_pk_mul_f32 v[216:217], v[192:193], v[214:215]
	s_nop 0
	v_pk_fma_f32 v[216:217], v[194:195], v[210:211], v[216:217]
	v_pk_mul_f32 v[194:195], v[194:195], v[214:215]
	v_mul_f64 v[214:215], v[180:181], v[148:149]
	v_pk_fma_f32 v[192:193], v[192:193], v[210:211], v[194:195] neg_lo:[0,0,1] neg_hi:[0,0,1]
	v_mul_f64 v[194:195], v[182:183], v[148:149]
	v_rndne_f64_e32 v[194:195], v[194:195]
	v_fma_f64 v[194:195], v[182:183], v[148:149], -v[194:195]
	v_rndne_f64_e32 v[214:215], v[214:215]
	v_cvt_f32_f64_e32 v147, v[194:195]
	v_fma_f64 v[148:149], v[180:181], v[148:149], -v[214:215]
	v_cos_f32_e32 v194, v147
	v_sin_f32_e32 v210, v147
	v_cvt_f32_f64_e32 v147, v[148:149]
	v_cos_f32_e32 v195, v147
	v_sin_f32_e32 v211, v147
	v_pk_mul_f32 v[148:149], v[58:59], v[146:147] op_sel_hi:[1,0]
	v_pk_mul_f32 v[146:147], v[50:51], v[146:147] op_sel_hi:[1,0]
	v_pk_mul_f32 v[148:149], v[134:135], v[148:149]
	v_pk_mul_f32 v[146:147], v[130:131], v[146:147]
	s_nop 0
	v_pk_mul_f32 v[214:215], v[194:195], v[146:147]
	v_pk_mul_f32 v[146:147], v[210:211], v[146:147]
	v_pk_fma_f32 v[214:215], v[210:211], v[148:149], v[214:215]
	v_pk_fma_f32 v[148:149], v[194:195], v[148:149], v[146:147] neg_lo:[0,0,1] neg_hi:[0,0,1]
	v_lshl_add_u64 v[194:195], v[144:145], 0, v[188:189]
	v_cvt_pk_bf16_f32 v144, v150, v151
	v_cvt_pk_bf16_f32 v145, v190, v191
	v_cvt_pk_bf16_f32 v146, v192, v193
	v_cvt_pk_bf16_f32 v147, v148, v149
	global_store_dwordx4 v[194:195], v[144:147], off
	v_pk_mul_f32 v[148:149], v[44:45], v[44:45]
	s_nop 0
	v_cvt_pk_bf16_f32 v144, v196, v197
	v_cvt_pk_bf16_f32 v145, v212, v213
	v_cvt_pk_bf16_f32 v146, v216, v217
	v_cvt_pk_bf16_f32 v147, v214, v215
	global_store_dwordx4 v[194:195], v[144:147], off offset:64
	s_nop 1
	v_pk_mul_f32 v[146:147], v[46:47], v[46:47]
	v_mul_f32_e32 v145, v32, v32
	v_pk_mov_b32 v[150:151], v[148:149], v[146:147] op_sel:[1,0]
	v_mov_b32_e32 v149, v147
	v_pk_add_f32 v[146:147], v[150:151], v[148:149]
	v_pk_mul_f32 v[148:149], v[42:43], v[42:43]
	v_pk_mul_f32 v[150:151], v[40:41], v[40:41]
	v_pk_add_f32 v[146:147], v[146:147], v[146:147] op_sel:[0,1] op_sel_hi:[1,0]
	v_pk_mov_b32 v[190:191], v[150:151], v[148:149] op_sel:[1,0]
	v_mov_b32_e32 v151, v149
	v_pk_add_f32 v[148:149], v[190:191], v[150:151]
	v_mul_f32_e32 v150, v33, v33
	v_pk_add_f32 v[148:149], v[148:149], v[148:149] op_sel:[0,1] op_sel_hi:[1,0]
	v_mov_b32_e32 v147, v145
	v_mov_b32_e32 v149, v150
	v_pk_add_f32 v[146:147], v[146:147], v[148:149]
	v_mul_f32_e32 v148, v37, v37
	v_mul_f32_e32 v151, v34, v34
	v_pk_fma_f32 v[148:149], v[36:37], v[36:37], v[148:149] op_sel_hi:[1,1,0]
	v_mul_f32_e32 v150, v39, v39
	v_mul_f32_e32 v190, v35, v35
	v_mov_b32_e32 v149, v151
	v_pk_fma_f32 v[150:151], v[38:39], v[38:39], v[150:151] op_sel_hi:[1,1,0]
	v_add_u32_e32 v144, 0x90, v168
	v_mov_b32_e32 v151, v190
	v_pk_add_f32 v[148:149], v[148:149], v[150:151]
	v_and_b32_e32 v214, 0xfdf, v144
	v_pk_add_f32 v[146:147], v[146:147], v[148:149]
	s_nop 0
	v_add_f32_e32 v145, v146, v147
	ds_bpermute_b32 v146, v208, v145
	s_waitcnt lgkmcnt(0)
	v_add_f32_e32 v145, v145, v146
	ds_bpermute_b32 v146, v209, v145
	s_waitcnt lgkmcnt(0)
	v_add_f32_e32 v215, v145, v146
	v_ashrrev_i32_e32 v145, 31, v144
	v_lshlrev_b64 v[146:147], 6, v[144:145]
	v_lshl_add_u64 v[150:151], s[18:19], 0, v[146:147]
	s_nop 1
	ds_read_b32 v194, v253 offset:576
	v_mov_b32_e32 v195, 0
	v_mov_b32_e32 v196, 0
	v_mov_b32_e32 v197, 0
	v_mov_b32_e32 v146, 0
	v_mov_b32_e32 v147, 0
	v_mov_b32_e32 v148, 0
	v_mov_b32_e32 v149, 0
	v_mov_b32_e32 v210, 0
	v_mov_b32_e32 v211, 0
	v_mov_b32_e32 v212, 0
	v_mov_b32_e32 v213, 0
	v_mov_b32_e32 v190, 0
	v_mov_b32_e32 v191, 0
	v_mov_b32_e32 v192, 0
	v_mov_b32_e32 v193, 0
	s_waitcnt lgkmcnt(0)
	v_lshlrev_b64 v[144:145], 12, v[144:145]
	v_lshl_add_u64 v[144:145], s[22:23], 0, v[144:145]
	v_lshl_add_u64 v[144:145], v[144:145], 0, s[10:11]
	s_waitcnt vmcnt(1)
	v_mov_b32_e32 v150, v194
	s_waitcnt vmcnt(0)
;     __device__ __forceinline__ void operator()(const f32x4 (&acc)[2][2][4][2], const Unit& u, int wr, int wc, int fr, int fq) const {
;     ...
;                 const float rx = 1.0f / sqrtf(ssq_sum(ssq_in + (size_t)row * 16) * (1.0f / DM) + EPS);
;                 const float rs = (head < 8 ? qscale : 1.0f) * rx / sqrtf(s * rx * rx * (1.0f / 64.0f) + EPS);
;                 float o1[8], o2[8];
; #pragma unroll
;                 for (int n = 0; n < 2; ++n)
; #pragma unroll
;                     for (int e = 0; e < 4; ++e) {
;                         float cs, sn; rope_cs(pos, 8 * fq + 4 * n + e, cs, sn);
;                         const float x1 = acc[ai][0][m][n][e] * rs * gv[0][n][e], x2 = acc[ai][1][m][n][e] * rs * gv[1][n][e];
;                         o1[4 * n + e] = x1 * cs - x2 * sn; o2[4 * n + e] = x1 * sn + x2 * cs;
	v_mov_b32_e32 v151, v210
	v_mov_b32_e32 v210, v195
	v_mov_b32_e32 v194, v196
	v_mov_b32_e32 v195, v212
	v_mov_b32_e32 v212, v197
	v_pk_add_f32 v[150:151], v[150:151], v[210:211]
	v_pk_add_f32 v[194:195], v[194:195], v[212:213]
	s_nop 0
	v_pk_add_f32 v[150:151], v[150:151], v[194:195]
	v_mov_b32_e32 v194, v146
	v_mov_b32_e32 v195, v190
	v_mov_b32_e32 v190, v147
	v_pk_add_f32 v[146:147], v[194:195], v[190:191]
	v_mov_b32_e32 v190, v148
	v_mov_b32_e32 v191, v192
	v_mov_b32_e32 v192, v149
	v_pk_add_f32 v[148:149], v[190:191], v[192:193]
	s_nop 0
	v_pk_add_f32 v[146:147], v[146:147], v[148:149]
	s_nop 0
	v_pk_add_f32 v[146:147], v[150:151], v[146:147]
	s_nop 0
	v_add_f32_e32 v146, v146, v147
	v_fmamk_f32 v146, v146, 0x3a800000, v202
	v_cmp_gt_f32_e32 vcc, s62, v146
	v_mul_f32_e32 v147, 0x4f800000, v146
	s_nop 0
	v_cndmask_b32_e32 v146, v146, v147, vcc
	v_sqrt_f32_e32 v147, v146
	s_nop 0
	v_add_u32_e32 v148, -1, v147
	v_fma_f32 v149, -v148, v147, v146
	v_cmp_ge_f32_e64 s[8:9], 0, v149
	v_add_u32_e32 v149, 1, v147
	s_nop 0
	v_cndmask_b32_e64 v148, v147, v148, s[8:9]
	v_fma_f32 v147, -v149, v147, v146
	v_cmp_lt_f32_e64 s[8:9], 0, v147
	s_nop 1
	v_cndmask_b32_e64 v147, v148, v149, s[8:9]
	v_mul_f32_e32 v148, 0x37800000, v147
	v_cndmask_b32_e32 v147, v147, v148, vcc
	v_cmp_class_f32_e32 vcc, v146, v203
	s_nop 1
	v_cndmask_b32_e32 v146, v147, v146, vcc
	v_div_scale_f32 v147, s[0:1], v146, v146, 1.0
	v_rcp_f32_e32 v148, v147
	s_nop 0
	v_fma_f32 v149, -v147, v148, 1.0
	v_fmac_f32_e32 v148, v149, v148
	v_div_scale_f32 v149, vcc, 1.0, v146, 1.0
	v_mul_f32_e32 v150, v149, v148
	v_fma_f32 v151, -v147, v150, v149
	v_fmac_f32_e32 v150, v151, v148
	v_fma_f32 v147, -v147, v150, v149
	v_div_fmas_f32 v147, v147, v148, v150
	v_div_fixup_f32 v146, v147, v146, 1.0
	v_mul_f32_e32 v148, v215, v146
	v_mul_f32_e32 v147, v207, v146
	v_mul_f32_e32 v146, v146, v148
	v_fmamk_f32 v146, v146, 0x3c800000, v202
	v_cmp_gt_f32_e32 vcc, s62, v146
	v_mul_f32_e32 v148, 0x4f800000, v146
	s_nop 0
	v_cndmask_b32_e32 v146, v146, v148, vcc
	v_sqrt_f32_e32 v148, v146
	s_nop 0
	v_add_u32_e32 v149, -1, v148
	v_fma_f32 v150, -v149, v148, v146
	v_cmp_ge_f32_e64 s[8:9], 0, v150
	v_add_u32_e32 v150, 1, v148
	s_nop 0
	v_cndmask_b32_e64 v149, v148, v149, s[8:9]
	v_fma_f32 v148, -v150, v148, v146
	v_cmp_lt_f32_e64 s[8:9], 0, v148
	s_nop 1
	v_cndmask_b32_e64 v148, v149, v150, s[8:9]
	v_mul_f32_e32 v149, 0x37800000, v148
	v_cndmask_b32_e32 v148, v148, v149, vcc
	v_cmp_class_f32_e32 vcc, v146, v203
	s_nop 1
	v_cndmask_b32_e32 v146, v148, v146, vcc
	v_div_scale_f32 v148, s[0:1], v146, v146, v147
	v_rcp_f32_e32 v149, v148
	s_nop 0
	v_fma_f32 v150, -v148, v149, 1.0
	v_fmac_f32_e32 v149, v150, v149
	v_div_scale_f32 v150, vcc, v147, v146, v147
	v_mul_f32_e32 v151, v150, v149
	v_fma_f32 v190, -v148, v151, v150
	v_fmac_f32_e32 v151, v190, v149
	v_fma_f32 v148, -v148, v151, v150
	v_div_fmas_f32 v148, v148, v149, v151
	v_div_fixup_f32 v146, v148, v146, v147
	v_cvt_f64_u32_e32 v[148:149], v214
	v_mul_f64 v[150:151], v[172:173], v[148:149]
	v_rndne_f64_e32 v[150:151], v[150:151]
	v_mul_f64 v[192:193], v[174:175], v[148:149]
	v_fma_f64 v[150:151], v[172:173], v[148:149], -v[150:151]
	v_rndne_f64_e32 v[192:193], v[192:193]
	v_cvt_f32_f64_e32 v147, v[150:151]
	v_fma_f64 v[192:193], v[174:175], v[148:149], -v[192:193]
	v_cos_f32_e32 v150, v147
	v_sin_f32_e32 v190, v147
	v_cvt_f32_f64_e32 v147, v[192:193]
	v_pk_mul_f32 v[194:195], v[36:37], v[146:147] op_sel_hi:[1,0]
	v_cos_f32_e32 v151, v147
	v_sin_f32_e32 v191, v147
	v_pk_mul_f32 v[192:193], v[44:45], v[146:147] op_sel_hi:[1,0]
	v_pk_mul_f32 v[194:195], v[140:141], v[194:195]
	v_pk_mul_f32 v[192:193], v[136:137], v[192:193]
	v_pk_mul_f32 v[196:197], v[150:151], v[194:195]
	s_nop 0
	v_pk_fma_f32 v[196:197], v[190:191], v[192:193], v[196:197]
	v_pk_mul_f32 v[190:191], v[190:191], v[194:195]
	v_mul_f64 v[194:195], v[178:179], v[148:149]
	v_pk_fma_f32 v[150:151], v[150:151], v[192:193], v[190:191] neg_lo:[0,0,1] neg_hi:[0,0,1]
	v_mul_f64 v[190:191], v[176:177], v[148:149]
	v_rndne_f64_e32 v[190:191], v[190:191]
	v_fma_f64 v[190:191], v[176:177], v[148:149], -v[190:191]
	v_rndne_f64_e32 v[194:195], v[194:195]
	v_cvt_f32_f64_e32 v147, v[190:191]
	v_fma_f64 v[194:195], v[178:179], v[148:149], -v[194:195]
	v_cos_f32_e32 v190, v147
	v_sin_f32_e32 v192, v147
	v_cvt_f32_f64_e32 v147, v[194:195]
	v_pk_mul_f32 v[210:211], v[38:39], v[146:147] op_sel_hi:[1,0]
	v_cos_f32_e32 v191, v147
	v_sin_f32_e32 v193, v147
	v_pk_mul_f32 v[194:195], v[46:47], v[146:147] op_sel_hi:[1,0]
	v_pk_mul_f32 v[210:211], v[142:143], v[210:211]
	v_pk_mul_f32 v[194:195], v[138:139], v[194:195]
	v_pk_mul_f32 v[212:213], v[190:191], v[210:211]
	s_nop 0
	v_pk_fma_f32 v[212:213], v[192:193], v[194:195], v[212:213]
	v_pk_mul_f32 v[192:193], v[192:193], v[210:211]
	v_mul_f64 v[210:211], v[186:187], v[148:149]
	v_pk_fma_f32 v[190:191], v[190:191], v[194:195], v[192:193] neg_lo:[0,0,1] neg_hi:[0,0,1]
	v_mul_f64 v[192:193], v[184:185], v[148:149]
	v_rndne_f64_e32 v[192:193], v[192:193]
	v_fma_f64 v[192:193], v[184:185], v[148:149], -v[192:193]
	v_rndne_f64_e32 v[210:211], v[210:211]
	v_cvt_f32_f64_e32 v147, v[192:193]
	v_fma_f64 v[210:211], v[186:187], v[148:149], -v[210:211]
	v_cos_f32_e32 v192, v147
	v_sin_f32_e32 v194, v147
	v_cvt_f32_f64_e32 v147, v[210:211]
	v_pk_mul_f32 v[214:215], v[32:33], v[146:147] op_sel_hi:[1,0]
	v_cos_f32_e32 v193, v147
	v_sin_f32_e32 v195, v147
	v_pk_mul_f32 v[210:211], v[40:41], v[146:147] op_sel_hi:[1,0]
	v_pk_mul_f32 v[214:215], v[128:129], v[214:215]
	v_pk_mul_f32 v[210:211], v[132:133], v[210:211]
	v_pk_mul_f32 v[216:217], v[192:193], v[214:215]
	s_nop 0
; __device__ __forceinline__ unsigned cvtpk(float lo, float hi) { f32x2_t v = {lo, hi}; bf16x2_t b = __builtin_convertvector(v, bf16x2_t); return __builtin_bit_cast(unsigned, b); }
;     __device__ __forceinline__ void operator()(const f32x4 (&acc)[2][2][4][2], const Unit& u, int wr, int wc, int fr, int fq) const {
;     ...
;                 const int row = row0 + ai * HALF + m * 16; const int pos = row & (SEQ - 1);
;                 float s = 0.f;
; #pragma unroll
;                 for (int bj = 0; bj < 2; ++bj)
; #pragma unroll
;                     for (int n = 0; n < 2; ++n) { const f32x4 v = acc[ai][bj][m][n]; s += (v[0] * v[0] + v[1] * v[1]) + (v[2] * v[2] + v[3] * v[3]); }
;                 s += __shfl_xor(s, 16); s += __shfl_xor(s, 32);
;                 const float rx = 1.0f / sqrtf(ssq_sum(ssq_in + (size_t)row * 16) * (1.0f / DM) + EPS);
;                 const float rs = (head < 8 ? qscale : 1.0f) * rx / sqrtf(s * rx * rx * (1.0f / 64.0f) + EPS);
;     ...
;                         float cs, sn; rope_cs(pos, 8 * fq + 4 * n + e, cs, sn);
;                         const float x1 = acc[ai][0][m][n][e] * rs * gv[0][n][e], x2 = acc[ai][1][m][n][e] * rs * gv[1][n][e];
;                         o1[4 * n + e] = x1 * cs - x2 * sn; o2[4 * n + e] = x1 * sn + x2 * cs;
;                     }
;                 bf16_t* op = O + (size_t)row * 2048 + head * 64 + 8 * fq;
;                 u32x4 w; w.x = cvtpk(o1[0], o1[1]); w.y = cvtpk(o1[2], o1[3]); w.z = cvtpk(o1[4], o1[5]); w.w = cvtpk(o1[6], o1[7]);
;                 *(u32x4*)op = w;
;                 w.x = cvtpk(o2[0], o2[1]); w.y = cvtpk(o2[2], o2[3]); w.z = cvtpk(o2[4], o2[5]); w.w = cvtpk(o2[6], o2[7]);
;                 *(u32x4*)(op + 32) = w;
	v_pk_fma_f32 v[216:217], v[194:195], v[210:211], v[216:217]
	v_pk_mul_f32 v[194:195], v[194:195], v[214:215]
	v_mul_f64 v[214:215], v[180:181], v[148:149]
	v_pk_fma_f32 v[192:193], v[192:193], v[210:211], v[194:195] neg_lo:[0,0,1] neg_hi:[0,0,1]
	v_mul_f64 v[194:195], v[182:183], v[148:149]
	v_rndne_f64_e32 v[194:195], v[194:195]
	v_fma_f64 v[194:195], v[182:183], v[148:149], -v[194:195]
	v_rndne_f64_e32 v[214:215], v[214:215]
	v_cvt_f32_f64_e32 v147, v[194:195]
	v_fma_f64 v[148:149], v[180:181], v[148:149], -v[214:215]
	v_cos_f32_e32 v194, v147
	v_sin_f32_e32 v210, v147
	v_cvt_f32_f64_e32 v147, v[148:149]
	v_cos_f32_e32 v195, v147
	v_sin_f32_e32 v211, v147
	v_pk_mul_f32 v[148:149], v[42:43], v[146:147] op_sel_hi:[1,0]
	v_pk_mul_f32 v[146:147], v[34:35], v[146:147] op_sel_hi:[1,0]
	v_pk_mul_f32 v[148:149], v[134:135], v[148:149]
	v_pk_mul_f32 v[146:147], v[130:131], v[146:147]
	s_nop 0
	v_pk_mul_f32 v[214:215], v[194:195], v[146:147]
	v_pk_mul_f32 v[146:147], v[210:211], v[146:147]
	v_pk_fma_f32 v[214:215], v[210:211], v[148:149], v[214:215]
	v_pk_fma_f32 v[148:149], v[194:195], v[148:149], v[146:147] neg_lo:[0,0,1] neg_hi:[0,0,1]
	v_lshl_add_u64 v[194:195], v[144:145], 0, v[188:189]
	v_cvt_pk_bf16_f32 v144, v150, v151
	v_cvt_pk_bf16_f32 v145, v190, v191
	v_cvt_pk_bf16_f32 v146, v192, v193
	v_cvt_pk_bf16_f32 v147, v148, v149
	global_store_dwordx4 v[194:195], v[144:147], off
	v_add_u32_e32 v190, 0xa0, v168
	v_ashrrev_i32_e32 v191, 31, v190
	v_cvt_pk_bf16_f32 v144, v196, v197
	v_cvt_pk_bf16_f32 v145, v212, v213
	v_cvt_pk_bf16_f32 v146, v216, v217
	v_cvt_pk_bf16_f32 v147, v214, v215
	global_store_dwordx4 v[194:195], v[144:147], off offset:64
	v_and_b32_e32 v194, 0xfef, v190
	s_nop 0
	v_pk_mul_f32 v[144:145], v[30:31], v[30:31]
	v_pk_mul_f32 v[146:147], v[28:29], v[28:29]
	s_nop 0
	v_pk_mov_b32 v[148:149], v[146:147], v[144:145] op_sel:[1,0]
	v_mov_b32_e32 v147, v145
	v_pk_add_f32 v[144:145], v[148:149], v[146:147]
	v_pk_mul_f32 v[146:147], v[26:27], v[26:27]
	v_pk_mul_f32 v[148:149], v[24:25], v[24:25]
	v_pk_add_f32 v[144:145], v[144:145], v[144:145] op_sel:[0,1] op_sel_hi:[1,0]
	v_pk_mov_b32 v[150:151], v[148:149], v[146:147] op_sel:[1,0]
	v_mov_b32_e32 v149, v147
	v_pk_add_f32 v[146:147], v[150:151], v[148:149]
	v_mul_f32_e32 v148, v16, v16
	v_mul_f32_e32 v149, v17, v17
	v_pk_add_f32 v[146:147], v[146:147], v[146:147] op_sel:[0,1] op_sel_hi:[1,0]
	v_mov_b32_e32 v145, v148
	v_mov_b32_e32 v147, v149
	v_pk_add_f32 v[144:145], v[144:145], v[146:147]
	v_mul_f32_e32 v146, v21, v21
	v_mul_f32_e32 v148, v23, v23
	v_mul_f32_e32 v150, v18, v18
	v_mul_f32_e32 v151, v19, v19
	v_pk_fma_f32 v[146:147], v[20:21], v[20:21], v[146:147] op_sel_hi:[1,1,0]
	v_pk_fma_f32 v[148:149], v[22:23], v[22:23], v[148:149] op_sel_hi:[1,1,0]
	v_mov_b32_e32 v147, v150
	v_mov_b32_e32 v149, v151
	v_pk_add_f32 v[146:147], v[146:147], v[148:149]
	s_nop 0
	v_pk_add_f32 v[144:145], v[144:145], v[146:147]
	s_nop 0
	v_add_f32_e32 v144, v144, v145
	ds_bpermute_b32 v145, v208, v144
	s_waitcnt lgkmcnt(0)
	v_add_f32_e32 v144, v144, v145
	ds_bpermute_b32 v145, v209, v144
	s_waitcnt lgkmcnt(0)
	v_add_f32_e32 v195, v144, v145
	v_lshlrev_b64 v[144:145], 6, v[190:191]
	v_lshl_add_u64 v[192:193], s[18:19], 0, v[144:145]
	s_nop 1
	ds_read_b32 v210, v253 offset:640
	v_mov_b32_e32 v211, 0
	v_mov_b32_e32 v212, 0
	v_mov_b32_e32 v213, 0
	v_mov_b32_e32 v144, 0
	v_mov_b32_e32 v145, 0
	v_mov_b32_e32 v146, 0
	v_mov_b32_e32 v147, 0
	v_mov_b32_e32 v214, 0
	v_mov_b32_e32 v215, 0
	v_mov_b32_e32 v216, 0
	v_mov_b32_e32 v217, 0
	v_mov_b32_e32 v148, 0
	v_mov_b32_e32 v149, 0
	v_mov_b32_e32 v150, 0
	v_mov_b32_e32 v151, 0
	s_waitcnt lgkmcnt(0)
	s_waitcnt vmcnt(1)
	v_mov_b32_e32 v192, v210
	s_waitcnt vmcnt(0)
	v_mov_b32_e32 v193, v214
	v_mov_b32_e32 v214, v211
	v_mov_b32_e32 v196, v212
	v_mov_b32_e32 v197, v216
	v_mov_b32_e32 v216, v213
	v_pk_add_f32 v[192:193], v[192:193], v[214:215]
	v_pk_add_f32 v[196:197], v[196:197], v[216:217]
	s_nop 0
	v_pk_add_f32 v[192:193], v[192:193], v[196:197]
	v_mov_b32_e32 v196, v144
	v_mov_b32_e32 v197, v148
	v_mov_b32_e32 v148, v145
	v_pk_add_f32 v[144:145], v[196:197], v[148:149]
	v_mov_b32_e32 v148, v146
	v_mov_b32_e32 v149, v150
	v_mov_b32_e32 v150, v147
	v_pk_add_f32 v[146:147], v[148:149], v[150:151]
	s_nop 0
	v_pk_add_f32 v[144:145], v[144:145], v[146:147]
	s_nop 0
	v_pk_add_f32 v[144:145], v[192:193], v[144:145]
	s_nop 0
	v_add_f32_e32 v144, v144, v145
	v_fmamk_f32 v144, v144, 0x3a800000, v202
	v_cmp_gt_f32_e32 vcc, s62, v144
	v_mul_f32_e32 v145, 0x4f800000, v144
	s_nop 0
	v_cndmask_b32_e32 v144, v144, v145, vcc
	v_sqrt_f32_e32 v145, v144
	s_nop 0
	v_add_u32_e32 v146, -1, v145
	v_fma_f32 v147, -v146, v145, v144
	v_cmp_ge_f32_e64 s[8:9], 0, v147
	v_add_u32_e32 v147, 1, v145
	s_nop 0
	v_cndmask_b32_e64 v146, v145, v146, s[8:9]
	v_fma_f32 v145, -v147, v145, v144
	v_cmp_lt_f32_e64 s[8:9], 0, v145
	s_nop 1
	v_cndmask_b32_e64 v145, v146, v147, s[8:9]
	v_mul_f32_e32 v146, 0x37800000, v145
	v_cndmask_b32_e32 v145, v145, v146, vcc
	v_cmp_class_f32_e32 vcc, v144, v203
	s_nop 1
	v_cndmask_b32_e32 v144, v145, v144, vcc
	v_div_scale_f32 v145, s[0:1], v144, v144, 1.0
	v_rcp_f32_e32 v146, v145
	s_nop 0
	v_fma_f32 v147, -v145, v146, 1.0
	v_fmac_f32_e32 v146, v147, v146
	v_div_scale_f32 v147, vcc, 1.0, v144, 1.0
	v_mul_f32_e32 v148, v147, v146
	v_fma_f32 v149, -v145, v148, v147
	v_fmac_f32_e32 v148, v149, v146
	v_fma_f32 v145, -v145, v148, v147
	v_div_fmas_f32 v145, v145, v146, v148
	v_div_fixup_f32 v144, v145, v144, 1.0
	v_mul_f32_e32 v146, v195, v144
	v_mul_f32_e32 v145, v207, v144
	v_mul_f32_e32 v144, v144, v146
	v_fmamk_f32 v144, v144, 0x3c800000, v202
	v_cmp_gt_f32_e32 vcc, s62, v144
; __device__ __forceinline__ unsigned cvtpk(float lo, float hi) { f32x2_t v = {lo, hi}; bf16x2_t b = __builtin_convertvector(v, bf16x2_t); return __builtin_bit_cast(unsigned, b); }
;     __device__ __forceinline__ void operator()(const f32x4 (&acc)[2][2][4][2], const Unit& u, int wr, int wc, int fr, int fq) const {
;     ...
; #pragma unroll
;                     for (int n = 0; n < 2; ++n) { const f32x4 v = acc[ai][bj][m][n]; s += (v[0] * v[0] + v[1] * v[1]) + (v[2] * v[2] + v[3] * v[3]); }
;                 s += __shfl_xor(s, 16); s += __shfl_xor(s, 32);
;                 const float rx = 1.0f / sqrtf(ssq_sum(ssq_in + (size_t)row * 16) * (1.0f / DM) + EPS);
;                 const float rs = (head < 8 ? qscale : 1.0f) * rx / sqrtf(s * rx * rx * (1.0f / 64.0f) + EPS);
;                 float o1[8], o2[8];
; #pragma unroll
;                 for (int n = 0; n < 2; ++n)
; #pragma unroll
;                     for (int e = 0; e < 4; ++e) {
;                         float cs, sn; rope_cs(pos, 8 * fq + 4 * n + e, cs, sn);
;                         const float x1 = acc[ai][0][m][n][e] * rs * gv[0][n][e], x2 = acc[ai][1][m][n][e] * rs * gv[1][n][e];
;                         o1[4 * n + e] = x1 * cs - x2 * sn; o2[4 * n + e] = x1 * sn + x2 * cs;
;                     }
;                 bf16_t* op = O + (size_t)row * 2048 + head * 64 + 8 * fq;
;                 u32x4 w; w.x = cvtpk(o1[0], o1[1]); w.y = cvtpk(o1[2], o1[3]); w.z = cvtpk(o1[4], o1[5]); w.w = cvtpk(o1[6], o1[7]);
;                 *(u32x4*)op = w;
;                 w.x = cvtpk(o2[0], o2[1]); w.y = cvtpk(o2[2], o2[3]); w.z = cvtpk(o2[4], o2[5]); w.w = cvtpk(o2[6], o2[7]);
;                 *(u32x4*)(op + 32) = w;
	v_mul_f32_e32 v146, 0x4f800000, v144
	s_nop 0
	v_cndmask_b32_e32 v144, v144, v146, vcc
	v_sqrt_f32_e32 v146, v144
	s_nop 0
	v_add_u32_e32 v147, -1, v146
	v_fma_f32 v148, -v147, v146, v144
	v_cmp_ge_f32_e64 s[8:9], 0, v148
	v_add_u32_e32 v148, 1, v146
	s_nop 0
	v_cndmask_b32_e64 v147, v146, v147, s[8:9]
	v_fma_f32 v146, -v148, v146, v144
	v_cmp_lt_f32_e64 s[8:9], 0, v146
	s_nop 1
	v_cndmask_b32_e64 v146, v147, v148, s[8:9]
	v_mul_f32_e32 v147, 0x37800000, v146
	v_cndmask_b32_e32 v146, v146, v147, vcc
	v_cmp_class_f32_e32 vcc, v144, v203
	s_nop 1
	v_cndmask_b32_e32 v144, v146, v144, vcc
	v_div_scale_f32 v146, s[0:1], v144, v144, v145
	v_rcp_f32_e32 v147, v146
	s_nop 0
	v_fma_f32 v148, -v146, v147, 1.0
	v_fmac_f32_e32 v147, v148, v147
	v_div_scale_f32 v148, vcc, v145, v144, v145
	v_mul_f32_e32 v149, v148, v147
	v_fma_f32 v150, -v146, v149, v148
	v_fmac_f32_e32 v149, v150, v147
	v_fma_f32 v146, -v146, v149, v148
	v_div_fmas_f32 v146, v146, v147, v149
	v_cvt_f64_u32_e32 v[150:151], v194
	v_div_fixup_f32 v144, v146, v144, v145
	v_mul_f64 v[146:147], v[172:173], v[150:151]
	v_rndne_f64_e32 v[146:147], v[146:147]
	v_fma_f64 v[146:147], v[172:173], v[150:151], -v[146:147]
	v_cvt_f32_f64_e32 v145, v[146:147]
	v_mul_f64 v[146:147], v[174:175], v[150:151]
	v_rndne_f64_e32 v[146:147], v[146:147]
	v_fma_f64 v[146:147], v[174:175], v[150:151], -v[146:147]
	v_cos_f32_e32 v148, v145
	v_sin_f32_e32 v192, v145
	v_cvt_f32_f64_e32 v145, v[146:147]
	v_pk_mul_f32 v[146:147], v[28:29], v[144:145] op_sel_hi:[1,0]
	v_cos_f32_e32 v149, v145
	v_pk_mul_f32 v[194:195], v[136:137], v[146:147]
	v_pk_mul_f32 v[146:147], v[20:21], v[144:145] op_sel_hi:[1,0]
	v_sin_f32_e32 v193, v145
	v_pk_mul_f32 v[196:197], v[140:141], v[146:147]
	s_nop 0
	v_pk_mul_f32 v[146:147], v[148:149], v[196:197]
	s_nop 0
	v_pk_fma_f32 v[146:147], v[192:193], v[194:195], v[146:147]
	v_pk_mul_f32 v[192:193], v[192:193], v[196:197]
	s_nop 0
	v_pk_fma_f32 v[148:149], v[148:149], v[194:195], v[192:193] neg_lo:[0,0,1] neg_hi:[0,0,1]
	v_mul_f64 v[192:193], v[176:177], v[150:151]
	v_rndne_f64_e32 v[192:193], v[192:193]
	v_fma_f64 v[192:193], v[176:177], v[150:151], -v[192:193]
	v_cvt_f32_f64_e32 v145, v[192:193]
	v_mul_f64 v[192:193], v[178:179], v[150:151]
	v_rndne_f64_e32 v[192:193], v[192:193]
	v_fma_f64 v[192:193], v[178:179], v[150:151], -v[192:193]
	v_cos_f32_e32 v194, v145
	v_sin_f32_e32 v196, v145
	v_cvt_f32_f64_e32 v145, v[192:193]
	v_pk_mul_f32 v[192:193], v[30:31], v[144:145] op_sel_hi:[1,0]
	v_cos_f32_e32 v195, v145
	v_pk_mul_f32 v[210:211], v[138:139], v[192:193]
	v_pk_mul_f32 v[192:193], v[22:23], v[144:145] op_sel_hi:[1,0]
	v_sin_f32_e32 v197, v145
	v_pk_mul_f32 v[212:213], v[142:143], v[192:193]
	v_cvt_pk_bf16_f32 v148, v148, v149
	v_pk_mul_f32 v[192:193], v[194:195], v[212:213]
	s_nop 0
	v_pk_fma_f32 v[192:193], v[196:197], v[210:211], v[192:193]
	v_pk_mul_f32 v[196:197], v[196:197], v[212:213]
	v_mul_f64 v[212:213], v[186:187], v[150:151]
	v_pk_fma_f32 v[194:195], v[194:195], v[210:211], v[196:197] neg_lo:[0,0,1] neg_hi:[0,0,1]
	v_mul_f64 v[196:197], v[184:185], v[150:151]
	v_rndne_f64_e32 v[196:197], v[196:197]
	v_fma_f64 v[196:197], v[184:185], v[150:151], -v[196:197]
	v_rndne_f64_e32 v[212:213], v[212:213]
	v_cvt_f32_f64_e32 v145, v[196:197]
	v_fma_f64 v[212:213], v[186:187], v[150:151], -v[212:213]
	v_cos_f32_e32 v196, v145
	v_sin_f32_e32 v210, v145
	v_cvt_f32_f64_e32 v145, v[212:213]
	v_pk_mul_f32 v[214:215], v[16:17], v[144:145] op_sel_hi:[1,0]
	v_cos_f32_e32 v197, v145
	v_sin_f32_e32 v211, v145
	v_pk_mul_f32 v[212:213], v[24:25], v[144:145] op_sel_hi:[1,0]
	v_pk_mul_f32 v[214:215], v[128:129], v[214:215]
	v_pk_mul_f32 v[212:213], v[132:133], v[212:213]
	v_pk_mul_f32 v[216:217], v[196:197], v[214:215]
	v_cvt_pk_bf16_f32 v149, v194, v195
	v_pk_fma_f32 v[216:217], v[210:211], v[212:213], v[216:217]
	v_pk_mul_f32 v[210:211], v[210:211], v[214:215]
	v_mul_f64 v[214:215], v[180:181], v[150:151]
	v_pk_fma_f32 v[196:197], v[196:197], v[212:213], v[210:211] neg_lo:[0,0,1] neg_hi:[0,0,1]
	v_mul_f64 v[210:211], v[182:183], v[150:151]
	v_rndne_f64_e32 v[210:211], v[210:211]
	v_fma_f64 v[210:211], v[182:183], v[150:151], -v[210:211]
	v_rndne_f64_e32 v[214:215], v[214:215]
	v_cvt_f32_f64_e32 v145, v[210:211]
	v_fma_f64 v[150:151], v[180:181], v[150:151], -v[214:215]
	v_cos_f32_e32 v210, v145
	v_sin_f32_e32 v212, v145
	v_cvt_f32_f64_e32 v145, v[150:151]
	v_cos_f32_e32 v211, v145
	v_sin_f32_e32 v213, v145
	v_pk_mul_f32 v[150:151], v[26:27], v[144:145] op_sel_hi:[1,0]
	v_pk_mul_f32 v[144:145], v[18:19], v[144:145] op_sel_hi:[1,0]
	v_pk_mul_f32 v[150:151], v[134:135], v[150:151]
	v_pk_mul_f32 v[144:145], v[130:131], v[144:145]
	s_nop 0
	v_pk_mul_f32 v[214:215], v[210:211], v[144:145]
	v_pk_mul_f32 v[144:145], v[212:213], v[144:145]
	v_pk_fma_f32 v[214:215], v[212:213], v[150:151], v[214:215]
	v_pk_fma_f32 v[144:145], v[210:211], v[150:151], v[144:145] neg_lo:[0,0,1] neg_hi:[0,0,1]
	v_lshlrev_b64 v[150:151], 12, v[190:191]
	v_lshl_add_u64 v[150:151], s[22:23], 0, v[150:151]
	v_lshl_add_u64 v[150:151], v[150:151], 0, s[10:11]
	v_lshl_add_u64 v[190:191], v[150:151], 0, v[188:189]
	v_cvt_pk_bf16_f32 v150, v196, v197
	v_cvt_pk_bf16_f32 v151, v144, v145
	v_cvt_pk_bf16_f32 v144, v146, v147
	v_cvt_pk_bf16_f32 v145, v192, v193
	v_cvt_pk_bf16_f32 v146, v216, v217
	v_cvt_pk_bf16_f32 v147, v214, v215
	global_store_dwordx4 v[190:191], v[148:151], off
	global_store_dwordx4 v[190:191], v[144:147], off offset:64
	s_nop 0
	v_pk_mul_f32 v[148:149], v[12:13], v[12:13]
	v_pk_mul_f32 v[146:147], v[14:15], v[14:15]
	v_mul_f32_e32 v145, v0, v0
	v_pk_mov_b32 v[150:151], v[148:149], v[146:147] op_sel:[1,0]
	v_mov_b32_e32 v149, v147
	v_pk_add_f32 v[146:147], v[150:151], v[148:149]
	v_pk_mul_f32 v[148:149], v[10:11], v[10:11]
	v_pk_mul_f32 v[150:151], v[8:9], v[8:9]
	v_pk_add_f32 v[146:147], v[146:147], v[146:147] op_sel:[0,1] op_sel_hi:[1,0]
	v_pk_mov_b32 v[190:191], v[150:151], v[148:149] op_sel:[1,0]
	v_mov_b32_e32 v151, v149
	v_pk_add_f32 v[148:149], v[190:191], v[150:151]
	v_mul_f32_e32 v150, v1, v1
	v_pk_add_f32 v[148:149], v[148:149], v[148:149] op_sel:[0,1] op_sel_hi:[1,0]
	v_mov_b32_e32 v147, v145
	v_mov_b32_e32 v149, v150
	v_pk_add_f32 v[146:147], v[146:147], v[148:149]
	v_mul_f32_e32 v148, v5, v5
	v_mul_f32_e32 v151, v2, v2
	v_pk_fma_f32 v[148:149], v[4:5], v[4:5], v[148:149] op_sel_hi:[1,1,0]
	v_mul_f32_e32 v150, v7, v7
	v_mul_f32_e32 v190, v3, v3
	v_mov_b32_e32 v149, v151
	v_pk_fma_f32 v[150:151], v[6:7], v[6:7], v[150:151] op_sel_hi:[1,1,0]
	v_add_u32_e32 v144, 0xb0, v168
	v_mov_b32_e32 v151, v190
	v_pk_add_f32 v[148:149], v[148:149], v[150:151]
	v_and_b32_e32 v212, 0xfff, v144
	v_pk_add_f32 v[146:147], v[146:147], v[148:149]
	s_nop 0
	v_add_f32_e32 v145, v146, v147
	ds_bpermute_b32 v146, v208, v145
	s_waitcnt lgkmcnt(0)
; __device__ __forceinline__ unsigned cvtpk(float lo, float hi) { f32x2_t v = {lo, hi}; bf16x2_t b = __builtin_convertvector(v, bf16x2_t); return __builtin_bit_cast(unsigned, b); }
;     __device__ __forceinline__ void operator()(const f32x4 (&acc)[2][2][4][2], const Unit& u, int wr, int wc, int fr, int fq) const {
;     ...
;                 s += __shfl_xor(s, 16); s += __shfl_xor(s, 32);
;                 const float rx = 1.0f / sqrtf(ssq_sum(ssq_in + (size_t)row * 16) * (1.0f / DM) + EPS);
;                 const float rs = (head < 8 ? qscale : 1.0f) * rx / sqrtf(s * rx * rx * (1.0f / 64.0f) + EPS);
;                 float o1[8], o2[8];
; #pragma unroll
;                 for (int n = 0; n < 2; ++n)
; #pragma unroll
;                     for (int e = 0; e < 4; ++e) {
;                         float cs, sn; rope_cs(pos, 8 * fq + 4 * n + e, cs, sn);
;                         const float x1 = acc[ai][0][m][n][e] * rs * gv[0][n][e], x2 = acc[ai][1][m][n][e] * rs * gv[1][n][e];
;                         o1[4 * n + e] = x1 * cs - x2 * sn; o2[4 * n + e] = x1 * sn + x2 * cs;
;                     }
;                 bf16_t* op = O + (size_t)row * 2048 + head * 64 + 8 * fq;
;                 u32x4 w; w.x = cvtpk(o1[0], o1[1]); w.y = cvtpk(o1[2], o1[3]); w.z = cvtpk(o1[4], o1[5]); w.w = cvtpk(o1[6], o1[7]);
;                 *(u32x4*)op = w;
;                 w.x = cvtpk(o2[0], o2[1]); w.y = cvtpk(o2[2], o2[3]); w.z = cvtpk(o2[4], o2[5]); w.w = cvtpk(o2[6], o2[7]);
;                 *(u32x4*)(op + 32) = w;
	v_add_f32_e32 v145, v145, v146
	ds_bpermute_b32 v146, v209, v145
	s_waitcnt lgkmcnt(0)
	v_add_f32_e32 v213, v145, v146
	v_ashrrev_i32_e32 v145, 31, v144
	v_lshlrev_b64 v[146:147], 6, v[144:145]
	v_lshl_add_u64 v[150:151], s[18:19], 0, v[146:147]
	s_nop 1
	ds_read_b32 v194, v253 offset:704
	v_mov_b32_e32 v195, 0
	v_mov_b32_e32 v196, 0
	v_mov_b32_e32 v197, 0
	v_mov_b32_e32 v146, 0
	v_mov_b32_e32 v147, 0
	v_mov_b32_e32 v148, 0
	v_mov_b32_e32 v149, 0
	v_mov_b32_e32 v208, 0
	v_mov_b32_e32 v209, 0
	v_mov_b32_e32 v210, 0
	v_mov_b32_e32 v211, 0
	v_mov_b32_e32 v190, 0
	v_mov_b32_e32 v191, 0
	v_mov_b32_e32 v192, 0
	v_mov_b32_e32 v193, 0
	s_waitcnt lgkmcnt(0)
	s_waitcnt vmcnt(1)
	v_mov_b32_e32 v150, v194
	s_waitcnt vmcnt(0)
	v_mov_b32_e32 v151, v208
	v_mov_b32_e32 v208, v195
	v_mov_b32_e32 v194, v196
	v_mov_b32_e32 v195, v210
	v_mov_b32_e32 v210, v197
	v_pk_add_f32 v[150:151], v[150:151], v[208:209]
	v_pk_add_f32 v[194:195], v[194:195], v[210:211]
	s_nop 0
	v_pk_add_f32 v[150:151], v[150:151], v[194:195]
	v_mov_b32_e32 v194, v146
	v_mov_b32_e32 v195, v190
	v_mov_b32_e32 v190, v147
	v_pk_add_f32 v[146:147], v[194:195], v[190:191]
	v_mov_b32_e32 v190, v148
	v_mov_b32_e32 v191, v192
	v_mov_b32_e32 v192, v149
	v_pk_add_f32 v[148:149], v[190:191], v[192:193]
	s_nop 0
	v_pk_add_f32 v[146:147], v[146:147], v[148:149]
	s_nop 0
	v_pk_add_f32 v[146:147], v[150:151], v[146:147]
	s_nop 0
	v_add_f32_e32 v146, v146, v147
	v_fmamk_f32 v146, v146, 0x3a800000, v202
	v_cmp_gt_f32_e32 vcc, s62, v146
	v_mul_f32_e32 v147, 0x4f800000, v146
	s_nop 0
	v_cndmask_b32_e32 v146, v146, v147, vcc
	v_sqrt_f32_e32 v147, v146
	s_nop 0
	v_add_u32_e32 v148, -1, v147
	v_fma_f32 v149, -v148, v147, v146
	v_cmp_ge_f32_e64 s[8:9], 0, v149
	v_add_u32_e32 v149, 1, v147
	s_nop 0
	v_cndmask_b32_e64 v148, v147, v148, s[8:9]
	v_fma_f32 v147, -v149, v147, v146
	v_cmp_lt_f32_e64 s[8:9], 0, v147
	s_nop 1
	v_cndmask_b32_e64 v147, v148, v149, s[8:9]
	v_mul_f32_e32 v148, 0x37800000, v147
	v_cndmask_b32_e32 v147, v147, v148, vcc
	v_cmp_class_f32_e32 vcc, v146, v203
	s_nop 1
	v_cndmask_b32_e32 v146, v147, v146, vcc
	v_div_scale_f32 v147, s[0:1], v146, v146, 1.0
	v_rcp_f32_e32 v148, v147
	s_nop 0
	v_fma_f32 v149, -v147, v148, 1.0
	v_fmac_f32_e32 v148, v149, v148
	v_div_scale_f32 v149, vcc, 1.0, v146, 1.0
	v_mul_f32_e32 v150, v149, v148
	v_fma_f32 v151, -v147, v150, v149
	v_fmac_f32_e32 v150, v151, v148
	v_fma_f32 v147, -v147, v150, v149
	v_div_fmas_f32 v147, v147, v148, v150
	v_div_fixup_f32 v146, v147, v146, 1.0
	v_mul_f32_e32 v148, v213, v146
	v_mul_f32_e32 v147, v207, v146
	v_mul_f32_e32 v146, v146, v148
	v_fmamk_f32 v146, v146, 0x3c800000, v202
	v_cmp_gt_f32_e32 vcc, s62, v146
	v_mul_f32_e32 v148, 0x4f800000, v146
	s_nop 0
	v_cndmask_b32_e32 v146, v146, v148, vcc
	v_sqrt_f32_e32 v148, v146
	s_nop 0
	v_add_u32_e32 v149, -1, v148
	v_fma_f32 v150, -v149, v148, v146
	v_cmp_ge_f32_e64 s[8:9], 0, v150
	v_add_u32_e32 v150, 1, v148
	s_nop 0
	v_cndmask_b32_e64 v149, v148, v149, s[8:9]
	v_fma_f32 v148, -v150, v148, v146
	v_cmp_lt_f32_e64 s[8:9], 0, v148
	s_nop 1
	v_cndmask_b32_e64 v148, v149, v150, s[8:9]
	v_mul_f32_e32 v149, 0x37800000, v148
	v_cndmask_b32_e32 v148, v148, v149, vcc
	v_cmp_class_f32_e32 vcc, v146, v203
	s_nop 1
	v_cndmask_b32_e32 v146, v148, v146, vcc
	v_div_scale_f32 v148, s[0:1], v146, v146, v147
	v_rcp_f32_e32 v149, v148
	s_nop 0
	v_fma_f32 v150, -v148, v149, 1.0
	v_fmac_f32_e32 v149, v150, v149
	v_div_scale_f32 v150, vcc, v147, v146, v147
	v_mul_f32_e32 v151, v150, v149
	v_fma_f32 v190, -v148, v151, v150
	v_fmac_f32_e32 v151, v190, v149
	v_fma_f32 v148, -v148, v151, v150
	v_div_fmas_f32 v148, v148, v149, v151
	v_div_fixup_f32 v146, v148, v146, v147
	v_cvt_f64_u32_e32 v[148:149], v212
	v_mul_f64 v[150:151], v[172:173], v[148:149]
	v_rndne_f64_e32 v[150:151], v[150:151]
	v_mul_f64 v[190:191], v[174:175], v[148:149]
	v_fma_f64 v[150:151], v[172:173], v[148:149], -v[150:151]
	v_rndne_f64_e32 v[190:191], v[190:191]
	v_cvt_f32_f64_e32 v147, v[150:151]
	v_fma_f64 v[174:175], v[174:175], v[148:149], -v[190:191]
	v_cos_f32_e32 v150, v147
	v_sin_f32_e32 v172, v147
	v_cvt_f32_f64_e32 v147, v[174:175]
	v_pk_mul_f32 v[174:175], v[12:13], v[146:147] op_sel_hi:[1,0]
	v_cos_f32_e32 v151, v147
	v_pk_mul_f32 v[136:137], v[136:137], v[174:175]
	v_pk_mul_f32 v[174:175], v[4:5], v[146:147] op_sel_hi:[1,0]
	v_sin_f32_e32 v173, v147
	v_pk_mul_f32 v[140:141], v[140:141], v[174:175]
	s_nop 0
	v_pk_mul_f32 v[174:175], v[150:151], v[140:141]
	v_pk_mul_f32 v[140:141], v[172:173], v[140:141]
	v_pk_fma_f32 v[174:175], v[172:173], v[136:137], v[174:175]
	v_mul_f64 v[172:173], v[178:179], v[148:149]
	v_rndne_f64_e32 v[172:173], v[172:173]
	v_pk_fma_f32 v[136:137], v[150:151], v[136:137], v[140:141] neg_lo:[0,0,1] neg_hi:[0,0,1]
	v_mul_f64 v[140:141], v[176:177], v[148:149]
	v_fma_f64 v[172:173], v[178:179], v[148:149], -v[172:173]
	v_rndne_f64_e32 v[140:141], v[140:141]
	v_cvt_f32_f64_e32 v147, v[172:173]
	v_fma_f64 v[140:141], v[176:177], v[148:149], -v[140:141]
	v_pk_mul_f32 v[172:173], v[14:15], v[146:147] op_sel_hi:[1,0]
	v_cvt_f32_f64_e32 v141, v[140:141]
	v_pk_mul_f32 v[138:139], v[138:139], v[172:173]
	v_pk_mul_f32 v[172:173], v[6:7], v[146:147] op_sel_hi:[1,0]
	v_cos_f32_e32 v140, v141
	v_sin_f32_e32 v150, v141
	v_cos_f32_e32 v141, v147
	v_sin_f32_e32 v151, v147
	v_pk_mul_f32 v[142:143], v[142:143], v[172:173]
	s_nop 0
	v_pk_mul_f32 v[172:173], v[140:141], v[142:143]
	v_pk_mul_f32 v[142:143], v[150:151], v[142:143]
	v_pk_fma_f32 v[172:173], v[150:151], v[138:139], v[172:173]
	v_mul_f64 v[150:151], v[186:187], v[148:149]
	v_pk_fma_f32 v[138:139], v[140:141], v[138:139], v[142:143] neg_lo:[0,0,1] neg_hi:[0,0,1]
; __device__ __forceinline__ unsigned cvtpk(float lo, float hi) { f32x2_t v = {lo, hi}; bf16x2_t b = __builtin_convertvector(v, bf16x2_t); return __builtin_bit_cast(unsigned, b); }
;     __device__ __forceinline__ void operator()(const f32x4 (&acc)[2][2][4][2], const Unit& u, int wr, int wc, int fr, int fq) const {
;     ...
;         if (u.pn >= 4) {
;             const int col0 = u.pn * BM + wc * 32 + 8 * fq;
; #pragma unroll
;             for (int ai = 0; ai < 2; ++ai)
; #pragma unroll
;                 for (int m = 0; m < 4; ++m) {
;                     const int row = row0 + ai * HALF + m * 16;
;                     const float rs = (u.pn < 6 ? qscale : 1.0f) / sqrtf(ssq_sum(ssq_in + (size_t)row * 16) * (1.0f / DM) + EPS);
; #pragma unroll
;                     for (int bj = 0; bj < 2; ++bj) {
;                         const f32x4 v0 = acc[ai][bj][m][0] * rs, v1 = acc[ai][bj][m][1] * rs;
;                         u32x4 w; w.x = cvtpk(v0[0], v0[1]); w.y = cvtpk(v0[2], v0[3]); w.z = cvtpk(v1[0], v1[1]); w.w = cvtpk(v1[2], v1[3]);
;                         *(u32x4*)(O + (size_t)row * 2048 + col0 + bj * HALF) = w;
;                     }
;                 }
;     ...
;                         float cs, sn; rope_cs(pos, 8 * fq + 4 * n + e, cs, sn);
;                         const float x1 = acc[ai][0][m][n][e] * rs * gv[0][n][e], x2 = acc[ai][1][m][n][e] * rs * gv[1][n][e];
;                         o1[4 * n + e] = x1 * cs - x2 * sn; o2[4 * n + e] = x1 * sn + x2 * cs;
;                     }
;                 bf16_t* op = O + (size_t)row * 2048 + head * 64 + 8 * fq;
;                 u32x4 w; w.x = cvtpk(o1[0], o1[1]); w.y = cvtpk(o1[2], o1[3]); w.z = cvtpk(o1[4], o1[5]); w.w = cvtpk(o1[6], o1[7]);
;                 *(u32x4*)op = w;
;                 w.x = cvtpk(o2[0], o2[1]); w.y = cvtpk(o2[2], o2[3]); w.z = cvtpk(o2[4], o2[5]); w.w = cvtpk(o2[6], o2[7]);
;                 *(u32x4*)(op + 32) = w;
	v_mul_f64 v[140:141], v[184:185], v[148:149]
	v_rndne_f64_e32 v[150:151], v[150:151]
	v_rndne_f64_e32 v[140:141], v[140:141]
	v_fma_f64 v[150:151], v[186:187], v[148:149], -v[150:151]
	v_fma_f64 v[140:141], v[184:185], v[148:149], -v[140:141]
	v_cvt_f32_f64_e32 v143, v[150:151]
	v_pk_mul_f32 v[150:151], v[8:9], v[146:147] op_sel_hi:[1,0]
	v_cvt_f32_f64_e32 v141, v[140:141]
	v_pk_mul_f32 v[132:133], v[132:133], v[150:151]
	v_pk_mul_f32 v[150:151], v[0:1], v[146:147] op_sel_hi:[1,0]
	v_cos_f32_e32 v140, v141
	v_sin_f32_e32 v142, v141
	v_cos_f32_e32 v141, v143
	v_sin_f32_e32 v143, v143
	v_pk_mul_f32 v[128:129], v[128:129], v[150:151]
	s_nop 0
	v_pk_mul_f32 v[150:151], v[140:141], v[128:129]
	v_pk_mul_f32 v[128:129], v[142:143], v[128:129]
	v_pk_fma_f32 v[150:151], v[142:143], v[132:133], v[150:151]
	v_mul_f64 v[142:143], v[180:181], v[148:149]
	v_pk_fma_f32 v[132:133], v[140:141], v[132:133], v[128:129] neg_lo:[0,0,1] neg_hi:[0,0,1]
	v_mul_f64 v[128:129], v[182:183], v[148:149]
	v_rndne_f64_e32 v[142:143], v[142:143]
	v_rndne_f64_e32 v[128:129], v[128:129]
	v_fma_f64 v[142:143], v[180:181], v[148:149], -v[142:143]
	v_fma_f64 v[128:129], v[182:183], v[148:149], -v[128:129]
	v_cvt_f32_f64_e32 v141, v[142:143]
	v_pk_mul_f32 v[142:143], v[10:11], v[146:147] op_sel_hi:[1,0]
	v_cvt_f32_f64_e32 v129, v[128:129]
	v_pk_mul_f32 v[134:135], v[134:135], v[142:143]
	v_pk_mul_f32 v[142:143], v[2:3], v[146:147] op_sel_hi:[1,0]
	v_cos_f32_e32 v128, v129
	v_sin_f32_e32 v140, v129
	v_cos_f32_e32 v129, v141
	v_sin_f32_e32 v141, v141
	v_pk_mul_f32 v[130:131], v[130:131], v[142:143]
	s_nop 0
	v_pk_mul_f32 v[142:143], v[128:129], v[130:131]
	v_pk_mul_f32 v[130:131], v[140:141], v[130:131]
	v_pk_fma_f32 v[142:143], v[140:141], v[134:135], v[142:143]
	v_pk_fma_f32 v[134:135], v[128:129], v[134:135], v[130:131] neg_lo:[0,0,1] neg_hi:[0,0,1]
	v_lshlrev_b64 v[128:129], 12, v[144:145]
	v_lshl_add_u64 v[128:129], s[22:23], 0, v[128:129]
	v_lshl_add_u64 v[128:129], v[128:129], 0, s[10:11]
	v_lshl_add_u64 v[140:141], v[128:129], 0, v[188:189]
	v_cvt_pk_bf16_f32 v128, v136, v137
	v_cvt_pk_bf16_f32 v129, v138, v139
	v_cvt_pk_bf16_f32 v130, v132, v133
	v_cvt_pk_bf16_f32 v131, v134, v135
	global_store_dwordx4 v[140:141], v[128:131], off
	s_nop 1
	v_cvt_pk_bf16_f32 v128, v174, v175
	v_cvt_pk_bf16_f32 v129, v172, v173
	v_cvt_pk_bf16_f32 v130, v150, v151
	v_cvt_pk_bf16_f32 v131, v142, v143
	global_store_dwordx4 v[140:141], v[128:131], off offset:64
	s_cbranch_execnz .LBB0_477
.LBB0_479:
	s_nop 0
	v_lshlrev_b64 v[128:129], 6, v[168:169]
	v_lshl_add_u64 v[140:141], s[18:19], 0, v[128:129]
	s_nop 1
	ds_read_b32 v128, v253 offset:0
	v_mov_b32_e32 v129, 0
	v_mov_b32_e32 v130, 0
	v_mov_b32_e32 v131, 0
	v_mov_b32_e32 v136, 0
	v_mov_b32_e32 v137, 0
	v_mov_b32_e32 v138, 0
	v_mov_b32_e32 v139, 0
	v_mov_b32_e32 v132, 0
	v_mov_b32_e32 v133, 0
	v_mov_b32_e32 v134, 0
	v_mov_b32_e32 v135, 0
	v_mov_b32_e32 v140, 0
	v_mov_b32_e32 v141, 0
	v_mov_b32_e32 v142, 0
	v_mov_b32_e32 v143, 0
	s_waitcnt lgkmcnt(0)
	s_lshl_b32 s0, s66, 8
	s_or_b32 s0, s0, s55
	s_cmp_lt_u32 s66, 6
	s_cselect_b64 s[8:9], -1, 0
	v_lshl_add_u32 v148, v206, 3, s0
	v_lshlrev_b64 v[144:145], 12, v[168:169]
	v_ashrrev_i32_e32 v149, 31, v148
	v_lshl_add_u64 v[144:145], s[22:23], 0, v[144:145]
	v_lshlrev_b64 v[146:147], 6, v[170:171]
	v_lshl_add_u64 v[146:147], s[18:19], 0, v[146:147]
	s_waitcnt vmcnt(0)
	v_mov_b32_e32 v150, v128
	v_mov_b32_e32 v151, v132
	v_mov_b32_e32 v132, v129
	v_mov_b32_e32 v128, v130
	v_mov_b32_e32 v129, v134
	v_mov_b32_e32 v134, v131
	v_mov_b32_e32 v130, v136
	v_mov_b32_e32 v131, v140
	v_mov_b32_e32 v140, v137
	v_mov_b32_e32 v136, v138
	v_mov_b32_e32 v137, v142
	v_mov_b32_e32 v142, v139
	v_pk_add_f32 v[132:133], v[150:151], v[132:133]
	v_pk_add_f32 v[128:129], v[128:129], v[134:135]
	v_pk_add_f32 v[130:131], v[130:131], v[140:141]
	v_pk_add_f32 v[134:135], v[136:137], v[142:143]
	v_pk_add_f32 v[128:129], v[132:133], v[128:129]
	v_pk_add_f32 v[130:131], v[130:131], v[134:135]
	s_nop 0
	v_pk_add_f32 v[128:129], v[128:129], v[130:131]
	v_cndmask_b32_e64 v130, 1.0, v205, s[8:9]
	v_add_f32_e32 v128, v128, v129
	v_fmamk_f32 v128, v128, 0x3a800000, v202
	v_mul_f32_e32 v129, 0x4f800000, v128
	v_cmp_gt_f32_e32 vcc, s62, v128
	s_nop 1
	v_cndmask_b32_e32 v131, v128, v129, vcc
	v_sqrt_f32_e32 v132, v131
	v_lshlrev_b64 v[128:129], 1, v[148:149]
	v_add_u32_e32 v133, -1, v132
	v_add_u32_e32 v134, 1, v132
	v_fma_f32 v135, -v133, v132, v131
	v_fma_f32 v136, -v134, v132, v131
	v_cmp_ge_f32_e64 s[8:9], 0, v135
	s_nop 1
	v_cndmask_b32_e64 v132, v132, v133, s[8:9]
	v_cmp_lt_f32_e64 s[8:9], 0, v136
	s_nop 1
	v_cndmask_b32_e64 v132, v132, v134, s[8:9]
	v_mul_f32_e32 v133, 0x37800000, v132
	v_cndmask_b32_e32 v132, v132, v133, vcc
	v_cmp_class_f32_e32 vcc, v131, v203
	s_nop 1
	v_cndmask_b32_e32 v131, v132, v131, vcc
	v_div_scale_f32 v134, s[0:1], v131, v131, v130
	v_rcp_f32_e32 v135, v134
	v_div_scale_f32 v136, vcc, v130, v131, v130
	v_lshl_add_u64 v[132:133], v[144:145], 0, v[128:129]
	v_fma_f32 v137, -v134, v135, 1.0
	v_fmac_f32_e32 v135, v137, v135
	v_mul_f32_e32 v137, v136, v135
	v_fma_f32 v138, -v134, v137, v136
	v_fmac_f32_e32 v137, v138, v135
	v_fma_f32 v134, -v134, v137, v136
	v_div_fmas_f32 v134, v134, v135, v137
	v_div_fixup_f32 v134, v134, v131, v130
	v_pk_mul_f32 v[126:127], v[126:127], v[134:135] op_sel_hi:[1,0]
	v_pk_mul_f32 v[124:125], v[124:125], v[134:135] op_sel_hi:[1,0]
	v_pk_mul_f32 v[122:123], v[122:123], v[134:135] op_sel_hi:[1,0]
	v_pk_mul_f32 v[120:121], v[120:121], v[134:135] op_sel_hi:[1,0]
	v_pk_mul_f32 v[118:119], v[118:119], v[134:135] op_sel_hi:[1,0]
	v_pk_mul_f32 v[116:117], v[116:117], v[134:135] op_sel_hi:[1,0]
	v_pk_mul_f32 v[136:137], v[114:115], v[134:135] op_sel_hi:[1,0]
	v_pk_mul_f32 v[134:135], v[112:113], v[134:135] op_sel_hi:[1,0]
	v_cvt_pk_bf16_f32 v112, v124, v125
	v_cvt_pk_bf16_f32 v113, v126, v127
	v_cvt_pk_bf16_f32 v114, v120, v121
	v_cvt_pk_bf16_f32 v115, v122, v123
	v_cvt_pk_bf16_f32 v116, v116, v117
	v_cvt_pk_bf16_f32 v117, v118, v119
	v_cvt_pk_bf16_f32 v118, v134, v135
	v_cvt_pk_bf16_f32 v119, v136, v137
	global_store_dwordx4 v[132:133], v[112:115], off
	global_store_dwordx4 v[132:133], v[116:119], off offset:256
	s_nop 1
	ds_read_b32 v112, v253 offset:64
	v_mov_b32_e32 v113, 0
	v_mov_b32_e32 v114, 0
	v_mov_b32_e32 v115, 0
	v_mov_b32_e32 v120, 0
	v_mov_b32_e32 v121, 0
	v_mov_b32_e32 v122, 0
	v_mov_b32_e32 v123, 0
	v_mov_b32_e32 v116, 0
	v_mov_b32_e32 v117, 0
	v_mov_b32_e32 v118, 0
	v_mov_b32_e32 v119, 0
	v_mov_b32_e32 v124, 0
	v_mov_b32_e32 v125, 0
	v_mov_b32_e32 v126, 0
	v_mov_b32_e32 v127, 0
	s_waitcnt lgkmcnt(0)
; __device__ __forceinline__ unsigned cvtpk(float lo, float hi) { f32x2_t v = {lo, hi}; bf16x2_t b = __builtin_convertvector(v, bf16x2_t); return __builtin_bit_cast(unsigned, b); }
;     __device__ __forceinline__ void operator()(const f32x4 (&acc)[2][2][4][2], const Unit& u, int wr, int wc, int fr, int fq) const {
;     ...
;             for (int ai = 0; ai < 2; ++ai)
; #pragma unroll
;                 for (int m = 0; m < 4; ++m) {
;                     const int row = row0 + ai * HALF + m * 16;
;                     const float rs = (u.pn < 6 ? qscale : 1.0f) / sqrtf(ssq_sum(ssq_in + (size_t)row * 16) * (1.0f / DM) + EPS);
; #pragma unroll
;                     for (int bj = 0; bj < 2; ++bj) {
;                         const f32x4 v0 = acc[ai][bj][m][0] * rs, v1 = acc[ai][bj][m][1] * rs;
;                         u32x4 w; w.x = cvtpk(v0[0], v0[1]); w.y = cvtpk(v0[2], v0[3]); w.z = cvtpk(v1[0], v1[1]); w.w = cvtpk(v1[2], v1[3]);
;                         *(u32x4*)(O + (size_t)row * 2048 + col0 + bj * HALF) = w;
;                     }
;                 }
	v_lshlrev_b64 v[132:133], 12, v[170:171]
	v_or_b32_e32 v134, 32, v168
	v_lshl_add_u64 v[132:133], s[22:23], 0, v[132:133]
	v_ashrrev_i32_e32 v135, 31, v134
	s_waitcnt vmcnt(3)
	v_mov_b32_e32 v136, v112
	s_waitcnt vmcnt(2)
	v_mov_b32_e32 v137, v116
	v_mov_b32_e32 v116, v113
	v_mov_b32_e32 v112, v114
	v_mov_b32_e32 v113, v118
	v_mov_b32_e32 v118, v115
	s_waitcnt vmcnt(1)
	v_mov_b32_e32 v114, v120
	s_waitcnt vmcnt(0)
	v_mov_b32_e32 v115, v124
	v_mov_b32_e32 v124, v121
	v_mov_b32_e32 v120, v122
	v_mov_b32_e32 v121, v126
	v_mov_b32_e32 v126, v123
	v_pk_add_f32 v[116:117], v[136:137], v[116:117]
	v_pk_add_f32 v[112:113], v[112:113], v[118:119]
	v_pk_add_f32 v[114:115], v[114:115], v[124:125]
	v_pk_add_f32 v[118:119], v[120:121], v[126:127]
	v_pk_add_f32 v[112:113], v[116:117], v[112:113]
	v_pk_add_f32 v[114:115], v[114:115], v[118:119]
	s_nop 0
	v_pk_add_f32 v[112:113], v[112:113], v[114:115]
	s_nop 0
	v_add_f32_e32 v112, v112, v113
	v_fmamk_f32 v112, v112, 0x3a800000, v202
	v_mul_f32_e32 v113, 0x4f800000, v112
	v_cmp_gt_f32_e32 vcc, s62, v112
	s_nop 1
	v_cndmask_b32_e32 v114, v112, v113, vcc
	v_sqrt_f32_e32 v115, v114
	v_lshlrev_b64 v[112:113], 6, v[134:135]
	v_lshl_add_u64 v[112:113], s[18:19], 0, v[112:113]
	v_add_u32_e32 v116, -1, v115
	v_add_u32_e32 v117, 1, v115
	v_fma_f32 v118, -v116, v115, v114
	v_fma_f32 v119, -v117, v115, v114
	v_cmp_ge_f32_e64 s[8:9], 0, v118
	s_nop 1
	v_cndmask_b32_e64 v115, v115, v116, s[8:9]
	v_cmp_lt_f32_e64 s[8:9], 0, v119
	s_nop 1
	v_cndmask_b32_e64 v115, v115, v117, s[8:9]
	v_mul_f32_e32 v116, 0x37800000, v115
	v_cndmask_b32_e32 v115, v115, v116, vcc
	v_cmp_class_f32_e32 vcc, v114, v203
	s_nop 1
	v_cndmask_b32_e32 v116, v115, v114, vcc
	v_div_scale_f32 v117, s[0:1], v116, v116, v130
	v_rcp_f32_e32 v118, v117
	v_div_scale_f32 v119, vcc, v130, v116, v130
	v_lshl_add_u64 v[114:115], v[132:133], 0, v[128:129]
	v_fma_f32 v120, -v117, v118, 1.0
	v_fmac_f32_e32 v118, v120, v118
	v_mul_f32_e32 v120, v119, v118
	v_fma_f32 v121, -v117, v120, v119
	v_fmac_f32_e32 v120, v121, v118
	v_fma_f32 v117, -v117, v120, v119
	v_div_fmas_f32 v117, v117, v118, v120
	v_div_fixup_f32 v116, v117, v116, v130
	v_pk_mul_f32 v[110:111], v[110:111], v[116:117] op_sel_hi:[1,0]
	v_pk_mul_f32 v[108:109], v[108:109], v[116:117] op_sel_hi:[1,0]
	v_pk_mul_f32 v[106:107], v[106:107], v[116:117] op_sel_hi:[1,0]
	v_pk_mul_f32 v[104:105], v[104:105], v[116:117] op_sel_hi:[1,0]
	v_pk_mul_f32 v[102:103], v[102:103], v[116:117] op_sel_hi:[1,0]
	v_pk_mul_f32 v[100:101], v[100:101], v[116:117] op_sel_hi:[1,0]
	v_pk_mul_f32 v[118:119], v[98:99], v[116:117] op_sel_hi:[1,0]
	v_pk_mul_f32 v[116:117], v[96:97], v[116:117] op_sel_hi:[1,0]
	v_cvt_pk_bf16_f32 v96, v108, v109
	v_cvt_pk_bf16_f32 v97, v110, v111
	v_cvt_pk_bf16_f32 v98, v104, v105
	v_cvt_pk_bf16_f32 v99, v106, v107
	v_cvt_pk_bf16_f32 v100, v100, v101
	v_cvt_pk_bf16_f32 v101, v102, v103
	v_cvt_pk_bf16_f32 v102, v116, v117
	v_cvt_pk_bf16_f32 v103, v118, v119
	global_store_dwordx4 v[114:115], v[96:99], off
	global_store_dwordx4 v[114:115], v[100:103], off offset:256
	s_nop 1
	ds_read_b32 v96, v253 offset:128
	v_mov_b32_e32 v97, 0
	v_mov_b32_e32 v98, 0
	v_mov_b32_e32 v99, 0
	v_mov_b32_e32 v104, 0
	v_mov_b32_e32 v105, 0
	v_mov_b32_e32 v106, 0
	v_mov_b32_e32 v107, 0
	v_mov_b32_e32 v100, 0
	v_mov_b32_e32 v101, 0
	v_mov_b32_e32 v102, 0
	v_mov_b32_e32 v103, 0
	v_mov_b32_e32 v108, 0
	v_mov_b32_e32 v109, 0
	v_mov_b32_e32 v110, 0
	v_mov_b32_e32 v111, 0
	s_waitcnt lgkmcnt(0)
	v_or_b32_e32 v112, 48, v168
	v_lshlrev_b64 v[114:115], 12, v[134:135]
	v_ashrrev_i32_e32 v113, 31, v112
	s_waitcnt vmcnt(3)
	v_mov_b32_e32 v116, v96
	s_waitcnt vmcnt(2)
	v_mov_b32_e32 v117, v100
	v_mov_b32_e32 v100, v97
	v_mov_b32_e32 v96, v98
	v_mov_b32_e32 v97, v102
	v_mov_b32_e32 v102, v99
	s_waitcnt vmcnt(1)
	v_mov_b32_e32 v98, v104
	s_waitcnt vmcnt(0)
	v_mov_b32_e32 v99, v108
	v_mov_b32_e32 v108, v105
	v_mov_b32_e32 v104, v106
	v_mov_b32_e32 v105, v110
	v_mov_b32_e32 v110, v107
	v_pk_add_f32 v[100:101], v[116:117], v[100:101]
	v_pk_add_f32 v[96:97], v[96:97], v[102:103]
	v_pk_add_f32 v[98:99], v[98:99], v[108:109]
	v_pk_add_f32 v[102:103], v[104:105], v[110:111]
	v_pk_add_f32 v[96:97], v[100:101], v[96:97]
	v_pk_add_f32 v[98:99], v[98:99], v[102:103]
	s_nop 0
	v_pk_add_f32 v[96:97], v[96:97], v[98:99]
	v_lshl_add_u64 v[98:99], s[22:23], 0, v[114:115]
	v_add_f32_e32 v96, v96, v97
	v_fmamk_f32 v96, v96, 0x3a800000, v202
	v_mul_f32_e32 v97, 0x4f800000, v96
	v_cmp_gt_f32_e32 vcc, s62, v96
	v_lshl_add_u64 v[98:99], v[98:99], 0, v[128:129]
	s_nop 0
	v_cndmask_b32_e32 v100, v96, v97, vcc
	v_sqrt_f32_e32 v101, v100
	v_lshlrev_b64 v[96:97], 6, v[112:113]
	v_lshl_add_u64 v[96:97], s[18:19], 0, v[96:97]
	v_add_u32_e32 v102, -1, v101
	v_add_u32_e32 v103, 1, v101
	v_fma_f32 v104, -v102, v101, v100
	v_fma_f32 v105, -v103, v101, v100
	v_cmp_ge_f32_e64 s[8:9], 0, v104
	s_nop 1
	v_cndmask_b32_e64 v101, v101, v102, s[8:9]
	v_cmp_lt_f32_e64 s[8:9], 0, v105
	s_nop 1
	v_cndmask_b32_e64 v101, v101, v103, s[8:9]
	v_mul_f32_e32 v102, 0x37800000, v101
	v_cndmask_b32_e32 v101, v101, v102, vcc
	v_cmp_class_f32_e32 vcc, v100, v203
	s_nop 1
	v_cndmask_b32_e32 v100, v101, v100, vcc
	v_div_scale_f32 v101, s[0:1], v100, v100, v130
	v_rcp_f32_e32 v102, v101
	v_div_scale_f32 v103, vcc, v130, v100, v130
	v_fma_f32 v104, -v101, v102, 1.0
	v_fmac_f32_e32 v102, v104, v102
	v_mul_f32_e32 v104, v103, v102
	v_fma_f32 v105, -v101, v104, v103
	v_fmac_f32_e32 v104, v105, v102
	v_fma_f32 v101, -v101, v104, v103
	v_div_fmas_f32 v101, v101, v102, v104
	v_div_fixup_f32 v100, v101, v100, v130
	v_pk_mul_f32 v[94:95], v[94:95], v[100:101] op_sel_hi:[1,0]
	v_pk_mul_f32 v[92:93], v[92:93], v[100:101] op_sel_hi:[1,0]
	v_pk_mul_f32 v[90:91], v[90:91], v[100:101] op_sel_hi:[1,0]
	v_pk_mul_f32 v[88:89], v[88:89], v[100:101] op_sel_hi:[1,0]
	v_pk_mul_f32 v[86:87], v[86:87], v[100:101] op_sel_hi:[1,0]
	v_pk_mul_f32 v[84:85], v[84:85], v[100:101] op_sel_hi:[1,0]
	v_pk_mul_f32 v[102:103], v[82:83], v[100:101] op_sel_hi:[1,0]
	v_pk_mul_f32 v[100:101], v[80:81], v[100:101] op_sel_hi:[1,0]
	v_cvt_pk_bf16_f32 v80, v92, v93
	v_cvt_pk_bf16_f32 v81, v94, v95
	v_cvt_pk_bf16_f32 v82, v88, v89
	v_cvt_pk_bf16_f32 v83, v90, v91
	v_cvt_pk_bf16_f32 v84, v84, v85
	v_cvt_pk_bf16_f32 v85, v86, v87
	v_cvt_pk_bf16_f32 v86, v100, v101
	v_cvt_pk_bf16_f32 v87, v102, v103
	global_store_dwordx4 v[98:99], v[80:83], off
	global_store_dwordx4 v[98:99], v[84:87], off offset:256
	s_nop 1
	ds_read_b32 v80, v253 offset:192
	v_mov_b32_e32 v81, 0
	v_mov_b32_e32 v82, 0
	v_mov_b32_e32 v83, 0
	v_mov_b32_e32 v88, 0
	v_mov_b32_e32 v89, 0
	v_mov_b32_e32 v90, 0
	v_mov_b32_e32 v91, 0
	v_mov_b32_e32 v84, 0
	v_mov_b32_e32 v85, 0
	v_mov_b32_e32 v86, 0
	v_mov_b32_e32 v87, 0
	v_mov_b32_e32 v92, 0
	v_mov_b32_e32 v93, 0
	v_mov_b32_e32 v94, 0
	v_mov_b32_e32 v95, 0
	s_waitcnt lgkmcnt(0)
; __device__ __forceinline__ unsigned cvtpk(float lo, float hi) { f32x2_t v = {lo, hi}; bf16x2_t b = __builtin_convertvector(v, bf16x2_t); return __builtin_bit_cast(unsigned, b); }
;     __device__ __forceinline__ void operator()(const f32x4 (&acc)[2][2][4][2], const Unit& u, int wr, int wc, int fr, int fq) const {
;     ...
;             for (int ai = 0; ai < 2; ++ai)
; #pragma unroll
;                 for (int m = 0; m < 4; ++m) {
;                     const int row = row0 + ai * HALF + m * 16;
;                     const float rs = (u.pn < 6 ? qscale : 1.0f) / sqrtf(ssq_sum(ssq_in + (size_t)row * 16) * (1.0f / DM) + EPS);
; #pragma unroll
;                     for (int bj = 0; bj < 2; ++bj) {
;                         const f32x4 v0 = acc[ai][bj][m][0] * rs, v1 = acc[ai][bj][m][1] * rs;
;                         u32x4 w; w.x = cvtpk(v0[0], v0[1]); w.y = cvtpk(v0[2], v0[3]); w.z = cvtpk(v1[0], v1[1]); w.w = cvtpk(v1[2], v1[3]);
;                         *(u32x4*)(O + (size_t)row * 2048 + col0 + bj * HALF) = w;
;                     }
;                 }
	v_add_u32_e32 v96, 0x80, v168
	v_lshlrev_b64 v[98:99], 12, v[112:113]
	v_ashrrev_i32_e32 v97, 31, v96
	s_waitcnt vmcnt(3)
	v_mov_b32_e32 v100, v80
	s_waitcnt vmcnt(2)
	v_mov_b32_e32 v101, v84
	v_mov_b32_e32 v84, v81
	v_mov_b32_e32 v80, v82
	v_mov_b32_e32 v81, v86
	v_mov_b32_e32 v86, v83
	s_waitcnt vmcnt(1)
	v_mov_b32_e32 v82, v88
	s_waitcnt vmcnt(0)
	v_mov_b32_e32 v83, v92
	v_mov_b32_e32 v92, v89
	v_mov_b32_e32 v88, v90
	v_mov_b32_e32 v89, v94
	v_mov_b32_e32 v94, v91
	v_pk_add_f32 v[84:85], v[100:101], v[84:85]
	v_pk_add_f32 v[80:81], v[80:81], v[86:87]
	v_pk_add_f32 v[82:83], v[82:83], v[92:93]
	v_pk_add_f32 v[86:87], v[88:89], v[94:95]
	v_pk_add_f32 v[80:81], v[84:85], v[80:81]
	v_pk_add_f32 v[82:83], v[82:83], v[86:87]
	s_nop 0
	v_pk_add_f32 v[80:81], v[80:81], v[82:83]
	v_lshl_add_u64 v[82:83], s[22:23], 0, v[98:99]
	v_add_f32_e32 v80, v80, v81
	v_fmamk_f32 v80, v80, 0x3a800000, v202
	v_mul_f32_e32 v81, 0x4f800000, v80
	v_cmp_gt_f32_e32 vcc, s62, v80
	v_lshl_add_u64 v[82:83], v[82:83], 0, v[128:129]
	s_nop 0
	v_cndmask_b32_e32 v84, v80, v81, vcc
	v_sqrt_f32_e32 v85, v84
	v_lshlrev_b64 v[80:81], 6, v[96:97]
	v_lshl_add_u64 v[80:81], s[18:19], 0, v[80:81]
	v_add_u32_e32 v86, -1, v85
	v_add_u32_e32 v87, 1, v85
	v_fma_f32 v88, -v86, v85, v84
	v_fma_f32 v89, -v87, v85, v84
	v_cmp_ge_f32_e64 s[8:9], 0, v88
	s_nop 1
	v_cndmask_b32_e64 v85, v85, v86, s[8:9]
	v_cmp_lt_f32_e64 s[8:9], 0, v89
	s_nop 1
	v_cndmask_b32_e64 v85, v85, v87, s[8:9]
	v_mul_f32_e32 v86, 0x37800000, v85
	v_cndmask_b32_e32 v85, v85, v86, vcc
	v_cmp_class_f32_e32 vcc, v84, v203
	s_nop 1
	v_cndmask_b32_e32 v84, v85, v84, vcc
	v_div_scale_f32 v85, s[0:1], v84, v84, v130
	v_rcp_f32_e32 v86, v85
	v_div_scale_f32 v87, vcc, v130, v84, v130
	v_fma_f32 v88, -v85, v86, 1.0
	v_fmac_f32_e32 v86, v88, v86
	v_mul_f32_e32 v88, v87, v86
	v_fma_f32 v89, -v85, v88, v87
	v_fmac_f32_e32 v88, v89, v86
	v_fma_f32 v85, -v85, v88, v87
	v_div_fmas_f32 v85, v85, v86, v88
	v_div_fixup_f32 v84, v85, v84, v130
	v_pk_mul_f32 v[78:79], v[78:79], v[84:85] op_sel_hi:[1,0]
	v_pk_mul_f32 v[76:77], v[76:77], v[84:85] op_sel_hi:[1,0]
	v_pk_mul_f32 v[74:75], v[74:75], v[84:85] op_sel_hi:[1,0]
	v_pk_mul_f32 v[72:73], v[72:73], v[84:85] op_sel_hi:[1,0]
	v_pk_mul_f32 v[70:71], v[70:71], v[84:85] op_sel_hi:[1,0]
	v_pk_mul_f32 v[68:69], v[68:69], v[84:85] op_sel_hi:[1,0]
	v_pk_mul_f32 v[86:87], v[66:67], v[84:85] op_sel_hi:[1,0]
	v_pk_mul_f32 v[84:85], v[64:65], v[84:85] op_sel_hi:[1,0]
	v_cvt_pk_bf16_f32 v64, v76, v77
	v_cvt_pk_bf16_f32 v65, v78, v79
	v_cvt_pk_bf16_f32 v66, v72, v73
	v_cvt_pk_bf16_f32 v67, v74, v75
	v_cvt_pk_bf16_f32 v68, v68, v69
	v_cvt_pk_bf16_f32 v69, v70, v71
	v_cvt_pk_bf16_f32 v70, v84, v85
	v_cvt_pk_bf16_f32 v71, v86, v87
	global_store_dwordx4 v[82:83], v[64:67], off
	global_store_dwordx4 v[82:83], v[68:71], off offset:256
	s_nop 1
	ds_read_b32 v64, v253 offset:512
	v_mov_b32_e32 v65, 0
	v_mov_b32_e32 v66, 0
	v_mov_b32_e32 v67, 0
	v_mov_b32_e32 v72, 0
	v_mov_b32_e32 v73, 0
	v_mov_b32_e32 v74, 0
	v_mov_b32_e32 v75, 0
	v_mov_b32_e32 v68, 0
	v_mov_b32_e32 v69, 0
	v_mov_b32_e32 v70, 0
	v_mov_b32_e32 v71, 0
	v_mov_b32_e32 v76, 0
	v_mov_b32_e32 v77, 0
	v_mov_b32_e32 v78, 0
	v_mov_b32_e32 v79, 0
	s_waitcnt lgkmcnt(0)
	v_add_u32_e32 v80, 0x90, v168
	v_lshlrev_b64 v[82:83], 12, v[96:97]
	v_ashrrev_i32_e32 v81, 31, v80
	s_waitcnt vmcnt(3)
	v_mov_b32_e32 v84, v64
	s_waitcnt vmcnt(2)
	v_mov_b32_e32 v85, v68
	v_mov_b32_e32 v68, v65
	v_mov_b32_e32 v64, v66
	v_mov_b32_e32 v65, v70
	v_mov_b32_e32 v70, v67
	s_waitcnt vmcnt(1)
	v_mov_b32_e32 v66, v72
	s_waitcnt vmcnt(0)
	v_mov_b32_e32 v67, v76
	v_mov_b32_e32 v76, v73
	v_mov_b32_e32 v72, v74
	v_mov_b32_e32 v73, v78
	v_mov_b32_e32 v78, v75
	v_pk_add_f32 v[68:69], v[84:85], v[68:69]
	v_pk_add_f32 v[64:65], v[64:65], v[70:71]
	v_pk_add_f32 v[66:67], v[66:67], v[76:77]
	v_pk_add_f32 v[70:71], v[72:73], v[78:79]
	v_pk_add_f32 v[64:65], v[68:69], v[64:65]
	v_pk_add_f32 v[66:67], v[66:67], v[70:71]
	s_nop 0
	v_pk_add_f32 v[64:65], v[64:65], v[66:67]
	v_lshl_add_u64 v[66:67], s[22:23], 0, v[82:83]
	v_add_f32_e32 v64, v64, v65
	v_fmamk_f32 v64, v64, 0x3a800000, v202
	v_mul_f32_e32 v65, 0x4f800000, v64
	v_cmp_gt_f32_e32 vcc, s62, v64
	v_lshl_add_u64 v[66:67], v[66:67], 0, v[128:129]
	s_nop 0
	v_cndmask_b32_e32 v68, v64, v65, vcc
	v_sqrt_f32_e32 v69, v68
	v_lshlrev_b64 v[64:65], 6, v[80:81]
	v_lshl_add_u64 v[64:65], s[18:19], 0, v[64:65]
	v_add_u32_e32 v70, -1, v69
	v_add_u32_e32 v71, 1, v69
	v_fma_f32 v72, -v70, v69, v68
	v_fma_f32 v73, -v71, v69, v68
	v_cmp_ge_f32_e64 s[8:9], 0, v72
	s_nop 1
	v_cndmask_b32_e64 v69, v69, v70, s[8:9]
	v_cmp_lt_f32_e64 s[8:9], 0, v73
	s_nop 1
	v_cndmask_b32_e64 v69, v69, v71, s[8:9]
	v_mul_f32_e32 v70, 0x37800000, v69
	v_cndmask_b32_e32 v69, v69, v70, vcc
	v_cmp_class_f32_e32 vcc, v68, v203
	s_nop 1
	v_cndmask_b32_e32 v68, v69, v68, vcc
	v_div_scale_f32 v69, s[0:1], v68, v68, v130
	v_rcp_f32_e32 v70, v69
	v_div_scale_f32 v71, vcc, v130, v68, v130
	v_fma_f32 v72, -v69, v70, 1.0
	v_fmac_f32_e32 v70, v72, v70
	v_mul_f32_e32 v72, v71, v70
	v_fma_f32 v73, -v69, v72, v71
	v_fmac_f32_e32 v72, v73, v70
	v_fma_f32 v69, -v69, v72, v71
	v_div_fmas_f32 v69, v69, v70, v72
	v_div_fixup_f32 v68, v69, v68, v130
	v_pk_mul_f32 v[62:63], v[62:63], v[68:69] op_sel_hi:[1,0]
	v_pk_mul_f32 v[60:61], v[60:61], v[68:69] op_sel_hi:[1,0]
	v_pk_mul_f32 v[58:59], v[58:59], v[68:69] op_sel_hi:[1,0]
	v_pk_mul_f32 v[56:57], v[56:57], v[68:69] op_sel_hi:[1,0]
	v_pk_mul_f32 v[54:55], v[54:55], v[68:69] op_sel_hi:[1,0]
	v_pk_mul_f32 v[52:53], v[52:53], v[68:69] op_sel_hi:[1,0]
	v_pk_mul_f32 v[70:71], v[50:51], v[68:69] op_sel_hi:[1,0]
	v_pk_mul_f32 v[68:69], v[48:49], v[68:69] op_sel_hi:[1,0]
	v_cvt_pk_bf16_f32 v48, v60, v61
	v_cvt_pk_bf16_f32 v49, v62, v63
	v_cvt_pk_bf16_f32 v50, v56, v57
	v_cvt_pk_bf16_f32 v51, v58, v59
	v_cvt_pk_bf16_f32 v52, v52, v53
	v_cvt_pk_bf16_f32 v53, v54, v55
	v_cvt_pk_bf16_f32 v54, v68, v69
	v_cvt_pk_bf16_f32 v55, v70, v71
	global_store_dwordx4 v[66:67], v[48:51], off
	global_store_dwordx4 v[66:67], v[52:55], off offset:256
	s_nop 1
	ds_read_b32 v48, v253 offset:576
	v_mov_b32_e32 v49, 0
	v_mov_b32_e32 v50, 0
	v_mov_b32_e32 v51, 0
	v_mov_b32_e32 v56, 0
	v_mov_b32_e32 v57, 0
	v_mov_b32_e32 v58, 0
	v_mov_b32_e32 v59, 0
	v_mov_b32_e32 v52, 0
	v_mov_b32_e32 v53, 0
	v_mov_b32_e32 v54, 0
	v_mov_b32_e32 v55, 0
	v_mov_b32_e32 v60, 0
	v_mov_b32_e32 v61, 0
	v_mov_b32_e32 v62, 0
	v_mov_b32_e32 v63, 0
	s_waitcnt lgkmcnt(0)
; __device__ __forceinline__ unsigned cvtpk(float lo, float hi) { f32x2_t v = {lo, hi}; bf16x2_t b = __builtin_convertvector(v, bf16x2_t); return __builtin_bit_cast(unsigned, b); }
;     __device__ __forceinline__ void operator()(const f32x4 (&acc)[2][2][4][2], const Unit& u, int wr, int wc, int fr, int fq) const {
;     ...
;             for (int ai = 0; ai < 2; ++ai)
; #pragma unroll
;                 for (int m = 0; m < 4; ++m) {
;                     const int row = row0 + ai * HALF + m * 16;
;                     const float rs = (u.pn < 6 ? qscale : 1.0f) / sqrtf(ssq_sum(ssq_in + (size_t)row * 16) * (1.0f / DM) + EPS);
; #pragma unroll
;                     for (int bj = 0; bj < 2; ++bj) {
;                         const f32x4 v0 = acc[ai][bj][m][0] * rs, v1 = acc[ai][bj][m][1] * rs;
;                         u32x4 w; w.x = cvtpk(v0[0], v0[1]); w.y = cvtpk(v0[2], v0[3]); w.z = cvtpk(v1[0], v1[1]); w.w = cvtpk(v1[2], v1[3]);
;                         *(u32x4*)(O + (size_t)row * 2048 + col0 + bj * HALF) = w;
;                     }
;                 }
	v_add_u32_e32 v64, 0xa0, v168
	v_lshlrev_b64 v[66:67], 12, v[80:81]
	v_ashrrev_i32_e32 v65, 31, v64
	s_waitcnt vmcnt(3)
	v_mov_b32_e32 v68, v48
	s_waitcnt vmcnt(2)
	v_mov_b32_e32 v69, v52
	v_mov_b32_e32 v52, v49
	v_mov_b32_e32 v48, v50
	v_mov_b32_e32 v49, v54
	v_mov_b32_e32 v54, v51
	s_waitcnt vmcnt(1)
	v_mov_b32_e32 v50, v56
	s_waitcnt vmcnt(0)
	v_mov_b32_e32 v51, v60
	v_mov_b32_e32 v60, v57
	v_mov_b32_e32 v56, v58
	v_mov_b32_e32 v57, v62
	v_mov_b32_e32 v62, v59
	v_pk_add_f32 v[52:53], v[68:69], v[52:53]
	v_pk_add_f32 v[48:49], v[48:49], v[54:55]
	v_pk_add_f32 v[50:51], v[50:51], v[60:61]
	v_pk_add_f32 v[54:55], v[56:57], v[62:63]
	v_pk_add_f32 v[48:49], v[52:53], v[48:49]
	v_pk_add_f32 v[50:51], v[50:51], v[54:55]
	s_nop 0
	v_pk_add_f32 v[48:49], v[48:49], v[50:51]
	v_lshl_add_u64 v[50:51], s[22:23], 0, v[66:67]
	v_add_f32_e32 v48, v48, v49
	v_fmamk_f32 v48, v48, 0x3a800000, v202
	v_mul_f32_e32 v49, 0x4f800000, v48
	v_cmp_gt_f32_e32 vcc, s62, v48
	v_lshl_add_u64 v[50:51], v[50:51], 0, v[128:129]
	s_nop 0
	v_cndmask_b32_e32 v52, v48, v49, vcc
	v_sqrt_f32_e32 v53, v52
	v_lshlrev_b64 v[48:49], 6, v[64:65]
	v_lshl_add_u64 v[48:49], s[18:19], 0, v[48:49]
	v_add_u32_e32 v54, -1, v53
	v_add_u32_e32 v55, 1, v53
	v_fma_f32 v56, -v54, v53, v52
	v_fma_f32 v57, -v55, v53, v52
	v_cmp_ge_f32_e64 s[8:9], 0, v56
	s_nop 1
	v_cndmask_b32_e64 v53, v53, v54, s[8:9]
	v_cmp_lt_f32_e64 s[8:9], 0, v57
	s_nop 1
	v_cndmask_b32_e64 v53, v53, v55, s[8:9]
	v_mul_f32_e32 v54, 0x37800000, v53
	v_cndmask_b32_e32 v53, v53, v54, vcc
	v_cmp_class_f32_e32 vcc, v52, v203
	s_nop 1
	v_cndmask_b32_e32 v52, v53, v52, vcc
	v_div_scale_f32 v53, s[0:1], v52, v52, v130
	v_rcp_f32_e32 v54, v53
	v_div_scale_f32 v55, vcc, v130, v52, v130
	v_fma_f32 v56, -v53, v54, 1.0
	v_fmac_f32_e32 v54, v56, v54
	v_mul_f32_e32 v56, v55, v54
	v_fma_f32 v57, -v53, v56, v55
	v_fmac_f32_e32 v56, v57, v54
	v_fma_f32 v53, -v53, v56, v55
	v_div_fmas_f32 v53, v53, v54, v56
	v_div_fixup_f32 v52, v53, v52, v130
	v_pk_mul_f32 v[46:47], v[46:47], v[52:53] op_sel_hi:[1,0]
	v_pk_mul_f32 v[44:45], v[44:45], v[52:53] op_sel_hi:[1,0]
	v_pk_mul_f32 v[42:43], v[42:43], v[52:53] op_sel_hi:[1,0]
	v_pk_mul_f32 v[40:41], v[40:41], v[52:53] op_sel_hi:[1,0]
	v_pk_mul_f32 v[38:39], v[38:39], v[52:53] op_sel_hi:[1,0]
	v_pk_mul_f32 v[36:37], v[36:37], v[52:53] op_sel_hi:[1,0]
	v_pk_mul_f32 v[54:55], v[34:35], v[52:53] op_sel_hi:[1,0]
	v_pk_mul_f32 v[52:53], v[32:33], v[52:53] op_sel_hi:[1,0]
	v_cvt_pk_bf16_f32 v32, v44, v45
	v_cvt_pk_bf16_f32 v33, v46, v47
	v_cvt_pk_bf16_f32 v34, v40, v41
	v_cvt_pk_bf16_f32 v35, v42, v43
	v_cvt_pk_bf16_f32 v36, v36, v37
	v_cvt_pk_bf16_f32 v37, v38, v39
	v_cvt_pk_bf16_f32 v38, v52, v53
	v_cvt_pk_bf16_f32 v39, v54, v55
	global_store_dwordx4 v[50:51], v[32:35], off
	global_store_dwordx4 v[50:51], v[36:39], off offset:256
	s_nop 1
	ds_read_b32 v32, v253 offset:640
	v_mov_b32_e32 v33, 0
	v_mov_b32_e32 v34, 0
	v_mov_b32_e32 v35, 0
	v_mov_b32_e32 v40, 0
	v_mov_b32_e32 v41, 0
	v_mov_b32_e32 v42, 0
	v_mov_b32_e32 v43, 0
	v_mov_b32_e32 v36, 0
	v_mov_b32_e32 v37, 0
	v_mov_b32_e32 v38, 0
	v_mov_b32_e32 v39, 0
	v_mov_b32_e32 v44, 0
	v_mov_b32_e32 v45, 0
	v_mov_b32_e32 v46, 0
	v_mov_b32_e32 v47, 0
	s_waitcnt lgkmcnt(0)
	v_add_u32_e32 v48, 0xb0, v168
	v_lshlrev_b64 v[50:51], 12, v[64:65]
	v_ashrrev_i32_e32 v49, 31, v48
	s_waitcnt vmcnt(3)
	v_mov_b32_e32 v52, v32
	s_waitcnt vmcnt(2)
	v_mov_b32_e32 v53, v36
	v_mov_b32_e32 v36, v33
	v_mov_b32_e32 v32, v34
	v_mov_b32_e32 v33, v38
	v_mov_b32_e32 v38, v35
	s_waitcnt vmcnt(1)
	v_mov_b32_e32 v34, v40
	s_waitcnt vmcnt(0)
; __device__ __forceinline__ unsigned cvtpk(float lo, float hi) { f32x2_t v = {lo, hi}; bf16x2_t b = __builtin_convertvector(v, bf16x2_t); return __builtin_bit_cast(unsigned, b); }
;     __device__ __forceinline__ void operator()(const f32x4 (&acc)[2][2][4][2], const Unit& u, int wr, int wc, int fr, int fq) const {
;     ...
;             for (int ai = 0; ai < 2; ++ai)
; #pragma unroll
;                 for (int m = 0; m < 4; ++m) {
;                     const int row = row0 + ai * HALF + m * 16;
;                     const float rs = (u.pn < 6 ? qscale : 1.0f) / sqrtf(ssq_sum(ssq_in + (size_t)row * 16) * (1.0f / DM) + EPS);
; #pragma unroll
;                     for (int bj = 0; bj < 2; ++bj) {
;                         const f32x4 v0 = acc[ai][bj][m][0] * rs, v1 = acc[ai][bj][m][1] * rs;
;                         u32x4 w; w.x = cvtpk(v0[0], v0[1]); w.y = cvtpk(v0[2], v0[3]); w.z = cvtpk(v1[0], v1[1]); w.w = cvtpk(v1[2], v1[3]);
;                         *(u32x4*)(O + (size_t)row * 2048 + col0 + bj * HALF) = w;
;                     }
;                 }
	v_mov_b32_e32 v35, v44
	v_mov_b32_e32 v44, v41
	v_mov_b32_e32 v40, v42
	v_mov_b32_e32 v41, v46
	v_mov_b32_e32 v46, v43
	v_pk_add_f32 v[36:37], v[52:53], v[36:37]
	v_pk_add_f32 v[32:33], v[32:33], v[38:39]
	v_pk_add_f32 v[34:35], v[34:35], v[44:45]
	v_pk_add_f32 v[38:39], v[40:41], v[46:47]
	v_pk_add_f32 v[32:33], v[36:37], v[32:33]
	v_pk_add_f32 v[34:35], v[34:35], v[38:39]
	s_nop 0
	v_pk_add_f32 v[32:33], v[32:33], v[34:35]
	v_lshl_add_u64 v[34:35], s[22:23], 0, v[50:51]
	v_add_f32_e32 v32, v32, v33
	v_fmamk_f32 v32, v32, 0x3a800000, v202
	v_mul_f32_e32 v33, 0x4f800000, v32
	v_cmp_gt_f32_e32 vcc, s62, v32
	v_lshl_add_u64 v[34:35], v[34:35], 0, v[128:129]
	s_nop 0
	v_cndmask_b32_e32 v36, v32, v33, vcc
	v_sqrt_f32_e32 v37, v36
	v_lshlrev_b64 v[32:33], 6, v[48:49]
	v_lshl_add_u64 v[32:33], s[18:19], 0, v[32:33]
	v_add_u32_e32 v38, -1, v37
	v_add_u32_e32 v39, 1, v37
	v_fma_f32 v40, -v38, v37, v36
	v_fma_f32 v41, -v39, v37, v36
	v_cmp_ge_f32_e64 s[8:9], 0, v40
	s_nop 1
	v_cndmask_b32_e64 v37, v37, v38, s[8:9]
	v_cmp_lt_f32_e64 s[8:9], 0, v41
	s_nop 1
	v_cndmask_b32_e64 v37, v37, v39, s[8:9]
	v_mul_f32_e32 v38, 0x37800000, v37
	v_cndmask_b32_e32 v37, v37, v38, vcc
	v_cmp_class_f32_e32 vcc, v36, v203
	s_nop 1
	v_cndmask_b32_e32 v36, v37, v36, vcc
	v_div_scale_f32 v37, s[0:1], v36, v36, v130
	v_rcp_f32_e32 v38, v37
	v_div_scale_f32 v39, vcc, v130, v36, v130
	v_fma_f32 v40, -v37, v38, 1.0
	v_fmac_f32_e32 v38, v40, v38
	v_mul_f32_e32 v40, v39, v38
	v_fma_f32 v41, -v37, v40, v39
	v_fmac_f32_e32 v40, v41, v38
	v_fma_f32 v37, -v37, v40, v39
	v_div_fmas_f32 v37, v37, v38, v40
	v_div_fixup_f32 v36, v37, v36, v130
	v_pk_mul_f32 v[30:31], v[30:31], v[36:37] op_sel_hi:[1,0]
	v_pk_mul_f32 v[28:29], v[28:29], v[36:37] op_sel_hi:[1,0]
	v_pk_mul_f32 v[26:27], v[26:27], v[36:37] op_sel_hi:[1,0]
	v_pk_mul_f32 v[24:25], v[24:25], v[36:37] op_sel_hi:[1,0]
	v_pk_mul_f32 v[22:23], v[22:23], v[36:37] op_sel_hi:[1,0]
	v_pk_mul_f32 v[20:21], v[20:21], v[36:37] op_sel_hi:[1,0]
	v_pk_mul_f32 v[38:39], v[18:19], v[36:37] op_sel_hi:[1,0]
	v_pk_mul_f32 v[36:37], v[16:17], v[36:37] op_sel_hi:[1,0]
	v_cvt_pk_bf16_f32 v16, v28, v29
	v_cvt_pk_bf16_f32 v17, v30, v31
	v_cvt_pk_bf16_f32 v18, v24, v25
	v_cvt_pk_bf16_f32 v19, v26, v27
	v_cvt_pk_bf16_f32 v20, v20, v21
	v_cvt_pk_bf16_f32 v21, v22, v23
	v_cvt_pk_bf16_f32 v22, v36, v37
	v_cvt_pk_bf16_f32 v23, v38, v39
	global_store_dwordx4 v[34:35], v[16:19], off
	global_store_dwordx4 v[34:35], v[20:23], off offset:256
	s_nop 1
	ds_read_b32 v16, v253 offset:704
	v_mov_b32_e32 v17, 0
	v_mov_b32_e32 v18, 0
	v_mov_b32_e32 v19, 0
	v_mov_b32_e32 v24, 0
	v_mov_b32_e32 v25, 0
	v_mov_b32_e32 v26, 0
	v_mov_b32_e32 v27, 0
	v_mov_b32_e32 v20, 0
	v_mov_b32_e32 v21, 0
	v_mov_b32_e32 v22, 0
	v_mov_b32_e32 v23, 0
	v_mov_b32_e32 v28, 0
	v_mov_b32_e32 v29, 0
	v_mov_b32_e32 v30, 0
	v_mov_b32_e32 v31, 0
	s_waitcnt lgkmcnt(0)
	s_waitcnt vmcnt(3)
	v_mov_b32_e32 v32, v16
	s_waitcnt vmcnt(2)
	v_mov_b32_e32 v33, v20
	v_mov_b32_e32 v20, v17
	v_mov_b32_e32 v16, v18
	v_mov_b32_e32 v17, v22
	v_mov_b32_e32 v22, v19
	s_waitcnt vmcnt(1)
	v_mov_b32_e32 v18, v24
	s_waitcnt vmcnt(0)
	v_mov_b32_e32 v19, v28
	v_mov_b32_e32 v28, v25
	v_mov_b32_e32 v24, v26
	v_mov_b32_e32 v25, v30
	v_mov_b32_e32 v30, v27
	v_pk_add_f32 v[20:21], v[32:33], v[20:21]
	v_pk_add_f32 v[16:17], v[16:17], v[22:23]
	v_pk_add_f32 v[18:19], v[18:19], v[28:29]
	v_pk_add_f32 v[22:23], v[24:25], v[30:31]
	v_pk_add_f32 v[16:17], v[20:21], v[16:17]
	v_pk_add_f32 v[18:19], v[18:19], v[22:23]
	s_nop 0
	v_pk_add_f32 v[16:17], v[16:17], v[18:19]
	s_nop 0
	v_add_f32_e32 v16, v16, v17
	v_fmamk_f32 v16, v16, 0x3a800000, v202
	v_mul_f32_e32 v17, 0x4f800000, v16
	v_cmp_gt_f32_e32 vcc, s62, v16
	s_nop 1
	v_cndmask_b32_e32 v18, v16, v17, vcc
	v_sqrt_f32_e32 v19, v18
	v_lshlrev_b64 v[16:17], 12, v[48:49]
	v_lshl_add_u64 v[16:17], s[22:23], 0, v[16:17]
	v_lshl_add_u64 v[16:17], v[16:17], 0, v[128:129]
	v_add_u32_e32 v20, -1, v19
	v_add_u32_e32 v21, 1, v19
	v_fma_f32 v22, -v20, v19, v18
	v_fma_f32 v23, -v21, v19, v18
	v_cmp_ge_f32_e64 s[8:9], 0, v22
	s_nop 1
	v_cndmask_b32_e64 v19, v19, v20, s[8:9]
	v_cmp_lt_f32_e64 s[8:9], 0, v23
	s_nop 1
	v_cndmask_b32_e64 v19, v19, v21, s[8:9]
	v_mul_f32_e32 v20, 0x37800000, v19
	v_cndmask_b32_e32 v19, v19, v20, vcc
	v_cmp_class_f32_e32 vcc, v18, v203
	s_nop 1
	v_cndmask_b32_e32 v18, v19, v18, vcc
	v_div_scale_f32 v19, s[0:1], v18, v18, v130
	v_rcp_f32_e32 v20, v19
	v_div_scale_f32 v21, vcc, v130, v18, v130
	v_fma_f32 v22, -v19, v20, 1.0
	v_fmac_f32_e32 v20, v22, v20
	v_mul_f32_e32 v22, v21, v20
	v_fma_f32 v23, -v19, v22, v21
	v_fmac_f32_e32 v22, v23, v20
	v_fma_f32 v19, -v19, v22, v21
	v_div_fmas_f32 v19, v19, v20, v22
	v_div_fixup_f32 v18, v19, v18, v130
	v_pk_mul_f32 v[14:15], v[14:15], v[18:19] op_sel_hi:[1,0]
	v_pk_mul_f32 v[12:13], v[12:13], v[18:19] op_sel_hi:[1,0]
	v_pk_mul_f32 v[10:11], v[10:11], v[18:19] op_sel_hi:[1,0]
	v_pk_mul_f32 v[8:9], v[8:9], v[18:19] op_sel_hi:[1,0]
	v_pk_mul_f32 v[6:7], v[6:7], v[18:19] op_sel_hi:[1,0]
	v_pk_mul_f32 v[4:5], v[4:5], v[18:19] op_sel_hi:[1,0]
	v_pk_mul_f32 v[20:21], v[2:3], v[18:19] op_sel_hi:[1,0]
	v_pk_mul_f32 v[18:19], v[0:1], v[18:19] op_sel_hi:[1,0]
	v_cvt_pk_bf16_f32 v0, v12, v13
	v_cvt_pk_bf16_f32 v1, v14, v15
	v_cvt_pk_bf16_f32 v2, v8, v9
	v_cvt_pk_bf16_f32 v3, v10, v11
	v_cvt_pk_bf16_f32 v4, v4, v5
	v_cvt_pk_bf16_f32 v5, v6, v7
	v_cvt_pk_bf16_f32 v6, v18, v19
	v_cvt_pk_bf16_f32 v7, v20, v21
	global_store_dwordx4 v[16:17], v[0:3], off
	global_store_dwordx4 v[16:17], v[4:7], off offset:256
	s_andn2_b64 vcc, exec, s[6:7]
	s_mov_b64 s[6:7], -1
	s_cbranch_vccnz .LBB0_464

; __device__ __forceinline__ unsigned cvtpk(float lo, float hi) { f32x2_t v = {lo, hi}; bf16x2_t b = __builtin_convertvector(v, bf16x2_t); return __builtin_bit_cast(unsigned, b); }
;     __device__ __forceinline__ void operator()(const f32x4 (&acc)[2][2][4][2], const Unit& u, int wr, int wc, int fr, int fq) const {
;         const int row0 = u.pm * BM + wr * 64 + fr, col0 = u.pn * BM + wc * 32 + 8 * fq;
;         float* so = (u.pn == 0) ? ssq_o[0] : (u.pn == 1) ? ssq_o[1] : (u.pn == 2) ? ssq_o[2] : (u.pn == 3) ? ssq_o[3] : nullptr;
; #pragma unroll
;         for (int ai = 0; ai < 2; ++ai)
; #pragma unroll
;             for (int m = 0; m < 4; ++m) {
;                 const int row = row0 + ai * HALF + m * 16; float s = 0.f;
;                 const float rs = ssq_in ? 1.0f / sqrtf(ssq_sum(ssq_in + (size_t)row * 16) * inv_dim + EPS) : 1.0f;
; #pragma unroll
;                 for (int bj = 0; bj < 2; ++bj) {
;                     int col = col0 + bj * HALF; if (hd_in) col = (col / hd_in) * hd_out + (col % hd_in);
;                     const f32x4 v0 = acc[ai][bj][m][0] * rs, v1 = acc[ai][bj][m][1] * rs;
;                     u32x4 w; w.x = cvtpk(v0[0], v0[1]); w.y = cvtpk(v0[2], v0[3]); w.z = cvtpk(v1[0], v1[1]); w.w = cvtpk(v1[2], v1[3]);
;                     *(u32x4*)(O + (size_t)row * ldc + col) = w;
;                     s += (v0[0] * v0[0] + v0[1] * v0[1]) + (v0[2] * v0[2] + v0[3] * v0[3]) + (v1[0] * v1[0] + v1[1] * v1[1]) + (v1[2] * v1[2] + v1[3] * v1[3]);
;                 }
;                 if (so) { s += __shfl_xor(s, 16); s += __shfl_xor(s, 32); if (fq == 0) so[(size_t)row * 16 + (u.pn & 1) * 4 + wc] = s; }
.LBB0_1422:
	v_lshl_add_u32 v146, s12, 8, v150
	v_readlane_b32 vcc_lo, v254, 7
	v_mbcnt_lo_u32_b32 v218, -1, 0
	v_mbcnt_hi_u32_b32 v218, -1, v218
	v_lshrrev_b32_e32 v219, 1, v218
	v_lshl_add_u32 v219, vcc_lo, 5, v219
	v_and_b32_e32 v220, 1, v218
	v_lshl_add_u32 v221, s12, 8, v219
	v_lshlrev_b32_e32 v221, 6, v221
	v_lshl_add_u32 v221, v220, 5, v221
	global_load_dwordx4 v[222:225], v221, s[20:21]
	global_load_dwordx4 v[226:229], v221, s[20:21] offset:16
	v_mov_b32_e32 v253, v150
	v_lshlrev_b32_e32 v253, 2, v253
	v_add_u32_e32 v253, 0x20100, v253
	v_lshlrev_b32_e32 v219, 2, v219
	v_add_u32_e32 v219, 0x20100, v219
	s_waitcnt vmcnt(0)
	v_pk_add_f32 v[222:223], v[222:223], v[224:225]
	v_pk_add_f32 v[226:227], v[226:227], v[228:229]
	v_pk_add_f32 v[222:223], v[222:223], v[226:227]
	v_add_f32_e32 v222, v222, v223
	s_nop 1
	v_add_f32_dpp v222, v222, v222 quad_perm:[1,0,3,2] row_mask:0xf bank_mask:0xf
	ds_write_b32 v219, v222
	s_waitcnt lgkmcnt(0)
	s_barrier
	v_ashrrev_i32_e32 v147, 31, v146
	v_lshlrev_b64 v[148:149], 6, v[146:147]
	v_lshl_add_u64 v[144:145], s[20:21], 0, v[148:149]
	s_nop 1
	ds_read_b32 v160, v253 offset:0
	v_mov_b32_e32 v161, 0
	v_mov_b32_e32 v162, 0
	v_mov_b32_e32 v163, 0
	v_mov_b32_e32 v168, 0
	v_mov_b32_e32 v169, 0
	v_mov_b32_e32 v170, 0
	v_mov_b32_e32 v171, 0
	v_mov_b32_e32 v164, 0
	v_mov_b32_e32 v165, 0
	v_mov_b32_e32 v166, 0
	v_mov_b32_e32 v167, 0
	v_mov_b32_e32 v172, 0
	v_mov_b32_e32 v173, 0
	v_mov_b32_e32 v174, 0
	v_mov_b32_e32 v175, 0
	s_waitcnt lgkmcnt(0)
	v_lshlrev_b64 v[176:177], 11, v[146:147]
	s_cmp_lg_u64 s[44:45], 0
	v_lshl_or_b32 v144, s10, 8, v152
	s_cselect_b64 s[42:43], -1, 0
	s_lshl_b32 s10, s10, 4
	s_and_b32 s10, s10, 16
	s_add_u32 s10, s44, s10
	s_addc_u32 s11, s45, 0
	s_add_u32 s40, s10, s56
	s_addc_u32 s41, s11, 0
	v_ashrrev_i32_e32 v145, 31, v144
	v_lshl_add_u64 v[176:177], s[18:19], 0, v[176:177]
	s_cmp_eq_u64 s[44:45], 0
	s_waitcnt vmcnt(0)
	v_mov_b32_e32 v178, v160
	v_mov_b32_e32 v179, v164
	v_mov_b32_e32 v164, v161
	v_mov_b32_e32 v160, v162
	v_mov_b32_e32 v161, v166
	v_mov_b32_e32 v166, v163
	v_mov_b32_e32 v162, v168
	v_mov_b32_e32 v163, v172
	v_mov_b32_e32 v172, v169
	v_mov_b32_e32 v168, v170
	v_mov_b32_e32 v169, v174
	v_mov_b32_e32 v174, v171
	v_pk_add_f32 v[164:165], v[178:179], v[164:165]
	v_pk_add_f32 v[160:161], v[160:161], v[166:167]
	v_pk_add_f32 v[162:163], v[162:163], v[172:173]
	v_pk_add_f32 v[166:167], v[168:169], v[174:175]
	v_pk_add_f32 v[160:161], v[164:165], v[160:161]
	v_pk_add_f32 v[162:163], v[162:163], v[166:167]
	v_lshl_add_u64 v[168:169], v[144:145], 1, v[176:177]
	v_pk_add_f32 v[160:161], v[160:161], v[162:163]
	s_nop 0
	v_add_f32_e32 v147, v160, v161
	v_fmamk_f32 v147, v147, 0x3a800000, v156
	v_mul_f32_e32 v159, 0x4f800000, v147
	v_cmp_gt_f32_e32 vcc, s57, v147
	s_nop 1
	v_cndmask_b32_e32 v147, v147, v159, vcc
	v_sqrt_f32_e32 v159, v147
	s_nop 0
	v_add_u32_e32 v160, -1, v159
	v_add_u32_e32 v161, 1, v159
	v_fma_f32 v162, -v160, v159, v147
	v_fma_f32 v163, -v161, v159, v147
	v_cmp_ge_f32_e64 s[10:11], 0, v162
	s_nop 1
	v_cndmask_b32_e64 v159, v159, v160, s[10:11]
	v_cmp_lt_f32_e64 s[10:11], 0, v163
	s_nop 1
	v_cndmask_b32_e64 v159, v159, v161, s[10:11]
	v_mul_f32_e32 v160, 0x37800000, v159
	v_cndmask_b32_e32 v159, v159, v160, vcc
	v_cmp_class_f32_e32 vcc, v147, v157
	s_nop 1
	v_cndmask_b32_e32 v147, v159, v147, vcc
	v_div_scale_f32 v159, s[10:11], v147, v147, 1.0
	v_rcp_f32_e32 v160, v159
	v_div_scale_f32 v161, vcc, 1.0, v147, 1.0
	v_fma_f32 v162, -v159, v160, 1.0
	v_fmac_f32_e32 v160, v162, v160
	v_mul_f32_e32 v162, v161, v160
	v_fma_f32 v163, -v159, v162, v161
	v_fmac_f32_e32 v162, v163, v160
	v_fma_f32 v159, -v159, v162, v161
	v_div_fmas_f32 v159, v159, v160, v162
	v_div_fixup_f32 v160, v159, v147, 1.0
	v_pk_mul_f32 v[126:127], v[126:127], v[160:161] op_sel_hi:[1,0]
	v_pk_mul_f32 v[124:125], v[124:125], v[160:161] op_sel_hi:[1,0]
	v_pk_mul_f32 v[122:123], v[122:123], v[160:161] op_sel_hi:[1,0]
	v_pk_mul_f32 v[120:121], v[120:121], v[160:161] op_sel_hi:[1,0]
	v_pk_mul_f32 v[118:119], v[118:119], v[160:161] op_sel_hi:[1,0]
	v_pk_mul_f32 v[116:117], v[116:117], v[160:161] op_sel_hi:[1,0]
	v_pk_mul_f32 v[114:115], v[114:115], v[160:161] op_sel_hi:[1,0]
	v_pk_mul_f32 v[112:113], v[112:113], v[160:161] op_sel_hi:[1,0]
	v_cvt_pk_bf16_f32 v160, v124, v125
	v_cvt_pk_bf16_f32 v161, v126, v127
	v_cvt_pk_bf16_f32 v162, v120, v121
	v_cvt_pk_bf16_f32 v163, v122, v123
	v_cvt_pk_bf16_f32 v164, v116, v117
	v_cvt_pk_bf16_f32 v165, v118, v119
	v_cvt_pk_bf16_f32 v166, v112, v113
	v_cvt_pk_bf16_f32 v167, v114, v115
	global_store_dwordx4 v[168:169], v[160:163], off
	global_store_dwordx4 v[168:169], v[164:167], off offset:256
	s_cbranch_scc1 .LBB0_1426
	v_mul_f32_e32 v115, v115, v115
	v_fmac_f32_e32 v115, v114, v114
	v_mul_f32_e32 v114, v117, v117
	v_mul_f32_e32 v123, v123, v123
	v_fmac_f32_e32 v114, v116, v116
	v_mul_f32_e32 v116, v119, v119
	v_fmac_f32_e32 v123, v122, v122
	v_mul_f32_e32 v122, v125, v125
	v_fmac_f32_e32 v116, v118, v118
	v_mul_f32_e32 v113, v113, v113
	v_fmac_f32_e32 v122, v124, v124
	v_mul_f32_e32 v124, v127, v127
	v_add_f32_e32 v114, v114, v116
	v_fmac_f32_e32 v113, v112, v112
	v_fmac_f32_e32 v124, v126, v126
	v_mul_f32_e32 v121, v121, v121
	v_add_f32_e32 v112, v113, v114
	v_and_b32_e32 v114, 64, v158
	v_add_f32_e32 v122, v122, v124
	v_fmac_f32_e32 v121, v120, v120
	v_xor_b32_e32 v113, 16, v158
	v_add_u32_e32 v114, 64, v114
	v_add_f32_e32 v120, v121, v122
	v_cmp_lt_i32_e32 vcc, v113, v114
	v_add_f32_e32 v120, v123, v120
	v_add_f32_e32 v112, v115, v112
	v_cndmask_b32_e32 v113, v158, v113, vcc
	v_add_f32_e32 v112, v120, v112
	v_lshlrev_b32_e32 v113, 2, v113
	ds_bpermute_b32 v113, v113, v112
	s_waitcnt lgkmcnt(0)
	v_add_f32_e32 v112, v112, v113
	v_xor_b32_e32 v113, 32, v158
	v_cmp_lt_i32_e32 vcc, v113, v114
	s_nop 1
	v_cndmask_b32_e32 v113, v158, v113, vcc
	v_lshlrev_b32_e32 v113, 2, v113
	ds_bpermute_b32 v113, v113, v112
	s_and_saveexec_b64 s[10:11], s[6:7]
	s_cbranch_execz .LBB0_1425
	s_waitcnt lgkmcnt(0)
	v_add_f32_e32 v114, v112, v113
	v_lshl_add_u64 v[112:113], s[40:41], 0, v[148:149]
	global_store_dword v[112:113], v114, off

; __device__ __forceinline__ unsigned cvtpk(float lo, float hi) { f32x2_t v = {lo, hi}; bf16x2_t b = __builtin_convertvector(v, bf16x2_t); return __builtin_bit_cast(unsigned, b); }
;     __device__ __forceinline__ void operator()(const f32x4 (&acc)[2][2][4][2], const Unit& u, int wr, int wc, int fr, int fq) const {
;     ...
;             for (int m = 0; m < 4; ++m) {
;                 const int row = row0 + ai * HALF + m * 16; float s = 0.f;
;                 const float rs = ssq_in ? 1.0f / sqrtf(ssq_sum(ssq_in + (size_t)row * 16) * inv_dim + EPS) : 1.0f;
; #pragma unroll
;                 for (int bj = 0; bj < 2; ++bj) {
;                     int col = col0 + bj * HALF; if (hd_in) col = (col / hd_in) * hd_out + (col % hd_in);
;                     const f32x4 v0 = acc[ai][bj][m][0] * rs, v1 = acc[ai][bj][m][1] * rs;
;                     u32x4 w; w.x = cvtpk(v0[0], v0[1]); w.y = cvtpk(v0[2], v0[3]); w.z = cvtpk(v1[0], v1[1]); w.w = cvtpk(v1[2], v1[3]);
;                     *(u32x4*)(O + (size_t)row * ldc + col) = w;
;                     s += (v0[0] * v0[0] + v0[1] * v0[1]) + (v0[2] * v0[2] + v0[3] * v0[3]) + (v1[0] * v1[0] + v1[1] * v1[1]) + (v1[2] * v1[2] + v1[3] * v1[3]);
;                 }
;                 if (so) { s += __shfl_xor(s, 16); s += __shfl_xor(s, 32); if (fq == 0) so[(size_t)row * 16 + (u.pn & 1) * 4 + wc] = s; }
.LBB0_1426:
	v_or_b32_e32 v126, 16, v146
	v_ashrrev_i32_e32 v127, 31, v126
	s_waitcnt lgkmcnt(0)
	v_lshlrev_b64 v[112:113], 6, v[126:127]
	v_lshl_add_u64 v[148:149], s[20:21], 0, v[112:113]
	s_nop 1
	ds_read_b32 v114, v253 offset:64
	v_mov_b32_e32 v115, 0
	v_mov_b32_e32 v116, 0
	v_mov_b32_e32 v117, 0
	v_mov_b32_e32 v122, 0
	v_mov_b32_e32 v123, 0
	v_mov_b32_e32 v124, 0
	v_mov_b32_e32 v125, 0
	v_mov_b32_e32 v118, 0
	v_mov_b32_e32 v119, 0
	v_mov_b32_e32 v120, 0
	v_mov_b32_e32 v121, 0
	v_mov_b32_e32 v160, 0
	v_mov_b32_e32 v161, 0
	v_mov_b32_e32 v162, 0
	v_mov_b32_e32 v163, 0
	s_waitcnt lgkmcnt(0)
	v_cndmask_b32_e64 v147, 0, 1, s[42:43]
	v_cmp_ne_u32_e64 s[10:11], 1, v147
	s_waitcnt vmcnt(3)
	v_mov_b32_e32 v148, v114
	s_waitcnt vmcnt(2)
	v_mov_b32_e32 v149, v118
	v_mov_b32_e32 v118, v115
	v_mov_b32_e32 v114, v116
	v_mov_b32_e32 v115, v120
	v_mov_b32_e32 v120, v117
	s_waitcnt vmcnt(1)
	v_mov_b32_e32 v116, v122
	s_waitcnt vmcnt(0)
	v_mov_b32_e32 v117, v160
	v_mov_b32_e32 v160, v123
	v_mov_b32_e32 v122, v124
	v_mov_b32_e32 v123, v162
	v_mov_b32_e32 v162, v125
	v_pk_add_f32 v[118:119], v[148:149], v[118:119]
	v_pk_add_f32 v[114:115], v[114:115], v[120:121]
	v_pk_add_f32 v[116:117], v[116:117], v[160:161]
	v_pk_add_f32 v[120:121], v[122:123], v[162:163]
	v_pk_add_f32 v[114:115], v[118:119], v[114:115]
	v_pk_add_f32 v[116:117], v[116:117], v[120:121]
	s_nop 0
	v_pk_add_f32 v[114:115], v[114:115], v[116:117]
	s_nop 0
	v_add_f32_e32 v114, v114, v115
	v_fmamk_f32 v114, v114, 0x3a800000, v156
	v_mul_f32_e32 v115, 0x4f800000, v114
	v_cmp_gt_f32_e32 vcc, s57, v114
	s_nop 1
	v_cndmask_b32_e32 v116, v114, v115, vcc
	v_sqrt_f32_e32 v117, v116
	v_lshlrev_b64 v[114:115], 11, v[126:127]
	v_lshl_add_u64 v[114:115], s[18:19], 0, v[114:115]
	v_lshl_add_u64 v[122:123], v[144:145], 1, v[114:115]
	v_add_u32_e32 v118, -1, v117
	v_add_u32_e32 v119, 1, v117
	v_fma_f32 v120, -v118, v117, v116
	v_fma_f32 v121, -v119, v117, v116
	v_cmp_ge_f32_e64 s[12:13], 0, v120
	s_nop 1
	v_cndmask_b32_e64 v117, v117, v118, s[12:13]
	v_cmp_lt_f32_e64 s[12:13], 0, v121
	s_nop 1
	v_cndmask_b32_e64 v117, v117, v119, s[12:13]
	v_mul_f32_e32 v118, 0x37800000, v117
	v_cndmask_b32_e32 v117, v117, v118, vcc
	v_cmp_class_f32_e32 vcc, v116, v157
	s_nop 1
	v_cndmask_b32_e32 v116, v117, v116, vcc
	v_div_scale_f32 v117, s[12:13], v116, v116, 1.0
	v_rcp_f32_e32 v118, v117
	v_div_scale_f32 v114, vcc, 1.0, v116, 1.0
	v_fma_f32 v115, -v117, v118, 1.0
	v_fmac_f32_e32 v118, v115, v118
	v_mul_f32_e32 v115, v114, v118
	v_fma_f32 v119, -v117, v115, v114
	v_fmac_f32_e32 v115, v119, v118
	v_fma_f32 v114, -v117, v115, v114
	v_div_fmas_f32 v114, v114, v118, v115
	v_div_fixup_f32 v114, v114, v116, 1.0
	v_pk_mul_f32 v[110:111], v[110:111], v[114:115] op_sel_hi:[1,0]
	v_pk_mul_f32 v[108:109], v[108:109], v[114:115] op_sel_hi:[1,0]
	v_pk_mul_f32 v[106:107], v[106:107], v[114:115] op_sel_hi:[1,0]
	v_pk_mul_f32 v[104:105], v[104:105], v[114:115] op_sel_hi:[1,0]
	s_andn2_b64 vcc, exec, s[42:43]
	v_pk_mul_f32 v[102:103], v[102:103], v[114:115] op_sel_hi:[1,0]
	v_pk_mul_f32 v[100:101], v[100:101], v[114:115] op_sel_hi:[1,0]
	v_pk_mul_f32 v[98:99], v[98:99], v[114:115] op_sel_hi:[1,0]
	v_pk_mul_f32 v[96:97], v[96:97], v[114:115] op_sel_hi:[1,0]
	v_cvt_pk_bf16_f32 v114, v108, v109
	v_cvt_pk_bf16_f32 v115, v110, v111
	v_cvt_pk_bf16_f32 v116, v104, v105
	v_cvt_pk_bf16_f32 v117, v106, v107
	v_cvt_pk_bf16_f32 v118, v100, v101
	v_cvt_pk_bf16_f32 v119, v102, v103
	v_cvt_pk_bf16_f32 v120, v96, v97
	v_cvt_pk_bf16_f32 v121, v98, v99
	global_store_dwordx4 v[122:123], v[114:117], off
	global_store_dwordx4 v[122:123], v[118:121], off offset:256
	s_cbranch_vccnz .LBB0_1430
	v_mul_f32_e32 v99, v99, v99
	v_fmac_f32_e32 v99, v98, v98
	v_mul_f32_e32 v98, v101, v101
	v_mul_f32_e32 v107, v107, v107
	v_fmac_f32_e32 v98, v100, v100
	v_mul_f32_e32 v100, v103, v103
	v_fmac_f32_e32 v107, v106, v106
	v_mul_f32_e32 v106, v109, v109
	v_fmac_f32_e32 v100, v102, v102
	v_mul_f32_e32 v97, v97, v97
	v_fmac_f32_e32 v106, v108, v108
	v_mul_f32_e32 v108, v111, v111
	v_add_f32_e32 v98, v98, v100
	v_fmac_f32_e32 v97, v96, v96
	v_fmac_f32_e32 v108, v110, v110
	v_mul_f32_e32 v105, v105, v105
	v_add_f32_e32 v96, v97, v98
	v_and_b32_e32 v98, 64, v158
	v_add_f32_e32 v106, v106, v108
	v_fmac_f32_e32 v105, v104, v104
	v_xor_b32_e32 v97, 16, v158
	v_add_u32_e32 v98, 64, v98
	v_add_f32_e32 v104, v105, v106
	v_cmp_lt_i32_e32 vcc, v97, v98
	v_add_f32_e32 v104, v107, v104
	v_add_f32_e32 v96, v99, v96
	v_cndmask_b32_e32 v97, v158, v97, vcc
	v_add_f32_e32 v96, v104, v96
	v_lshlrev_b32_e32 v97, 2, v97
	ds_bpermute_b32 v97, v97, v96
	s_waitcnt lgkmcnt(0)
	v_add_f32_e32 v96, v96, v97
	v_xor_b32_e32 v97, 32, v158
	v_cmp_lt_i32_e32 vcc, v97, v98
	s_nop 1
	v_cndmask_b32_e32 v97, v158, v97, vcc
	v_lshlrev_b32_e32 v97, 2, v97
	ds_bpermute_b32 v97, v97, v96
	s_and_saveexec_b64 s[12:13], s[6:7]
	s_cbranch_execz .LBB0_1429
	s_waitcnt lgkmcnt(0)
	v_add_f32_e32 v98, v96, v97
	v_lshl_add_u64 v[96:97], s[40:41], 0, v[112:113]
	global_store_dword v[96:97], v98, off

; __device__ __forceinline__ unsigned cvtpk(float lo, float hi) { f32x2_t v = {lo, hi}; bf16x2_t b = __builtin_convertvector(v, bf16x2_t); return __builtin_bit_cast(unsigned, b); }
;     __device__ __forceinline__ void operator()(const f32x4 (&acc)[2][2][4][2], const Unit& u, int wr, int wc, int fr, int fq) const {
;     ...
;             for (int m = 0; m < 4; ++m) {
;                 const int row = row0 + ai * HALF + m * 16; float s = 0.f;
;                 const float rs = ssq_in ? 1.0f / sqrtf(ssq_sum(ssq_in + (size_t)row * 16) * inv_dim + EPS) : 1.0f;
; #pragma unroll
;                 for (int bj = 0; bj < 2; ++bj) {
;                     int col = col0 + bj * HALF; if (hd_in) col = (col / hd_in) * hd_out + (col % hd_in);
;                     const f32x4 v0 = acc[ai][bj][m][0] * rs, v1 = acc[ai][bj][m][1] * rs;
;                     u32x4 w; w.x = cvtpk(v0[0], v0[1]); w.y = cvtpk(v0[2], v0[3]); w.z = cvtpk(v1[0], v1[1]); w.w = cvtpk(v1[2], v1[3]);
;                     *(u32x4*)(O + (size_t)row * ldc + col) = w;
;                     s += (v0[0] * v0[0] + v0[1] * v0[1]) + (v0[2] * v0[2] + v0[3] * v0[3]) + (v1[0] * v1[0] + v1[1] * v1[1]) + (v1[2] * v1[2] + v1[3] * v1[3]);
;                 }
;                 if (so) { s += __shfl_xor(s, 16); s += __shfl_xor(s, 32); if (fq == 0) so[(size_t)row * 16 + (u.pn & 1) * 4 + wc] = s; }
.LBB0_1430:
	v_or_b32_e32 v114, 32, v146
	v_ashrrev_i32_e32 v115, 31, v114
	s_waitcnt lgkmcnt(0)
	v_lshlrev_b64 v[96:97], 6, v[114:115]
	v_lshl_add_u64 v[110:111], s[20:21], 0, v[96:97]
	s_nop 1
	ds_read_b32 v98, v253 offset:128
	v_mov_b32_e32 v99, 0
	v_mov_b32_e32 v100, 0
	v_mov_b32_e32 v101, 0
	v_mov_b32_e32 v106, 0
	v_mov_b32_e32 v107, 0
	v_mov_b32_e32 v108, 0
	v_mov_b32_e32 v109, 0
	v_mov_b32_e32 v102, 0
	v_mov_b32_e32 v103, 0
	v_mov_b32_e32 v104, 0
	v_mov_b32_e32 v105, 0
	v_mov_b32_e32 v110, 0
	v_mov_b32_e32 v111, 0
	v_mov_b32_e32 v112, 0
	v_mov_b32_e32 v113, 0
	s_waitcnt lgkmcnt(0)
	s_waitcnt vmcnt(3)
	v_mov_b32_e32 v116, v98
	s_waitcnt vmcnt(2)
	v_mov_b32_e32 v117, v102
	v_mov_b32_e32 v102, v99
	v_mov_b32_e32 v98, v100
	v_mov_b32_e32 v99, v104
	v_mov_b32_e32 v104, v101
	s_waitcnt vmcnt(1)
	v_mov_b32_e32 v100, v106
	s_waitcnt vmcnt(0)
	v_mov_b32_e32 v101, v110
	v_mov_b32_e32 v110, v107
	v_mov_b32_e32 v106, v108
	v_mov_b32_e32 v107, v112
	v_mov_b32_e32 v112, v109
	v_pk_add_f32 v[102:103], v[116:117], v[102:103]
	v_pk_add_f32 v[98:99], v[98:99], v[104:105]
	v_pk_add_f32 v[100:101], v[100:101], v[110:111]
	v_pk_add_f32 v[104:105], v[106:107], v[112:113]
	v_pk_add_f32 v[98:99], v[102:103], v[98:99]
	v_pk_add_f32 v[100:101], v[100:101], v[104:105]
	s_nop 0
	v_pk_add_f32 v[98:99], v[98:99], v[100:101]
	s_nop 0
	v_add_f32_e32 v98, v98, v99
	v_fmamk_f32 v98, v98, 0x3a800000, v156
	v_mul_f32_e32 v99, 0x4f800000, v98
	v_cmp_gt_f32_e32 vcc, s57, v98
	s_nop 1
	v_cndmask_b32_e32 v100, v98, v99, vcc
	v_sqrt_f32_e32 v101, v100
	v_lshlrev_b64 v[98:99], 11, v[114:115]
	v_lshl_add_u64 v[98:99], s[18:19], 0, v[98:99]
	v_lshl_add_u64 v[106:107], v[144:145], 1, v[98:99]
	v_add_u32_e32 v102, -1, v101
	v_add_u32_e32 v103, 1, v101
	v_fma_f32 v104, -v102, v101, v100
	v_fma_f32 v105, -v103, v101, v100
	v_cmp_ge_f32_e64 s[12:13], 0, v104
	s_nop 1
	v_cndmask_b32_e64 v101, v101, v102, s[12:13]
	v_cmp_lt_f32_e64 s[12:13], 0, v105
	s_nop 1
	v_cndmask_b32_e64 v101, v101, v103, s[12:13]
	v_mul_f32_e32 v102, 0x37800000, v101
	v_cndmask_b32_e32 v101, v101, v102, vcc
	v_cmp_class_f32_e32 vcc, v100, v157
	s_nop 1
	v_cndmask_b32_e32 v100, v101, v100, vcc
	v_div_scale_f32 v101, s[12:13], v100, v100, 1.0
	v_rcp_f32_e32 v102, v101
	v_div_scale_f32 v98, vcc, 1.0, v100, 1.0
	v_fma_f32 v99, -v101, v102, 1.0
	v_fmac_f32_e32 v102, v99, v102
	v_mul_f32_e32 v99, v98, v102
	v_fma_f32 v103, -v101, v99, v98
	v_fmac_f32_e32 v99, v103, v102
	v_fma_f32 v98, -v101, v99, v98
	v_div_fmas_f32 v98, v98, v102, v99
	v_div_fixup_f32 v98, v98, v100, 1.0
	v_pk_mul_f32 v[94:95], v[94:95], v[98:99] op_sel_hi:[1,0]
	v_pk_mul_f32 v[92:93], v[92:93], v[98:99] op_sel_hi:[1,0]
	v_pk_mul_f32 v[90:91], v[90:91], v[98:99] op_sel_hi:[1,0]
	v_pk_mul_f32 v[88:89], v[88:89], v[98:99] op_sel_hi:[1,0]
	s_and_b64 vcc, exec, s[10:11]
	v_pk_mul_f32 v[86:87], v[86:87], v[98:99] op_sel_hi:[1,0]
	v_pk_mul_f32 v[84:85], v[84:85], v[98:99] op_sel_hi:[1,0]
	v_pk_mul_f32 v[82:83], v[82:83], v[98:99] op_sel_hi:[1,0]
	v_pk_mul_f32 v[80:81], v[80:81], v[98:99] op_sel_hi:[1,0]
	v_cvt_pk_bf16_f32 v98, v92, v93
	v_cvt_pk_bf16_f32 v99, v94, v95
	v_cvt_pk_bf16_f32 v100, v88, v89
	v_cvt_pk_bf16_f32 v101, v90, v91
	v_cvt_pk_bf16_f32 v102, v84, v85
	v_cvt_pk_bf16_f32 v103, v86, v87
	v_cvt_pk_bf16_f32 v104, v80, v81
	v_cvt_pk_bf16_f32 v105, v82, v83
	global_store_dwordx4 v[106:107], v[98:101], off
	global_store_dwordx4 v[106:107], v[102:105], off offset:256
	s_cbranch_vccnz .LBB0_1434
	v_mul_f32_e32 v83, v83, v83
	v_fmac_f32_e32 v83, v82, v82
	v_mul_f32_e32 v82, v85, v85
	v_mul_f32_e32 v91, v91, v91
	v_fmac_f32_e32 v82, v84, v84
	v_mul_f32_e32 v84, v87, v87
	v_fmac_f32_e32 v91, v90, v90
	v_mul_f32_e32 v90, v93, v93
	v_fmac_f32_e32 v84, v86, v86
	v_mul_f32_e32 v81, v81, v81
	v_fmac_f32_e32 v90, v92, v92
	v_mul_f32_e32 v92, v95, v95
	v_add_f32_e32 v82, v82, v84
	v_fmac_f32_e32 v81, v80, v80
	v_fmac_f32_e32 v92, v94, v94
	v_mul_f32_e32 v89, v89, v89
	v_add_f32_e32 v80, v81, v82
	v_and_b32_e32 v82, 64, v158
	v_add_f32_e32 v90, v90, v92
	v_fmac_f32_e32 v89, v88, v88
	v_xor_b32_e32 v81, 16, v158
	v_add_u32_e32 v82, 64, v82
	v_add_f32_e32 v88, v89, v90
	v_cmp_lt_i32_e32 vcc, v81, v82
	v_add_f32_e32 v88, v91, v88
	v_add_f32_e32 v80, v83, v80
	v_cndmask_b32_e32 v81, v158, v81, vcc
	v_add_f32_e32 v80, v88, v80
	v_lshlrev_b32_e32 v81, 2, v81
	ds_bpermute_b32 v81, v81, v80
	s_waitcnt lgkmcnt(0)
	v_add_f32_e32 v80, v80, v81
	v_xor_b32_e32 v81, 32, v158
	v_cmp_lt_i32_e32 vcc, v81, v82
	s_nop 1
	v_cndmask_b32_e32 v81, v158, v81, vcc
	v_lshlrev_b32_e32 v81, 2, v81
	ds_bpermute_b32 v81, v81, v80
	s_and_saveexec_b64 s[12:13], s[6:7]
	s_cbranch_execz .LBB0_1433
	s_waitcnt lgkmcnt(0)
	v_add_f32_e32 v82, v80, v81
	v_lshl_add_u64 v[80:81], s[40:41], 0, v[96:97]
	global_store_dword v[80:81], v82, off

; __device__ __forceinline__ unsigned cvtpk(float lo, float hi) { f32x2_t v = {lo, hi}; bf16x2_t b = __builtin_convertvector(v, bf16x2_t); return __builtin_bit_cast(unsigned, b); }
;     __device__ __forceinline__ void operator()(const f32x4 (&acc)[2][2][4][2], const Unit& u, int wr, int wc, int fr, int fq) const {
;     ...
;             for (int m = 0; m < 4; ++m) {
;                 const int row = row0 + ai * HALF + m * 16; float s = 0.f;
;                 const float rs = ssq_in ? 1.0f / sqrtf(ssq_sum(ssq_in + (size_t)row * 16) * inv_dim + EPS) : 1.0f;
; #pragma unroll
;                 for (int bj = 0; bj < 2; ++bj) {
;                     int col = col0 + bj * HALF; if (hd_in) col = (col / hd_in) * hd_out + (col % hd_in);
;                     const f32x4 v0 = acc[ai][bj][m][0] * rs, v1 = acc[ai][bj][m][1] * rs;
;                     u32x4 w; w.x = cvtpk(v0[0], v0[1]); w.y = cvtpk(v0[2], v0[3]); w.z = cvtpk(v1[0], v1[1]); w.w = cvtpk(v1[2], v1[3]);
;                     *(u32x4*)(O + (size_t)row * ldc + col) = w;
;                     s += (v0[0] * v0[0] + v0[1] * v0[1]) + (v0[2] * v0[2] + v0[3] * v0[3]) + (v1[0] * v1[0] + v1[1] * v1[1]) + (v1[2] * v1[2] + v1[3] * v1[3]);
;                 }
;                 if (so) { s += __shfl_xor(s, 16); s += __shfl_xor(s, 32); if (fq == 0) so[(size_t)row * 16 + (u.pn & 1) * 4 + wc] = s; }
.LBB0_1434:
	v_or_b32_e32 v98, 48, v146
	v_ashrrev_i32_e32 v99, 31, v98
	s_waitcnt lgkmcnt(0)
	v_lshlrev_b64 v[80:81], 6, v[98:99]
	v_lshl_add_u64 v[94:95], s[20:21], 0, v[80:81]
	s_nop 1
	ds_read_b32 v82, v253 offset:192
	v_mov_b32_e32 v83, 0
	v_mov_b32_e32 v84, 0
	v_mov_b32_e32 v85, 0
	v_mov_b32_e32 v90, 0
	v_mov_b32_e32 v91, 0
	v_mov_b32_e32 v92, 0
	v_mov_b32_e32 v93, 0
	v_mov_b32_e32 v86, 0
	v_mov_b32_e32 v87, 0
	v_mov_b32_e32 v88, 0
	v_mov_b32_e32 v89, 0
	v_mov_b32_e32 v94, 0
	v_mov_b32_e32 v95, 0
	v_mov_b32_e32 v96, 0
	v_mov_b32_e32 v97, 0
	s_waitcnt lgkmcnt(0)
	s_waitcnt vmcnt(3)
	v_mov_b32_e32 v100, v82
	s_waitcnt vmcnt(2)
	v_mov_b32_e32 v101, v86
	v_mov_b32_e32 v86, v83
	v_mov_b32_e32 v82, v84
	v_mov_b32_e32 v83, v88
	v_mov_b32_e32 v88, v85
	s_waitcnt vmcnt(1)
	v_mov_b32_e32 v84, v90
	s_waitcnt vmcnt(0)
	v_mov_b32_e32 v85, v94
	v_mov_b32_e32 v94, v91
	v_mov_b32_e32 v90, v92
	v_mov_b32_e32 v91, v96
	v_mov_b32_e32 v96, v93
	v_pk_add_f32 v[86:87], v[100:101], v[86:87]
	v_pk_add_f32 v[82:83], v[82:83], v[88:89]
	v_pk_add_f32 v[84:85], v[84:85], v[94:95]
	v_pk_add_f32 v[88:89], v[90:91], v[96:97]
	v_pk_add_f32 v[82:83], v[86:87], v[82:83]
	v_pk_add_f32 v[84:85], v[84:85], v[88:89]
	s_nop 0
	v_pk_add_f32 v[82:83], v[82:83], v[84:85]
	s_nop 0
	v_add_f32_e32 v82, v82, v83
	v_fmamk_f32 v82, v82, 0x3a800000, v156
	v_mul_f32_e32 v83, 0x4f800000, v82
	v_cmp_gt_f32_e32 vcc, s57, v82
	s_nop 1
	v_cndmask_b32_e32 v84, v82, v83, vcc
	v_sqrt_f32_e32 v85, v84
	v_lshlrev_b64 v[82:83], 11, v[98:99]
	v_lshl_add_u64 v[82:83], s[18:19], 0, v[82:83]
	v_lshl_add_u64 v[90:91], v[144:145], 1, v[82:83]
	v_add_u32_e32 v86, -1, v85
	v_add_u32_e32 v87, 1, v85
	v_fma_f32 v88, -v86, v85, v84
	v_fma_f32 v89, -v87, v85, v84
	v_cmp_ge_f32_e64 s[12:13], 0, v88
	s_nop 1
	v_cndmask_b32_e64 v85, v85, v86, s[12:13]
	v_cmp_lt_f32_e64 s[12:13], 0, v89
	s_nop 1
	v_cndmask_b32_e64 v85, v85, v87, s[12:13]
	v_mul_f32_e32 v86, 0x37800000, v85
	v_cndmask_b32_e32 v85, v85, v86, vcc
	v_cmp_class_f32_e32 vcc, v84, v157
	s_nop 1
	v_cndmask_b32_e32 v84, v85, v84, vcc
	v_div_scale_f32 v85, s[12:13], v84, v84, 1.0
	v_rcp_f32_e32 v86, v85
	v_div_scale_f32 v82, vcc, 1.0, v84, 1.0
	v_fma_f32 v83, -v85, v86, 1.0
	v_fmac_f32_e32 v86, v83, v86
	v_mul_f32_e32 v83, v82, v86
	v_fma_f32 v87, -v85, v83, v82
	v_fmac_f32_e32 v83, v87, v86
	v_fma_f32 v82, -v85, v83, v82
	v_div_fmas_f32 v82, v82, v86, v83
	v_div_fixup_f32 v82, v82, v84, 1.0
	v_pk_mul_f32 v[78:79], v[78:79], v[82:83] op_sel_hi:[1,0]
	v_pk_mul_f32 v[76:77], v[76:77], v[82:83] op_sel_hi:[1,0]
	v_pk_mul_f32 v[74:75], v[74:75], v[82:83] op_sel_hi:[1,0]
	v_pk_mul_f32 v[72:73], v[72:73], v[82:83] op_sel_hi:[1,0]
	s_and_b64 vcc, exec, s[10:11]
	v_pk_mul_f32 v[70:71], v[70:71], v[82:83] op_sel_hi:[1,0]
	v_pk_mul_f32 v[68:69], v[68:69], v[82:83] op_sel_hi:[1,0]
	v_pk_mul_f32 v[66:67], v[66:67], v[82:83] op_sel_hi:[1,0]
	v_pk_mul_f32 v[64:65], v[64:65], v[82:83] op_sel_hi:[1,0]
	v_cvt_pk_bf16_f32 v82, v76, v77
	v_cvt_pk_bf16_f32 v83, v78, v79
	v_cvt_pk_bf16_f32 v84, v72, v73
	v_cvt_pk_bf16_f32 v85, v74, v75
	v_cvt_pk_bf16_f32 v86, v68, v69
	v_cvt_pk_bf16_f32 v87, v70, v71
	v_cvt_pk_bf16_f32 v88, v64, v65
	v_cvt_pk_bf16_f32 v89, v66, v67
	global_store_dwordx4 v[90:91], v[82:85], off
	global_store_dwordx4 v[90:91], v[86:89], off offset:256
	s_cbranch_vccnz .LBB0_1438
	v_mul_f32_e32 v67, v67, v67
	v_fmac_f32_e32 v67, v66, v66
	v_mul_f32_e32 v66, v69, v69
	v_mul_f32_e32 v75, v75, v75
	v_fmac_f32_e32 v66, v68, v68
	v_mul_f32_e32 v68, v71, v71
	v_fmac_f32_e32 v75, v74, v74
	v_mul_f32_e32 v74, v77, v77
	v_fmac_f32_e32 v68, v70, v70
	v_mul_f32_e32 v65, v65, v65
	v_fmac_f32_e32 v74, v76, v76
	v_mul_f32_e32 v76, v79, v79
	v_add_f32_e32 v66, v66, v68
	v_fmac_f32_e32 v65, v64, v64
	v_fmac_f32_e32 v76, v78, v78
	v_mul_f32_e32 v73, v73, v73
	v_add_f32_e32 v64, v65, v66
	v_and_b32_e32 v66, 64, v158
	v_add_f32_e32 v74, v74, v76
	v_fmac_f32_e32 v73, v72, v72
	v_xor_b32_e32 v65, 16, v158
	v_add_u32_e32 v66, 64, v66
	v_add_f32_e32 v72, v73, v74
	v_cmp_lt_i32_e32 vcc, v65, v66
	v_add_f32_e32 v72, v75, v72
	v_add_f32_e32 v64, v67, v64
	v_cndmask_b32_e32 v65, v158, v65, vcc
	v_add_f32_e32 v64, v72, v64
	v_lshlrev_b32_e32 v65, 2, v65
	ds_bpermute_b32 v65, v65, v64
	s_waitcnt lgkmcnt(0)
	v_add_f32_e32 v64, v64, v65
	v_xor_b32_e32 v65, 32, v158
	v_cmp_lt_i32_e32 vcc, v65, v66
	s_nop 1
	v_cndmask_b32_e32 v65, v158, v65, vcc
	v_lshlrev_b32_e32 v65, 2, v65
	ds_bpermute_b32 v65, v65, v64
	s_and_saveexec_b64 s[12:13], s[6:7]
	s_cbranch_execz .LBB0_1437
	s_waitcnt lgkmcnt(0)
	v_add_f32_e32 v66, v64, v65
	v_lshl_add_u64 v[64:65], s[40:41], 0, v[80:81]
	global_store_dword v[64:65], v66, off

; __device__ __forceinline__ unsigned cvtpk(float lo, float hi) { f32x2_t v = {lo, hi}; bf16x2_t b = __builtin_convertvector(v, bf16x2_t); return __builtin_bit_cast(unsigned, b); }
;     __device__ __forceinline__ void operator()(const f32x4 (&acc)[2][2][4][2], const Unit& u, int wr, int wc, int fr, int fq) const {
;     ...
;             for (int m = 0; m < 4; ++m) {
;                 const int row = row0 + ai * HALF + m * 16; float s = 0.f;
;                 const float rs = ssq_in ? 1.0f / sqrtf(ssq_sum(ssq_in + (size_t)row * 16) * inv_dim + EPS) : 1.0f;
; #pragma unroll
;                 for (int bj = 0; bj < 2; ++bj) {
;                     int col = col0 + bj * HALF; if (hd_in) col = (col / hd_in) * hd_out + (col % hd_in);
;                     const f32x4 v0 = acc[ai][bj][m][0] * rs, v1 = acc[ai][bj][m][1] * rs;
;                     u32x4 w; w.x = cvtpk(v0[0], v0[1]); w.y = cvtpk(v0[2], v0[3]); w.z = cvtpk(v1[0], v1[1]); w.w = cvtpk(v1[2], v1[3]);
;                     *(u32x4*)(O + (size_t)row * ldc + col) = w;
;                     s += (v0[0] * v0[0] + v0[1] * v0[1]) + (v0[2] * v0[2] + v0[3] * v0[3]) + (v1[0] * v1[0] + v1[1] * v1[1]) + (v1[2] * v1[2] + v1[3] * v1[3]);
;                 }
;                 if (so) { s += __shfl_xor(s, 16); s += __shfl_xor(s, 32); if (fq == 0) so[(size_t)row * 16 + (u.pn & 1) * 4 + wc] = s; }
.LBB0_1438:
	v_add_u32_e32 v82, 0x80, v146
	v_ashrrev_i32_e32 v83, 31, v82
	s_waitcnt lgkmcnt(0)
	v_lshlrev_b64 v[64:65], 6, v[82:83]
	v_lshl_add_u64 v[78:79], s[20:21], 0, v[64:65]
	s_nop 1
	ds_read_b32 v66, v253 offset:512
	v_mov_b32_e32 v67, 0
	v_mov_b32_e32 v68, 0
	v_mov_b32_e32 v69, 0
	v_mov_b32_e32 v74, 0
	v_mov_b32_e32 v75, 0
	v_mov_b32_e32 v76, 0
	v_mov_b32_e32 v77, 0
	v_mov_b32_e32 v70, 0
	v_mov_b32_e32 v71, 0
	v_mov_b32_e32 v72, 0
	v_mov_b32_e32 v73, 0
	v_mov_b32_e32 v78, 0
	v_mov_b32_e32 v79, 0
	v_mov_b32_e32 v80, 0
	v_mov_b32_e32 v81, 0
	s_waitcnt lgkmcnt(0)
	s_waitcnt vmcnt(3)
	v_mov_b32_e32 v84, v66
	s_waitcnt vmcnt(2)
	v_mov_b32_e32 v85, v70
	v_mov_b32_e32 v70, v67
	v_mov_b32_e32 v66, v68
	v_mov_b32_e32 v67, v72
	v_mov_b32_e32 v72, v69
	s_waitcnt vmcnt(1)
	v_mov_b32_e32 v68, v74
	s_waitcnt vmcnt(0)
	v_mov_b32_e32 v69, v78
	v_mov_b32_e32 v78, v75
	v_mov_b32_e32 v74, v76
	v_mov_b32_e32 v75, v80
	v_mov_b32_e32 v80, v77
	v_pk_add_f32 v[70:71], v[84:85], v[70:71]
	v_pk_add_f32 v[66:67], v[66:67], v[72:73]
	v_pk_add_f32 v[68:69], v[68:69], v[78:79]
	v_pk_add_f32 v[72:73], v[74:75], v[80:81]
	v_pk_add_f32 v[66:67], v[70:71], v[66:67]
	v_pk_add_f32 v[68:69], v[68:69], v[72:73]
	s_nop 0
	v_pk_add_f32 v[66:67], v[66:67], v[68:69]
	s_nop 0
	v_add_f32_e32 v66, v66, v67
	v_fmamk_f32 v66, v66, 0x3a800000, v156
	v_mul_f32_e32 v67, 0x4f800000, v66
	v_cmp_gt_f32_e32 vcc, s57, v66
	s_nop 1
	v_cndmask_b32_e32 v68, v66, v67, vcc
	v_sqrt_f32_e32 v69, v68
	v_lshlrev_b64 v[66:67], 11, v[82:83]
	v_lshl_add_u64 v[66:67], s[18:19], 0, v[66:67]
	v_lshl_add_u64 v[74:75], v[144:145], 1, v[66:67]
	v_add_u32_e32 v70, -1, v69
	v_add_u32_e32 v71, 1, v69
	v_fma_f32 v72, -v70, v69, v68
	v_fma_f32 v73, -v71, v69, v68
	v_cmp_ge_f32_e64 s[12:13], 0, v72
	s_nop 1
	v_cndmask_b32_e64 v69, v69, v70, s[12:13]
	v_cmp_lt_f32_e64 s[12:13], 0, v73
	s_nop 1
	v_cndmask_b32_e64 v69, v69, v71, s[12:13]
	v_mul_f32_e32 v70, 0x37800000, v69
	v_cndmask_b32_e32 v69, v69, v70, vcc
	v_cmp_class_f32_e32 vcc, v68, v157
	s_nop 1
	v_cndmask_b32_e32 v68, v69, v68, vcc
	v_div_scale_f32 v69, s[12:13], v68, v68, 1.0
	v_rcp_f32_e32 v70, v69
	v_div_scale_f32 v66, vcc, 1.0, v68, 1.0
	v_fma_f32 v67, -v69, v70, 1.0
	v_fmac_f32_e32 v70, v67, v70
	v_mul_f32_e32 v67, v66, v70
	v_fma_f32 v71, -v69, v67, v66
	v_fmac_f32_e32 v67, v71, v70
	v_fma_f32 v66, -v69, v67, v66
	v_div_fmas_f32 v66, v66, v70, v67
	v_div_fixup_f32 v66, v66, v68, 1.0
	v_pk_mul_f32 v[62:63], v[62:63], v[66:67] op_sel_hi:[1,0]
	v_pk_mul_f32 v[60:61], v[60:61], v[66:67] op_sel_hi:[1,0]
	v_pk_mul_f32 v[58:59], v[58:59], v[66:67] op_sel_hi:[1,0]
	v_pk_mul_f32 v[56:57], v[56:57], v[66:67] op_sel_hi:[1,0]
	s_and_b64 vcc, exec, s[10:11]
	v_pk_mul_f32 v[54:55], v[54:55], v[66:67] op_sel_hi:[1,0]
	v_pk_mul_f32 v[52:53], v[52:53], v[66:67] op_sel_hi:[1,0]
	v_pk_mul_f32 v[50:51], v[50:51], v[66:67] op_sel_hi:[1,0]
	v_pk_mul_f32 v[48:49], v[48:49], v[66:67] op_sel_hi:[1,0]
	v_cvt_pk_bf16_f32 v66, v60, v61
	v_cvt_pk_bf16_f32 v67, v62, v63
	v_cvt_pk_bf16_f32 v68, v56, v57
	v_cvt_pk_bf16_f32 v69, v58, v59
	v_cvt_pk_bf16_f32 v70, v52, v53
	v_cvt_pk_bf16_f32 v71, v54, v55
	v_cvt_pk_bf16_f32 v72, v48, v49
	v_cvt_pk_bf16_f32 v73, v50, v51
	global_store_dwordx4 v[74:75], v[66:69], off
	global_store_dwordx4 v[74:75], v[70:73], off offset:256
	s_cbranch_vccnz .LBB0_1442
	v_mul_f32_e32 v51, v51, v51
	v_fmac_f32_e32 v51, v50, v50
	v_mul_f32_e32 v50, v53, v53
	v_mul_f32_e32 v59, v59, v59
	v_fmac_f32_e32 v50, v52, v52
	v_mul_f32_e32 v52, v55, v55
	v_fmac_f32_e32 v59, v58, v58
	v_mul_f32_e32 v58, v61, v61
	v_fmac_f32_e32 v52, v54, v54
	v_mul_f32_e32 v49, v49, v49
	v_fmac_f32_e32 v58, v60, v60
	v_mul_f32_e32 v60, v63, v63
	v_add_f32_e32 v50, v50, v52
	v_fmac_f32_e32 v49, v48, v48
	v_fmac_f32_e32 v60, v62, v62
	v_mul_f32_e32 v57, v57, v57
	v_add_f32_e32 v48, v49, v50
	v_and_b32_e32 v50, 64, v158
	v_add_f32_e32 v58, v58, v60
	v_fmac_f32_e32 v57, v56, v56
	v_xor_b32_e32 v49, 16, v158
	v_add_u32_e32 v50, 64, v50
	v_add_f32_e32 v56, v57, v58
	v_cmp_lt_i32_e32 vcc, v49, v50
	v_add_f32_e32 v56, v59, v56
	v_add_f32_e32 v48, v51, v48
	v_cndmask_b32_e32 v49, v158, v49, vcc
	v_add_f32_e32 v48, v56, v48
	v_lshlrev_b32_e32 v49, 2, v49
	ds_bpermute_b32 v49, v49, v48
	s_waitcnt lgkmcnt(0)
	v_add_f32_e32 v48, v48, v49
	v_xor_b32_e32 v49, 32, v158
	v_cmp_lt_i32_e32 vcc, v49, v50
	s_nop 1
	v_cndmask_b32_e32 v49, v158, v49, vcc
	v_lshlrev_b32_e32 v49, 2, v49
	ds_bpermute_b32 v49, v49, v48
	s_and_saveexec_b64 s[12:13], s[6:7]
	s_cbranch_execz .LBB0_1441
	s_waitcnt lgkmcnt(0)
	v_add_f32_e32 v50, v48, v49
	v_lshl_add_u64 v[48:49], s[40:41], 0, v[64:65]
	global_store_dword v[48:49], v50, off

; __device__ __forceinline__ unsigned cvtpk(float lo, float hi) { f32x2_t v = {lo, hi}; bf16x2_t b = __builtin_convertvector(v, bf16x2_t); return __builtin_bit_cast(unsigned, b); }
;     __device__ __forceinline__ void operator()(const f32x4 (&acc)[2][2][4][2], const Unit& u, int wr, int wc, int fr, int fq) const {
;     ...
;             for (int m = 0; m < 4; ++m) {
;                 const int row = row0 + ai * HALF + m * 16; float s = 0.f;
;                 const float rs = ssq_in ? 1.0f / sqrtf(ssq_sum(ssq_in + (size_t)row * 16) * inv_dim + EPS) : 1.0f;
; #pragma unroll
;                 for (int bj = 0; bj < 2; ++bj) {
;                     int col = col0 + bj * HALF; if (hd_in) col = (col / hd_in) * hd_out + (col % hd_in);
;                     const f32x4 v0 = acc[ai][bj][m][0] * rs, v1 = acc[ai][bj][m][1] * rs;
;                     u32x4 w; w.x = cvtpk(v0[0], v0[1]); w.y = cvtpk(v0[2], v0[3]); w.z = cvtpk(v1[0], v1[1]); w.w = cvtpk(v1[2], v1[3]);
;                     *(u32x4*)(O + (size_t)row * ldc + col) = w;
;                     s += (v0[0] * v0[0] + v0[1] * v0[1]) + (v0[2] * v0[2] + v0[3] * v0[3]) + (v1[0] * v1[0] + v1[1] * v1[1]) + (v1[2] * v1[2] + v1[3] * v1[3]);
;                 }
;                 if (so) { s += __shfl_xor(s, 16); s += __shfl_xor(s, 32); if (fq == 0) so[(size_t)row * 16 + (u.pn & 1) * 4 + wc] = s; }
.LBB0_1442:
	v_add_u32_e32 v66, 0x90, v146
	v_ashrrev_i32_e32 v67, 31, v66
	s_waitcnt lgkmcnt(0)
	v_lshlrev_b64 v[48:49], 6, v[66:67]
	v_lshl_add_u64 v[62:63], s[20:21], 0, v[48:49]
	s_nop 1
	ds_read_b32 v50, v253 offset:576
	v_mov_b32_e32 v51, 0
	v_mov_b32_e32 v52, 0
	v_mov_b32_e32 v53, 0
	v_mov_b32_e32 v58, 0
	v_mov_b32_e32 v59, 0
	v_mov_b32_e32 v60, 0
	v_mov_b32_e32 v61, 0
	v_mov_b32_e32 v54, 0
	v_mov_b32_e32 v55, 0
	v_mov_b32_e32 v56, 0
	v_mov_b32_e32 v57, 0
	v_mov_b32_e32 v62, 0
	v_mov_b32_e32 v63, 0
	v_mov_b32_e32 v64, 0
	v_mov_b32_e32 v65, 0
	s_waitcnt lgkmcnt(0)
	s_waitcnt vmcnt(3)
	v_mov_b32_e32 v68, v50
	s_waitcnt vmcnt(2)
	v_mov_b32_e32 v69, v54
	v_mov_b32_e32 v54, v51
	v_mov_b32_e32 v50, v52
	v_mov_b32_e32 v51, v56
	v_mov_b32_e32 v56, v53
	s_waitcnt vmcnt(1)
	v_mov_b32_e32 v52, v58
	s_waitcnt vmcnt(0)
	v_mov_b32_e32 v53, v62
	v_mov_b32_e32 v62, v59
	v_mov_b32_e32 v58, v60
	v_mov_b32_e32 v59, v64
	v_mov_b32_e32 v64, v61
	v_pk_add_f32 v[54:55], v[68:69], v[54:55]
	v_pk_add_f32 v[50:51], v[50:51], v[56:57]
	v_pk_add_f32 v[52:53], v[52:53], v[62:63]
	v_pk_add_f32 v[56:57], v[58:59], v[64:65]
	v_pk_add_f32 v[50:51], v[54:55], v[50:51]
	v_pk_add_f32 v[52:53], v[52:53], v[56:57]
	s_nop 0
	v_pk_add_f32 v[50:51], v[50:51], v[52:53]
	s_nop 0
	v_add_f32_e32 v50, v50, v51
	v_fmamk_f32 v50, v50, 0x3a800000, v156
	v_mul_f32_e32 v51, 0x4f800000, v50
	v_cmp_gt_f32_e32 vcc, s57, v50
	s_nop 1
	v_cndmask_b32_e32 v52, v50, v51, vcc
	v_sqrt_f32_e32 v53, v52
	v_lshlrev_b64 v[50:51], 11, v[66:67]
	v_lshl_add_u64 v[50:51], s[18:19], 0, v[50:51]
	v_lshl_add_u64 v[58:59], v[144:145], 1, v[50:51]
	v_add_u32_e32 v54, -1, v53
	v_add_u32_e32 v55, 1, v53
	v_fma_f32 v56, -v54, v53, v52
	v_fma_f32 v57, -v55, v53, v52
	v_cmp_ge_f32_e64 s[12:13], 0, v56
	s_nop 1
	v_cndmask_b32_e64 v53, v53, v54, s[12:13]
	v_cmp_lt_f32_e64 s[12:13], 0, v57
	s_nop 1
	v_cndmask_b32_e64 v53, v53, v55, s[12:13]
	v_mul_f32_e32 v54, 0x37800000, v53
	v_cndmask_b32_e32 v53, v53, v54, vcc
	v_cmp_class_f32_e32 vcc, v52, v157
	s_nop 1
	v_cndmask_b32_e32 v52, v53, v52, vcc
	v_div_scale_f32 v53, s[12:13], v52, v52, 1.0
	v_rcp_f32_e32 v54, v53
	v_div_scale_f32 v50, vcc, 1.0, v52, 1.0
	v_fma_f32 v51, -v53, v54, 1.0
	v_fmac_f32_e32 v54, v51, v54
	v_mul_f32_e32 v51, v50, v54
	v_fma_f32 v55, -v53, v51, v50
	v_fmac_f32_e32 v51, v55, v54
	v_fma_f32 v50, -v53, v51, v50
	v_div_fmas_f32 v50, v50, v54, v51
	v_div_fixup_f32 v50, v50, v52, 1.0
	v_pk_mul_f32 v[46:47], v[46:47], v[50:51] op_sel_hi:[1,0]
	v_pk_mul_f32 v[44:45], v[44:45], v[50:51] op_sel_hi:[1,0]
	v_pk_mul_f32 v[42:43], v[42:43], v[50:51] op_sel_hi:[1,0]
	v_pk_mul_f32 v[40:41], v[40:41], v[50:51] op_sel_hi:[1,0]
	s_and_b64 vcc, exec, s[10:11]
	v_pk_mul_f32 v[38:39], v[38:39], v[50:51] op_sel_hi:[1,0]
	v_pk_mul_f32 v[36:37], v[36:37], v[50:51] op_sel_hi:[1,0]
	v_pk_mul_f32 v[34:35], v[34:35], v[50:51] op_sel_hi:[1,0]
	v_pk_mul_f32 v[32:33], v[32:33], v[50:51] op_sel_hi:[1,0]
	v_cvt_pk_bf16_f32 v50, v44, v45
	v_cvt_pk_bf16_f32 v51, v46, v47
	v_cvt_pk_bf16_f32 v52, v40, v41
	v_cvt_pk_bf16_f32 v53, v42, v43
	v_cvt_pk_bf16_f32 v54, v36, v37
	v_cvt_pk_bf16_f32 v55, v38, v39
	v_cvt_pk_bf16_f32 v56, v32, v33
	v_cvt_pk_bf16_f32 v57, v34, v35
	global_store_dwordx4 v[58:59], v[50:53], off
	global_store_dwordx4 v[58:59], v[54:57], off offset:256
	s_cbranch_vccnz .LBB0_1446
	v_mul_f32_e32 v35, v35, v35
	v_fmac_f32_e32 v35, v34, v34
	v_mul_f32_e32 v34, v37, v37
	v_mul_f32_e32 v43, v43, v43
	v_fmac_f32_e32 v34, v36, v36
	v_mul_f32_e32 v36, v39, v39
	v_fmac_f32_e32 v43, v42, v42
	v_mul_f32_e32 v42, v45, v45
	v_fmac_f32_e32 v36, v38, v38
	v_mul_f32_e32 v33, v33, v33
	v_fmac_f32_e32 v42, v44, v44
	v_mul_f32_e32 v44, v47, v47
	v_add_f32_e32 v34, v34, v36
	v_fmac_f32_e32 v33, v32, v32
	v_fmac_f32_e32 v44, v46, v46
	v_mul_f32_e32 v41, v41, v41
	v_add_f32_e32 v32, v33, v34
	v_and_b32_e32 v34, 64, v158
	v_add_f32_e32 v42, v42, v44
	v_fmac_f32_e32 v41, v40, v40
	v_xor_b32_e32 v33, 16, v158
	v_add_u32_e32 v34, 64, v34
	v_add_f32_e32 v40, v41, v42
	v_cmp_lt_i32_e32 vcc, v33, v34
	v_add_f32_e32 v40, v43, v40
	v_add_f32_e32 v32, v35, v32
	v_cndmask_b32_e32 v33, v158, v33, vcc
	v_add_f32_e32 v32, v40, v32
	v_lshlrev_b32_e32 v33, 2, v33
	ds_bpermute_b32 v33, v33, v32
	s_waitcnt lgkmcnt(0)
	v_add_f32_e32 v32, v32, v33
	v_xor_b32_e32 v33, 32, v158
	v_cmp_lt_i32_e32 vcc, v33, v34
	s_nop 1
	v_cndmask_b32_e32 v33, v158, v33, vcc
	v_lshlrev_b32_e32 v33, 2, v33
	ds_bpermute_b32 v33, v33, v32
	s_and_saveexec_b64 s[12:13], s[6:7]
	s_cbranch_execz .LBB0_1445
	s_waitcnt lgkmcnt(0)
	v_add_f32_e32 v34, v32, v33
	v_lshl_add_u64 v[32:33], s[40:41], 0, v[48:49]
	global_store_dword v[32:33], v34, off

; __device__ __forceinline__ unsigned cvtpk(float lo, float hi) { f32x2_t v = {lo, hi}; bf16x2_t b = __builtin_convertvector(v, bf16x2_t); return __builtin_bit_cast(unsigned, b); }
;     __device__ __forceinline__ void operator()(const f32x4 (&acc)[2][2][4][2], const Unit& u, int wr, int wc, int fr, int fq) const {
;     ...
;             for (int m = 0; m < 4; ++m) {
;                 const int row = row0 + ai * HALF + m * 16; float s = 0.f;
;                 const float rs = ssq_in ? 1.0f / sqrtf(ssq_sum(ssq_in + (size_t)row * 16) * inv_dim + EPS) : 1.0f;
; #pragma unroll
;                 for (int bj = 0; bj < 2; ++bj) {
;                     int col = col0 + bj * HALF; if (hd_in) col = (col / hd_in) * hd_out + (col % hd_in);
;                     const f32x4 v0 = acc[ai][bj][m][0] * rs, v1 = acc[ai][bj][m][1] * rs;
;                     u32x4 w; w.x = cvtpk(v0[0], v0[1]); w.y = cvtpk(v0[2], v0[3]); w.z = cvtpk(v1[0], v1[1]); w.w = cvtpk(v1[2], v1[3]);
;                     *(u32x4*)(O + (size_t)row * ldc + col) = w;
;                     s += (v0[0] * v0[0] + v0[1] * v0[1]) + (v0[2] * v0[2] + v0[3] * v0[3]) + (v1[0] * v1[0] + v1[1] * v1[1]) + (v1[2] * v1[2] + v1[3] * v1[3]);
;                 }
;                 if (so) { s += __shfl_xor(s, 16); s += __shfl_xor(s, 32); if (fq == 0) so[(size_t)row * 16 + (u.pn & 1) * 4 + wc] = s; }
.LBB0_1446:
	v_add_u32_e32 v50, 0xa0, v146
	v_ashrrev_i32_e32 v51, 31, v50
	s_waitcnt lgkmcnt(0)
	v_lshlrev_b64 v[32:33], 6, v[50:51]
	v_lshl_add_u64 v[46:47], s[20:21], 0, v[32:33]
	s_nop 1
	ds_read_b32 v34, v253 offset:640
	v_mov_b32_e32 v35, 0
	v_mov_b32_e32 v36, 0
	v_mov_b32_e32 v37, 0
	v_mov_b32_e32 v42, 0
	v_mov_b32_e32 v43, 0
	v_mov_b32_e32 v44, 0
	v_mov_b32_e32 v45, 0
	v_mov_b32_e32 v38, 0
	v_mov_b32_e32 v39, 0
	v_mov_b32_e32 v40, 0
	v_mov_b32_e32 v41, 0
	v_mov_b32_e32 v46, 0
	v_mov_b32_e32 v47, 0
	v_mov_b32_e32 v48, 0
	v_mov_b32_e32 v49, 0
	s_waitcnt lgkmcnt(0)
	s_waitcnt vmcnt(3)
	v_mov_b32_e32 v52, v34
	s_waitcnt vmcnt(2)
	v_mov_b32_e32 v53, v38
	v_mov_b32_e32 v38, v35
	v_mov_b32_e32 v34, v36
	v_mov_b32_e32 v35, v40
	v_mov_b32_e32 v40, v37
	s_waitcnt vmcnt(1)
	v_mov_b32_e32 v36, v42
	s_waitcnt vmcnt(0)
	v_mov_b32_e32 v37, v46
	v_mov_b32_e32 v46, v43
	v_mov_b32_e32 v42, v44
	v_mov_b32_e32 v43, v48
	v_mov_b32_e32 v48, v45
	v_pk_add_f32 v[38:39], v[52:53], v[38:39]
	v_pk_add_f32 v[34:35], v[34:35], v[40:41]
	v_pk_add_f32 v[36:37], v[36:37], v[46:47]
	v_pk_add_f32 v[40:41], v[42:43], v[48:49]
	v_pk_add_f32 v[34:35], v[38:39], v[34:35]
	v_pk_add_f32 v[36:37], v[36:37], v[40:41]
	s_nop 0
	v_pk_add_f32 v[34:35], v[34:35], v[36:37]
	s_nop 0
	v_add_f32_e32 v34, v34, v35
	v_fmamk_f32 v34, v34, 0x3a800000, v156
	v_mul_f32_e32 v35, 0x4f800000, v34
	v_cmp_gt_f32_e32 vcc, s57, v34
	s_nop 1
	v_cndmask_b32_e32 v36, v34, v35, vcc
	v_sqrt_f32_e32 v37, v36
	v_lshlrev_b64 v[34:35], 11, v[50:51]
	v_lshl_add_u64 v[34:35], s[18:19], 0, v[34:35]
	v_lshl_add_u64 v[42:43], v[144:145], 1, v[34:35]
	v_add_u32_e32 v38, -1, v37
	v_add_u32_e32 v39, 1, v37
	v_fma_f32 v40, -v38, v37, v36
	v_fma_f32 v41, -v39, v37, v36
	v_cmp_ge_f32_e64 s[12:13], 0, v40
	s_nop 1
	v_cndmask_b32_e64 v37, v37, v38, s[12:13]
	v_cmp_lt_f32_e64 s[12:13], 0, v41
	s_nop 1
	v_cndmask_b32_e64 v37, v37, v39, s[12:13]
	v_mul_f32_e32 v38, 0x37800000, v37
	v_cndmask_b32_e32 v37, v37, v38, vcc
	v_cmp_class_f32_e32 vcc, v36, v157
	s_nop 1
	v_cndmask_b32_e32 v36, v37, v36, vcc
	v_div_scale_f32 v37, s[12:13], v36, v36, 1.0
	v_rcp_f32_e32 v38, v37
	v_div_scale_f32 v34, vcc, 1.0, v36, 1.0
	v_fma_f32 v35, -v37, v38, 1.0
	v_fmac_f32_e32 v38, v35, v38
	v_mul_f32_e32 v35, v34, v38
	v_fma_f32 v39, -v37, v35, v34
	v_fmac_f32_e32 v35, v39, v38
	v_fma_f32 v34, -v37, v35, v34
	v_div_fmas_f32 v34, v34, v38, v35
	v_div_fixup_f32 v34, v34, v36, 1.0
	v_pk_mul_f32 v[30:31], v[30:31], v[34:35] op_sel_hi:[1,0]
	v_pk_mul_f32 v[28:29], v[28:29], v[34:35] op_sel_hi:[1,0]
	v_pk_mul_f32 v[26:27], v[26:27], v[34:35] op_sel_hi:[1,0]
	v_pk_mul_f32 v[24:25], v[24:25], v[34:35] op_sel_hi:[1,0]
	s_and_b64 vcc, exec, s[10:11]
	v_pk_mul_f32 v[22:23], v[22:23], v[34:35] op_sel_hi:[1,0]
	v_pk_mul_f32 v[20:21], v[20:21], v[34:35] op_sel_hi:[1,0]
	v_pk_mul_f32 v[18:19], v[18:19], v[34:35] op_sel_hi:[1,0]
	v_pk_mul_f32 v[16:17], v[16:17], v[34:35] op_sel_hi:[1,0]
	v_cvt_pk_bf16_f32 v34, v28, v29
	v_cvt_pk_bf16_f32 v35, v30, v31
	v_cvt_pk_bf16_f32 v36, v24, v25
	v_cvt_pk_bf16_f32 v37, v26, v27
	v_cvt_pk_bf16_f32 v38, v20, v21
	v_cvt_pk_bf16_f32 v39, v22, v23
	v_cvt_pk_bf16_f32 v40, v16, v17
	v_cvt_pk_bf16_f32 v41, v18, v19
	global_store_dwordx4 v[42:43], v[34:37], off
	global_store_dwordx4 v[42:43], v[38:41], off offset:256
	s_cbranch_vccnz .LBB0_1450
	v_mul_f32_e32 v19, v19, v19
	v_fmac_f32_e32 v19, v18, v18
	v_mul_f32_e32 v18, v21, v21
	v_mul_f32_e32 v27, v27, v27
	v_fmac_f32_e32 v18, v20, v20
	v_mul_f32_e32 v20, v23, v23
	v_fmac_f32_e32 v27, v26, v26
	v_mul_f32_e32 v26, v29, v29
	v_fmac_f32_e32 v20, v22, v22
	v_mul_f32_e32 v17, v17, v17
	v_fmac_f32_e32 v26, v28, v28
	v_mul_f32_e32 v28, v31, v31
	v_add_f32_e32 v18, v18, v20
	v_fmac_f32_e32 v17, v16, v16
	v_fmac_f32_e32 v28, v30, v30
	v_mul_f32_e32 v25, v25, v25
	v_add_f32_e32 v16, v17, v18
	v_and_b32_e32 v18, 64, v158
	v_add_f32_e32 v26, v26, v28
	v_fmac_f32_e32 v25, v24, v24
	v_xor_b32_e32 v17, 16, v158
	v_add_u32_e32 v18, 64, v18
	v_add_f32_e32 v24, v25, v26
	v_cmp_lt_i32_e32 vcc, v17, v18
	v_add_f32_e32 v24, v27, v24
	v_add_f32_e32 v16, v19, v16
	v_cndmask_b32_e32 v17, v158, v17, vcc
	v_add_f32_e32 v16, v24, v16
	v_lshlrev_b32_e32 v17, 2, v17
	ds_bpermute_b32 v17, v17, v16
	s_waitcnt lgkmcnt(0)
	v_add_f32_e32 v16, v16, v17
	v_xor_b32_e32 v17, 32, v158
	v_cmp_lt_i32_e32 vcc, v17, v18
	s_nop 1
	v_cndmask_b32_e32 v17, v158, v17, vcc
	v_lshlrev_b32_e32 v17, 2, v17
	ds_bpermute_b32 v17, v17, v16
	s_and_saveexec_b64 s[12:13], s[6:7]
	s_cbranch_execz .LBB0_1449
	s_waitcnt lgkmcnt(0)
	v_add_f32_e32 v18, v16, v17
	v_lshl_add_u64 v[16:17], s[40:41], 0, v[32:33]
	global_store_dword v[16:17], v18, off

; __device__ __forceinline__ unsigned cvtpk(float lo, float hi) { f32x2_t v = {lo, hi}; bf16x2_t b = __builtin_convertvector(v, bf16x2_t); return __builtin_bit_cast(unsigned, b); }
;     __device__ __forceinline__ void operator()(const f32x4 (&acc)[2][2][4][2], const Unit& u, int wr, int wc, int fr, int fq) const {
;     ...
;             for (int m = 0; m < 4; ++m) {
;                 const int row = row0 + ai * HALF + m * 16; float s = 0.f;
;                 const float rs = ssq_in ? 1.0f / sqrtf(ssq_sum(ssq_in + (size_t)row * 16) * inv_dim + EPS) : 1.0f;
; #pragma unroll
;                 for (int bj = 0; bj < 2; ++bj) {
;                     int col = col0 + bj * HALF; if (hd_in) col = (col / hd_in) * hd_out + (col % hd_in);
;                     const f32x4 v0 = acc[ai][bj][m][0] * rs, v1 = acc[ai][bj][m][1] * rs;
;                     u32x4 w; w.x = cvtpk(v0[0], v0[1]); w.y = cvtpk(v0[2], v0[3]); w.z = cvtpk(v1[0], v1[1]); w.w = cvtpk(v1[2], v1[3]);
;                     *(u32x4*)(O + (size_t)row * ldc + col) = w;
;                     s += (v0[0] * v0[0] + v0[1] * v0[1]) + (v0[2] * v0[2] + v0[3] * v0[3]) + (v1[0] * v1[0] + v1[1] * v1[1]) + (v1[2] * v1[2] + v1[3] * v1[3]);
;                 }
;                 if (so) { s += __shfl_xor(s, 16); s += __shfl_xor(s, 32); if (fq == 0) so[(size_t)row * 16 + (u.pn & 1) * 4 + wc] = s; }
.LBB0_1450:
	v_add_u32_e32 v34, 0xb0, v146
	v_ashrrev_i32_e32 v35, 31, v34
	s_waitcnt lgkmcnt(0)
	v_lshlrev_b64 v[16:17], 6, v[34:35]
	v_lshl_add_u64 v[30:31], s[20:21], 0, v[16:17]
	s_nop 1
	ds_read_b32 v18, v253 offset:704
	v_mov_b32_e32 v19, 0
	v_mov_b32_e32 v20, 0
	v_mov_b32_e32 v21, 0
	v_mov_b32_e32 v26, 0
	v_mov_b32_e32 v27, 0
	v_mov_b32_e32 v28, 0
	v_mov_b32_e32 v29, 0
	v_mov_b32_e32 v22, 0
	v_mov_b32_e32 v23, 0
	v_mov_b32_e32 v24, 0
	v_mov_b32_e32 v25, 0
	v_mov_b32_e32 v30, 0
	v_mov_b32_e32 v31, 0
	v_mov_b32_e32 v32, 0
	v_mov_b32_e32 v33, 0
	s_waitcnt lgkmcnt(0)
	s_waitcnt vmcnt(3)
	v_mov_b32_e32 v36, v18
	s_waitcnt vmcnt(2)
	v_mov_b32_e32 v37, v22
	v_mov_b32_e32 v22, v19
	v_mov_b32_e32 v18, v20
	v_mov_b32_e32 v19, v24
	v_mov_b32_e32 v24, v21
	s_waitcnt vmcnt(1)
	v_mov_b32_e32 v20, v26
	s_waitcnt vmcnt(0)
	v_mov_b32_e32 v21, v30
	v_mov_b32_e32 v30, v27
	v_mov_b32_e32 v26, v28
	v_mov_b32_e32 v27, v32
	v_mov_b32_e32 v32, v29
	v_pk_add_f32 v[22:23], v[36:37], v[22:23]
	v_pk_add_f32 v[18:19], v[18:19], v[24:25]
	v_pk_add_f32 v[20:21], v[20:21], v[30:31]
	v_pk_add_f32 v[24:25], v[26:27], v[32:33]
	v_pk_add_f32 v[18:19], v[22:23], v[18:19]
	v_pk_add_f32 v[20:21], v[20:21], v[24:25]
	s_nop 0
	v_pk_add_f32 v[18:19], v[18:19], v[20:21]
	s_nop 0
	v_add_f32_e32 v18, v18, v19
	v_fmamk_f32 v18, v18, 0x3a800000, v156
	v_mul_f32_e32 v19, 0x4f800000, v18
	v_cmp_gt_f32_e32 vcc, s57, v18
	s_nop 1
	v_cndmask_b32_e32 v20, v18, v19, vcc
	v_sqrt_f32_e32 v21, v20
	v_lshlrev_b64 v[18:19], 11, v[34:35]
	v_lshl_add_u64 v[18:19], s[18:19], 0, v[18:19]
	v_lshl_add_u64 v[26:27], v[144:145], 1, v[18:19]
	v_add_u32_e32 v22, -1, v21
	v_add_u32_e32 v23, 1, v21
	v_fma_f32 v24, -v22, v21, v20
	v_fma_f32 v25, -v23, v21, v20
	v_cmp_ge_f32_e64 s[12:13], 0, v24
	s_nop 1
	v_cndmask_b32_e64 v21, v21, v22, s[12:13]
	v_cmp_lt_f32_e64 s[12:13], 0, v25
	s_nop 1
	v_cndmask_b32_e64 v21, v21, v23, s[12:13]
	v_mul_f32_e32 v22, 0x37800000, v21
	v_cndmask_b32_e32 v21, v21, v22, vcc
	v_cmp_class_f32_e32 vcc, v20, v157
	s_nop 1
	v_cndmask_b32_e32 v20, v21, v20, vcc
	v_div_scale_f32 v21, s[12:13], v20, v20, 1.0
	v_rcp_f32_e32 v22, v21
	v_div_scale_f32 v18, vcc, 1.0, v20, 1.0
	v_fma_f32 v19, -v21, v22, 1.0
	v_fmac_f32_e32 v22, v19, v22
	v_mul_f32_e32 v19, v18, v22
	v_fma_f32 v23, -v21, v19, v18
	v_fmac_f32_e32 v19, v23, v22
	v_fma_f32 v18, -v21, v19, v18
	v_div_fmas_f32 v18, v18, v22, v19
	v_div_fixup_f32 v18, v18, v20, 1.0
	v_pk_mul_f32 v[14:15], v[14:15], v[18:19] op_sel_hi:[1,0]
	v_pk_mul_f32 v[12:13], v[12:13], v[18:19] op_sel_hi:[1,0]
	v_pk_mul_f32 v[10:11], v[10:11], v[18:19] op_sel_hi:[1,0]
	v_pk_mul_f32 v[8:9], v[8:9], v[18:19] op_sel_hi:[1,0]
	s_and_b64 vcc, exec, s[10:11]
	v_pk_mul_f32 v[6:7], v[6:7], v[18:19] op_sel_hi:[1,0]
	v_pk_mul_f32 v[4:5], v[4:5], v[18:19] op_sel_hi:[1,0]
	v_pk_mul_f32 v[2:3], v[2:3], v[18:19] op_sel_hi:[1,0]
	v_pk_mul_f32 v[0:1], v[0:1], v[18:19] op_sel_hi:[1,0]
	v_cvt_pk_bf16_f32 v18, v12, v13
	v_cvt_pk_bf16_f32 v19, v14, v15
	v_cvt_pk_bf16_f32 v20, v8, v9
	v_cvt_pk_bf16_f32 v21, v10, v11
	v_cvt_pk_bf16_f32 v22, v4, v5
	v_cvt_pk_bf16_f32 v23, v6, v7
	v_cvt_pk_bf16_f32 v24, v0, v1
	v_cvt_pk_bf16_f32 v25, v2, v3
	global_store_dwordx4 v[26:27], v[18:21], off
	global_store_dwordx4 v[26:27], v[22:25], off offset:256
	s_cbranch_vccnz .LBB0_1454
	v_mul_f32_e32 v3, v3, v3
	v_fmac_f32_e32 v3, v2, v2
	v_mul_f32_e32 v2, v5, v5
	v_mul_f32_e32 v11, v11, v11
	v_fmac_f32_e32 v2, v4, v4
	v_mul_f32_e32 v4, v7, v7
	v_fmac_f32_e32 v11, v10, v10
	v_mul_f32_e32 v10, v13, v13
	v_fmac_f32_e32 v4, v6, v6
	v_mul_f32_e32 v1, v1, v1
	v_fmac_f32_e32 v10, v12, v12
	v_mul_f32_e32 v12, v15, v15
	v_add_f32_e32 v2, v2, v4
	v_fmac_f32_e32 v1, v0, v0
	v_fmac_f32_e32 v12, v14, v14
	v_mul_f32_e32 v9, v9, v9
	v_add_f32_e32 v0, v1, v2
	v_and_b32_e32 v2, 64, v158
	v_add_f32_e32 v10, v10, v12
	v_fmac_f32_e32 v9, v8, v8
	v_xor_b32_e32 v1, 16, v158
	v_add_u32_e32 v2, 64, v2
	v_add_f32_e32 v8, v9, v10
	v_cmp_lt_i32_e32 vcc, v1, v2
	v_add_f32_e32 v8, v11, v8
	v_add_f32_e32 v0, v3, v0
	v_cndmask_b32_e32 v1, v158, v1, vcc
	v_add_f32_e32 v0, v8, v0
	v_lshlrev_b32_e32 v1, 2, v1
	ds_bpermute_b32 v1, v1, v0
	s_waitcnt lgkmcnt(0)
	v_add_f32_e32 v0, v0, v1
	v_xor_b32_e32 v1, 32, v158
	v_cmp_lt_i32_e32 vcc, v1, v2
	s_nop 1
	v_cndmask_b32_e32 v1, v158, v1, vcc
	v_lshlrev_b32_e32 v1, 2, v1
	ds_bpermute_b32 v1, v1, v0
	s_and_saveexec_b64 s[10:11], s[6:7]
	s_cbranch_execz .LBB0_1453
	s_waitcnt lgkmcnt(0)
	v_add_f32_e32 v2, v0, v1
	v_lshl_add_u64 v[0:1], s[40:41], 0, v[16:17]
	global_store_dword v[0:1], v2, off

; __device__ __forceinline__ int lane_now() { int l; asm volatile("v_mbcnt_lo_u32_b32 %0, -1, 0\n\tv_mbcnt_hi_u32_b32 %0, -1, %0" : "=v"(l)); return l; }
; __device__ __forceinline__ unsigned cvtpk(float lo, float hi) { f32x2_t v = {lo, hi}; bf16x2_t b = __builtin_convertvector(v, bf16x2_t); return __builtin_bit_cast(unsigned, b); }
;     __device__ __forceinline__ void operator()(const f32x4 (&acc)[2][2][4][2], const Unit& u, int wr, int wc, int fr, int fq) const {
;         { const int l_ = lane_now(); fq = l_ >> 4; fr = l_ & 15; }
;         const int row0 = u.pm * BM + wr * 64 + fr;
;         const int head = u.pn * 4 + wc;
;         float rhs[8];
; #pragma unroll
;         for (int ai = 0; ai < 2; ++ai)
; #pragma unroll
;             for (int m = 0; m < 4; ++m) {
;                 const int row = row0 + ai * HALF + m * 16;
;                 const float rkv = 1.0f / sqrtf(ssq_sum(ssq_in + (size_t)row * 16) * (1.0f / 256.0f) + EPS);
;                 const u32x4 kw = *(const u32x4*)(T1 + (size_t)row * 1024 + 768 + 8 * fq);
;                 float s = (bflo(kw.x) * bflo(kw.x) + bfhi(kw.x) * bfhi(kw.x)) + (bflo(kw.y) * bflo(kw.y) + bfhi(kw.y) * bfhi(kw.y))
;                         + (bflo(kw.z) * bflo(kw.z) + bfhi(kw.z) * bfhi(kw.z)) + (bflo(kw.w) * bflo(kw.w) + bfhi(kw.w) * bfhi(kw.w));
; #pragma unroll
;                 for (int bj = 0; bj < 2; ++bj)
; #pragma unroll
;                     for (int n = 0; n < 2; ++n) { const f32x4 v = acc[ai][bj][m][n] * rkv; s += (v[0] * v[0] + v[1] * v[1]) + (v[2] * v[2] + v[3] * v[3]); }
;                 s += __shfl_xor(s, 16); s += __shfl_xor(s, 32);
;                 const float rh = 1.0f / sqrtf(s * (1.0f / 96.0f) + EPS), rs = rkv * rh;
;                 rhs[ai * 4 + m] = rh;
;                 bf16_t* op = O + (size_t)row * 1536 + head * 96;
; #pragma unroll
;                 for (int bj = 0; bj < 2; ++bj) {
;                     const f32x4 g0 = *(const f32x4*)(gk + bj * 32 + 8 * fq), g1 = *(const f32x4*)(gk + bj * 32 + 8 * fq + 4);
;                     const f32x4 v0 = acc[ai][bj][m][0] * rs * g0, v1 = acc[ai][bj][m][1] * rs * g1;
;                     u32x4 w; w.x = cvtpk(v0[0], v0[1]); w.y = cvtpk(v0[2], v0[3]); w.z = cvtpk(v1[0], v1[1]); w.w = cvtpk(v1[2], v1[3]);
;                     *(u32x4*)(op + bj * 32 + 8 * fq) = w;
.LBB0_1549:
	s_lshl_b32 s37, s8, 8
	v_mbcnt_lo_u32_b32 v162, -1, 0
	v_mbcnt_hi_u32_b32 v162, -1, v162
	s_add_i32 s37, s37, s59
	v_and_b32_e32 v161, 15, v162
	v_or_b32_e32 v140, s37, v161
	v_readlane_b32 vcc_lo, v254, 7
	v_mbcnt_lo_u32_b32 v218, -1, 0
	v_mbcnt_hi_u32_b32 v218, -1, v218
	v_lshrrev_b32_e32 v219, 1, v218
	v_lshl_add_u32 v219, vcc_lo, 5, v219
	v_and_b32_e32 v220, 1, v218
	v_add_u32_e32 v221, s37, v219
	v_subrev_u32_e32 v221, s59, v221
	v_lshlrev_b32_e32 v221, 6, v221
	v_lshl_add_u32 v221, v220, 5, v221
	global_load_dwordx4 v[222:225], v221, s[14:15]
	global_load_dwordx4 v[226:229], v221, s[14:15] offset:16
	v_and_b32_e32 v253, 0xff, v140
	v_lshlrev_b32_e32 v253, 2, v253
	v_add_u32_e32 v253, 0x20100, v253
	v_lshlrev_b32_e32 v219, 2, v219
	v_add_u32_e32 v219, 0x20100, v219
	s_waitcnt vmcnt(0)
	v_pk_add_f32 v[222:223], v[222:223], v[224:225]
	v_pk_add_f32 v[226:227], v[226:227], v[228:229]
	v_pk_add_f32 v[222:223], v[222:223], v[226:227]
	v_add_f32_e32 v222, v222, v223
	s_nop 1
	v_add_f32_dpp v222, v222, v222 quad_perm:[1,0,3,2] row_mask:0xf bank_mask:0xf
	ds_write_b32 v219, v222
	s_waitcnt lgkmcnt(0)
	s_barrier
	v_ashrrev_i32_e32 v141, 31, v140
	v_lshlrev_b64 v[142:143], 6, v[140:141]
	v_lshl_add_u64 v[142:143], s[14:15], 0, v[142:143]
	s_nop 1
	ds_read_b32 v164, v253 offset:0
	v_mov_b32_e32 v165, 0
	v_mov_b32_e32 v166, 0
	v_mov_b32_e32 v167, 0
	v_mov_b32_e32 v172, 0
	v_mov_b32_e32 v173, 0
	v_mov_b32_e32 v174, 0
	v_mov_b32_e32 v175, 0
	v_mov_b32_e32 v168, 0
	v_mov_b32_e32 v169, 0
	v_mov_b32_e32 v170, 0
	v_mov_b32_e32 v171, 0
	v_mov_b32_e32 v176, 0
	v_mov_b32_e32 v177, 0
	v_mov_b32_e32 v178, 0
	v_mov_b32_e32 v179, 0
	s_waitcnt lgkmcnt(0)
	v_ashrrev_i32_e32 v160, 4, v162
	v_lshlrev_b32_e32 v144, 3, v160
	v_ashrrev_i32_e32 v145, 31, v144
	v_lshlrev_b64 v[142:143], 11, v[140:141]
	v_lshlrev_b64 v[146:147], 1, v[144:145]
	v_lshl_add_u64 v[142:143], s[10:11], 0, v[142:143]
	v_lshl_add_u64 v[142:143], v[142:143], 0, v[146:147]
	global_load_dwordx4 v[180:183], v[142:143], off offset:1536
	v_and_b32_e32 v148, 64, v157
	v_lshl_add_u64 v[150:151], v[144:145], 2, s[18:19]
	v_xor_b32_e32 v141, 16, v157
	v_add_u32_e32 v194, 64, v148
	v_cmp_lt_i32_e32 vcc, v141, v194
	global_load_dwordx4 v[184:187], v[150:151], off offset:16
	global_load_dwordx4 v[188:191], v[150:151], off
	v_cndmask_b32_e32 v141, v157, v141, vcc
	v_lshlrev_b32_e32 v163, 2, v141
	s_lshl_b32 s2, s2, 2
	s_or_b32 s2, s2, s58
	s_waitcnt vmcnt(0)
	v_mov_b32_e32 v144, v164
	v_mov_b32_e32 v145, v168
	v_mov_b32_e32 v168, v165
	v_mov_b32_e32 v152, v166
	v_mov_b32_e32 v153, v170
	v_mov_b32_e32 v170, v167
	v_mov_b32_e32 v164, v172
	v_mov_b32_e32 v165, v176
	v_mov_b32_e32 v176, v173
	v_mov_b32_e32 v166, v174
	v_mov_b32_e32 v167, v178
	v_mov_b32_e32 v178, v175
	v_pk_add_f32 v[144:145], v[144:145], v[168:169]
	v_pk_add_f32 v[152:153], v[152:153], v[170:171]
	v_pk_add_f32 v[164:165], v[164:165], v[176:177]
	v_pk_add_f32 v[166:167], v[166:167], v[178:179]
	v_pk_add_f32 v[144:145], v[144:145], v[152:153]
	v_pk_add_f32 v[152:153], v[164:165], v[166:167]
	v_and_b32_e32 v173, 0xffff0000, v182
	v_pk_add_f32 v[144:145], v[144:145], v[152:153]
	v_lshlrev_b32_e32 v172, 16, v182
	v_add_f32_e32 v141, v144, v145
	v_fmamk_f32 v141, v141, 0x3b800000, v158
	v_mul_f32_e32 v144, 0x4f800000, v141
	v_cmp_gt_f32_e32 vcc, s66, v141
	v_and_b32_e32 v171, 0xffff0000, v181
	v_and_b32_e32 v170, 0xffff0000, v180
	v_cndmask_b32_e32 v141, v141, v144, vcc
	v_sqrt_f32_e32 v148, v141
	v_mul_f32_e32 v144, v173, v173
	v_pk_fma_f32 v[144:145], v[172:173], v[172:173], v[144:145] op_sel_hi:[1,1,0]
	v_lshlrev_b32_e32 v169, 16, v181
	v_lshlrev_b32_e32 v168, 16, v180
	v_pk_mul_f32 v[164:165], v[170:171], v[170:171]
	v_add_u32_e32 v145, -1, v148
	v_pk_fma_f32 v[152:153], v[168:169], v[168:169], v[164:165]
	v_add_u32_e32 v164, 1, v148
	v_fma_f32 v165, -v145, v148, v141
	v_fma_f32 v166, -v164, v148, v141
	v_cmp_ge_f32_e64 s[8:9], 0, v165
	v_pk_add_f32 v[152:153], v[152:153], v[152:153] op_sel:[0,1] op_sel_hi:[1,0]
	v_and_b32_e32 v176, 0xffff0000, v183
	v_cndmask_b32_e64 v145, v148, v145, s[8:9]
	v_cmp_lt_f32_e64 s[8:9], 0, v166
	v_lshlrev_b32_e32 v174, 16, v183
	s_nop 0
	v_cndmask_b32_e64 v145, v145, v164, s[8:9]
	v_mul_f32_e32 v148, 0x37800000, v145
	v_cndmask_b32_e32 v145, v145, v148, vcc
	v_cmp_class_f32_e32 vcc, v141, v159
	s_nop 1
	v_cndmask_b32_e32 v141, v145, v141, vcc
	v_div_scale_f32 v145, s[8:9], v141, v141, 1.0
	v_rcp_f32_e32 v148, v145
	v_div_scale_f32 v153, vcc, 1.0, v141, 1.0
	v_fma_f32 v164, -v145, v148, 1.0
	v_fmac_f32_e32 v148, v164, v148
	v_mul_f32_e32 v164, v153, v148
	v_fma_f32 v165, -v145, v164, v153
	v_fmac_f32_e32 v164, v165, v148
	v_fma_f32 v145, -v145, v164, v153
	v_div_fmas_f32 v145, v145, v148, v164
	v_div_fixup_f32 v164, v145, v141, 1.0
	v_pk_mul_f32 v[166:167], v[124:125], v[164:165] op_sel_hi:[1,0]
	v_pk_mul_f32 v[168:169], v[126:127], v[164:165] op_sel_hi:[1,0]
	v_pk_mul_f32 v[170:171], v[120:121], v[164:165] op_sel_hi:[1,0]
	v_pk_mul_f32 v[172:173], v[122:123], v[164:165] op_sel_hi:[1,0]
	v_mov_b32_e32 v177, v167
	v_mul_f32_e32 v145, v168, v168
	v_mul_f32_e32 v153, v169, v169
	v_mov_b32_e32 v175, v166
	v_pk_mul_f32 v[166:167], v[172:173], v[172:173]
	v_pk_mul_f32 v[168:169], v[170:171], v[170:171]
	v_pk_mul_f32 v[172:173], v[176:177], v[176:177]
	v_pk_mul_f32 v[178:179], v[114:115], v[164:165] op_sel_hi:[1,0]
	v_pk_mul_f32 v[180:181], v[112:113], v[164:165] op_sel_hi:[1,0]
	v_pk_mov_b32 v[176:177], v[168:169], v[166:167] op_sel:[1,0]
	v_mov_b32_e32 v169, v167
	v_pk_fma_f32 v[172:173], v[174:175], v[174:175], v[172:173]
	v_pk_add_f32 v[144:145], v[144:145], v[152:153]
	v_mul_f32_e32 v148, v180, v180
	v_mul_f32_e32 v170, v178, v178
	v_pk_add_f32 v[152:153], v[176:177], v[168:169]
	v_pk_add_f32 v[144:145], v[172:173], v[144:145]
	v_pk_mul_f32 v[182:183], v[118:119], v[164:165] op_sel_hi:[1,0]
	v_pk_mul_f32 v[192:193], v[116:117], v[164:165] op_sel_hi:[1,0]
	v_pk_fma_f32 v[166:167], v[180:181], v[180:181], v[148:149] op_sel_hi:[1,1,0]
	v_pk_fma_f32 v[170:171], v[178:179], v[178:179], v[170:171] op_sel_hi:[1,1,0]
	v_pk_add_f32 v[152:153], v[152:153], v[152:153] op_sel_hi:[0,1]
	v_pk_add_f32 v[144:145], v[144:145], v[144:145] op_sel_hi:[0,1]
	v_mul_f32_e32 v166, v192, v192
	v_mul_f32_e32 v170, v193, v193
	v_mul_f32_e32 v152, v182, v182
	v_mul_f32_e32 v144, v183, v183
	v_pk_add_f32 v[166:167], v[166:167], v[170:171]
	v_pk_add_f32 v[144:145], v[152:153], v[144:145]
	v_xor_b32_e32 v141, 32, v157
	v_pk_add_f32 v[144:145], v[166:167], v[144:145]
	v_cmp_lt_i32_e32 vcc, v141, v194
	v_add_f32_e32 v144, v144, v145
	ds_bpermute_b32 v145, v163, v144
	v_cndmask_b32_e32 v141, v157, v141, vcc
	v_lshlrev_b32_e32 v141, 2, v141
	s_waitcnt lgkmcnt(0)
; __device__ __forceinline__ unsigned cvtpk(float lo, float hi) { f32x2_t v = {lo, hi}; bf16x2_t b = __builtin_convertvector(v, bf16x2_t); return __builtin_bit_cast(unsigned, b); }
; __device__ __forceinline__ float bflo(unsigned w) { return __uint_as_float(w << 16); }
; __device__ __forceinline__ float bfhi(unsigned w) { return __uint_as_float(w & 0xffff0000u); }
;     __device__ __forceinline__ void operator()(const f32x4 (&acc)[2][2][4][2], const Unit& u, int wr, int wc, int fr, int fq) const {
;     ...
;             for (int m = 0; m < 4; ++m) {
;                 const int row = row0 + ai * HALF + m * 16;
;                 const float rkv = 1.0f / sqrtf(ssq_sum(ssq_in + (size_t)row * 16) * (1.0f / 256.0f) + EPS);
;                 const u32x4 kw = *(const u32x4*)(T1 + (size_t)row * 1024 + 768 + 8 * fq);
;                 float s = (bflo(kw.x) * bflo(kw.x) + bfhi(kw.x) * bfhi(kw.x)) + (bflo(kw.y) * bflo(kw.y) + bfhi(kw.y) * bfhi(kw.y))
;                         + (bflo(kw.z) * bflo(kw.z) + bfhi(kw.z) * bfhi(kw.z)) + (bflo(kw.w) * bflo(kw.w) + bfhi(kw.w) * bfhi(kw.w));
; #pragma unroll
;                 for (int bj = 0; bj < 2; ++bj)
; #pragma unroll
;                     for (int n = 0; n < 2; ++n) { const f32x4 v = acc[ai][bj][m][n] * rkv; s += (v[0] * v[0] + v[1] * v[1]) + (v[2] * v[2] + v[3] * v[3]); }
;                 s += __shfl_xor(s, 16); s += __shfl_xor(s, 32);
;                 const float rh = 1.0f / sqrtf(s * (1.0f / 96.0f) + EPS), rs = rkv * rh;
;                 rhs[ai * 4 + m] = rh;
;                 bf16_t* op = O + (size_t)row * 1536 + head * 96;
; #pragma unroll
;                 for (int bj = 0; bj < 2; ++bj) {
;                     const f32x4 g0 = *(const f32x4*)(gk + bj * 32 + 8 * fq), g1 = *(const f32x4*)(gk + bj * 32 + 8 * fq + 4);
;                     const f32x4 v0 = acc[ai][bj][m][0] * rs * g0, v1 = acc[ai][bj][m][1] * rs * g1;
;                     u32x4 w; w.x = cvtpk(v0[0], v0[1]); w.y = cvtpk(v0[2], v0[3]); w.z = cvtpk(v1[0], v1[1]); w.w = cvtpk(v1[2], v1[3]);
;                     *(u32x4*)(op + bj * 32 + 8 * fq) = w;
	v_add_f32_e32 v144, v144, v145
	ds_bpermute_b32 v145, v141, v144
	s_waitcnt lgkmcnt(0)
	v_add_f32_e32 v144, v144, v145
	v_fmamk_f32 v144, v144, 0x3c2aaaab, v158
	v_mul_f32_e32 v145, 0x4f800000, v144
	v_cmp_gt_f32_e32 vcc, s66, v144
	s_nop 1
	v_cndmask_b32_e32 v144, v144, v145, vcc
	v_sqrt_f32_e32 v145, v144
	s_nop 0
	v_add_u32_e32 v148, -1, v145
	v_add_u32_e32 v152, 1, v145
	v_fma_f32 v153, -v148, v145, v144
	v_fma_f32 v165, -v152, v145, v144
	v_cmp_ge_f32_e64 s[8:9], 0, v153
	s_nop 1
	v_cndmask_b32_e64 v145, v145, v148, s[8:9]
	v_cmp_lt_f32_e64 s[8:9], 0, v165
	s_nop 1
	v_cndmask_b32_e64 v145, v145, v152, s[8:9]
	v_mul_f32_e32 v148, 0x37800000, v145
	v_cndmask_b32_e32 v145, v145, v148, vcc
	v_cmp_class_f32_e32 vcc, v144, v159
	s_nop 1
	v_cndmask_b32_e32 v144, v145, v144, vcc
	v_div_scale_f32 v145, s[8:9], v144, v144, 1.0
	v_rcp_f32_e32 v148, v145
	s_mul_i32 s8, s2, 0x60
	s_ashr_i32 s9, s8, 31
	v_fma_f32 v152, -v145, v148, 1.0
	v_fmac_f32_e32 v148, v152, v148
	v_div_scale_f32 v152, vcc, 1.0, v144, 1.0
	v_mul_f32_e32 v153, v152, v148
	v_fma_f32 v165, -v145, v153, v152
	v_fmac_f32_e32 v153, v165, v148
	v_fma_f32 v145, -v145, v153, v152
	v_div_fmas_f32 v145, v145, v148, v153
	v_div_fixup_f32 v148, v145, v144, 1.0
	v_mov_b64_e32 v[152:153], s[22:23]
	v_mul_f32_e32 v168, v164, v148
	v_mad_i64_i32 v[144:145], s[44:45], v140, s67, v[152:153]
	s_lshl_b64 s[44:45], s[8:9], 1
	v_pk_mul_f32 v[124:125], v[124:125], v[168:169] op_sel_hi:[1,0]
	v_pk_mul_f32 v[126:127], v[126:127], v[168:169] op_sel_hi:[1,0]
	v_pk_mul_f32 v[120:121], v[120:121], v[168:169] op_sel_hi:[1,0]
	v_pk_mul_f32 v[122:123], v[122:123], v[168:169] op_sel_hi:[1,0]
	v_lshl_add_u64 v[144:145], v[144:145], 0, s[44:45]
	v_pk_mul_f32 v[126:127], v[190:191], v[126:127]
	v_pk_mul_f32 v[124:125], v[188:189], v[124:125]
	v_pk_mul_f32 v[164:165], v[186:187], v[122:123]
	v_pk_mul_f32 v[122:123], v[184:185], v[120:121]
	v_lshl_add_u64 v[144:145], v[144:145], 0, v[146:147]
	v_cvt_pk_bf16_f32 v120, v124, v125
	v_cvt_pk_bf16_f32 v121, v126, v127
	v_cvt_pk_bf16_f32 v122, v122, v123
	v_cvt_pk_bf16_f32 v123, v164, v165
	global_store_dwordx4 v[144:145], v[120:123], off
	global_load_dwordx4 v[122:125], v[150:151], off offset:128
	s_nop 0
	global_load_dwordx4 v[164:167], v[150:151], off offset:144
	v_pk_mul_f32 v[112:113], v[112:113], v[168:169] op_sel_hi:[1,0]
	v_pk_mul_f32 v[114:115], v[114:115], v[168:169] op_sel_hi:[1,0]
	v_pk_mul_f32 v[116:117], v[116:117], v[168:169] op_sel_hi:[1,0]
	v_pk_mul_f32 v[118:119], v[118:119], v[168:169] op_sel_hi:[1,0]
	v_or_b32_e32 v120, 16, v140
	v_ashrrev_i32_e32 v121, 31, v120
	v_lshlrev_b64 v[126:127], 6, v[120:121]
	v_lshl_add_u64 v[126:127], s[14:15], 0, v[126:127]
	s_waitcnt vmcnt(1)
	v_pk_mul_f32 v[114:115], v[124:125], v[114:115]
	v_pk_mul_f32 v[112:113], v[122:123], v[112:113]
	s_waitcnt vmcnt(0)
	v_pk_mul_f32 v[118:119], v[166:167], v[118:119]
	v_pk_mul_f32 v[116:117], v[164:165], v[116:117]
	v_cvt_pk_bf16_f32 v112, v112, v113
	v_cvt_pk_bf16_f32 v113, v114, v115
	v_cvt_pk_bf16_f32 v114, v116, v117
	v_cvt_pk_bf16_f32 v115, v118, v119
	global_store_dwordx4 v[144:145], v[112:115], off offset:64
	s_nop 1
	ds_read_b32 v114, v253 offset:64
	v_mov_b32_e32 v115, 0
	v_mov_b32_e32 v116, 0
	v_mov_b32_e32 v117, 0
	v_mov_b32_e32 v164, 0
	v_mov_b32_e32 v165, 0
	v_mov_b32_e32 v166, 0
	v_mov_b32_e32 v167, 0
	v_mov_b32_e32 v122, 0
	v_mov_b32_e32 v123, 0
	v_mov_b32_e32 v124, 0
	v_mov_b32_e32 v125, 0
	v_mov_b32_e32 v168, 0
	v_mov_b32_e32 v169, 0
	v_mov_b32_e32 v170, 0
	v_mov_b32_e32 v171, 0
	s_waitcnt lgkmcnt(0)
	v_lshlrev_b64 v[112:113], 11, v[120:121]
	v_lshl_add_u64 v[112:113], s[10:11], 0, v[112:113]
	v_lshl_add_u64 v[112:113], v[112:113], 0, v[146:147]
	global_load_dwordx4 v[172:175], v[112:113], off offset:1536
	global_load_dwordx4 v[176:179], v[150:151], off offset:16
	global_load_dwordx4 v[180:183], v[150:151], off
	s_waitcnt vmcnt(6)
	v_mov_b32_e32 v118, v114
	s_waitcnt vmcnt(5)
	v_mov_b32_e32 v119, v122
	v_mov_b32_e32 v122, v115
	v_mov_b32_e32 v114, v116
	v_mov_b32_e32 v115, v124
	v_mov_b32_e32 v124, v117
	s_waitcnt vmcnt(4)
	v_mov_b32_e32 v116, v164
	s_waitcnt vmcnt(3)
	v_mov_b32_e32 v117, v168
	v_mov_b32_e32 v168, v165
	v_mov_b32_e32 v126, v166
	v_mov_b32_e32 v127, v170
	v_mov_b32_e32 v170, v167
	v_pk_add_f32 v[118:119], v[118:119], v[122:123]
	v_pk_add_f32 v[114:115], v[114:115], v[124:125]
	v_pk_add_f32 v[116:117], v[116:117], v[168:169]
	v_pk_add_f32 v[122:123], v[126:127], v[170:171]
	v_pk_add_f32 v[114:115], v[118:119], v[114:115]
	v_pk_add_f32 v[116:117], v[116:117], v[122:123]
	s_waitcnt vmcnt(2)
; __device__ __forceinline__ unsigned cvtpk(float lo, float hi) { f32x2_t v = {lo, hi}; bf16x2_t b = __builtin_convertvector(v, bf16x2_t); return __builtin_bit_cast(unsigned, b); }
; __device__ __forceinline__ float bflo(unsigned w) { return __uint_as_float(w << 16); }
; __device__ __forceinline__ float bfhi(unsigned w) { return __uint_as_float(w & 0xffff0000u); }
;     __device__ __forceinline__ void operator()(const f32x4 (&acc)[2][2][4][2], const Unit& u, int wr, int wc, int fr, int fq) const {
;     ...
;             for (int m = 0; m < 4; ++m) {
;                 const int row = row0 + ai * HALF + m * 16;
;                 const float rkv = 1.0f / sqrtf(ssq_sum(ssq_in + (size_t)row * 16) * (1.0f / 256.0f) + EPS);
;                 const u32x4 kw = *(const u32x4*)(T1 + (size_t)row * 1024 + 768 + 8 * fq);
;                 float s = (bflo(kw.x) * bflo(kw.x) + bfhi(kw.x) * bfhi(kw.x)) + (bflo(kw.y) * bflo(kw.y) + bfhi(kw.y) * bfhi(kw.y))
;                         + (bflo(kw.z) * bflo(kw.z) + bfhi(kw.z) * bfhi(kw.z)) + (bflo(kw.w) * bflo(kw.w) + bfhi(kw.w) * bfhi(kw.w));
; #pragma unroll
;                 for (int bj = 0; bj < 2; ++bj)
; #pragma unroll
;                     for (int n = 0; n < 2; ++n) { const f32x4 v = acc[ai][bj][m][n] * rkv; s += (v[0] * v[0] + v[1] * v[1]) + (v[2] * v[2] + v[3] * v[3]); }
;                 s += __shfl_xor(s, 16); s += __shfl_xor(s, 32);
;                 const float rh = 1.0f / sqrtf(s * (1.0f / 96.0f) + EPS), rs = rkv * rh;
;                 rhs[ai * 4 + m] = rh;
;                 bf16_t* op = O + (size_t)row * 1536 + head * 96;
; #pragma unroll
;                 for (int bj = 0; bj < 2; ++bj) {
;                     const f32x4 g0 = *(const f32x4*)(gk + bj * 32 + 8 * fq), g1 = *(const f32x4*)(gk + bj * 32 + 8 * fq + 4);
;                     const f32x4 v0 = acc[ai][bj][m][0] * rs * g0, v1 = acc[ai][bj][m][1] * rs * g1;
;                     u32x4 w; w.x = cvtpk(v0[0], v0[1]); w.y = cvtpk(v0[2], v0[3]); w.z = cvtpk(v1[0], v1[1]); w.w = cvtpk(v1[2], v1[3]);
;                     *(u32x4*)(op + bj * 32 + 8 * fq) = w;
	v_lshlrev_b32_e32 v165, 16, v173
	v_pk_add_f32 v[114:115], v[114:115], v[116:117]
	v_and_b32_e32 v167, 0xffff0000, v173
	v_add_f32_e32 v114, v114, v115
	v_fmamk_f32 v114, v114, 0x3b800000, v158
	v_mul_f32_e32 v115, 0x4f800000, v114
	v_cmp_gt_f32_e32 vcc, s66, v114
	v_and_b32_e32 v173, 0xffff0000, v174
	v_lshlrev_b32_e32 v164, 16, v172
	v_cndmask_b32_e32 v118, v114, v115, vcc
	v_sqrt_f32_e32 v119, v118
	v_and_b32_e32 v166, 0xffff0000, v172
	v_lshlrev_b32_e32 v172, 16, v174
	v_mul_f32_e32 v114, v173, v173
	v_pk_fma_f32 v[114:115], v[172:173], v[172:173], v[114:115] op_sel_hi:[1,1,0]
	v_add_u32_e32 v121, 1, v119
	v_add_u32_e32 v115, -1, v119
	v_fma_f32 v122, -v115, v119, v118
	v_fma_f32 v123, -v121, v119, v118
	v_cmp_ge_f32_e64 s[8:9], 0, v122
	v_pk_mul_f32 v[124:125], v[166:167], v[166:167]
	v_and_b32_e32 v184, 0xffff0000, v175
	v_cndmask_b32_e64 v115, v119, v115, s[8:9]
	v_cmp_lt_f32_e64 s[8:9], 0, v123
	v_pk_fma_f32 v[116:117], v[164:165], v[164:165], v[124:125]
	v_lshlrev_b32_e32 v174, 16, v175
	v_cndmask_b32_e64 v115, v115, v121, s[8:9]
	v_mul_f32_e32 v119, 0x37800000, v115
	v_cndmask_b32_e32 v115, v115, v119, vcc
	v_cmp_class_f32_e32 vcc, v118, v159
	v_pk_add_f32 v[116:117], v[116:117], v[116:117] op_sel:[0,1] op_sel_hi:[1,0]
	s_nop 0
	v_cndmask_b32_e32 v115, v115, v118, vcc
	v_div_scale_f32 v118, s[8:9], v115, v115, 1.0
	v_rcp_f32_e32 v119, v118
	v_div_scale_f32 v117, vcc, 1.0, v115, 1.0
	v_fma_f32 v121, -v118, v119, 1.0
	v_fmac_f32_e32 v119, v121, v119
	v_mul_f32_e32 v121, v117, v119
	v_fma_f32 v122, -v118, v121, v117
	v_fmac_f32_e32 v121, v122, v119
	v_fma_f32 v117, -v118, v121, v117
	v_div_fmas_f32 v117, v117, v119, v121
	v_div_fixup_f32 v118, v117, v115, 1.0
	v_pk_mul_f32 v[122:123], v[108:109], v[118:119] op_sel_hi:[1,0]
	v_pk_mul_f32 v[124:125], v[110:111], v[118:119] op_sel_hi:[1,0]
	v_pk_mul_f32 v[126:127], v[104:105], v[118:119] op_sel_hi:[1,0]
	v_pk_mul_f32 v[164:165], v[106:107], v[118:119] op_sel_hi:[1,0]
	v_pk_mul_f32 v[166:167], v[98:99], v[118:119] op_sel_hi:[1,0]
	v_pk_mul_f32 v[168:169], v[96:97], v[118:119] op_sel_hi:[1,0]
	v_mov_b32_e32 v185, v123
	v_mul_f32_e32 v115, v124, v124
	v_mul_f32_e32 v117, v125, v125
	v_mov_b32_e32 v175, v122
	v_pk_mul_f32 v[122:123], v[164:165], v[164:165]
	v_pk_mul_f32 v[124:125], v[126:127], v[126:127]
	v_mul_f32_e32 v126, v168, v168
	v_mul_f32_e32 v164, v166, v166
	v_pk_mul_f32 v[184:185], v[184:185], v[184:185]
	v_pk_mov_b32 v[186:187], v[124:125], v[122:123] op_sel:[1,0]
	v_mov_b32_e32 v125, v123
	v_pk_fma_f32 v[122:123], v[168:169], v[168:169], v[126:127] op_sel_hi:[1,1,0]
	v_pk_fma_f32 v[126:127], v[166:167], v[166:167], v[164:165] op_sel_hi:[1,1,0]
	v_pk_fma_f32 v[164:165], v[174:175], v[174:175], v[184:185]
	v_pk_add_f32 v[114:115], v[114:115], v[116:117]
	v_pk_add_f32 v[116:117], v[186:187], v[124:125]
	v_pk_add_f32 v[114:115], v[164:165], v[114:115]
	v_pk_mul_f32 v[170:171], v[102:103], v[118:119] op_sel_hi:[1,0]
	v_pk_mul_f32 v[172:173], v[100:101], v[118:119] op_sel_hi:[1,0]
	v_pk_add_f32 v[116:117], v[116:117], v[116:117] op_sel_hi:[0,1]
	v_pk_add_f32 v[114:115], v[114:115], v[114:115] op_sel_hi:[0,1]
	v_mul_f32_e32 v122, v172, v172
	v_mul_f32_e32 v126, v173, v173
	v_mul_f32_e32 v116, v170, v170
	v_mul_f32_e32 v114, v171, v171
	v_pk_add_f32 v[122:123], v[122:123], v[126:127]
	v_pk_add_f32 v[114:115], v[116:117], v[114:115]
	s_nop 0
	v_pk_add_f32 v[114:115], v[122:123], v[114:115]
	s_nop 0
	v_add_f32_e32 v114, v114, v115
	ds_bpermute_b32 v115, v163, v114
	s_waitcnt lgkmcnt(0)
	v_add_f32_e32 v114, v114, v115
	ds_bpermute_b32 v115, v141, v114
	s_waitcnt lgkmcnt(0)
	v_add_f32_e32 v114, v114, v115
	v_fmamk_f32 v114, v114, 0x3c2aaaab, v158
	v_mul_f32_e32 v115, 0x4f800000, v114
	v_cmp_gt_f32_e32 vcc, s66, v114
	s_nop 1
	v_cndmask_b32_e32 v116, v114, v115, vcc
	v_sqrt_f32_e32 v117, v116
	v_mad_i64_i32 v[114:115], s[8:9], v120, s67, v[152:153]
	v_lshl_add_u64 v[114:115], v[114:115], 0, s[44:45]
	v_add_u32_e32 v119, -1, v117
	v_add_u32_e32 v120, 1, v117
	v_fma_f32 v121, -v119, v117, v116
	v_fma_f32 v122, -v120, v117, v116
	v_cmp_ge_f32_e64 s[8:9], 0, v121
	v_lshl_add_u64 v[114:115], v[114:115], 0, v[146:147]
	s_nop 0
	v_cndmask_b32_e64 v117, v117, v119, s[8:9]
	v_cmp_lt_f32_e64 s[8:9], 0, v122
	s_nop 1
	v_cndmask_b32_e64 v117, v117, v120, s[8:9]
	v_mul_f32_e32 v119, 0x37800000, v117
	v_cndmask_b32_e32 v117, v117, v119, vcc
	v_cmp_class_f32_e32 vcc, v116, v159
	s_nop 1
	v_cndmask_b32_e32 v116, v117, v116, vcc
	v_div_scale_f32 v117, s[8:9], v116, v116, 1.0
	v_rcp_f32_e32 v119, v117
	v_div_scale_f32 v120, vcc, 1.0, v116, 1.0
	v_fma_f32 v121, -v117, v119, 1.0
	v_fmac_f32_e32 v119, v121, v119
	v_mul_f32_e32 v121, v120, v119
	v_fma_f32 v122, -v117, v121, v120
	v_fmac_f32_e32 v121, v122, v119
	v_fma_f32 v117, -v117, v121, v120
	v_div_fmas_f32 v117, v117, v119, v121
	v_div_fixup_f32 v116, v117, v116, 1.0
	v_mul_f32_e32 v122, v118, v116
	v_pk_mul_f32 v[108:109], v[108:109], v[122:123] op_sel_hi:[1,0]
	v_pk_mul_f32 v[110:111], v[110:111], v[122:123] op_sel_hi:[1,0]
	v_pk_mul_f32 v[104:105], v[104:105], v[122:123] op_sel_hi:[1,0]
	v_pk_mul_f32 v[106:107], v[106:107], v[122:123] op_sel_hi:[1,0]
	s_waitcnt vmcnt(0)
	v_pk_mul_f32 v[110:111], v[182:183], v[110:111]
	v_pk_mul_f32 v[108:109], v[180:181], v[108:109]
	v_pk_mul_f32 v[118:119], v[178:179], v[106:107]
	v_pk_mul_f32 v[106:107], v[176:177], v[104:105]
	v_cvt_pk_bf16_f32 v104, v108, v109
	v_cvt_pk_bf16_f32 v105, v110, v111
	v_cvt_pk_bf16_f32 v106, v106, v107
	v_cvt_pk_bf16_f32 v107, v118, v119
	global_store_dwordx4 v[114:115], v[104:107], off
	global_load_dwordx4 v[106:109], v[150:151], off offset:128
	s_nop 0
	global_load_dwordx4 v[118:121], v[150:151], off offset:144
	v_pk_mul_f32 v[96:97], v[96:97], v[122:123] op_sel_hi:[1,0]
	v_pk_mul_f32 v[98:99], v[98:99], v[122:123] op_sel_hi:[1,0]
	v_pk_mul_f32 v[100:101], v[100:101], v[122:123] op_sel_hi:[1,0]
	v_pk_mul_f32 v[102:103], v[102:103], v[122:123] op_sel_hi:[1,0]
	v_or_b32_e32 v104, 32, v140
	v_ashrrev_i32_e32 v105, 31, v104
	v_lshlrev_b64 v[110:111], 6, v[104:105]
	v_lshl_add_u64 v[110:111], s[14:15], 0, v[110:111]
	s_waitcnt vmcnt(1)
; __device__ __forceinline__ unsigned cvtpk(float lo, float hi) { f32x2_t v = {lo, hi}; bf16x2_t b = __builtin_convertvector(v, bf16x2_t); return __builtin_bit_cast(unsigned, b); }
; __device__ __forceinline__ float bflo(unsigned w) { return __uint_as_float(w << 16); }
; __device__ __forceinline__ float bfhi(unsigned w) { return __uint_as_float(w & 0xffff0000u); }
;     __device__ __forceinline__ void operator()(const f32x4 (&acc)[2][2][4][2], const Unit& u, int wr, int wc, int fr, int fq) const {
;     ...
;             for (int m = 0; m < 4; ++m) {
;                 const int row = row0 + ai * HALF + m * 16;
;                 const float rkv = 1.0f / sqrtf(ssq_sum(ssq_in + (size_t)row * 16) * (1.0f / 256.0f) + EPS);
;                 const u32x4 kw = *(const u32x4*)(T1 + (size_t)row * 1024 + 768 + 8 * fq);
;                 float s = (bflo(kw.x) * bflo(kw.x) + bfhi(kw.x) * bfhi(kw.x)) + (bflo(kw.y) * bflo(kw.y) + bfhi(kw.y) * bfhi(kw.y))
;                         + (bflo(kw.z) * bflo(kw.z) + bfhi(kw.z) * bfhi(kw.z)) + (bflo(kw.w) * bflo(kw.w) + bfhi(kw.w) * bfhi(kw.w));
; #pragma unroll
;                 for (int bj = 0; bj < 2; ++bj)
; #pragma unroll
;                     for (int n = 0; n < 2; ++n) { const f32x4 v = acc[ai][bj][m][n] * rkv; s += (v[0] * v[0] + v[1] * v[1]) + (v[2] * v[2] + v[3] * v[3]); }
;                 s += __shfl_xor(s, 16); s += __shfl_xor(s, 32);
;                 const float rh = 1.0f / sqrtf(s * (1.0f / 96.0f) + EPS), rs = rkv * rh;
;                 rhs[ai * 4 + m] = rh;
;                 bf16_t* op = O + (size_t)row * 1536 + head * 96;
; #pragma unroll
;                 for (int bj = 0; bj < 2; ++bj) {
;                     const f32x4 g0 = *(const f32x4*)(gk + bj * 32 + 8 * fq), g1 = *(const f32x4*)(gk + bj * 32 + 8 * fq + 4);
;                     const f32x4 v0 = acc[ai][bj][m][0] * rs * g0, v1 = acc[ai][bj][m][1] * rs * g1;
;                     u32x4 w; w.x = cvtpk(v0[0], v0[1]); w.y = cvtpk(v0[2], v0[3]); w.z = cvtpk(v1[0], v1[1]); w.w = cvtpk(v1[2], v1[3]);
;                     *(u32x4*)(op + bj * 32 + 8 * fq) = w;
	v_pk_mul_f32 v[98:99], v[108:109], v[98:99]
	v_pk_mul_f32 v[96:97], v[106:107], v[96:97]
	s_waitcnt vmcnt(0)
	v_pk_mul_f32 v[102:103], v[120:121], v[102:103]
	v_pk_mul_f32 v[100:101], v[118:119], v[100:101]
	v_cvt_pk_bf16_f32 v96, v96, v97
	v_cvt_pk_bf16_f32 v97, v98, v99
	v_cvt_pk_bf16_f32 v98, v100, v101
	v_cvt_pk_bf16_f32 v99, v102, v103
	global_store_dwordx4 v[114:115], v[96:99], off offset:64
	s_nop 1
	ds_read_b32 v98, v253 offset:128
	v_mov_b32_e32 v99, 0
	v_mov_b32_e32 v100, 0
	v_mov_b32_e32 v101, 0
	v_mov_b32_e32 v118, 0
	v_mov_b32_e32 v119, 0
	v_mov_b32_e32 v120, 0
	v_mov_b32_e32 v121, 0
	v_mov_b32_e32 v106, 0
	v_mov_b32_e32 v107, 0
	v_mov_b32_e32 v108, 0
	v_mov_b32_e32 v109, 0
	v_mov_b32_e32 v122, 0
	v_mov_b32_e32 v123, 0
	v_mov_b32_e32 v124, 0
	v_mov_b32_e32 v125, 0
	s_waitcnt lgkmcnt(0)
	v_lshlrev_b64 v[96:97], 11, v[104:105]
	v_lshl_add_u64 v[96:97], s[10:11], 0, v[96:97]
	v_lshl_add_u64 v[96:97], v[96:97], 0, v[146:147]
	global_load_dwordx4 v[164:167], v[96:97], off offset:1536
	global_load_dwordx4 v[168:171], v[150:151], off offset:16
	global_load_dwordx4 v[172:175], v[150:151], off
	s_waitcnt vmcnt(6)
	v_mov_b32_e32 v102, v98
	s_waitcnt vmcnt(5)
	v_mov_b32_e32 v103, v106
	v_mov_b32_e32 v106, v99
	v_mov_b32_e32 v98, v100
	v_mov_b32_e32 v99, v108
	v_mov_b32_e32 v108, v101
	s_waitcnt vmcnt(4)
	v_mov_b32_e32 v100, v118
	s_waitcnt vmcnt(3)
	v_mov_b32_e32 v101, v122
	v_mov_b32_e32 v122, v119
	v_mov_b32_e32 v110, v120
	v_mov_b32_e32 v111, v124
	v_mov_b32_e32 v124, v121
	v_pk_add_f32 v[102:103], v[102:103], v[106:107]
	v_pk_add_f32 v[98:99], v[98:99], v[108:109]
	v_pk_add_f32 v[100:101], v[100:101], v[122:123]
	v_pk_add_f32 v[106:107], v[110:111], v[124:125]
	v_pk_add_f32 v[98:99], v[102:103], v[98:99]
	v_pk_add_f32 v[100:101], v[100:101], v[106:107]
	s_waitcnt vmcnt(2)
	v_and_b32_e32 v127, 0xffff0000, v166
	v_pk_add_f32 v[98:99], v[98:99], v[100:101]
	v_lshlrev_b32_e32 v126, 16, v166
	v_add_f32_e32 v98, v98, v99
	v_fmamk_f32 v98, v98, 0x3b800000, v158
	v_mul_f32_e32 v99, 0x4f800000, v98
	v_cmp_gt_f32_e32 vcc, s66, v98
	v_and_b32_e32 v121, 0xffff0000, v165
	v_and_b32_e32 v120, 0xffff0000, v164
	v_cndmask_b32_e32 v102, v98, v99, vcc
	v_sqrt_f32_e32 v103, v102
	v_mul_f32_e32 v98, v127, v127
	v_pk_fma_f32 v[98:99], v[126:127], v[126:127], v[98:99] op_sel_hi:[1,1,0]
	v_lshlrev_b32_e32 v119, 16, v165
	v_add_u32_e32 v99, -1, v103
	v_add_u32_e32 v105, 1, v103
	v_fma_f32 v106, -v99, v103, v102
	v_fma_f32 v107, -v105, v103, v102
	v_cmp_ge_f32_e64 s[8:9], 0, v106
	v_lshlrev_b32_e32 v118, 16, v164
	v_pk_mul_f32 v[108:109], v[120:121], v[120:121]
	v_cndmask_b32_e64 v99, v103, v99, s[8:9]
	v_cmp_lt_f32_e64 s[8:9], 0, v107
	v_pk_fma_f32 v[100:101], v[118:119], v[118:119], v[108:109]
	v_lshlrev_b32_e32 v164, 16, v167
	v_cndmask_b32_e64 v99, v99, v105, s[8:9]
	v_mul_f32_e32 v103, 0x37800000, v99
	v_cndmask_b32_e32 v99, v99, v103, vcc
	v_cmp_class_f32_e32 vcc, v102, v159
	v_pk_add_f32 v[100:101], v[100:101], v[100:101] op_sel:[0,1] op_sel_hi:[1,0]
	v_and_b32_e32 v166, 0xffff0000, v167
	v_cndmask_b32_e32 v99, v99, v102, vcc
	v_div_scale_f32 v102, s[8:9], v99, v99, 1.0
	v_rcp_f32_e32 v103, v102
	v_div_scale_f32 v101, vcc, 1.0, v99, 1.0
	v_fma_f32 v105, -v102, v103, 1.0
	v_fmac_f32_e32 v103, v105, v103
	v_mul_f32_e32 v105, v101, v103
	v_fma_f32 v106, -v102, v105, v101
	v_fmac_f32_e32 v105, v106, v103
	v_fma_f32 v101, -v102, v105, v101
	v_div_fmas_f32 v101, v101, v103, v105
	v_div_fixup_f32 v102, v101, v99, 1.0
	v_pk_mul_f32 v[106:107], v[92:93], v[102:103] op_sel_hi:[1,0]
	v_pk_mul_f32 v[108:109], v[94:95], v[102:103] op_sel_hi:[1,0]
	v_pk_mul_f32 v[110:111], v[88:89], v[102:103] op_sel_hi:[1,0]
	v_pk_mul_f32 v[118:119], v[90:91], v[102:103] op_sel_hi:[1,0]
	v_pk_mul_f32 v[120:121], v[82:83], v[102:103] op_sel_hi:[1,0]
	v_pk_mul_f32 v[122:123], v[80:81], v[102:103] op_sel_hi:[1,0]
	v_mov_b32_e32 v167, v107
	v_mul_f32_e32 v99, v108, v108
	v_mul_f32_e32 v101, v109, v109
	v_mov_b32_e32 v165, v106
	v_pk_mul_f32 v[106:107], v[118:119], v[118:119]
	v_pk_mul_f32 v[108:109], v[110:111], v[110:111]
	v_mul_f32_e32 v110, v122, v122
	v_mul_f32_e32 v118, v120, v120
	v_pk_mul_f32 v[166:167], v[166:167], v[166:167]
	v_pk_mov_b32 v[176:177], v[108:109], v[106:107] op_sel:[1,0]
	v_mov_b32_e32 v109, v107
	v_pk_fma_f32 v[106:107], v[122:123], v[122:123], v[110:111] op_sel_hi:[1,1,0]
	v_pk_fma_f32 v[110:111], v[120:121], v[120:121], v[118:119] op_sel_hi:[1,1,0]
	v_pk_fma_f32 v[118:119], v[164:165], v[164:165], v[166:167]
	v_pk_add_f32 v[98:99], v[98:99], v[100:101]
	v_pk_add_f32 v[100:101], v[176:177], v[108:109]
	v_pk_add_f32 v[98:99], v[118:119], v[98:99]
	v_pk_mul_f32 v[124:125], v[86:87], v[102:103] op_sel_hi:[1,0]
	v_pk_mul_f32 v[126:127], v[84:85], v[102:103] op_sel_hi:[1,0]
	v_pk_add_f32 v[100:101], v[100:101], v[100:101] op_sel_hi:[0,1]
	v_pk_add_f32 v[98:99], v[98:99], v[98:99] op_sel_hi:[0,1]
	v_mul_f32_e32 v106, v126, v126
	v_mul_f32_e32 v110, v127, v127
	v_mul_f32_e32 v100, v124, v124
	v_mul_f32_e32 v98, v125, v125
	v_pk_add_f32 v[106:107], v[106:107], v[110:111]
	v_pk_add_f32 v[98:99], v[100:101], v[98:99]
	s_nop 0
	v_pk_add_f32 v[98:99], v[106:107], v[98:99]
	s_nop 0
	v_add_f32_e32 v98, v98, v99
	ds_bpermute_b32 v99, v163, v98
	s_waitcnt lgkmcnt(0)
	v_add_f32_e32 v98, v98, v99
	ds_bpermute_b32 v99, v141, v98
	s_waitcnt lgkmcnt(0)
; __device__ __forceinline__ unsigned cvtpk(float lo, float hi) { f32x2_t v = {lo, hi}; bf16x2_t b = __builtin_convertvector(v, bf16x2_t); return __builtin_bit_cast(unsigned, b); }
; __device__ __forceinline__ float bflo(unsigned w) { return __uint_as_float(w << 16); }
; __device__ __forceinline__ float bfhi(unsigned w) { return __uint_as_float(w & 0xffff0000u); }
;     __device__ __forceinline__ void operator()(const f32x4 (&acc)[2][2][4][2], const Unit& u, int wr, int wc, int fr, int fq) const {
;     ...
;             for (int m = 0; m < 4; ++m) {
;                 const int row = row0 + ai * HALF + m * 16;
;                 const float rkv = 1.0f / sqrtf(ssq_sum(ssq_in + (size_t)row * 16) * (1.0f / 256.0f) + EPS);
;                 const u32x4 kw = *(const u32x4*)(T1 + (size_t)row * 1024 + 768 + 8 * fq);
;                 float s = (bflo(kw.x) * bflo(kw.x) + bfhi(kw.x) * bfhi(kw.x)) + (bflo(kw.y) * bflo(kw.y) + bfhi(kw.y) * bfhi(kw.y))
;                         + (bflo(kw.z) * bflo(kw.z) + bfhi(kw.z) * bfhi(kw.z)) + (bflo(kw.w) * bflo(kw.w) + bfhi(kw.w) * bfhi(kw.w));
; #pragma unroll
;                 for (int bj = 0; bj < 2; ++bj)
; #pragma unroll
;                     for (int n = 0; n < 2; ++n) { const f32x4 v = acc[ai][bj][m][n] * rkv; s += (v[0] * v[0] + v[1] * v[1]) + (v[2] * v[2] + v[3] * v[3]); }
;                 s += __shfl_xor(s, 16); s += __shfl_xor(s, 32);
;                 const float rh = 1.0f / sqrtf(s * (1.0f / 96.0f) + EPS), rs = rkv * rh;
;                 rhs[ai * 4 + m] = rh;
;                 bf16_t* op = O + (size_t)row * 1536 + head * 96;
; #pragma unroll
;                 for (int bj = 0; bj < 2; ++bj) {
;                     const f32x4 g0 = *(const f32x4*)(gk + bj * 32 + 8 * fq), g1 = *(const f32x4*)(gk + bj * 32 + 8 * fq + 4);
;                     const f32x4 v0 = acc[ai][bj][m][0] * rs * g0, v1 = acc[ai][bj][m][1] * rs * g1;
;                     u32x4 w; w.x = cvtpk(v0[0], v0[1]); w.y = cvtpk(v0[2], v0[3]); w.z = cvtpk(v1[0], v1[1]); w.w = cvtpk(v1[2], v1[3]);
;                     *(u32x4*)(op + bj * 32 + 8 * fq) = w;
	v_add_f32_e32 v98, v98, v99
	v_fmamk_f32 v98, v98, 0x3c2aaaab, v158
	v_mul_f32_e32 v99, 0x4f800000, v98
	v_cmp_gt_f32_e32 vcc, s66, v98
	s_nop 1
	v_cndmask_b32_e32 v100, v98, v99, vcc
	v_sqrt_f32_e32 v101, v100
	v_mad_i64_i32 v[98:99], s[8:9], v104, s67, v[152:153]
	v_lshl_add_u64 v[98:99], v[98:99], 0, s[44:45]
	v_add_u32_e32 v103, -1, v101
	v_add_u32_e32 v104, 1, v101
	v_fma_f32 v105, -v103, v101, v100
	v_fma_f32 v106, -v104, v101, v100
	v_cmp_ge_f32_e64 s[8:9], 0, v105
	v_lshl_add_u64 v[98:99], v[98:99], 0, v[146:147]
	s_nop 0
	v_cndmask_b32_e64 v101, v101, v103, s[8:9]
	v_cmp_lt_f32_e64 s[8:9], 0, v106
	s_nop 1
	v_cndmask_b32_e64 v101, v101, v104, s[8:9]
	v_mul_f32_e32 v103, 0x37800000, v101
	v_cndmask_b32_e32 v101, v101, v103, vcc
	v_cmp_class_f32_e32 vcc, v100, v159
	s_nop 1
	v_cndmask_b32_e32 v100, v101, v100, vcc
	v_div_scale_f32 v101, s[8:9], v100, v100, 1.0
	v_rcp_f32_e32 v103, v101
	v_div_scale_f32 v104, vcc, 1.0, v100, 1.0
	v_fma_f32 v105, -v101, v103, 1.0
	v_fmac_f32_e32 v103, v105, v103
	v_mul_f32_e32 v105, v104, v103
	v_fma_f32 v106, -v101, v105, v104
	v_fmac_f32_e32 v105, v106, v103
	v_fma_f32 v101, -v101, v105, v104
	v_div_fmas_f32 v101, v101, v103, v105
	v_div_fixup_f32 v100, v101, v100, 1.0
	v_mul_f32_e32 v106, v102, v100
	v_pk_mul_f32 v[92:93], v[92:93], v[106:107] op_sel_hi:[1,0]
	v_pk_mul_f32 v[94:95], v[94:95], v[106:107] op_sel_hi:[1,0]
	v_pk_mul_f32 v[88:89], v[88:89], v[106:107] op_sel_hi:[1,0]
	v_pk_mul_f32 v[90:91], v[90:91], v[106:107] op_sel_hi:[1,0]
	s_waitcnt vmcnt(0)
	v_pk_mul_f32 v[94:95], v[174:175], v[94:95]
	v_pk_mul_f32 v[92:93], v[172:173], v[92:93]
	v_pk_mul_f32 v[102:103], v[170:171], v[90:91]
	v_pk_mul_f32 v[90:91], v[168:169], v[88:89]
	v_cvt_pk_bf16_f32 v88, v92, v93
	v_cvt_pk_bf16_f32 v89, v94, v95
	v_cvt_pk_bf16_f32 v90, v90, v91
	v_cvt_pk_bf16_f32 v91, v102, v103
	global_store_dwordx4 v[98:99], v[88:91], off
	global_load_dwordx4 v[90:93], v[150:151], off offset:128
	s_nop 0
	global_load_dwordx4 v[102:105], v[150:151], off offset:144
	v_pk_mul_f32 v[80:81], v[80:81], v[106:107] op_sel_hi:[1,0]
	v_pk_mul_f32 v[82:83], v[82:83], v[106:107] op_sel_hi:[1,0]
	v_pk_mul_f32 v[84:85], v[84:85], v[106:107] op_sel_hi:[1,0]
	v_pk_mul_f32 v[86:87], v[86:87], v[106:107] op_sel_hi:[1,0]
	v_or_b32_e32 v88, 48, v140
	v_ashrrev_i32_e32 v89, 31, v88
	v_lshlrev_b64 v[94:95], 6, v[88:89]
	v_lshl_add_u64 v[94:95], s[14:15], 0, v[94:95]
	s_waitcnt vmcnt(1)
	v_pk_mul_f32 v[82:83], v[92:93], v[82:83]
	v_pk_mul_f32 v[80:81], v[90:91], v[80:81]
	s_waitcnt vmcnt(0)
	v_pk_mul_f32 v[86:87], v[104:105], v[86:87]
	v_pk_mul_f32 v[84:85], v[102:103], v[84:85]
	v_cvt_pk_bf16_f32 v80, v80, v81
	v_cvt_pk_bf16_f32 v81, v82, v83
	v_cvt_pk_bf16_f32 v82, v84, v85
	v_cvt_pk_bf16_f32 v83, v86, v87
	global_store_dwordx4 v[98:99], v[80:83], off offset:64
	s_nop 1
	ds_read_b32 v82, v253 offset:192
	v_mov_b32_e32 v83, 0
	v_mov_b32_e32 v84, 0
	v_mov_b32_e32 v85, 0
	v_mov_b32_e32 v102, 0
	v_mov_b32_e32 v103, 0
	v_mov_b32_e32 v104, 0
	v_mov_b32_e32 v105, 0
	v_mov_b32_e32 v90, 0
	v_mov_b32_e32 v91, 0
	v_mov_b32_e32 v92, 0
	v_mov_b32_e32 v93, 0
	v_mov_b32_e32 v106, 0
	v_mov_b32_e32 v107, 0
	v_mov_b32_e32 v108, 0
	v_mov_b32_e32 v109, 0
	s_waitcnt lgkmcnt(0)
	v_lshlrev_b64 v[80:81], 11, v[88:89]
	v_lshl_add_u64 v[80:81], s[10:11], 0, v[80:81]
	v_lshl_add_u64 v[80:81], v[80:81], 0, v[146:147]
	global_load_dwordx4 v[118:121], v[80:81], off offset:1536
	global_load_dwordx4 v[122:125], v[150:151], off offset:16
	global_load_dwordx4 v[164:167], v[150:151], off
	s_waitcnt vmcnt(6)
	v_mov_b32_e32 v86, v82
	s_waitcnt vmcnt(5)
	v_mov_b32_e32 v87, v90
	v_mov_b32_e32 v90, v83
	v_mov_b32_e32 v82, v84
	v_mov_b32_e32 v83, v92
	v_mov_b32_e32 v92, v85
	s_waitcnt vmcnt(4)
	v_mov_b32_e32 v84, v102
	s_waitcnt vmcnt(3)
	v_mov_b32_e32 v85, v106
	v_mov_b32_e32 v106, v103
	v_mov_b32_e32 v94, v104
	v_mov_b32_e32 v95, v108
	v_mov_b32_e32 v108, v105
	v_pk_add_f32 v[86:87], v[86:87], v[90:91]
	v_pk_add_f32 v[82:83], v[82:83], v[92:93]
	v_pk_add_f32 v[84:85], v[84:85], v[106:107]
	v_pk_add_f32 v[90:91], v[94:95], v[108:109]
	v_pk_add_f32 v[82:83], v[86:87], v[82:83]
	v_pk_add_f32 v[84:85], v[84:85], v[90:91]
	s_waitcnt vmcnt(2)
	v_and_b32_e32 v111, 0xffff0000, v120
	v_pk_add_f32 v[82:83], v[82:83], v[84:85]
	v_lshlrev_b32_e32 v110, 16, v120
	v_add_f32_e32 v82, v82, v83
	v_fmamk_f32 v82, v82, 0x3b800000, v158
	v_mul_f32_e32 v83, 0x4f800000, v82
	v_cmp_gt_f32_e32 vcc, s66, v82
	v_and_b32_e32 v105, 0xffff0000, v119
	v_and_b32_e32 v104, 0xffff0000, v118
	v_cndmask_b32_e32 v86, v82, v83, vcc
	v_sqrt_f32_e32 v87, v86
	v_mul_f32_e32 v82, v111, v111
	v_pk_fma_f32 v[82:83], v[110:111], v[110:111], v[82:83] op_sel_hi:[1,1,0]
	v_lshlrev_b32_e32 v103, 16, v119
	v_add_u32_e32 v83, -1, v87
	v_add_u32_e32 v89, 1, v87
	v_fma_f32 v90, -v83, v87, v86
	v_fma_f32 v91, -v89, v87, v86
	v_cmp_ge_f32_e64 s[8:9], 0, v90
	v_lshlrev_b32_e32 v102, 16, v118
	v_pk_mul_f32 v[92:93], v[104:105], v[104:105]
	v_cndmask_b32_e64 v83, v87, v83, s[8:9]
	v_cmp_lt_f32_e64 s[8:9], 0, v91
	v_pk_fma_f32 v[84:85], v[102:103], v[102:103], v[92:93]
	v_lshlrev_b32_e32 v118, 16, v121
	v_cndmask_b32_e64 v83, v83, v89, s[8:9]
	v_mul_f32_e32 v87, 0x37800000, v83
	v_cndmask_b32_e32 v83, v83, v87, vcc
	v_cmp_class_f32_e32 vcc, v86, v159
	v_pk_add_f32 v[84:85], v[84:85], v[84:85] op_sel:[0,1] op_sel_hi:[1,0]
	v_and_b32_e32 v120, 0xffff0000, v121
	v_cndmask_b32_e32 v83, v83, v86, vcc
	v_div_scale_f32 v86, s[8:9], v83, v83, 1.0
	v_rcp_f32_e32 v87, v86
	v_div_scale_f32 v85, vcc, 1.0, v83, 1.0
	v_fma_f32 v89, -v86, v87, 1.0
	v_fmac_f32_e32 v87, v89, v87
	v_mul_f32_e32 v89, v85, v87
	v_fma_f32 v90, -v86, v89, v85
; __device__ __forceinline__ unsigned cvtpk(float lo, float hi) { f32x2_t v = {lo, hi}; bf16x2_t b = __builtin_convertvector(v, bf16x2_t); return __builtin_bit_cast(unsigned, b); }
; __device__ __forceinline__ float bflo(unsigned w) { return __uint_as_float(w << 16); }
; __device__ __forceinline__ float bfhi(unsigned w) { return __uint_as_float(w & 0xffff0000u); }
;     __device__ __forceinline__ void operator()(const f32x4 (&acc)[2][2][4][2], const Unit& u, int wr, int wc, int fr, int fq) const {
;     ...
;             for (int m = 0; m < 4; ++m) {
;                 const int row = row0 + ai * HALF + m * 16;
;                 const float rkv = 1.0f / sqrtf(ssq_sum(ssq_in + (size_t)row * 16) * (1.0f / 256.0f) + EPS);
;                 const u32x4 kw = *(const u32x4*)(T1 + (size_t)row * 1024 + 768 + 8 * fq);
;                 float s = (bflo(kw.x) * bflo(kw.x) + bfhi(kw.x) * bfhi(kw.x)) + (bflo(kw.y) * bflo(kw.y) + bfhi(kw.y) * bfhi(kw.y))
;                         + (bflo(kw.z) * bflo(kw.z) + bfhi(kw.z) * bfhi(kw.z)) + (bflo(kw.w) * bflo(kw.w) + bfhi(kw.w) * bfhi(kw.w));
; #pragma unroll
;                 for (int bj = 0; bj < 2; ++bj)
; #pragma unroll
;                     for (int n = 0; n < 2; ++n) { const f32x4 v = acc[ai][bj][m][n] * rkv; s += (v[0] * v[0] + v[1] * v[1]) + (v[2] * v[2] + v[3] * v[3]); }
;                 s += __shfl_xor(s, 16); s += __shfl_xor(s, 32);
;                 const float rh = 1.0f / sqrtf(s * (1.0f / 96.0f) + EPS), rs = rkv * rh;
;                 rhs[ai * 4 + m] = rh;
;                 bf16_t* op = O + (size_t)row * 1536 + head * 96;
; #pragma unroll
;                 for (int bj = 0; bj < 2; ++bj) {
;                     const f32x4 g0 = *(const f32x4*)(gk + bj * 32 + 8 * fq), g1 = *(const f32x4*)(gk + bj * 32 + 8 * fq + 4);
;                     const f32x4 v0 = acc[ai][bj][m][0] * rs * g0, v1 = acc[ai][bj][m][1] * rs * g1;
;                     u32x4 w; w.x = cvtpk(v0[0], v0[1]); w.y = cvtpk(v0[2], v0[3]); w.z = cvtpk(v1[0], v1[1]); w.w = cvtpk(v1[2], v1[3]);
;                     *(u32x4*)(op + bj * 32 + 8 * fq) = w;
	v_fmac_f32_e32 v89, v90, v87
	v_fma_f32 v85, -v86, v89, v85
	v_div_fmas_f32 v85, v85, v87, v89
	v_div_fixup_f32 v86, v85, v83, 1.0
	v_pk_mul_f32 v[90:91], v[76:77], v[86:87] op_sel_hi:[1,0]
	v_pk_mul_f32 v[92:93], v[78:79], v[86:87] op_sel_hi:[1,0]
	v_pk_mul_f32 v[94:95], v[72:73], v[86:87] op_sel_hi:[1,0]
	v_pk_mul_f32 v[102:103], v[74:75], v[86:87] op_sel_hi:[1,0]
	v_pk_mul_f32 v[104:105], v[66:67], v[86:87] op_sel_hi:[1,0]
	v_pk_mul_f32 v[106:107], v[64:65], v[86:87] op_sel_hi:[1,0]
	v_mov_b32_e32 v121, v91
	v_mul_f32_e32 v83, v92, v92
	v_mul_f32_e32 v85, v93, v93
	v_mov_b32_e32 v119, v90
	v_pk_mul_f32 v[90:91], v[102:103], v[102:103]
	v_pk_mul_f32 v[92:93], v[94:95], v[94:95]
	v_mul_f32_e32 v94, v106, v106
	v_mul_f32_e32 v102, v104, v104
	v_pk_mul_f32 v[120:121], v[120:121], v[120:121]
	v_pk_mov_b32 v[126:127], v[92:93], v[90:91] op_sel:[1,0]
	v_mov_b32_e32 v93, v91
	v_pk_fma_f32 v[90:91], v[106:107], v[106:107], v[94:95] op_sel_hi:[1,1,0]
	v_pk_fma_f32 v[94:95], v[104:105], v[104:105], v[102:103] op_sel_hi:[1,1,0]
	v_pk_fma_f32 v[102:103], v[118:119], v[118:119], v[120:121]
	v_pk_add_f32 v[82:83], v[82:83], v[84:85]
	v_pk_add_f32 v[84:85], v[126:127], v[92:93]
	v_pk_add_f32 v[82:83], v[102:103], v[82:83]
	v_pk_mul_f32 v[108:109], v[70:71], v[86:87] op_sel_hi:[1,0]
	v_pk_mul_f32 v[110:111], v[68:69], v[86:87] op_sel_hi:[1,0]
	v_pk_add_f32 v[84:85], v[84:85], v[84:85] op_sel_hi:[0,1]
	v_pk_add_f32 v[82:83], v[82:83], v[82:83] op_sel_hi:[0,1]
	v_mul_f32_e32 v90, v110, v110
	v_mul_f32_e32 v94, v111, v111
	v_mul_f32_e32 v84, v108, v108
	v_mul_f32_e32 v82, v109, v109
	v_pk_add_f32 v[90:91], v[90:91], v[94:95]
	v_pk_add_f32 v[82:83], v[84:85], v[82:83]
	s_nop 0
	v_pk_add_f32 v[82:83], v[90:91], v[82:83]
	s_nop 0
	v_add_f32_e32 v82, v82, v83
	ds_bpermute_b32 v83, v163, v82
	s_waitcnt lgkmcnt(0)
	v_add_f32_e32 v82, v82, v83
	ds_bpermute_b32 v83, v141, v82
	s_waitcnt lgkmcnt(0)
	v_add_f32_e32 v82, v82, v83
	v_fmamk_f32 v82, v82, 0x3c2aaaab, v158
	v_mul_f32_e32 v83, 0x4f800000, v82
	v_cmp_gt_f32_e32 vcc, s66, v82
	s_nop 1
	v_cndmask_b32_e32 v84, v82, v83, vcc
	v_sqrt_f32_e32 v85, v84
	v_mad_i64_i32 v[82:83], s[8:9], v88, s67, v[152:153]
	v_lshl_add_u64 v[82:83], v[82:83], 0, s[44:45]
	v_add_u32_e32 v87, -1, v85
	v_add_u32_e32 v88, 1, v85
	v_fma_f32 v89, -v87, v85, v84
	v_fma_f32 v90, -v88, v85, v84
	v_cmp_ge_f32_e64 s[8:9], 0, v89
	v_lshl_add_u64 v[82:83], v[82:83], 0, v[146:147]
	s_nop 0
	v_cndmask_b32_e64 v85, v85, v87, s[8:9]
	v_cmp_lt_f32_e64 s[8:9], 0, v90
	s_nop 1
	v_cndmask_b32_e64 v85, v85, v88, s[8:9]
	v_mul_f32_e32 v87, 0x37800000, v85
	v_cndmask_b32_e32 v85, v85, v87, vcc
	v_cmp_class_f32_e32 vcc, v84, v159
	s_nop 1
	v_cndmask_b32_e32 v84, v85, v84, vcc
	v_div_scale_f32 v85, s[8:9], v84, v84, 1.0
	v_rcp_f32_e32 v87, v85
	v_div_scale_f32 v88, vcc, 1.0, v84, 1.0
	v_fma_f32 v89, -v85, v87, 1.0
	v_fmac_f32_e32 v87, v89, v87
	v_mul_f32_e32 v89, v88, v87
	v_fma_f32 v90, -v85, v89, v88
	v_fmac_f32_e32 v89, v90, v87
	v_fma_f32 v85, -v85, v89, v88
	v_div_fmas_f32 v85, v85, v87, v89
	v_div_fixup_f32 v84, v85, v84, 1.0
	v_mul_f32_e32 v90, v86, v84
	v_pk_mul_f32 v[76:77], v[76:77], v[90:91] op_sel_hi:[1,0]
	v_pk_mul_f32 v[78:79], v[78:79], v[90:91] op_sel_hi:[1,0]
	v_pk_mul_f32 v[72:73], v[72:73], v[90:91] op_sel_hi:[1,0]
	v_pk_mul_f32 v[74:75], v[74:75], v[90:91] op_sel_hi:[1,0]
	s_waitcnt vmcnt(0)
	v_pk_mul_f32 v[78:79], v[166:167], v[78:79]
	v_pk_mul_f32 v[76:77], v[164:165], v[76:77]
	v_pk_mul_f32 v[86:87], v[124:125], v[74:75]
	v_pk_mul_f32 v[74:75], v[122:123], v[72:73]
	v_cvt_pk_bf16_f32 v72, v76, v77
	v_cvt_pk_bf16_f32 v73, v78, v79
	v_cvt_pk_bf16_f32 v74, v74, v75
	v_cvt_pk_bf16_f32 v75, v86, v87
	global_store_dwordx4 v[82:83], v[72:75], off
	global_load_dwordx4 v[74:77], v[150:151], off offset:128
	s_nop 0
	global_load_dwordx4 v[86:89], v[150:151], off offset:144
	v_pk_mul_f32 v[64:65], v[64:65], v[90:91] op_sel_hi:[1,0]
	v_pk_mul_f32 v[66:67], v[66:67], v[90:91] op_sel_hi:[1,0]
	v_pk_mul_f32 v[68:69], v[68:69], v[90:91] op_sel_hi:[1,0]
	v_pk_mul_f32 v[70:71], v[70:71], v[90:91] op_sel_hi:[1,0]
	v_add_u32_e32 v72, 0x80, v140
	v_ashrrev_i32_e32 v73, 31, v72
	v_lshlrev_b64 v[78:79], 6, v[72:73]
	v_lshl_add_u64 v[78:79], s[14:15], 0, v[78:79]
	s_waitcnt vmcnt(1)
	v_pk_mul_f32 v[66:67], v[76:77], v[66:67]
	v_pk_mul_f32 v[64:65], v[74:75], v[64:65]
	s_waitcnt vmcnt(0)
	v_pk_mul_f32 v[70:71], v[88:89], v[70:71]
	v_pk_mul_f32 v[68:69], v[86:87], v[68:69]
	v_cvt_pk_bf16_f32 v64, v64, v65
	v_cvt_pk_bf16_f32 v65, v66, v67
	v_cvt_pk_bf16_f32 v66, v68, v69
	v_cvt_pk_bf16_f32 v67, v70, v71
	global_store_dwordx4 v[82:83], v[64:67], off offset:64
	s_nop 1
	ds_read_b32 v66, v253 offset:512
	v_mov_b32_e32 v67, 0
	v_mov_b32_e32 v68, 0
	v_mov_b32_e32 v69, 0
	v_mov_b32_e32 v86, 0
	v_mov_b32_e32 v87, 0
	v_mov_b32_e32 v88, 0
	v_mov_b32_e32 v89, 0
	v_mov_b32_e32 v74, 0
	v_mov_b32_e32 v75, 0
	v_mov_b32_e32 v76, 0
	v_mov_b32_e32 v77, 0
	v_mov_b32_e32 v90, 0
	v_mov_b32_e32 v91, 0
	v_mov_b32_e32 v92, 0
	v_mov_b32_e32 v93, 0
	s_waitcnt lgkmcnt(0)
	v_lshlrev_b64 v[64:65], 11, v[72:73]
	v_lshl_add_u64 v[64:65], s[10:11], 0, v[64:65]
	v_lshl_add_u64 v[64:65], v[64:65], 0, v[146:147]
	global_load_dwordx4 v[102:105], v[64:65], off offset:1536
	global_load_dwordx4 v[106:109], v[150:151], off offset:16
	global_load_dwordx4 v[118:121], v[150:151], off
	s_waitcnt vmcnt(6)
	v_mov_b32_e32 v70, v66
	s_waitcnt vmcnt(5)
	v_mov_b32_e32 v71, v74
	v_mov_b32_e32 v74, v67
	v_mov_b32_e32 v66, v68
	v_mov_b32_e32 v67, v76
	v_mov_b32_e32 v76, v69
	s_waitcnt vmcnt(4)
	v_mov_b32_e32 v68, v86
	s_waitcnt vmcnt(3)
; __device__ __forceinline__ unsigned cvtpk(float lo, float hi) { f32x2_t v = {lo, hi}; bf16x2_t b = __builtin_convertvector(v, bf16x2_t); return __builtin_bit_cast(unsigned, b); }
; __device__ __forceinline__ float bflo(unsigned w) { return __uint_as_float(w << 16); }
; __device__ __forceinline__ float bfhi(unsigned w) { return __uint_as_float(w & 0xffff0000u); }
;     __device__ __forceinline__ void operator()(const f32x4 (&acc)[2][2][4][2], const Unit& u, int wr, int wc, int fr, int fq) const {
;     ...
;             for (int m = 0; m < 4; ++m) {
;                 const int row = row0 + ai * HALF + m * 16;
;                 const float rkv = 1.0f / sqrtf(ssq_sum(ssq_in + (size_t)row * 16) * (1.0f / 256.0f) + EPS);
;                 const u32x4 kw = *(const u32x4*)(T1 + (size_t)row * 1024 + 768 + 8 * fq);
;                 float s = (bflo(kw.x) * bflo(kw.x) + bfhi(kw.x) * bfhi(kw.x)) + (bflo(kw.y) * bflo(kw.y) + bfhi(kw.y) * bfhi(kw.y))
;                         + (bflo(kw.z) * bflo(kw.z) + bfhi(kw.z) * bfhi(kw.z)) + (bflo(kw.w) * bflo(kw.w) + bfhi(kw.w) * bfhi(kw.w));
; #pragma unroll
;                 for (int bj = 0; bj < 2; ++bj)
; #pragma unroll
;                     for (int n = 0; n < 2; ++n) { const f32x4 v = acc[ai][bj][m][n] * rkv; s += (v[0] * v[0] + v[1] * v[1]) + (v[2] * v[2] + v[3] * v[3]); }
;                 s += __shfl_xor(s, 16); s += __shfl_xor(s, 32);
;                 const float rh = 1.0f / sqrtf(s * (1.0f / 96.0f) + EPS), rs = rkv * rh;
;                 rhs[ai * 4 + m] = rh;
;                 bf16_t* op = O + (size_t)row * 1536 + head * 96;
; #pragma unroll
;                 for (int bj = 0; bj < 2; ++bj) {
;                     const f32x4 g0 = *(const f32x4*)(gk + bj * 32 + 8 * fq), g1 = *(const f32x4*)(gk + bj * 32 + 8 * fq + 4);
;                     const f32x4 v0 = acc[ai][bj][m][0] * rs * g0, v1 = acc[ai][bj][m][1] * rs * g1;
;                     u32x4 w; w.x = cvtpk(v0[0], v0[1]); w.y = cvtpk(v0[2], v0[3]); w.z = cvtpk(v1[0], v1[1]); w.w = cvtpk(v1[2], v1[3]);
;                     *(u32x4*)(op + bj * 32 + 8 * fq) = w;
;                 }
;                 asm volatile("" ::: "memory");
	v_mov_b32_e32 v69, v90
	v_mov_b32_e32 v90, v87
	v_mov_b32_e32 v78, v88
	v_mov_b32_e32 v79, v92
	v_mov_b32_e32 v92, v89
	v_pk_add_f32 v[70:71], v[70:71], v[74:75]
	v_pk_add_f32 v[66:67], v[66:67], v[76:77]
	v_pk_add_f32 v[68:69], v[68:69], v[90:91]
	v_pk_add_f32 v[74:75], v[78:79], v[92:93]
	v_pk_add_f32 v[66:67], v[70:71], v[66:67]
	v_pk_add_f32 v[68:69], v[68:69], v[74:75]
	s_waitcnt vmcnt(2)
	v_and_b32_e32 v95, 0xffff0000, v104
	v_pk_add_f32 v[66:67], v[66:67], v[68:69]
	v_lshlrev_b32_e32 v94, 16, v104
	v_add_f32_e32 v66, v66, v67
	v_fmamk_f32 v66, v66, 0x3b800000, v158
	v_mul_f32_e32 v67, 0x4f800000, v66
	v_cmp_gt_f32_e32 vcc, s66, v66
	v_and_b32_e32 v89, 0xffff0000, v103
	v_and_b32_e32 v88, 0xffff0000, v102
	v_cndmask_b32_e32 v70, v66, v67, vcc
	v_sqrt_f32_e32 v71, v70
	v_mul_f32_e32 v66, v95, v95
	v_pk_fma_f32 v[66:67], v[94:95], v[94:95], v[66:67] op_sel_hi:[1,1,0]
	v_lshlrev_b32_e32 v87, 16, v103
	v_add_u32_e32 v67, -1, v71
	v_add_u32_e32 v73, 1, v71
	v_fma_f32 v74, -v67, v71, v70
	v_fma_f32 v75, -v73, v71, v70
	v_cmp_ge_f32_e64 s[8:9], 0, v74
	v_lshlrev_b32_e32 v86, 16, v102
	v_pk_mul_f32 v[76:77], v[88:89], v[88:89]
	v_cndmask_b32_e64 v67, v71, v67, s[8:9]
	v_cmp_lt_f32_e64 s[8:9], 0, v75
	v_pk_fma_f32 v[68:69], v[86:87], v[86:87], v[76:77]
	v_lshlrev_b32_e32 v102, 16, v105
	v_cndmask_b32_e64 v67, v67, v73, s[8:9]
	v_mul_f32_e32 v71, 0x37800000, v67
	v_cndmask_b32_e32 v67, v67, v71, vcc
	v_cmp_class_f32_e32 vcc, v70, v159
	v_pk_add_f32 v[68:69], v[68:69], v[68:69] op_sel:[0,1] op_sel_hi:[1,0]
	v_and_b32_e32 v104, 0xffff0000, v105
	v_cndmask_b32_e32 v67, v67, v70, vcc
	v_div_scale_f32 v70, s[8:9], v67, v67, 1.0
	v_rcp_f32_e32 v71, v70
	v_div_scale_f32 v69, vcc, 1.0, v67, 1.0
	v_fma_f32 v73, -v70, v71, 1.0
	v_fmac_f32_e32 v71, v73, v71
	v_mul_f32_e32 v73, v69, v71
	v_fma_f32 v74, -v70, v73, v69
	v_fmac_f32_e32 v73, v74, v71
	v_fma_f32 v69, -v70, v73, v69
	v_div_fmas_f32 v69, v69, v71, v73
	v_div_fixup_f32 v70, v69, v67, 1.0
	v_pk_mul_f32 v[74:75], v[60:61], v[70:71] op_sel_hi:[1,0]
	v_pk_mul_f32 v[76:77], v[62:63], v[70:71] op_sel_hi:[1,0]
	v_pk_mul_f32 v[78:79], v[56:57], v[70:71] op_sel_hi:[1,0]
	v_pk_mul_f32 v[86:87], v[58:59], v[70:71] op_sel_hi:[1,0]
	v_pk_mul_f32 v[88:89], v[50:51], v[70:71] op_sel_hi:[1,0]
	v_pk_mul_f32 v[90:91], v[48:49], v[70:71] op_sel_hi:[1,0]
	v_mov_b32_e32 v105, v75
	v_mul_f32_e32 v67, v76, v76
	v_mul_f32_e32 v69, v77, v77
	v_mov_b32_e32 v103, v74
	v_pk_mul_f32 v[74:75], v[86:87], v[86:87]
	v_pk_mul_f32 v[76:77], v[78:79], v[78:79]
	v_mul_f32_e32 v78, v90, v90
	v_mul_f32_e32 v86, v88, v88
	v_pk_mul_f32 v[104:105], v[104:105], v[104:105]
	v_pk_mov_b32 v[110:111], v[76:77], v[74:75] op_sel:[1,0]
	v_mov_b32_e32 v77, v75
	v_pk_fma_f32 v[74:75], v[90:91], v[90:91], v[78:79] op_sel_hi:[1,1,0]
	v_pk_fma_f32 v[78:79], v[88:89], v[88:89], v[86:87] op_sel_hi:[1,1,0]
	v_pk_fma_f32 v[86:87], v[102:103], v[102:103], v[104:105]
	v_pk_add_f32 v[66:67], v[66:67], v[68:69]
	v_pk_add_f32 v[68:69], v[110:111], v[76:77]
	v_pk_add_f32 v[66:67], v[86:87], v[66:67]
	v_pk_mul_f32 v[92:93], v[54:55], v[70:71] op_sel_hi:[1,0]
	v_pk_mul_f32 v[94:95], v[52:53], v[70:71] op_sel_hi:[1,0]
	v_pk_add_f32 v[68:69], v[68:69], v[68:69] op_sel_hi:[0,1]
	v_pk_add_f32 v[66:67], v[66:67], v[66:67] op_sel_hi:[0,1]
	v_mul_f32_e32 v74, v94, v94
	v_mul_f32_e32 v78, v95, v95
	v_mul_f32_e32 v68, v92, v92
	v_mul_f32_e32 v66, v93, v93
	v_pk_add_f32 v[74:75], v[74:75], v[78:79]
	v_pk_add_f32 v[66:67], v[68:69], v[66:67]
	s_nop 0
	v_pk_add_f32 v[66:67], v[74:75], v[66:67]
	s_nop 0
	v_add_f32_e32 v66, v66, v67
	ds_bpermute_b32 v67, v163, v66
	s_waitcnt lgkmcnt(0)
	v_add_f32_e32 v66, v66, v67
	ds_bpermute_b32 v67, v141, v66
	s_waitcnt lgkmcnt(0)
	v_add_f32_e32 v66, v66, v67
	v_fmamk_f32 v66, v66, 0x3c2aaaab, v158
	v_mul_f32_e32 v67, 0x4f800000, v66
	v_cmp_gt_f32_e32 vcc, s66, v66
	s_nop 1
	v_cndmask_b32_e32 v68, v66, v67, vcc
	v_sqrt_f32_e32 v69, v68
	v_mad_i64_i32 v[66:67], s[8:9], v72, s67, v[152:153]
	v_lshl_add_u64 v[66:67], v[66:67], 0, s[44:45]
	v_add_u32_e32 v71, -1, v69
	v_add_u32_e32 v73, 1, v69
	v_fma_f32 v74, -v71, v69, v68
	v_fma_f32 v75, -v73, v69, v68
	v_cmp_ge_f32_e64 s[8:9], 0, v74
	v_lshl_add_u64 v[66:67], v[66:67], 0, v[146:147]
	s_nop 0
	v_cndmask_b32_e64 v69, v69, v71, s[8:9]
	v_cmp_lt_f32_e64 s[8:9], 0, v75
	s_nop 1
	v_cndmask_b32_e64 v69, v69, v73, s[8:9]
	v_mul_f32_e32 v71, 0x37800000, v69
	v_cndmask_b32_e32 v69, v69, v71, vcc
	v_cmp_class_f32_e32 vcc, v68, v159
	s_nop 1
	v_cndmask_b32_e32 v68, v69, v68, vcc
	v_div_scale_f32 v69, s[8:9], v68, v68, 1.0
	v_rcp_f32_e32 v71, v69
	v_div_scale_f32 v73, vcc, 1.0, v68, 1.0
	v_fma_f32 v74, -v69, v71, 1.0
	v_fmac_f32_e32 v71, v74, v71
	v_mul_f32_e32 v74, v73, v71
	v_fma_f32 v75, -v69, v74, v73
	v_fmac_f32_e32 v74, v75, v71
	v_fma_f32 v69, -v69, v74, v73
	v_div_fmas_f32 v69, v69, v71, v74
	v_div_fixup_f32 v68, v69, v68, 1.0
	v_mul_f32_e32 v70, v70, v68
	v_pk_mul_f32 v[60:61], v[60:61], v[70:71] op_sel_hi:[1,0]
	v_pk_mul_f32 v[62:63], v[62:63], v[70:71] op_sel_hi:[1,0]
	v_pk_mul_f32 v[56:57], v[56:57], v[70:71] op_sel_hi:[1,0]
	v_pk_mul_f32 v[58:59], v[58:59], v[70:71] op_sel_hi:[1,0]
	s_waitcnt vmcnt(0)
	v_pk_mul_f32 v[62:63], v[120:121], v[62:63]
	v_pk_mul_f32 v[60:61], v[118:119], v[60:61]
	v_pk_mul_f32 v[74:75], v[108:109], v[58:59]
	v_pk_mul_f32 v[58:59], v[106:107], v[56:57]
	v_cvt_pk_bf16_f32 v56, v60, v61
	v_cvt_pk_bf16_f32 v57, v62, v63
	v_cvt_pk_bf16_f32 v58, v58, v59
	v_cvt_pk_bf16_f32 v59, v74, v75
	global_store_dwordx4 v[66:67], v[56:59], off
	global_load_dwordx4 v[58:61], v[150:151], off offset:128
	s_nop 0
	global_load_dwordx4 v[74:77], v[150:151], off offset:144
	v_pk_mul_f32 v[48:49], v[48:49], v[70:71] op_sel_hi:[1,0]
	v_pk_mul_f32 v[50:51], v[50:51], v[70:71] op_sel_hi:[1,0]
	v_pk_mul_f32 v[52:53], v[52:53], v[70:71] op_sel_hi:[1,0]
	v_pk_mul_f32 v[54:55], v[54:55], v[70:71] op_sel_hi:[1,0]
	v_add_u32_e32 v56, 0x90, v140
	v_ashrrev_i32_e32 v57, 31, v56
	v_lshlrev_b64 v[62:63], 6, v[56:57]
	v_lshl_add_u64 v[62:63], s[14:15], 0, v[62:63]
	s_waitcnt vmcnt(1)
; __device__ __forceinline__ unsigned cvtpk(float lo, float hi) { f32x2_t v = {lo, hi}; bf16x2_t b = __builtin_convertvector(v, bf16x2_t); return __builtin_bit_cast(unsigned, b); }
; __device__ __forceinline__ float bflo(unsigned w) { return __uint_as_float(w << 16); }
; __device__ __forceinline__ float bfhi(unsigned w) { return __uint_as_float(w & 0xffff0000u); }
;     __device__ __forceinline__ void operator()(const f32x4 (&acc)[2][2][4][2], const Unit& u, int wr, int wc, int fr, int fq) const {
;     ...
;             for (int m = 0; m < 4; ++m) {
;                 const int row = row0 + ai * HALF + m * 16;
;                 const float rkv = 1.0f / sqrtf(ssq_sum(ssq_in + (size_t)row * 16) * (1.0f / 256.0f) + EPS);
;                 const u32x4 kw = *(const u32x4*)(T1 + (size_t)row * 1024 + 768 + 8 * fq);
;                 float s = (bflo(kw.x) * bflo(kw.x) + bfhi(kw.x) * bfhi(kw.x)) + (bflo(kw.y) * bflo(kw.y) + bfhi(kw.y) * bfhi(kw.y))
;                         + (bflo(kw.z) * bflo(kw.z) + bfhi(kw.z) * bfhi(kw.z)) + (bflo(kw.w) * bflo(kw.w) + bfhi(kw.w) * bfhi(kw.w));
; #pragma unroll
;                 for (int bj = 0; bj < 2; ++bj)
; #pragma unroll
;                     for (int n = 0; n < 2; ++n) { const f32x4 v = acc[ai][bj][m][n] * rkv; s += (v[0] * v[0] + v[1] * v[1]) + (v[2] * v[2] + v[3] * v[3]); }
;                 s += __shfl_xor(s, 16); s += __shfl_xor(s, 32);
;                 const float rh = 1.0f / sqrtf(s * (1.0f / 96.0f) + EPS), rs = rkv * rh;
;                 rhs[ai * 4 + m] = rh;
;                 bf16_t* op = O + (size_t)row * 1536 + head * 96;
; #pragma unroll
;                 for (int bj = 0; bj < 2; ++bj) {
;                     const f32x4 g0 = *(const f32x4*)(gk + bj * 32 + 8 * fq), g1 = *(const f32x4*)(gk + bj * 32 + 8 * fq + 4);
;                     const f32x4 v0 = acc[ai][bj][m][0] * rs * g0, v1 = acc[ai][bj][m][1] * rs * g1;
;                     u32x4 w; w.x = cvtpk(v0[0], v0[1]); w.y = cvtpk(v0[2], v0[3]); w.z = cvtpk(v1[0], v1[1]); w.w = cvtpk(v1[2], v1[3]);
;                     *(u32x4*)(op + bj * 32 + 8 * fq) = w;
;                 }
;                 asm volatile("" ::: "memory");
	v_pk_mul_f32 v[50:51], v[60:61], v[50:51]
	v_pk_mul_f32 v[48:49], v[58:59], v[48:49]
	s_waitcnt vmcnt(0)
	v_pk_mul_f32 v[54:55], v[76:77], v[54:55]
	v_pk_mul_f32 v[52:53], v[74:75], v[52:53]
	v_cvt_pk_bf16_f32 v48, v48, v49
	v_cvt_pk_bf16_f32 v49, v50, v51
	v_cvt_pk_bf16_f32 v50, v52, v53
	v_cvt_pk_bf16_f32 v51, v54, v55
	global_store_dwordx4 v[66:67], v[48:51], off offset:64
	s_nop 1
	ds_read_b32 v50, v253 offset:576
	v_mov_b32_e32 v51, 0
	v_mov_b32_e32 v52, 0
	v_mov_b32_e32 v53, 0
	v_mov_b32_e32 v74, 0
	v_mov_b32_e32 v75, 0
	v_mov_b32_e32 v76, 0
	v_mov_b32_e32 v77, 0
	v_mov_b32_e32 v58, 0
	v_mov_b32_e32 v59, 0
	v_mov_b32_e32 v60, 0
	v_mov_b32_e32 v61, 0
	v_mov_b32_e32 v86, 0
	v_mov_b32_e32 v87, 0
	v_mov_b32_e32 v88, 0
	v_mov_b32_e32 v89, 0
	s_waitcnt lgkmcnt(0)
	v_lshlrev_b64 v[48:49], 11, v[56:57]
	v_lshl_add_u64 v[48:49], s[10:11], 0, v[48:49]
	v_lshl_add_u64 v[48:49], v[48:49], 0, v[146:147]
	global_load_dwordx4 v[90:93], v[48:49], off offset:1536
	global_load_dwordx4 v[102:105], v[150:151], off offset:16
	global_load_dwordx4 v[106:109], v[150:151], off
	s_waitcnt vmcnt(6)
	v_mov_b32_e32 v54, v50
	s_waitcnt vmcnt(5)
	v_mov_b32_e32 v55, v58
	v_mov_b32_e32 v58, v51
	v_mov_b32_e32 v50, v52
	v_mov_b32_e32 v51, v60
	v_mov_b32_e32 v60, v53
	s_waitcnt vmcnt(4)
	v_mov_b32_e32 v52, v74
	s_waitcnt vmcnt(3)
	v_mov_b32_e32 v53, v86
	v_mov_b32_e32 v86, v75
	v_mov_b32_e32 v62, v76
	v_mov_b32_e32 v63, v88
	v_mov_b32_e32 v88, v77
	v_pk_add_f32 v[54:55], v[54:55], v[58:59]
	v_pk_add_f32 v[50:51], v[50:51], v[60:61]
	v_pk_add_f32 v[52:53], v[52:53], v[86:87]
	v_pk_add_f32 v[58:59], v[62:63], v[88:89]
	v_pk_add_f32 v[50:51], v[54:55], v[50:51]
	v_pk_add_f32 v[52:53], v[52:53], v[58:59]
	s_waitcnt vmcnt(2)
	v_and_b32_e32 v77, 0xffff0000, v92
	v_pk_add_f32 v[50:51], v[50:51], v[52:53]
	v_lshlrev_b32_e32 v76, 16, v92
	v_add_f32_e32 v50, v50, v51
	v_fmamk_f32 v50, v50, 0x3b800000, v158
	v_mul_f32_e32 v51, 0x4f800000, v50
	v_cmp_gt_f32_e32 vcc, s66, v50
	v_and_b32_e32 v75, 0xffff0000, v91
	v_and_b32_e32 v74, 0xffff0000, v90
	v_cndmask_b32_e32 v54, v50, v51, vcc
	v_sqrt_f32_e32 v55, v54
	v_mul_f32_e32 v50, v77, v77
	v_pk_fma_f32 v[50:51], v[76:77], v[76:77], v[50:51] op_sel_hi:[1,1,0]
	v_lshlrev_b32_e32 v71, 16, v91
	v_add_u32_e32 v51, -1, v55
	v_add_u32_e32 v57, 1, v55
	v_fma_f32 v58, -v51, v55, v54
	v_fma_f32 v59, -v57, v55, v54
	v_cmp_ge_f32_e64 s[8:9], 0, v58
	v_lshlrev_b32_e32 v70, 16, v90
	v_pk_mul_f32 v[60:61], v[74:75], v[74:75]
	v_cndmask_b32_e64 v51, v55, v51, s[8:9]
	v_cmp_lt_f32_e64 s[8:9], 0, v59
	v_pk_fma_f32 v[52:53], v[70:71], v[70:71], v[60:61]
	v_and_b32_e32 v90, 0xffff0000, v93
	v_cndmask_b32_e64 v51, v51, v57, s[8:9]
	v_mul_f32_e32 v55, 0x37800000, v51
	v_cndmask_b32_e32 v51, v51, v55, vcc
	v_cmp_class_f32_e32 vcc, v54, v159
	v_pk_add_f32 v[52:53], v[52:53], v[52:53] op_sel:[0,1] op_sel_hi:[1,0]
	v_lshlrev_b32_e32 v78, 16, v93
	v_cndmask_b32_e32 v51, v51, v54, vcc
	v_div_scale_f32 v54, s[8:9], v51, v51, 1.0
	v_rcp_f32_e32 v55, v54
	v_div_scale_f32 v53, vcc, 1.0, v51, 1.0
	v_fma_f32 v57, -v54, v55, 1.0
	v_fmac_f32_e32 v55, v57, v55
	v_mul_f32_e32 v57, v53, v55
	v_fma_f32 v58, -v54, v57, v53
	v_fmac_f32_e32 v57, v58, v55
	v_fma_f32 v53, -v54, v57, v53
	v_div_fmas_f32 v53, v53, v55, v57
	v_div_fixup_f32 v54, v53, v51, 1.0
	v_pk_mul_f32 v[58:59], v[44:45], v[54:55] op_sel_hi:[1,0]
	v_pk_mul_f32 v[60:61], v[46:47], v[54:55] op_sel_hi:[1,0]
	v_pk_mul_f32 v[62:63], v[40:41], v[54:55] op_sel_hi:[1,0]
	v_pk_mul_f32 v[70:71], v[42:43], v[54:55] op_sel_hi:[1,0]
	v_pk_mul_f32 v[74:75], v[34:35], v[54:55] op_sel_hi:[1,0]
	v_pk_mul_f32 v[76:77], v[32:33], v[54:55] op_sel_hi:[1,0]
	v_mov_b32_e32 v91, v59
	v_mul_f32_e32 v51, v60, v60
	v_mul_f32_e32 v53, v61, v61
	v_mov_b32_e32 v79, v58
	v_pk_mul_f32 v[58:59], v[70:71], v[70:71]
	v_pk_mul_f32 v[60:61], v[62:63], v[62:63]
	v_mul_f32_e32 v62, v76, v76
	v_mul_f32_e32 v70, v74, v74
	v_pk_mul_f32 v[90:91], v[90:91], v[90:91]
	v_pk_mov_b32 v[92:93], v[60:61], v[58:59] op_sel:[1,0]
	v_mov_b32_e32 v61, v59
	v_pk_fma_f32 v[58:59], v[76:77], v[76:77], v[62:63] op_sel_hi:[1,1,0]
	v_pk_fma_f32 v[62:63], v[74:75], v[74:75], v[70:71] op_sel_hi:[1,1,0]
	v_pk_fma_f32 v[70:71], v[78:79], v[78:79], v[90:91]
	v_pk_add_f32 v[50:51], v[50:51], v[52:53]
	v_pk_add_f32 v[52:53], v[92:93], v[60:61]
	v_pk_add_f32 v[50:51], v[70:71], v[50:51]
	v_pk_mul_f32 v[86:87], v[38:39], v[54:55] op_sel_hi:[1,0]
	v_pk_mul_f32 v[88:89], v[36:37], v[54:55] op_sel_hi:[1,0]
	v_pk_add_f32 v[52:53], v[52:53], v[52:53] op_sel_hi:[0,1]
	v_pk_add_f32 v[50:51], v[50:51], v[50:51] op_sel_hi:[0,1]
	v_mul_f32_e32 v58, v88, v88
	v_mul_f32_e32 v62, v89, v89
	v_mul_f32_e32 v52, v86, v86
	v_mul_f32_e32 v50, v87, v87
	v_pk_add_f32 v[58:59], v[58:59], v[62:63]
	v_pk_add_f32 v[50:51], v[52:53], v[50:51]
	s_nop 0
	v_pk_add_f32 v[50:51], v[58:59], v[50:51]
	s_nop 0
	v_add_f32_e32 v50, v50, v51
	ds_bpermute_b32 v51, v163, v50
	s_waitcnt lgkmcnt(0)
	v_add_f32_e32 v50, v50, v51
	ds_bpermute_b32 v51, v141, v50
	s_waitcnt lgkmcnt(0)
; __device__ __forceinline__ unsigned cvtpk(float lo, float hi) { f32x2_t v = {lo, hi}; bf16x2_t b = __builtin_convertvector(v, bf16x2_t); return __builtin_bit_cast(unsigned, b); }
; __device__ __forceinline__ float bflo(unsigned w) { return __uint_as_float(w << 16); }
; __device__ __forceinline__ float bfhi(unsigned w) { return __uint_as_float(w & 0xffff0000u); }
;     __device__ __forceinline__ void operator()(const f32x4 (&acc)[2][2][4][2], const Unit& u, int wr, int wc, int fr, int fq) const {
;     ...
;             for (int m = 0; m < 4; ++m) {
;                 const int row = row0 + ai * HALF + m * 16;
;                 const float rkv = 1.0f / sqrtf(ssq_sum(ssq_in + (size_t)row * 16) * (1.0f / 256.0f) + EPS);
;                 const u32x4 kw = *(const u32x4*)(T1 + (size_t)row * 1024 + 768 + 8 * fq);
;                 float s = (bflo(kw.x) * bflo(kw.x) + bfhi(kw.x) * bfhi(kw.x)) + (bflo(kw.y) * bflo(kw.y) + bfhi(kw.y) * bfhi(kw.y))
;                         + (bflo(kw.z) * bflo(kw.z) + bfhi(kw.z) * bfhi(kw.z)) + (bflo(kw.w) * bflo(kw.w) + bfhi(kw.w) * bfhi(kw.w));
; #pragma unroll
;                 for (int bj = 0; bj < 2; ++bj)
; #pragma unroll
;                     for (int n = 0; n < 2; ++n) { const f32x4 v = acc[ai][bj][m][n] * rkv; s += (v[0] * v[0] + v[1] * v[1]) + (v[2] * v[2] + v[3] * v[3]); }
;                 s += __shfl_xor(s, 16); s += __shfl_xor(s, 32);
;                 const float rh = 1.0f / sqrtf(s * (1.0f / 96.0f) + EPS), rs = rkv * rh;
;                 rhs[ai * 4 + m] = rh;
;                 bf16_t* op = O + (size_t)row * 1536 + head * 96;
; #pragma unroll
;                 for (int bj = 0; bj < 2; ++bj) {
;                     const f32x4 g0 = *(const f32x4*)(gk + bj * 32 + 8 * fq), g1 = *(const f32x4*)(gk + bj * 32 + 8 * fq + 4);
;                     const f32x4 v0 = acc[ai][bj][m][0] * rs * g0, v1 = acc[ai][bj][m][1] * rs * g1;
;                     u32x4 w; w.x = cvtpk(v0[0], v0[1]); w.y = cvtpk(v0[2], v0[3]); w.z = cvtpk(v1[0], v1[1]); w.w = cvtpk(v1[2], v1[3]);
;                     *(u32x4*)(op + bj * 32 + 8 * fq) = w;
;                 }
;                 asm volatile("" ::: "memory");
	v_add_f32_e32 v50, v50, v51
	v_fmamk_f32 v50, v50, 0x3c2aaaab, v158
	v_mul_f32_e32 v51, 0x4f800000, v50
	v_cmp_gt_f32_e32 vcc, s66, v50
	s_nop 1
	v_cndmask_b32_e32 v52, v50, v51, vcc
	v_sqrt_f32_e32 v53, v52
	v_mad_i64_i32 v[50:51], s[8:9], v56, s67, v[152:153]
	v_lshl_add_u64 v[50:51], v[50:51], 0, s[44:45]
	v_add_u32_e32 v55, -1, v53
	v_add_u32_e32 v57, 1, v53
	v_fma_f32 v58, -v55, v53, v52
	v_fma_f32 v59, -v57, v53, v52
	v_cmp_ge_f32_e64 s[8:9], 0, v58
	v_lshl_add_u64 v[50:51], v[50:51], 0, v[146:147]
	s_nop 0
	v_cndmask_b32_e64 v53, v53, v55, s[8:9]
	v_cmp_lt_f32_e64 s[8:9], 0, v59
	s_nop 1
	v_cndmask_b32_e64 v53, v53, v57, s[8:9]
	v_mul_f32_e32 v55, 0x37800000, v53
	v_cndmask_b32_e32 v53, v53, v55, vcc
	v_cmp_class_f32_e32 vcc, v52, v159
	s_nop 1
	v_cndmask_b32_e32 v52, v53, v52, vcc
	v_div_scale_f32 v53, s[8:9], v52, v52, 1.0
	v_rcp_f32_e32 v55, v53
	v_div_scale_f32 v57, vcc, 1.0, v52, 1.0
	v_fma_f32 v58, -v53, v55, 1.0
	v_fmac_f32_e32 v55, v58, v55
	v_mul_f32_e32 v58, v57, v55
	v_fma_f32 v59, -v53, v58, v57
	v_fmac_f32_e32 v58, v59, v55
	v_fma_f32 v53, -v53, v58, v57
	v_div_fmas_f32 v53, v53, v55, v58
	v_div_fixup_f32 v52, v53, v52, 1.0
	v_mul_f32_e32 v54, v54, v52
	v_pk_mul_f32 v[44:45], v[44:45], v[54:55] op_sel_hi:[1,0]
	v_pk_mul_f32 v[46:47], v[46:47], v[54:55] op_sel_hi:[1,0]
	v_pk_mul_f32 v[40:41], v[40:41], v[54:55] op_sel_hi:[1,0]
	v_pk_mul_f32 v[42:43], v[42:43], v[54:55] op_sel_hi:[1,0]
	s_waitcnt vmcnt(0)
	v_pk_mul_f32 v[46:47], v[108:109], v[46:47]
	v_pk_mul_f32 v[44:45], v[106:107], v[44:45]
	v_pk_mul_f32 v[58:59], v[104:105], v[42:43]
	v_pk_mul_f32 v[42:43], v[102:103], v[40:41]
	v_cvt_pk_bf16_f32 v40, v44, v45
	v_cvt_pk_bf16_f32 v41, v46, v47
	v_cvt_pk_bf16_f32 v42, v42, v43
	v_cvt_pk_bf16_f32 v43, v58, v59
	global_store_dwordx4 v[50:51], v[40:43], off
	global_load_dwordx4 v[42:45], v[150:151], off offset:128
	s_nop 0
	global_load_dwordx4 v[58:61], v[150:151], off offset:144
	v_pk_mul_f32 v[32:33], v[32:33], v[54:55] op_sel_hi:[1,0]
	v_pk_mul_f32 v[34:35], v[34:35], v[54:55] op_sel_hi:[1,0]
	v_pk_mul_f32 v[36:37], v[36:37], v[54:55] op_sel_hi:[1,0]
	v_pk_mul_f32 v[38:39], v[38:39], v[54:55] op_sel_hi:[1,0]
	v_add_u32_e32 v40, 0xa0, v140
	v_ashrrev_i32_e32 v41, 31, v40
	v_lshlrev_b64 v[46:47], 6, v[40:41]
	v_lshl_add_u64 v[46:47], s[14:15], 0, v[46:47]
	s_waitcnt vmcnt(1)
	v_pk_mul_f32 v[34:35], v[44:45], v[34:35]
	v_pk_mul_f32 v[32:33], v[42:43], v[32:33]
	s_waitcnt vmcnt(0)
	v_pk_mul_f32 v[38:39], v[60:61], v[38:39]
	v_pk_mul_f32 v[36:37], v[58:59], v[36:37]
	v_cvt_pk_bf16_f32 v32, v32, v33
	v_cvt_pk_bf16_f32 v33, v34, v35
	v_cvt_pk_bf16_f32 v34, v36, v37
	v_cvt_pk_bf16_f32 v35, v38, v39
	global_store_dwordx4 v[50:51], v[32:35], off offset:64
	s_nop 1
	ds_read_b32 v34, v253 offset:640
	v_mov_b32_e32 v35, 0
	v_mov_b32_e32 v36, 0
	v_mov_b32_e32 v37, 0
	v_mov_b32_e32 v58, 0
	v_mov_b32_e32 v59, 0
	v_mov_b32_e32 v60, 0
	v_mov_b32_e32 v61, 0
	v_mov_b32_e32 v42, 0
	v_mov_b32_e32 v43, 0
	v_mov_b32_e32 v44, 0
	v_mov_b32_e32 v45, 0
	v_mov_b32_e32 v74, 0
	v_mov_b32_e32 v75, 0
	v_mov_b32_e32 v76, 0
	v_mov_b32_e32 v77, 0
	s_waitcnt lgkmcnt(0)
	v_lshlrev_b64 v[32:33], 11, v[40:41]
	v_lshl_add_u64 v[32:33], s[10:11], 0, v[32:33]
	v_lshl_add_u64 v[32:33], v[32:33], 0, v[146:147]
	global_load_dwordx4 v[86:89], v[32:33], off offset:1536
	global_load_dwordx4 v[90:93], v[150:151], off offset:16
	global_load_dwordx4 v[102:105], v[150:151], off
	s_waitcnt vmcnt(6)
	v_mov_b32_e32 v38, v34
	s_waitcnt vmcnt(5)
	v_mov_b32_e32 v39, v42
	v_mov_b32_e32 v42, v35
	v_mov_b32_e32 v34, v36
	v_mov_b32_e32 v35, v44
	v_mov_b32_e32 v44, v37
	s_waitcnt vmcnt(4)
	v_mov_b32_e32 v36, v58
	s_waitcnt vmcnt(3)
	v_mov_b32_e32 v37, v74
	v_mov_b32_e32 v74, v59
	v_mov_b32_e32 v46, v60
	v_mov_b32_e32 v47, v76
	v_mov_b32_e32 v76, v61
	v_pk_add_f32 v[38:39], v[38:39], v[42:43]
	v_pk_add_f32 v[34:35], v[34:35], v[44:45]
	v_pk_add_f32 v[36:37], v[36:37], v[74:75]
	v_pk_add_f32 v[42:43], v[46:47], v[76:77]
	v_pk_add_f32 v[34:35], v[38:39], v[34:35]
	v_pk_add_f32 v[36:37], v[36:37], v[42:43]
	s_waitcnt vmcnt(2)
	v_and_b32_e32 v61, 0xffff0000, v88
	v_pk_add_f32 v[34:35], v[34:35], v[36:37]
	v_lshlrev_b32_e32 v60, 16, v88
	v_add_f32_e32 v34, v34, v35
	v_fmamk_f32 v34, v34, 0x3b800000, v158
	v_mul_f32_e32 v35, 0x4f800000, v34
	v_cmp_gt_f32_e32 vcc, s66, v34
	v_and_b32_e32 v59, 0xffff0000, v87
	v_and_b32_e32 v58, 0xffff0000, v86
	v_cndmask_b32_e32 v38, v34, v35, vcc
	v_sqrt_f32_e32 v39, v38
	v_mul_f32_e32 v34, v61, v61
	v_pk_fma_f32 v[34:35], v[60:61], v[60:61], v[34:35] op_sel_hi:[1,1,0]
	v_lshlrev_b32_e32 v55, 16, v87
	v_add_u32_e32 v35, -1, v39
	v_add_u32_e32 v41, 1, v39
	v_fma_f32 v42, -v35, v39, v38
	v_fma_f32 v43, -v41, v39, v38
	v_cmp_ge_f32_e64 s[8:9], 0, v42
	v_lshlrev_b32_e32 v54, 16, v86
	v_pk_mul_f32 v[44:45], v[58:59], v[58:59]
	v_cndmask_b32_e64 v35, v39, v35, s[8:9]
	v_cmp_lt_f32_e64 s[8:9], 0, v43
	v_pk_fma_f32 v[36:37], v[54:55], v[54:55], v[44:45]
	v_and_b32_e32 v70, 0xffff0000, v89
	v_cndmask_b32_e64 v35, v35, v41, s[8:9]
	v_mul_f32_e32 v39, 0x37800000, v35
	v_cndmask_b32_e32 v35, v35, v39, vcc
	v_cmp_class_f32_e32 vcc, v38, v159
	v_pk_add_f32 v[36:37], v[36:37], v[36:37] op_sel:[0,1] op_sel_hi:[1,0]
	v_lshlrev_b32_e32 v62, 16, v89
	v_cndmask_b32_e32 v35, v35, v38, vcc
	v_div_scale_f32 v38, s[8:9], v35, v35, 1.0
	v_rcp_f32_e32 v39, v38
	v_div_scale_f32 v37, vcc, 1.0, v35, 1.0
	v_fma_f32 v41, -v38, v39, 1.0
	v_fmac_f32_e32 v39, v41, v39
	v_mul_f32_e32 v41, v37, v39
	v_fma_f32 v42, -v38, v41, v37
	v_fmac_f32_e32 v41, v42, v39
	v_fma_f32 v37, -v38, v41, v37
	v_div_fmas_f32 v37, v37, v39, v41
	v_div_fixup_f32 v38, v37, v35, 1.0
; __device__ __forceinline__ unsigned cvtpk(float lo, float hi) { f32x2_t v = {lo, hi}; bf16x2_t b = __builtin_convertvector(v, bf16x2_t); return __builtin_bit_cast(unsigned, b); }
; __device__ __forceinline__ float bflo(unsigned w) { return __uint_as_float(w << 16); }
; __device__ __forceinline__ float bfhi(unsigned w) { return __uint_as_float(w & 0xffff0000u); }
;     __device__ __forceinline__ void operator()(const f32x4 (&acc)[2][2][4][2], const Unit& u, int wr, int wc, int fr, int fq) const {
;     ...
;             for (int m = 0; m < 4; ++m) {
;                 const int row = row0 + ai * HALF + m * 16;
;                 const float rkv = 1.0f / sqrtf(ssq_sum(ssq_in + (size_t)row * 16) * (1.0f / 256.0f) + EPS);
;                 const u32x4 kw = *(const u32x4*)(T1 + (size_t)row * 1024 + 768 + 8 * fq);
;                 float s = (bflo(kw.x) * bflo(kw.x) + bfhi(kw.x) * bfhi(kw.x)) + (bflo(kw.y) * bflo(kw.y) + bfhi(kw.y) * bfhi(kw.y))
;                         + (bflo(kw.z) * bflo(kw.z) + bfhi(kw.z) * bfhi(kw.z)) + (bflo(kw.w) * bflo(kw.w) + bfhi(kw.w) * bfhi(kw.w));
; #pragma unroll
;                 for (int bj = 0; bj < 2; ++bj)
; #pragma unroll
;                     for (int n = 0; n < 2; ++n) { const f32x4 v = acc[ai][bj][m][n] * rkv; s += (v[0] * v[0] + v[1] * v[1]) + (v[2] * v[2] + v[3] * v[3]); }
;                 s += __shfl_xor(s, 16); s += __shfl_xor(s, 32);
;                 const float rh = 1.0f / sqrtf(s * (1.0f / 96.0f) + EPS), rs = rkv * rh;
;                 rhs[ai * 4 + m] = rh;
;                 bf16_t* op = O + (size_t)row * 1536 + head * 96;
; #pragma unroll
;                 for (int bj = 0; bj < 2; ++bj) {
;                     const f32x4 g0 = *(const f32x4*)(gk + bj * 32 + 8 * fq), g1 = *(const f32x4*)(gk + bj * 32 + 8 * fq + 4);
;                     const f32x4 v0 = acc[ai][bj][m][0] * rs * g0, v1 = acc[ai][bj][m][1] * rs * g1;
;                     u32x4 w; w.x = cvtpk(v0[0], v0[1]); w.y = cvtpk(v0[2], v0[3]); w.z = cvtpk(v1[0], v1[1]); w.w = cvtpk(v1[2], v1[3]);
;                     *(u32x4*)(op + bj * 32 + 8 * fq) = w;
;                 }
;                 asm volatile("" ::: "memory");
	v_pk_mul_f32 v[42:43], v[28:29], v[38:39] op_sel_hi:[1,0]
	v_pk_mul_f32 v[44:45], v[30:31], v[38:39] op_sel_hi:[1,0]
	v_pk_mul_f32 v[46:47], v[24:25], v[38:39] op_sel_hi:[1,0]
	v_pk_mul_f32 v[54:55], v[26:27], v[38:39] op_sel_hi:[1,0]
	v_pk_mul_f32 v[58:59], v[18:19], v[38:39] op_sel_hi:[1,0]
	v_pk_mul_f32 v[60:61], v[16:17], v[38:39] op_sel_hi:[1,0]
	v_mov_b32_e32 v71, v43
	v_mul_f32_e32 v35, v44, v44
	v_mul_f32_e32 v37, v45, v45
	v_mov_b32_e32 v63, v42
	v_pk_mul_f32 v[42:43], v[54:55], v[54:55]
	v_pk_mul_f32 v[44:45], v[46:47], v[46:47]
	v_mul_f32_e32 v46, v60, v60
	v_mul_f32_e32 v54, v58, v58
	v_pk_mul_f32 v[70:71], v[70:71], v[70:71]
	v_pk_mov_b32 v[78:79], v[44:45], v[42:43] op_sel:[1,0]
	v_mov_b32_e32 v45, v43
	v_pk_fma_f32 v[42:43], v[60:61], v[60:61], v[46:47] op_sel_hi:[1,1,0]
	v_pk_fma_f32 v[46:47], v[58:59], v[58:59], v[54:55] op_sel_hi:[1,1,0]
	v_pk_fma_f32 v[54:55], v[62:63], v[62:63], v[70:71]
	v_pk_add_f32 v[34:35], v[34:35], v[36:37]
	v_pk_add_f32 v[36:37], v[78:79], v[44:45]
	v_pk_add_f32 v[34:35], v[54:55], v[34:35]
	v_pk_mul_f32 v[74:75], v[22:23], v[38:39] op_sel_hi:[1,0]
	v_pk_mul_f32 v[76:77], v[20:21], v[38:39] op_sel_hi:[1,0]
	v_pk_add_f32 v[36:37], v[36:37], v[36:37] op_sel_hi:[0,1]
	v_pk_add_f32 v[34:35], v[34:35], v[34:35] op_sel_hi:[0,1]
	v_mul_f32_e32 v42, v76, v76
	v_mul_f32_e32 v46, v77, v77
	v_mul_f32_e32 v36, v74, v74
	v_mul_f32_e32 v34, v75, v75
	v_pk_add_f32 v[42:43], v[42:43], v[46:47]
	v_pk_add_f32 v[34:35], v[36:37], v[34:35]
	s_nop 0
	v_pk_add_f32 v[34:35], v[42:43], v[34:35]
	s_nop 0
	v_add_f32_e32 v34, v34, v35
	ds_bpermute_b32 v35, v163, v34
	s_waitcnt lgkmcnt(0)
	v_add_f32_e32 v34, v34, v35
	ds_bpermute_b32 v35, v141, v34
	s_waitcnt lgkmcnt(0)
	v_add_f32_e32 v34, v34, v35
	v_fmamk_f32 v34, v34, 0x3c2aaaab, v158
	v_mul_f32_e32 v35, 0x4f800000, v34
	v_cmp_gt_f32_e32 vcc, s66, v34
	s_nop 1
	v_cndmask_b32_e32 v36, v34, v35, vcc
	v_sqrt_f32_e32 v37, v36
	v_mad_i64_i32 v[34:35], s[8:9], v40, s67, v[152:153]
	v_lshl_add_u64 v[34:35], v[34:35], 0, s[44:45]
	v_add_u32_e32 v39, -1, v37
	v_add_u32_e32 v41, 1, v37
	v_fma_f32 v42, -v39, v37, v36
	v_fma_f32 v43, -v41, v37, v36
	v_cmp_ge_f32_e64 s[8:9], 0, v42
	v_lshl_add_u64 v[34:35], v[34:35], 0, v[146:147]
	s_nop 0
	v_cndmask_b32_e64 v37, v37, v39, s[8:9]
	v_cmp_lt_f32_e64 s[8:9], 0, v43
	s_nop 1
	v_cndmask_b32_e64 v37, v37, v41, s[8:9]
	v_mul_f32_e32 v39, 0x37800000, v37
	v_cndmask_b32_e32 v37, v37, v39, vcc
	v_cmp_class_f32_e32 vcc, v36, v159
	s_nop 1
	v_cndmask_b32_e32 v36, v37, v36, vcc
	v_div_scale_f32 v37, s[8:9], v36, v36, 1.0
	v_rcp_f32_e32 v39, v37
	v_div_scale_f32 v41, vcc, 1.0, v36, 1.0
	v_fma_f32 v42, -v37, v39, 1.0
	v_fmac_f32_e32 v39, v42, v39
	v_mul_f32_e32 v42, v41, v39
	v_fma_f32 v43, -v37, v42, v41
	v_fmac_f32_e32 v42, v43, v39
	v_fma_f32 v37, -v37, v42, v41
	v_div_fmas_f32 v37, v37, v39, v42
	v_div_fixup_f32 v36, v37, v36, 1.0
	v_mul_f32_e32 v38, v38, v36
	v_pk_mul_f32 v[28:29], v[28:29], v[38:39] op_sel_hi:[1,0]
	v_pk_mul_f32 v[30:31], v[30:31], v[38:39] op_sel_hi:[1,0]
	v_pk_mul_f32 v[24:25], v[24:25], v[38:39] op_sel_hi:[1,0]
	v_pk_mul_f32 v[26:27], v[26:27], v[38:39] op_sel_hi:[1,0]
	s_waitcnt vmcnt(0)
	v_pk_mul_f32 v[30:31], v[104:105], v[30:31]
	v_pk_mul_f32 v[28:29], v[102:103], v[28:29]
	v_pk_mul_f32 v[42:43], v[92:93], v[26:27]
	v_pk_mul_f32 v[26:27], v[90:91], v[24:25]
	v_cvt_pk_bf16_f32 v24, v28, v29
	v_cvt_pk_bf16_f32 v25, v30, v31
	v_cvt_pk_bf16_f32 v26, v26, v27
	v_cvt_pk_bf16_f32 v27, v42, v43
	global_store_dwordx4 v[34:35], v[24:27], off
	global_load_dwordx4 v[26:29], v[150:151], off offset:128
	s_nop 0
	global_load_dwordx4 v[42:45], v[150:151], off offset:144
	v_pk_mul_f32 v[16:17], v[16:17], v[38:39] op_sel_hi:[1,0]
	v_pk_mul_f32 v[18:19], v[18:19], v[38:39] op_sel_hi:[1,0]
	v_pk_mul_f32 v[20:21], v[20:21], v[38:39] op_sel_hi:[1,0]
	v_pk_mul_f32 v[22:23], v[22:23], v[38:39] op_sel_hi:[1,0]
	v_add_u32_e32 v24, 0xb0, v140
	v_ashrrev_i32_e32 v25, 31, v24
	v_lshlrev_b64 v[30:31], 6, v[24:25]
	v_lshl_add_u64 v[30:31], s[14:15], 0, v[30:31]
	s_waitcnt vmcnt(1)
	v_pk_mul_f32 v[18:19], v[28:29], v[18:19]
	v_pk_mul_f32 v[16:17], v[26:27], v[16:17]
	s_waitcnt vmcnt(0)
	v_pk_mul_f32 v[22:23], v[44:45], v[22:23]
	v_pk_mul_f32 v[20:21], v[42:43], v[20:21]
	v_cvt_pk_bf16_f32 v16, v16, v17
	v_cvt_pk_bf16_f32 v17, v18, v19
	v_cvt_pk_bf16_f32 v18, v20, v21
	v_cvt_pk_bf16_f32 v19, v22, v23
	global_store_dwordx4 v[34:35], v[16:19], off offset:64
	s_nop 1
	ds_read_b32 v18, v253 offset:704
	v_mov_b32_e32 v19, 0
	v_mov_b32_e32 v20, 0
	v_mov_b32_e32 v21, 0
	v_mov_b32_e32 v42, 0
	v_mov_b32_e32 v43, 0
	v_mov_b32_e32 v44, 0
	v_mov_b32_e32 v45, 0
	v_mov_b32_e32 v26, 0
	v_mov_b32_e32 v27, 0
	v_mov_b32_e32 v28, 0
	v_mov_b32_e32 v29, 0
	v_mov_b32_e32 v58, 0
	v_mov_b32_e32 v59, 0
	v_mov_b32_e32 v60, 0
	v_mov_b32_e32 v61, 0
	s_waitcnt lgkmcnt(0)
	v_lshlrev_b64 v[16:17], 11, v[24:25]
	v_lshl_add_u64 v[16:17], s[10:11], 0, v[16:17]
	v_lshl_add_u64 v[16:17], v[16:17], 0, v[146:147]
	global_load_dwordx4 v[74:77], v[16:17], off offset:1536
	global_load_dwordx4 v[86:89], v[150:151], off offset:16
	global_load_dwordx4 v[90:93], v[150:151], off
	s_waitcnt vmcnt(6)
	v_mov_b32_e32 v22, v18
	s_waitcnt vmcnt(5)
	v_mov_b32_e32 v23, v26
	v_mov_b32_e32 v26, v19
	v_mov_b32_e32 v18, v20
	v_mov_b32_e32 v19, v28
	v_mov_b32_e32 v28, v21
	s_waitcnt vmcnt(4)
	v_mov_b32_e32 v20, v42
	s_waitcnt vmcnt(3)
	v_mov_b32_e32 v21, v58
	v_mov_b32_e32 v58, v43
	v_mov_b32_e32 v30, v44
	v_mov_b32_e32 v31, v60
	v_mov_b32_e32 v60, v45
	v_pk_add_f32 v[22:23], v[22:23], v[26:27]
	v_pk_add_f32 v[18:19], v[18:19], v[28:29]
	v_pk_add_f32 v[20:21], v[20:21], v[58:59]
	v_pk_add_f32 v[26:27], v[30:31], v[60:61]
	v_pk_add_f32 v[18:19], v[22:23], v[18:19]
	v_pk_add_f32 v[20:21], v[20:21], v[26:27]
	s_waitcnt vmcnt(2)
; __device__ __forceinline__ unsigned cvtpk(float lo, float hi) { f32x2_t v = {lo, hi}; bf16x2_t b = __builtin_convertvector(v, bf16x2_t); return __builtin_bit_cast(unsigned, b); }
; __device__ __forceinline__ float bflo(unsigned w) { return __uint_as_float(w << 16); }
; __device__ __forceinline__ float bfhi(unsigned w) { return __uint_as_float(w & 0xffff0000u); }
;     __device__ __forceinline__ void operator()(const f32x4 (&acc)[2][2][4][2], const Unit& u, int wr, int wc, int fr, int fq) const {
;     ...
;             for (int m = 0; m < 4; ++m) {
;                 const int row = row0 + ai * HALF + m * 16;
;                 const float rkv = 1.0f / sqrtf(ssq_sum(ssq_in + (size_t)row * 16) * (1.0f / 256.0f) + EPS);
;                 const u32x4 kw = *(const u32x4*)(T1 + (size_t)row * 1024 + 768 + 8 * fq);
;                 float s = (bflo(kw.x) * bflo(kw.x) + bfhi(kw.x) * bfhi(kw.x)) + (bflo(kw.y) * bflo(kw.y) + bfhi(kw.y) * bfhi(kw.y))
;                         + (bflo(kw.z) * bflo(kw.z) + bfhi(kw.z) * bfhi(kw.z)) + (bflo(kw.w) * bflo(kw.w) + bfhi(kw.w) * bfhi(kw.w));
; #pragma unroll
;                 for (int bj = 0; bj < 2; ++bj)
; #pragma unroll
;                     for (int n = 0; n < 2; ++n) { const f32x4 v = acc[ai][bj][m][n] * rkv; s += (v[0] * v[0] + v[1] * v[1]) + (v[2] * v[2] + v[3] * v[3]); }
;                 s += __shfl_xor(s, 16); s += __shfl_xor(s, 32);
;                 const float rh = 1.0f / sqrtf(s * (1.0f / 96.0f) + EPS), rs = rkv * rh;
;                 rhs[ai * 4 + m] = rh;
;                 bf16_t* op = O + (size_t)row * 1536 + head * 96;
; #pragma unroll
;                 for (int bj = 0; bj < 2; ++bj) {
;                     const f32x4 g0 = *(const f32x4*)(gk + bj * 32 + 8 * fq), g1 = *(const f32x4*)(gk + bj * 32 + 8 * fq + 4);
;                     const f32x4 v0 = acc[ai][bj][m][0] * rs * g0, v1 = acc[ai][bj][m][1] * rs * g1;
;                     u32x4 w; w.x = cvtpk(v0[0], v0[1]); w.y = cvtpk(v0[2], v0[3]); w.z = cvtpk(v1[0], v1[1]); w.w = cvtpk(v1[2], v1[3]);
;                     *(u32x4*)(op + bj * 32 + 8 * fq) = w;
;                 }
;                 asm volatile("" ::: "memory");
;             }
;         const f32x4 gr0 = *(const f32x4*)(gk + 64 + 8 * fq), gr1 = *(const f32x4*)(gk + 64 + 8 * fq + 4);
	v_and_b32_e32 v45, 0xffff0000, v76
	v_pk_add_f32 v[18:19], v[18:19], v[20:21]
	v_lshlrev_b32_e32 v44, 16, v76
	v_add_f32_e32 v18, v18, v19
	v_fmamk_f32 v18, v18, 0x3b800000, v158
	v_mul_f32_e32 v19, 0x4f800000, v18
	v_cmp_gt_f32_e32 vcc, s66, v18
	v_and_b32_e32 v43, 0xffff0000, v75
	v_and_b32_e32 v42, 0xffff0000, v74
	v_cndmask_b32_e32 v22, v18, v19, vcc
	v_sqrt_f32_e32 v23, v22
	v_mul_f32_e32 v18, v45, v45
	v_pk_fma_f32 v[18:19], v[44:45], v[44:45], v[18:19] op_sel_hi:[1,1,0]
	v_lshlrev_b32_e32 v39, 16, v75
	v_add_u32_e32 v19, -1, v23
	v_add_u32_e32 v25, 1, v23
	v_fma_f32 v26, -v19, v23, v22
	v_fma_f32 v27, -v25, v23, v22
	v_cmp_ge_f32_e64 s[8:9], 0, v26
	v_lshlrev_b32_e32 v38, 16, v74
	v_pk_mul_f32 v[28:29], v[42:43], v[42:43]
	v_cndmask_b32_e64 v19, v23, v19, s[8:9]
	v_cmp_lt_f32_e64 s[8:9], 0, v27
	v_pk_fma_f32 v[20:21], v[38:39], v[38:39], v[28:29]
	v_and_b32_e32 v54, 0xffff0000, v77
	v_cndmask_b32_e64 v19, v19, v25, s[8:9]
	v_mul_f32_e32 v23, 0x37800000, v19
	v_cndmask_b32_e32 v19, v19, v23, vcc
	v_cmp_class_f32_e32 vcc, v22, v159
	v_pk_add_f32 v[20:21], v[20:21], v[20:21] op_sel:[0,1] op_sel_hi:[1,0]
	v_lshlrev_b32_e32 v46, 16, v77
	v_cndmask_b32_e32 v19, v19, v22, vcc
	v_div_scale_f32 v22, s[8:9], v19, v19, 1.0
	v_rcp_f32_e32 v23, v22
	v_div_scale_f32 v21, vcc, 1.0, v19, 1.0
	v_fma_f32 v25, -v22, v23, 1.0
	v_fmac_f32_e32 v23, v25, v23
	v_mul_f32_e32 v25, v21, v23
	v_fma_f32 v26, -v22, v25, v21
	v_fmac_f32_e32 v25, v26, v23
	v_fma_f32 v21, -v22, v25, v21
	v_div_fmas_f32 v21, v21, v23, v25
	v_div_fixup_f32 v22, v21, v19, 1.0
	v_pk_mul_f32 v[26:27], v[12:13], v[22:23] op_sel_hi:[1,0]
	v_pk_mul_f32 v[28:29], v[14:15], v[22:23] op_sel_hi:[1,0]
	v_pk_mul_f32 v[30:31], v[8:9], v[22:23] op_sel_hi:[1,0]
	v_pk_mul_f32 v[38:39], v[10:11], v[22:23] op_sel_hi:[1,0]
	v_pk_mul_f32 v[42:43], v[2:3], v[22:23] op_sel_hi:[1,0]
	v_pk_mul_f32 v[44:45], v[0:1], v[22:23] op_sel_hi:[1,0]
	v_mov_b32_e32 v55, v27
	v_mul_f32_e32 v19, v28, v28
	v_mul_f32_e32 v21, v29, v29
	v_mov_b32_e32 v47, v26
	v_pk_mul_f32 v[26:27], v[38:39], v[38:39]
	v_pk_mul_f32 v[28:29], v[30:31], v[30:31]
	v_mul_f32_e32 v30, v44, v44
	v_mul_f32_e32 v38, v42, v42
	v_pk_mul_f32 v[54:55], v[54:55], v[54:55]
	v_pk_mov_b32 v[62:63], v[28:29], v[26:27] op_sel:[1,0]
	v_mov_b32_e32 v29, v27
	v_pk_fma_f32 v[26:27], v[44:45], v[44:45], v[30:31] op_sel_hi:[1,1,0]
	v_pk_fma_f32 v[30:31], v[42:43], v[42:43], v[38:39] op_sel_hi:[1,1,0]
	v_pk_fma_f32 v[38:39], v[46:47], v[46:47], v[54:55]
	v_pk_add_f32 v[18:19], v[18:19], v[20:21]
	v_pk_add_f32 v[20:21], v[62:63], v[28:29]
	v_pk_add_f32 v[18:19], v[38:39], v[18:19]
	v_pk_mul_f32 v[58:59], v[6:7], v[22:23] op_sel_hi:[1,0]
	v_pk_mul_f32 v[60:61], v[4:5], v[22:23] op_sel_hi:[1,0]
	v_pk_add_f32 v[20:21], v[20:21], v[20:21] op_sel_hi:[0,1]
	v_pk_add_f32 v[18:19], v[18:19], v[18:19] op_sel_hi:[0,1]
	v_mul_f32_e32 v26, v60, v60
	v_mul_f32_e32 v30, v61, v61
	v_mul_f32_e32 v20, v58, v58
	v_mul_f32_e32 v18, v59, v59
	v_pk_add_f32 v[26:27], v[26:27], v[30:31]
	v_pk_add_f32 v[18:19], v[20:21], v[18:19]
	s_nop 0
	v_pk_add_f32 v[18:19], v[26:27], v[18:19]
	s_nop 0
	v_add_f32_e32 v18, v18, v19
	ds_bpermute_b32 v19, v163, v18
	s_waitcnt lgkmcnt(0)
	v_add_f32_e32 v18, v18, v19
	ds_bpermute_b32 v19, v141, v18
	s_waitcnt lgkmcnt(0)
	v_add_f32_e32 v18, v18, v19
	v_fmamk_f32 v18, v18, 0x3c2aaaab, v158
	v_mul_f32_e32 v19, 0x4f800000, v18
	v_cmp_gt_f32_e32 vcc, s66, v18
	s_nop 1
	v_cndmask_b32_e32 v20, v18, v19, vcc
	v_sqrt_f32_e32 v21, v20
	v_mad_i64_i32 v[18:19], s[8:9], v24, s67, v[152:153]
	v_lshl_add_u64 v[18:19], v[18:19], 0, s[44:45]
	v_add_u32_e32 v23, -1, v21
	v_add_u32_e32 v25, 1, v21
	v_fma_f32 v26, -v23, v21, v20
	v_fma_f32 v27, -v25, v21, v20
	v_cmp_ge_f32_e64 s[8:9], 0, v26
	v_lshl_add_u64 v[18:19], v[18:19], 0, v[146:147]
	s_nop 0
	v_cndmask_b32_e64 v21, v21, v23, s[8:9]
	v_cmp_lt_f32_e64 s[8:9], 0, v27
	s_nop 1
	v_cndmask_b32_e64 v21, v21, v25, s[8:9]
	v_mul_f32_e32 v23, 0x37800000, v21
	v_cndmask_b32_e32 v21, v21, v23, vcc
	v_cmp_class_f32_e32 vcc, v20, v159
	s_nop 1
	v_cndmask_b32_e32 v20, v21, v20, vcc
	v_div_scale_f32 v21, s[8:9], v20, v20, 1.0
	v_rcp_f32_e32 v23, v21
	v_div_scale_f32 v25, vcc, 1.0, v20, 1.0
	s_getpc_b64 s[8:9]
	s_add_u32 s8, s8, _ZL8ROPE_REV@rel32@lo+4
	s_addc_u32 s9, s9, _ZL8ROPE_REV@rel32@hi+12
	v_fma_f32 v26, -v21, v23, 1.0
	v_fmac_f32_e32 v23, v26, v23
	v_mul_f32_e32 v26, v25, v23
	v_fma_f32 v27, -v21, v26, v25
	v_fmac_f32_e32 v26, v27, v23
	v_fma_f32 v21, -v21, v26, v25
	v_div_fmas_f32 v21, v21, v23, v26
	v_div_fixup_f32 v20, v21, v20, 1.0
	v_mul_f32_e32 v22, v22, v20
	v_pk_mul_f32 v[12:13], v[12:13], v[22:23] op_sel_hi:[1,0]
	v_pk_mul_f32 v[14:15], v[14:15], v[22:23] op_sel_hi:[1,0]
	v_pk_mul_f32 v[8:9], v[8:9], v[22:23] op_sel_hi:[1,0]
	v_pk_mul_f32 v[10:11], v[10:11], v[22:23] op_sel_hi:[1,0]
	s_waitcnt vmcnt(0)
	v_pk_mul_f32 v[14:15], v[92:93], v[14:15]
	v_pk_mul_f32 v[12:13], v[90:91], v[12:13]
	v_pk_mul_f32 v[26:27], v[88:89], v[10:11]
	v_pk_mul_f32 v[10:11], v[86:87], v[8:9]
	v_cvt_pk_bf16_f32 v8, v12, v13
	v_cvt_pk_bf16_f32 v9, v14, v15
	v_cvt_pk_bf16_f32 v10, v10, v11
	v_cvt_pk_bf16_f32 v11, v26, v27
	global_store_dwordx4 v[18:19], v[8:11], off
	global_load_dwordx4 v[8:11], v[150:151], off offset:128
	s_nop 0
	global_load_dwordx4 v[12:15], v[150:151], off offset:144
	v_pk_mul_f32 v[0:1], v[0:1], v[22:23] op_sel_hi:[1,0]
	v_pk_mul_f32 v[2:3], v[2:3], v[22:23] op_sel_hi:[1,0]
	v_pk_mul_f32 v[4:5], v[4:5], v[22:23] op_sel_hi:[1,0]
	v_pk_mul_f32 v[6:7], v[6:7], v[22:23] op_sel_hi:[1,0]
	v_and_b32_e32 v21, 16, v162
	v_lshlrev_b32_e32 v21, 3, v21
	v_cmp_gt_i32_e32 vcc, 2, v160
	s_waitcnt vmcnt(1)
; __device__ __forceinline__ unsigned cvtpk(float lo, float hi) { f32x2_t v = {lo, hi}; bf16x2_t b = __builtin_convertvector(v, bf16x2_t); return __builtin_bit_cast(unsigned, b); }
; __device__ __forceinline__ float bflo(unsigned w) { return __uint_as_float(w << 16); }
; __device__ __forceinline__ float bfhi(unsigned w) { return __uint_as_float(w & 0xffff0000u); }
; __device__ __forceinline__ void rope_cs(int pos, int idx64, float& cs, float& sn) {
;     const double rev = (double)pos * ROPE_REV[idx64];
;     const float fr = (float)(rev - __builtin_rint(rev));
;     cs = __builtin_amdgcn_cosf(fr); sn = __builtin_amdgcn_sinf(fr);
;     asm volatile("" : "+v"(cs), "+v"(sn));
;     __device__ __forceinline__ void operator()(const f32x4 (&acc)[2][2][4][2], const Unit& u, int wr, int wc, int fr, int fq) const {
;     ...
;         const f32x4 gr0 = *(const f32x4*)(gk + 64 + 8 * fq), gr1 = *(const f32x4*)(gk + 64 + 8 * fq + 4);
; #pragma unroll
;         for (int ai = 0; ai < 2; ++ai)
; #pragma unroll
;             for (int m = 0; m < 4; ++m) {
;                 const int row = row0 + ai * HALF + m * 16; const int pos = row & (SEQ - 1);
;                 const float rh = rhs[ai * 4 + m];
;                 const u32x4 kw = *(const u32x4*)(T1 + (size_t)row * 1024 + 768 + 8 * fq);
;                 const float kr[8] = {bflo(kw.x), bfhi(kw.x), bflo(kw.y), bfhi(kw.y), bflo(kw.z), bfhi(kw.z), bflo(kw.w), bfhi(kw.w)};
;                 float ro[8];
; #pragma unroll
;                 for (int j = 0; j < 8; ++j) {
;                     const float x = kr[j] * rh * (j < 4 ? gr0[j & 3] : gr1[j & 3]);
;                     const float px = __shfl_xor(x, 32);
;                     float cs, sn; rope_cs(pos, 2 * (8 * (fq & 1) + j), cs, sn);
;                     ro[j] = (fq < 2) ? (x * cs - px * sn) : (px * sn + x * cs);
;                 }
;                 u32x4 w; w.x = cvtpk(ro[0], ro[1]); w.y = cvtpk(ro[2], ro[3]); w.z = cvtpk(ro[4], ro[5]); w.w = cvtpk(ro[6], ro[7]);
;                 *(u32x4*)(O + (size_t)row * 1536 + head * 96 + 64 + 8 * fq) = w;
;                 asm volatile("" ::: "memory");
	v_pk_mul_f32 v[2:3], v[10:11], v[2:3]
	v_pk_mul_f32 v[0:1], v[8:9], v[0:1]
	s_waitcnt vmcnt(0)
	v_pk_mul_f32 v[6:7], v[14:15], v[6:7]
	v_pk_mul_f32 v[4:5], v[12:13], v[4:5]
	v_cvt_pk_bf16_f32 v0, v0, v1
	v_cvt_pk_bf16_f32 v1, v2, v3
	v_cvt_pk_bf16_f32 v2, v4, v5
	v_cvt_pk_bf16_f32 v3, v6, v7
	global_store_dwordx4 v[18:19], v[0:3], off offset:64
	global_load_dwordx2 v[8:9], v21, s[8:9]
	s_getpc_b64 s[8:9]
	s_add_u32 s8, s8, _ZL8ROPE_REV@rel32@lo+20
	s_addc_u32 s9, s9, _ZL8ROPE_REV@rel32@hi+28
	v_mov_b32_e32 v0, s37
	v_bitop3_b32 v0, v161, s68, v0 bitop3:0xc8
	v_cvt_f64_u32_e32 v[38:39], v0
	s_waitcnt vmcnt(0)
	v_mul_f64 v[0:1], v[8:9], v[38:39]
	v_rndne_f64_e32 v[0:1], v[0:1]
	v_fma_f64 v[0:1], v[8:9], v[38:39], -v[0:1]
	v_cvt_f32_f64_e32 v0, v[0:1]
	v_cos_f32_e32 v46, v0
	v_sin_f32_e32 v54, v0
	global_load_dwordx4 v[0:3], v[150:151], off offset:272
	global_load_dwordx4 v[4:7], v[150:151], off offset:256
	global_load_dwordx4 v[42:45], v[142:143], off offset:1536
	global_load_dwordx2 v[10:11], v21, s[8:9]
	s_getpc_b64 s[8:9]
	s_add_u32 s8, s8, _ZL8ROPE_REV@rel32@lo+36
	s_addc_u32 s9, s9, _ZL8ROPE_REV@rel32@hi+44
	s_waitcnt vmcnt(1)
	v_lshlrev_b32_e32 v78, 16, v42
	v_and_b32_e32 v79, 0xffff0000, v42
	s_waitcnt vmcnt(0)
	v_mul_f64 v[12:13], v[10:11], v[38:39]
	v_rndne_f64_e32 v[12:13], v[12:13]
	v_fma_f64 v[12:13], v[10:11], v[38:39], -v[12:13]
	v_cvt_f32_f64_e32 v12, v[12:13]
	v_cos_f32_e32 v47, v12
	v_sin_f32_e32 v55, v12
	global_load_dwordx2 v[14:15], v21, s[8:9]
	s_getpc_b64 s[8:9]
	s_add_u32 s8, s8, _ZL8ROPE_REV@rel32@lo+52
	s_addc_u32 s9, s9, _ZL8ROPE_REV@rel32@hi+60
	v_lshlrev_b32_e32 v42, 16, v43
	v_and_b32_e32 v43, 0xffff0000, v43
	v_pk_mul_f32 v[78:79], v[148:149], v[78:79] op_sel_hi:[0,1]
	v_lshlrev_b32_e32 v86, 16, v44
	v_and_b32_e32 v87, 0xffff0000, v44
	v_lshlrev_b32_e32 v44, 16, v45
	v_and_b32_e32 v45, 0xffff0000, v45
	v_pk_mul_f32 v[42:43], v[148:149], v[42:43] op_sel_hi:[0,1]
	v_pk_mul_f32 v[78:79], v[4:5], v[78:79]
	v_pk_mul_f32 v[44:45], v[148:149], v[44:45] op_sel_hi:[0,1]
	v_pk_mul_f32 v[88:89], v[6:7], v[42:43]
	ds_bpermute_b32 v42, v141, v78
	ds_bpermute_b32 v43, v141, v79
	v_pk_mul_f32 v[90:91], v[2:3], v[44:45]
	ds_bpermute_b32 v44, v141, v88
	ds_bpermute_b32 v45, v141, v89
	v_pk_mul_f32 v[86:87], v[148:149], v[86:87] op_sel_hi:[0,1]
	v_pk_mul_f32 v[86:87], v[0:1], v[86:87]
	ds_bpermute_b32 v92, v141, v86
	ds_bpermute_b32 v93, v141, v87
	s_waitcnt lgkmcnt(4)
	v_pk_mul_f32 v[42:43], v[54:55], v[42:43]
	ds_bpermute_b32 v94, v141, v90
	v_cndmask_b32_e64 v43, v43, -v43, vcc
	v_cndmask_b32_e64 v42, v42, -v42, vcc
	ds_bpermute_b32 v95, v141, v91
	v_pk_fma_f32 v[42:43], v[46:47], v[78:79], v[42:43]
	s_waitcnt vmcnt(0)
	v_mul_f64 v[12:13], v[14:15], v[38:39]
	v_rndne_f64_e32 v[12:13], v[12:13]
	v_fma_f64 v[12:13], v[14:15], v[38:39], -v[12:13]
	v_cvt_f32_f64_e32 v12, v[12:13]
	v_cos_f32_e32 v58, v12
	v_sin_f32_e32 v60, v12
	global_load_dwordx2 v[22:23], v21, s[8:9]
	s_getpc_b64 s[8:9]
	s_add_u32 s8, s8, _ZL8ROPE_REV@rel32@lo+68
	s_addc_u32 s9, s9, _ZL8ROPE_REV@rel32@hi+76
	v_cvt_pk_bf16_f32 v42, v42, v43
	s_waitcnt vmcnt(0)
	v_mul_f64 v[12:13], v[22:23], v[38:39]
	v_rndne_f64_e32 v[12:13], v[12:13]
	v_fma_f64 v[12:13], v[22:23], v[38:39], -v[12:13]
	v_cvt_f32_f64_e32 v12, v[12:13]
	v_cos_f32_e32 v59, v12
	v_sin_f32_e32 v61, v12
	global_load_dwordx2 v[26:27], v21, s[8:9]
	s_getpc_b64 s[8:9]
	s_add_u32 s8, s8, _ZL8ROPE_REV@rel32@lo+84
	s_addc_u32 s9, s9, _ZL8ROPE_REV@rel32@hi+92
	s_waitcnt lgkmcnt(4)
	v_pk_mul_f32 v[44:45], v[60:61], v[44:45]
	s_waitcnt vmcnt(0)
	v_mul_f64 v[12:13], v[26:27], v[38:39]
	v_rndne_f64_e32 v[12:13], v[12:13]
	v_fma_f64 v[12:13], v[26:27], v[38:39], -v[12:13]
	v_cvt_f32_f64_e32 v12, v[12:13]
	v_cos_f32_e32 v62, v12
	v_sin_f32_e32 v70, v12
	global_load_dwordx2 v[28:29], v21, s[8:9]
	s_getpc_b64 s[8:9]
	s_add_u32 s8, s8, _ZL8ROPE_REV@rel32@lo+100
	s_addc_u32 s9, s9, _ZL8ROPE_REV@rel32@hi+108
	v_cndmask_b32_e64 v45, v45, -v45, vcc
	v_cndmask_b32_e64 v44, v44, -v44, vcc
	v_pk_fma_f32 v[44:45], v[88:89], v[58:59], v[44:45]
	s_waitcnt vmcnt(0)
	v_mul_f64 v[12:13], v[28:29], v[38:39]
	v_rndne_f64_e32 v[12:13], v[12:13]
	v_fma_f64 v[12:13], v[28:29], v[38:39], -v[12:13]
	v_cvt_f32_f64_e32 v12, v[12:13]
	v_cos_f32_e32 v63, v12
	v_sin_f32_e32 v71, v12
	global_load_dwordx2 v[30:31], v21, s[8:9]
	s_getpc_b64 s[8:9]
	s_add_u32 s8, s8, _ZL8ROPE_REV@rel32@lo+116
	s_addc_u32 s9, s9, _ZL8ROPE_REV@rel32@hi+124
	v_cvt_pk_bf16_f32 v43, v44, v45
	s_waitcnt lgkmcnt(2)
	v_pk_mul_f32 v[44:45], v[70:71], v[92:93]
	s_waitcnt vmcnt(0)
	v_mul_f64 v[12:13], v[30:31], v[38:39]
	v_rndne_f64_e32 v[12:13], v[12:13]
	v_fma_f64 v[12:13], v[30:31], v[38:39], -v[12:13]
	v_cvt_f32_f64_e32 v12, v[12:13]
	v_cos_f32_e32 v74, v12
	v_sin_f32_e32 v76, v12
	global_load_dwordx2 v[12:13], v21, s[8:9]
	v_cndmask_b32_e64 v45, v45, -v45, vcc
	v_cndmask_b32_e64 v44, v44, -v44, vcc
	s_waitcnt vmcnt(0)
	v_mul_f64 v[46:47], v[12:13], v[38:39]
	v_rndne_f64_e32 v[46:47], v[46:47]
	v_fma_f64 v[38:39], v[12:13], v[38:39], -v[46:47]
	v_cvt_f32_f64_e32 v21, v[38:39]
	v_cos_f32_e32 v75, v21
	v_sin_f32_e32 v77, v21
	v_pk_fma_f32 v[38:39], v[86:87], v[62:63], v[44:45]
	v_bitop3_b32 v21, v140, s69, 16 bitop3:0xc8
	v_cvt_pk_bf16_f32 v44, v38, v39
	s_waitcnt lgkmcnt(0)
; __device__ __forceinline__ unsigned cvtpk(float lo, float hi) { f32x2_t v = {lo, hi}; bf16x2_t b = __builtin_convertvector(v, bf16x2_t); return __builtin_bit_cast(unsigned, b); }
; __device__ __forceinline__ float bflo(unsigned w) { return __uint_as_float(w << 16); }
; __device__ __forceinline__ float bfhi(unsigned w) { return __uint_as_float(w & 0xffff0000u); }
;     __device__ __forceinline__ void operator()(const f32x4 (&acc)[2][2][4][2], const Unit& u, int wr, int wc, int fr, int fq) const {
;     ...
; #pragma unroll
;         for (int ai = 0; ai < 2; ++ai)
; #pragma unroll
;             for (int m = 0; m < 4; ++m) {
;                 const int row = row0 + ai * HALF + m * 16; const int pos = row & (SEQ - 1);
;                 const float rh = rhs[ai * 4 + m];
;                 const u32x4 kw = *(const u32x4*)(T1 + (size_t)row * 1024 + 768 + 8 * fq);
;                 const float kr[8] = {bflo(kw.x), bfhi(kw.x), bflo(kw.y), bfhi(kw.y), bflo(kw.z), bfhi(kw.z), bflo(kw.w), bfhi(kw.w)};
;                 float ro[8];
; #pragma unroll
;                 for (int j = 0; j < 8; ++j) {
;                     const float x = kr[j] * rh * (j < 4 ? gr0[j & 3] : gr1[j & 3]);
;                     const float px = __shfl_xor(x, 32);
;                     float cs, sn; rope_cs(pos, 2 * (8 * (fq & 1) + j), cs, sn);
;                     ro[j] = (fq < 2) ? (x * cs - px * sn) : (px * sn + x * cs);
;                 }
;                 u32x4 w; w.x = cvtpk(ro[0], ro[1]); w.y = cvtpk(ro[2], ro[3]); w.z = cvtpk(ro[4], ro[5]); w.w = cvtpk(ro[6], ro[7]);
;                 *(u32x4*)(O + (size_t)row * 1536 + head * 96 + 64 + 8 * fq) = w;
;                 asm volatile("" ::: "memory");
	v_pk_mul_f32 v[38:39], v[76:77], v[94:95]
	s_nop 0
	v_cndmask_b32_e64 v39, v39, -v39, vcc
	v_cndmask_b32_e64 v38, v38, -v38, vcc
	v_pk_fma_f32 v[38:39], v[90:91], v[74:75], v[38:39]
	s_nop 0
	v_cvt_pk_bf16_f32 v45, v38, v39
	global_store_dwordx4 v[144:145], v[42:45], off offset:128
	global_load_dwordx4 v[42:45], v[112:113], off offset:1536
	v_cvt_f64_u32_e32 v[38:39], v21
	v_mul_f64 v[46:47], v[8:9], v[38:39]
	v_rndne_f64_e32 v[46:47], v[46:47]
	v_mul_f64 v[58:59], v[10:11], v[38:39]
	v_fma_f64 v[46:47], v[8:9], v[38:39], -v[46:47]
	v_rndne_f64_e32 v[58:59], v[58:59]
	v_cvt_f32_f64_e32 v21, v[46:47]
	v_fma_f64 v[58:59], v[10:11], v[38:39], -v[58:59]
	v_cos_f32_e32 v46, v21
	v_sin_f32_e32 v54, v21
	v_cvt_f32_f64_e32 v21, v[58:59]
	v_mul_f64 v[58:59], v[14:15], v[38:39]
	v_rndne_f64_e32 v[58:59], v[58:59]
	v_mul_f64 v[62:63], v[22:23], v[38:39]
	v_fma_f64 v[58:59], v[14:15], v[38:39], -v[58:59]
	v_rndne_f64_e32 v[62:63], v[62:63]
	v_cos_f32_e32 v47, v21
	v_sin_f32_e32 v55, v21
	v_cvt_f32_f64_e32 v21, v[58:59]
	v_fma_f64 v[62:63], v[22:23], v[38:39], -v[62:63]
	v_cos_f32_e32 v58, v21
	v_sin_f32_e32 v60, v21
	v_cvt_f32_f64_e32 v21, v[62:63]
	v_mul_f64 v[62:63], v[26:27], v[38:39]
	v_rndne_f64_e32 v[62:63], v[62:63]
	v_mul_f64 v[74:75], v[28:29], v[38:39]
	v_fma_f64 v[62:63], v[26:27], v[38:39], -v[62:63]
	v_rndne_f64_e32 v[74:75], v[74:75]
	v_cos_f32_e32 v59, v21
	v_sin_f32_e32 v61, v21
	v_cvt_f32_f64_e32 v21, v[62:63]
	v_fma_f64 v[74:75], v[28:29], v[38:39], -v[74:75]
	v_cos_f32_e32 v62, v21
	v_sin_f32_e32 v70, v21
	v_cvt_f32_f64_e32 v21, v[74:75]
	v_mul_f64 v[74:75], v[30:31], v[38:39]
	v_rndne_f64_e32 v[74:75], v[74:75]
	v_mul_f64 v[78:79], v[12:13], v[38:39]
	v_fma_f64 v[74:75], v[30:31], v[38:39], -v[74:75]
	v_rndne_f64_e32 v[78:79], v[78:79]
	v_cos_f32_e32 v63, v21
	v_sin_f32_e32 v71, v21
	v_cvt_f32_f64_e32 v21, v[74:75]
	v_fma_f64 v[38:39], v[12:13], v[38:39], -v[78:79]
	v_cos_f32_e32 v74, v21
	v_sin_f32_e32 v76, v21
	v_cvt_f32_f64_e32 v21, v[38:39]
	v_cos_f32_e32 v75, v21
	v_sin_f32_e32 v77, v21
	v_bitop3_b32 v21, v140, s70, 32 bitop3:0xc8
	s_waitcnt vmcnt(0)
	v_lshlrev_b32_e32 v38, 16, v42
	v_and_b32_e32 v39, 0xffff0000, v42
	v_lshlrev_b32_e32 v42, 16, v43
	v_and_b32_e32 v43, 0xffff0000, v43
	v_lshlrev_b32_e32 v78, 16, v44
	v_and_b32_e32 v79, 0xffff0000, v44
	v_lshlrev_b32_e32 v44, 16, v45
	v_and_b32_e32 v45, 0xffff0000, v45
	v_pk_mul_f32 v[38:39], v[116:117], v[38:39] op_sel_hi:[0,1]
	v_pk_mul_f32 v[42:43], v[116:117], v[42:43] op_sel_hi:[0,1]
	v_pk_mul_f32 v[78:79], v[116:117], v[78:79] op_sel_hi:[0,1]
	v_pk_mul_f32 v[44:45], v[116:117], v[44:45] op_sel_hi:[0,1]
	v_pk_mul_f32 v[38:39], v[4:5], v[38:39]
	v_pk_mul_f32 v[42:43], v[6:7], v[42:43]
	v_pk_mul_f32 v[78:79], v[0:1], v[78:79]
	v_pk_mul_f32 v[44:45], v[2:3], v[44:45]
	ds_bpermute_b32 v86, v141, v38
	ds_bpermute_b32 v87, v141, v39
	ds_bpermute_b32 v88, v141, v42
	ds_bpermute_b32 v89, v141, v43
	ds_bpermute_b32 v90, v141, v78
	ds_bpermute_b32 v91, v141, v79
	ds_bpermute_b32 v92, v141, v44
	ds_bpermute_b32 v93, v141, v45
	s_waitcnt lgkmcnt(6)
	v_pk_mul_f32 v[54:55], v[54:55], v[86:87]
	s_waitcnt lgkmcnt(4)
	v_pk_mul_f32 v[60:61], v[60:61], v[88:89]
	s_waitcnt lgkmcnt(2)
	v_pk_mul_f32 v[70:71], v[70:71], v[90:91]
	v_cndmask_b32_e64 v55, v55, -v55, vcc
	s_waitcnt lgkmcnt(0)
	v_pk_mul_f32 v[76:77], v[76:77], v[92:93]
	v_cndmask_b32_e64 v54, v54, -v54, vcc
	v_cndmask_b32_e64 v61, v61, -v61, vcc
	v_cndmask_b32_e64 v60, v60, -v60, vcc
	v_cndmask_b32_e64 v71, v71, -v71, vcc
	v_cndmask_b32_e64 v70, v70, -v70, vcc
	v_cndmask_b32_e64 v77, v77, -v77, vcc
	v_cndmask_b32_e64 v76, v76, -v76, vcc
	v_pk_fma_f32 v[38:39], v[46:47], v[38:39], v[54:55]
	v_pk_fma_f32 v[46:47], v[42:43], v[58:59], v[60:61]
	v_pk_fma_f32 v[54:55], v[78:79], v[62:63], v[70:71]
	v_pk_fma_f32 v[58:59], v[44:45], v[74:75], v[76:77]
	v_cvt_pk_bf16_f32 v42, v38, v39
	v_cvt_pk_bf16_f32 v43, v46, v47
	v_cvt_pk_bf16_f32 v44, v54, v55
	v_cvt_pk_bf16_f32 v45, v58, v59
	global_store_dwordx4 v[114:115], v[42:45], off offset:128
	global_load_dwordx4 v[42:45], v[96:97], off offset:1536
	v_cvt_f64_u32_e32 v[38:39], v21
	v_mul_f64 v[46:47], v[8:9], v[38:39]
	v_rndne_f64_e32 v[46:47], v[46:47]
	v_mul_f64 v[58:59], v[10:11], v[38:39]
	v_fma_f64 v[46:47], v[8:9], v[38:39], -v[46:47]
	v_rndne_f64_e32 v[58:59], v[58:59]
	v_cvt_f32_f64_e32 v21, v[46:47]
	v_fma_f64 v[58:59], v[10:11], v[38:39], -v[58:59]
	v_cos_f32_e32 v46, v21
	v_sin_f32_e32 v54, v21
	v_cvt_f32_f64_e32 v21, v[58:59]
	v_mul_f64 v[58:59], v[14:15], v[38:39]
	v_rndne_f64_e32 v[58:59], v[58:59]
	v_mul_f64 v[62:63], v[22:23], v[38:39]
	v_fma_f64 v[58:59], v[14:15], v[38:39], -v[58:59]
	v_rndne_f64_e32 v[62:63], v[62:63]
	v_cos_f32_e32 v47, v21
	v_sin_f32_e32 v55, v21
	v_cvt_f32_f64_e32 v21, v[58:59]
	v_fma_f64 v[62:63], v[22:23], v[38:39], -v[62:63]
	v_cos_f32_e32 v58, v21
	v_sin_f32_e32 v60, v21
	v_cvt_f32_f64_e32 v21, v[62:63]
	v_mul_f64 v[62:63], v[26:27], v[38:39]
	v_rndne_f64_e32 v[62:63], v[62:63]
	v_mul_f64 v[74:75], v[28:29], v[38:39]
	v_fma_f64 v[62:63], v[26:27], v[38:39], -v[62:63]
	v_rndne_f64_e32 v[74:75], v[74:75]
	v_cos_f32_e32 v59, v21
	v_sin_f32_e32 v61, v21
	v_cvt_f32_f64_e32 v21, v[62:63]
	v_fma_f64 v[74:75], v[28:29], v[38:39], -v[74:75]
	v_cos_f32_e32 v62, v21
	v_sin_f32_e32 v70, v21
	v_cvt_f32_f64_e32 v21, v[74:75]
	v_mul_f64 v[74:75], v[30:31], v[38:39]
	v_rndne_f64_e32 v[74:75], v[74:75]
	v_mul_f64 v[78:79], v[12:13], v[38:39]
	v_fma_f64 v[74:75], v[30:31], v[38:39], -v[74:75]
	v_rndne_f64_e32 v[78:79], v[78:79]
	v_cos_f32_e32 v63, v21
	v_sin_f32_e32 v71, v21
	v_cvt_f32_f64_e32 v21, v[74:75]
	v_fma_f64 v[38:39], v[12:13], v[38:39], -v[78:79]
	v_cos_f32_e32 v74, v21
	v_sin_f32_e32 v76, v21
	v_cvt_f32_f64_e32 v21, v[38:39]
	v_cos_f32_e32 v75, v21
	v_sin_f32_e32 v77, v21
	v_bitop3_b32 v21, v140, s71, 48 bitop3:0xc8
	s_waitcnt vmcnt(0)
; __device__ __forceinline__ unsigned cvtpk(float lo, float hi) { f32x2_t v = {lo, hi}; bf16x2_t b = __builtin_convertvector(v, bf16x2_t); return __builtin_bit_cast(unsigned, b); }
; __device__ __forceinline__ float bflo(unsigned w) { return __uint_as_float(w << 16); }
; __device__ __forceinline__ float bfhi(unsigned w) { return __uint_as_float(w & 0xffff0000u); }
;     __device__ __forceinline__ void operator()(const f32x4 (&acc)[2][2][4][2], const Unit& u, int wr, int wc, int fr, int fq) const {
;     ...
; #pragma unroll
;         for (int ai = 0; ai < 2; ++ai)
; #pragma unroll
;             for (int m = 0; m < 4; ++m) {
;                 const int row = row0 + ai * HALF + m * 16; const int pos = row & (SEQ - 1);
;                 const float rh = rhs[ai * 4 + m];
;                 const u32x4 kw = *(const u32x4*)(T1 + (size_t)row * 1024 + 768 + 8 * fq);
;                 const float kr[8] = {bflo(kw.x), bfhi(kw.x), bflo(kw.y), bfhi(kw.y), bflo(kw.z), bfhi(kw.z), bflo(kw.w), bfhi(kw.w)};
;                 float ro[8];
; #pragma unroll
;                 for (int j = 0; j < 8; ++j) {
;                     const float x = kr[j] * rh * (j < 4 ? gr0[j & 3] : gr1[j & 3]);
;                     const float px = __shfl_xor(x, 32);
;                     float cs, sn; rope_cs(pos, 2 * (8 * (fq & 1) + j), cs, sn);
;                     ro[j] = (fq < 2) ? (x * cs - px * sn) : (px * sn + x * cs);
;                 }
;                 u32x4 w; w.x = cvtpk(ro[0], ro[1]); w.y = cvtpk(ro[2], ro[3]); w.z = cvtpk(ro[4], ro[5]); w.w = cvtpk(ro[6], ro[7]);
;                 *(u32x4*)(O + (size_t)row * 1536 + head * 96 + 64 + 8 * fq) = w;
;                 asm volatile("" ::: "memory");
	v_lshlrev_b32_e32 v38, 16, v42
	v_and_b32_e32 v39, 0xffff0000, v42
	v_lshlrev_b32_e32 v42, 16, v43
	v_and_b32_e32 v43, 0xffff0000, v43
	v_lshlrev_b32_e32 v78, 16, v44
	v_and_b32_e32 v79, 0xffff0000, v44
	v_lshlrev_b32_e32 v44, 16, v45
	v_and_b32_e32 v45, 0xffff0000, v45
	v_pk_mul_f32 v[38:39], v[100:101], v[38:39] op_sel_hi:[0,1]
	v_pk_mul_f32 v[42:43], v[100:101], v[42:43] op_sel_hi:[0,1]
	v_pk_mul_f32 v[78:79], v[100:101], v[78:79] op_sel_hi:[0,1]
	v_pk_mul_f32 v[44:45], v[100:101], v[44:45] op_sel_hi:[0,1]
	v_pk_mul_f32 v[38:39], v[4:5], v[38:39]
	v_pk_mul_f32 v[42:43], v[6:7], v[42:43]
	v_pk_mul_f32 v[78:79], v[0:1], v[78:79]
	v_pk_mul_f32 v[44:45], v[2:3], v[44:45]
	ds_bpermute_b32 v86, v141, v38
	ds_bpermute_b32 v87, v141, v39
	ds_bpermute_b32 v88, v141, v42
	ds_bpermute_b32 v89, v141, v43
	ds_bpermute_b32 v90, v141, v78
	ds_bpermute_b32 v91, v141, v79
	ds_bpermute_b32 v92, v141, v44
	ds_bpermute_b32 v93, v141, v45
	s_waitcnt lgkmcnt(6)
	v_pk_mul_f32 v[54:55], v[54:55], v[86:87]
	s_waitcnt lgkmcnt(4)
	v_pk_mul_f32 v[60:61], v[60:61], v[88:89]
	s_waitcnt lgkmcnt(2)
	v_pk_mul_f32 v[70:71], v[70:71], v[90:91]
	v_cndmask_b32_e64 v55, v55, -v55, vcc
	s_waitcnt lgkmcnt(0)
	v_pk_mul_f32 v[76:77], v[76:77], v[92:93]
	v_cndmask_b32_e64 v54, v54, -v54, vcc
	v_cndmask_b32_e64 v61, v61, -v61, vcc
	v_cndmask_b32_e64 v60, v60, -v60, vcc
	v_cndmask_b32_e64 v71, v71, -v71, vcc
	v_cndmask_b32_e64 v70, v70, -v70, vcc
	v_cndmask_b32_e64 v77, v77, -v77, vcc
	v_cndmask_b32_e64 v76, v76, -v76, vcc
	v_pk_fma_f32 v[38:39], v[46:47], v[38:39], v[54:55]
	v_pk_fma_f32 v[46:47], v[42:43], v[58:59], v[60:61]
	v_pk_fma_f32 v[54:55], v[78:79], v[62:63], v[70:71]
	v_pk_fma_f32 v[58:59], v[44:45], v[74:75], v[76:77]
	v_cvt_pk_bf16_f32 v42, v38, v39
	v_cvt_pk_bf16_f32 v43, v46, v47
	v_cvt_pk_bf16_f32 v44, v54, v55
	v_cvt_pk_bf16_f32 v45, v58, v59
	global_store_dwordx4 v[98:99], v[42:45], off offset:128
	global_load_dwordx4 v[42:45], v[80:81], off offset:1536
	v_cvt_f64_u32_e32 v[38:39], v21
	v_mul_f64 v[46:47], v[8:9], v[38:39]
	v_rndne_f64_e32 v[46:47], v[46:47]
	v_mul_f64 v[58:59], v[10:11], v[38:39]
	v_fma_f64 v[46:47], v[8:9], v[38:39], -v[46:47]
	v_rndne_f64_e32 v[58:59], v[58:59]
	v_cvt_f32_f64_e32 v21, v[46:47]
	v_fma_f64 v[58:59], v[10:11], v[38:39], -v[58:59]
	v_cos_f32_e32 v46, v21
	v_sin_f32_e32 v54, v21
	v_cvt_f32_f64_e32 v21, v[58:59]
	v_mul_f64 v[58:59], v[14:15], v[38:39]
	v_rndne_f64_e32 v[58:59], v[58:59]
	v_mul_f64 v[62:63], v[22:23], v[38:39]
	v_fma_f64 v[58:59], v[14:15], v[38:39], -v[58:59]
	v_rndne_f64_e32 v[62:63], v[62:63]
	v_cos_f32_e32 v47, v21
	v_sin_f32_e32 v55, v21
	v_cvt_f32_f64_e32 v21, v[58:59]
	v_fma_f64 v[62:63], v[22:23], v[38:39], -v[62:63]
	v_cos_f32_e32 v58, v21
	v_sin_f32_e32 v60, v21
	v_cvt_f32_f64_e32 v21, v[62:63]
	v_mul_f64 v[62:63], v[26:27], v[38:39]
	v_rndne_f64_e32 v[62:63], v[62:63]
	v_mul_f64 v[74:75], v[28:29], v[38:39]
	v_fma_f64 v[62:63], v[26:27], v[38:39], -v[62:63]
	v_rndne_f64_e32 v[74:75], v[74:75]
	v_cos_f32_e32 v59, v21
	v_sin_f32_e32 v61, v21
	v_cvt_f32_f64_e32 v21, v[62:63]
	v_fma_f64 v[74:75], v[28:29], v[38:39], -v[74:75]
	v_cos_f32_e32 v62, v21
	v_sin_f32_e32 v70, v21
	v_cvt_f32_f64_e32 v21, v[74:75]
	v_mul_f64 v[74:75], v[30:31], v[38:39]
	v_rndne_f64_e32 v[74:75], v[74:75]
	v_mul_f64 v[78:79], v[12:13], v[38:39]
	v_fma_f64 v[74:75], v[30:31], v[38:39], -v[74:75]
	v_rndne_f64_e32 v[78:79], v[78:79]
	v_cos_f32_e32 v63, v21
	v_sin_f32_e32 v71, v21
	v_cvt_f32_f64_e32 v21, v[74:75]
	v_fma_f64 v[38:39], v[12:13], v[38:39], -v[78:79]
	v_cos_f32_e32 v74, v21
	v_sin_f32_e32 v76, v21
	v_cvt_f32_f64_e32 v21, v[38:39]
	v_cos_f32_e32 v75, v21
	v_sin_f32_e32 v77, v21
	v_and_b32_e32 v21, 0xfcf, v72
	s_waitcnt vmcnt(0)
	v_lshlrev_b32_e32 v38, 16, v42
	v_and_b32_e32 v39, 0xffff0000, v42
	v_lshlrev_b32_e32 v42, 16, v43
	v_and_b32_e32 v43, 0xffff0000, v43
	v_lshlrev_b32_e32 v78, 16, v44
	v_and_b32_e32 v79, 0xffff0000, v44
	v_lshlrev_b32_e32 v44, 16, v45
	v_and_b32_e32 v45, 0xffff0000, v45
	v_pk_mul_f32 v[38:39], v[84:85], v[38:39] op_sel_hi:[0,1]
	v_pk_mul_f32 v[42:43], v[84:85], v[42:43] op_sel_hi:[0,1]
	v_pk_mul_f32 v[78:79], v[84:85], v[78:79] op_sel_hi:[0,1]
	v_pk_mul_f32 v[44:45], v[84:85], v[44:45] op_sel_hi:[0,1]
	v_pk_mul_f32 v[38:39], v[4:5], v[38:39]
	v_pk_mul_f32 v[42:43], v[6:7], v[42:43]
	v_pk_mul_f32 v[78:79], v[0:1], v[78:79]
	v_pk_mul_f32 v[44:45], v[2:3], v[44:45]
	ds_bpermute_b32 v80, v141, v38
	ds_bpermute_b32 v81, v141, v39
	ds_bpermute_b32 v84, v141, v42
	ds_bpermute_b32 v85, v141, v43
	ds_bpermute_b32 v86, v141, v78
	ds_bpermute_b32 v87, v141, v79
	ds_bpermute_b32 v88, v141, v44
	ds_bpermute_b32 v89, v141, v45
	s_waitcnt lgkmcnt(6)
	v_pk_mul_f32 v[54:55], v[54:55], v[80:81]
	s_waitcnt lgkmcnt(4)
	v_pk_mul_f32 v[60:61], v[60:61], v[84:85]
	s_waitcnt lgkmcnt(2)
	v_pk_mul_f32 v[70:71], v[70:71], v[86:87]
	v_cndmask_b32_e64 v55, v55, -v55, vcc
	s_waitcnt lgkmcnt(0)
; __device__ __forceinline__ unsigned cvtpk(float lo, float hi) { f32x2_t v = {lo, hi}; bf16x2_t b = __builtin_convertvector(v, bf16x2_t); return __builtin_bit_cast(unsigned, b); }
; __device__ __forceinline__ float bflo(unsigned w) { return __uint_as_float(w << 16); }
; __device__ __forceinline__ float bfhi(unsigned w) { return __uint_as_float(w & 0xffff0000u); }
;     __device__ __forceinline__ void operator()(const f32x4 (&acc)[2][2][4][2], const Unit& u, int wr, int wc, int fr, int fq) const {
;     ...
; #pragma unroll
;         for (int ai = 0; ai < 2; ++ai)
; #pragma unroll
;             for (int m = 0; m < 4; ++m) {
;                 const int row = row0 + ai * HALF + m * 16; const int pos = row & (SEQ - 1);
;                 const float rh = rhs[ai * 4 + m];
;                 const u32x4 kw = *(const u32x4*)(T1 + (size_t)row * 1024 + 768 + 8 * fq);
;                 const float kr[8] = {bflo(kw.x), bfhi(kw.x), bflo(kw.y), bfhi(kw.y), bflo(kw.z), bfhi(kw.z), bflo(kw.w), bfhi(kw.w)};
;                 float ro[8];
; #pragma unroll
;                 for (int j = 0; j < 8; ++j) {
;                     const float x = kr[j] * rh * (j < 4 ? gr0[j & 3] : gr1[j & 3]);
;                     const float px = __shfl_xor(x, 32);
;                     float cs, sn; rope_cs(pos, 2 * (8 * (fq & 1) + j), cs, sn);
;                     ro[j] = (fq < 2) ? (x * cs - px * sn) : (px * sn + x * cs);
;                 }
;                 u32x4 w; w.x = cvtpk(ro[0], ro[1]); w.y = cvtpk(ro[2], ro[3]); w.z = cvtpk(ro[4], ro[5]); w.w = cvtpk(ro[6], ro[7]);
;                 *(u32x4*)(O + (size_t)row * 1536 + head * 96 + 64 + 8 * fq) = w;
;                 asm volatile("" ::: "memory");
	v_pk_mul_f32 v[76:77], v[76:77], v[88:89]
	v_cndmask_b32_e64 v54, v54, -v54, vcc
	v_cndmask_b32_e64 v61, v61, -v61, vcc
	v_cndmask_b32_e64 v60, v60, -v60, vcc
	v_cndmask_b32_e64 v71, v71, -v71, vcc
	v_cndmask_b32_e64 v70, v70, -v70, vcc
	v_cndmask_b32_e64 v77, v77, -v77, vcc
	v_cndmask_b32_e64 v76, v76, -v76, vcc
	v_pk_fma_f32 v[38:39], v[46:47], v[38:39], v[54:55]
	v_pk_fma_f32 v[46:47], v[42:43], v[58:59], v[60:61]
	v_pk_fma_f32 v[54:55], v[78:79], v[62:63], v[70:71]
	v_pk_fma_f32 v[58:59], v[44:45], v[74:75], v[76:77]
	v_cvt_pk_bf16_f32 v42, v38, v39
	v_cvt_pk_bf16_f32 v43, v46, v47
	v_cvt_pk_bf16_f32 v44, v54, v55
	v_cvt_pk_bf16_f32 v45, v58, v59
	global_store_dwordx4 v[82:83], v[42:45], off offset:128
	global_load_dwordx4 v[42:45], v[64:65], off offset:1536
	v_cvt_f64_u32_e32 v[38:39], v21
	v_mul_f64 v[46:47], v[8:9], v[38:39]
	v_rndne_f64_e32 v[46:47], v[46:47]
	v_mul_f64 v[58:59], v[10:11], v[38:39]
	v_fma_f64 v[46:47], v[8:9], v[38:39], -v[46:47]
	v_rndne_f64_e32 v[58:59], v[58:59]
	v_cvt_f32_f64_e32 v21, v[46:47]
	v_fma_f64 v[58:59], v[10:11], v[38:39], -v[58:59]
	v_cos_f32_e32 v46, v21
	v_sin_f32_e32 v54, v21
	v_cvt_f32_f64_e32 v21, v[58:59]
	v_mul_f64 v[58:59], v[14:15], v[38:39]
	v_rndne_f64_e32 v[58:59], v[58:59]
	v_mul_f64 v[62:63], v[22:23], v[38:39]
	v_fma_f64 v[58:59], v[14:15], v[38:39], -v[58:59]
	v_rndne_f64_e32 v[62:63], v[62:63]
	v_cos_f32_e32 v47, v21
	v_sin_f32_e32 v55, v21
	v_cvt_f32_f64_e32 v21, v[58:59]
	v_fma_f64 v[62:63], v[22:23], v[38:39], -v[62:63]
	v_cos_f32_e32 v58, v21
	v_sin_f32_e32 v60, v21
	v_cvt_f32_f64_e32 v21, v[62:63]
	v_mul_f64 v[62:63], v[26:27], v[38:39]
	v_rndne_f64_e32 v[62:63], v[62:63]
	v_mul_f64 v[70:71], v[28:29], v[38:39]
	v_fma_f64 v[62:63], v[26:27], v[38:39], -v[62:63]
	v_rndne_f64_e32 v[70:71], v[70:71]
	v_cos_f32_e32 v59, v21
	v_sin_f32_e32 v61, v21
	v_cvt_f32_f64_e32 v21, v[62:63]
	v_fma_f64 v[70:71], v[28:29], v[38:39], -v[70:71]
	v_cos_f32_e32 v62, v21
	v_sin_f32_e32 v64, v21
	v_cvt_f32_f64_e32 v21, v[70:71]
	v_mul_f64 v[70:71], v[30:31], v[38:39]
	v_rndne_f64_e32 v[70:71], v[70:71]
	v_mul_f64 v[74:75], v[12:13], v[38:39]
	v_fma_f64 v[70:71], v[30:31], v[38:39], -v[70:71]
	v_rndne_f64_e32 v[74:75], v[74:75]
	v_cos_f32_e32 v63, v21
	v_sin_f32_e32 v65, v21
	v_cvt_f32_f64_e32 v21, v[70:71]
	v_fma_f64 v[38:39], v[12:13], v[38:39], -v[74:75]
	v_cos_f32_e32 v70, v21
	v_sin_f32_e32 v72, v21
	v_cvt_f32_f64_e32 v21, v[38:39]
	v_cos_f32_e32 v71, v21
	v_sin_f32_e32 v73, v21
	v_and_b32_e32 v21, 0xfdf, v56
	s_waitcnt vmcnt(0)
	v_lshlrev_b32_e32 v38, 16, v42
	v_and_b32_e32 v39, 0xffff0000, v42
	v_lshlrev_b32_e32 v42, 16, v43
	v_and_b32_e32 v43, 0xffff0000, v43
	v_lshlrev_b32_e32 v74, 16, v44
	v_and_b32_e32 v75, 0xffff0000, v44
	v_lshlrev_b32_e32 v44, 16, v45
	v_and_b32_e32 v45, 0xffff0000, v45
	v_pk_mul_f32 v[38:39], v[68:69], v[38:39] op_sel_hi:[0,1]
	v_pk_mul_f32 v[42:43], v[68:69], v[42:43] op_sel_hi:[0,1]
	v_pk_mul_f32 v[74:75], v[68:69], v[74:75] op_sel_hi:[0,1]
	v_pk_mul_f32 v[44:45], v[68:69], v[44:45] op_sel_hi:[0,1]
	v_pk_mul_f32 v[38:39], v[4:5], v[38:39]
	v_pk_mul_f32 v[42:43], v[6:7], v[42:43]
	v_pk_mul_f32 v[68:69], v[0:1], v[74:75]
	v_pk_mul_f32 v[44:45], v[2:3], v[44:45]
	ds_bpermute_b32 v74, v141, v38
	ds_bpermute_b32 v75, v141, v39
	ds_bpermute_b32 v76, v141, v42
	ds_bpermute_b32 v77, v141, v43
	ds_bpermute_b32 v78, v141, v68
	ds_bpermute_b32 v79, v141, v69
	ds_bpermute_b32 v80, v141, v44
	ds_bpermute_b32 v81, v141, v45
	s_waitcnt lgkmcnt(6)
	v_pk_mul_f32 v[54:55], v[54:55], v[74:75]
	s_waitcnt lgkmcnt(4)
	v_pk_mul_f32 v[60:61], v[60:61], v[76:77]
	s_waitcnt lgkmcnt(2)
	v_pk_mul_f32 v[64:65], v[64:65], v[78:79]
	v_cndmask_b32_e64 v55, v55, -v55, vcc
	s_waitcnt lgkmcnt(0)
	v_pk_mul_f32 v[72:73], v[72:73], v[80:81]
	v_cndmask_b32_e64 v54, v54, -v54, vcc
	v_cndmask_b32_e64 v61, v61, -v61, vcc
	v_cndmask_b32_e64 v60, v60, -v60, vcc
	v_cndmask_b32_e64 v65, v65, -v65, vcc
	v_cndmask_b32_e64 v64, v64, -v64, vcc
	v_cndmask_b32_e64 v73, v73, -v73, vcc
	v_cndmask_b32_e64 v72, v72, -v72, vcc
	v_pk_fma_f32 v[38:39], v[46:47], v[38:39], v[54:55]
	v_pk_fma_f32 v[46:47], v[42:43], v[58:59], v[60:61]
	v_pk_fma_f32 v[54:55], v[68:69], v[62:63], v[64:65]
	v_pk_fma_f32 v[58:59], v[44:45], v[70:71], v[72:73]
	v_cvt_pk_bf16_f32 v42, v38, v39
	v_cvt_pk_bf16_f32 v43, v46, v47
	v_cvt_pk_bf16_f32 v44, v54, v55
	v_cvt_pk_bf16_f32 v45, v58, v59
	global_store_dwordx4 v[66:67], v[42:45], off offset:128
	global_load_dwordx4 v[42:45], v[48:49], off offset:1536
	v_cvt_f64_u32_e32 v[38:39], v21
	v_mul_f64 v[46:47], v[8:9], v[38:39]
	v_rndne_f64_e32 v[46:47], v[46:47]
	v_mul_f64 v[54:55], v[10:11], v[38:39]
	v_fma_f64 v[46:47], v[8:9], v[38:39], -v[46:47]
	v_rndne_f64_e32 v[54:55], v[54:55]
	v_cvt_f32_f64_e32 v21, v[46:47]
	v_fma_f64 v[54:55], v[10:11], v[38:39], -v[54:55]
	v_cos_f32_e32 v46, v21
	v_sin_f32_e32 v48, v21
	v_cvt_f32_f64_e32 v21, v[54:55]
	v_mul_f64 v[54:55], v[14:15], v[38:39]
	v_rndne_f64_e32 v[54:55], v[54:55]
	v_mul_f64 v[58:59], v[22:23], v[38:39]
	v_fma_f64 v[54:55], v[14:15], v[38:39], -v[54:55]
	v_rndne_f64_e32 v[58:59], v[58:59]
	v_cos_f32_e32 v47, v21
	v_sin_f32_e32 v49, v21
	v_cvt_f32_f64_e32 v21, v[54:55]
	v_fma_f64 v[58:59], v[22:23], v[38:39], -v[58:59]
	v_cos_f32_e32 v54, v21
	v_sin_f32_e32 v56, v21
	v_cvt_f32_f64_e32 v21, v[58:59]
	v_mul_f64 v[58:59], v[26:27], v[38:39]
	v_rndne_f64_e32 v[58:59], v[58:59]
	v_mul_f64 v[62:63], v[28:29], v[38:39]
	v_fma_f64 v[58:59], v[26:27], v[38:39], -v[58:59]
	v_rndne_f64_e32 v[62:63], v[62:63]
	v_cos_f32_e32 v55, v21
	v_sin_f32_e32 v57, v21
	v_cvt_f32_f64_e32 v21, v[58:59]
	v_fma_f64 v[62:63], v[28:29], v[38:39], -v[62:63]
	v_cos_f32_e32 v58, v21
	v_sin_f32_e32 v60, v21
	v_cvt_f32_f64_e32 v21, v[62:63]
	v_mul_f64 v[62:63], v[30:31], v[38:39]
	v_rndne_f64_e32 v[62:63], v[62:63]
	v_mul_f64 v[66:67], v[12:13], v[38:39]
	v_fma_f64 v[62:63], v[30:31], v[38:39], -v[62:63]
	v_rndne_f64_e32 v[66:67], v[66:67]
	v_cos_f32_e32 v59, v21
	v_sin_f32_e32 v61, v21
	v_cvt_f32_f64_e32 v21, v[62:63]
	v_fma_f64 v[38:39], v[12:13], v[38:39], -v[66:67]
	v_cos_f32_e32 v62, v21
	v_sin_f32_e32 v64, v21
	v_cvt_f32_f64_e32 v21, v[38:39]
	v_cos_f32_e32 v63, v21
	v_sin_f32_e32 v65, v21
	v_and_b32_e32 v21, 0xfef, v40
	s_waitcnt vmcnt(0)
; __device__ __forceinline__ unsigned cvtpk(float lo, float hi) { f32x2_t v = {lo, hi}; bf16x2_t b = __builtin_convertvector(v, bf16x2_t); return __builtin_bit_cast(unsigned, b); }
; __device__ __forceinline__ float bflo(unsigned w) { return __uint_as_float(w << 16); }
; __device__ __forceinline__ float bfhi(unsigned w) { return __uint_as_float(w & 0xffff0000u); }
;     __device__ __forceinline__ void operator()(const f32x4 (&acc)[2][2][4][2], const Unit& u, int wr, int wc, int fr, int fq) const {
;     ...
; #pragma unroll
;         for (int ai = 0; ai < 2; ++ai)
; #pragma unroll
;             for (int m = 0; m < 4; ++m) {
;                 const int row = row0 + ai * HALF + m * 16; const int pos = row & (SEQ - 1);
;                 const float rh = rhs[ai * 4 + m];
;                 const u32x4 kw = *(const u32x4*)(T1 + (size_t)row * 1024 + 768 + 8 * fq);
;                 const float kr[8] = {bflo(kw.x), bfhi(kw.x), bflo(kw.y), bfhi(kw.y), bflo(kw.z), bfhi(kw.z), bflo(kw.w), bfhi(kw.w)};
;                 float ro[8];
; #pragma unroll
;                 for (int j = 0; j < 8; ++j) {
;                     const float x = kr[j] * rh * (j < 4 ? gr0[j & 3] : gr1[j & 3]);
;                     const float px = __shfl_xor(x, 32);
;                     float cs, sn; rope_cs(pos, 2 * (8 * (fq & 1) + j), cs, sn);
;                     ro[j] = (fq < 2) ? (x * cs - px * sn) : (px * sn + x * cs);
;                 }
;                 u32x4 w; w.x = cvtpk(ro[0], ro[1]); w.y = cvtpk(ro[2], ro[3]); w.z = cvtpk(ro[4], ro[5]); w.w = cvtpk(ro[6], ro[7]);
;                 *(u32x4*)(O + (size_t)row * 1536 + head * 96 + 64 + 8 * fq) = w;
;                 asm volatile("" ::: "memory");
	v_lshlrev_b32_e32 v38, 16, v42
	v_and_b32_e32 v39, 0xffff0000, v42
	v_lshlrev_b32_e32 v42, 16, v43
	v_and_b32_e32 v43, 0xffff0000, v43
	v_lshlrev_b32_e32 v66, 16, v44
	v_and_b32_e32 v67, 0xffff0000, v44
	v_lshlrev_b32_e32 v44, 16, v45
	v_and_b32_e32 v45, 0xffff0000, v45
	v_pk_mul_f32 v[38:39], v[52:53], v[38:39] op_sel_hi:[0,1]
	v_pk_mul_f32 v[42:43], v[52:53], v[42:43] op_sel_hi:[0,1]
	v_pk_mul_f32 v[66:67], v[52:53], v[66:67] op_sel_hi:[0,1]
	v_pk_mul_f32 v[44:45], v[52:53], v[44:45] op_sel_hi:[0,1]
	v_pk_mul_f32 v[38:39], v[4:5], v[38:39]
	v_pk_mul_f32 v[42:43], v[6:7], v[42:43]
	v_pk_mul_f32 v[52:53], v[0:1], v[66:67]
	v_pk_mul_f32 v[44:45], v[2:3], v[44:45]
	ds_bpermute_b32 v66, v141, v38
	ds_bpermute_b32 v67, v141, v39
	ds_bpermute_b32 v68, v141, v42
	ds_bpermute_b32 v69, v141, v43
	ds_bpermute_b32 v70, v141, v52
	ds_bpermute_b32 v71, v141, v53
	ds_bpermute_b32 v72, v141, v44
	ds_bpermute_b32 v73, v141, v45
	s_waitcnt lgkmcnt(6)
	v_pk_mul_f32 v[48:49], v[48:49], v[66:67]
	s_waitcnt lgkmcnt(4)
	v_pk_mul_f32 v[56:57], v[56:57], v[68:69]
	s_waitcnt lgkmcnt(2)
	v_pk_mul_f32 v[60:61], v[60:61], v[70:71]
	v_cndmask_b32_e64 v49, v49, -v49, vcc
	s_waitcnt lgkmcnt(0)
	v_pk_mul_f32 v[64:65], v[64:65], v[72:73]
	v_cndmask_b32_e64 v48, v48, -v48, vcc
	v_cndmask_b32_e64 v57, v57, -v57, vcc
	v_cndmask_b32_e64 v56, v56, -v56, vcc
	v_cndmask_b32_e64 v61, v61, -v61, vcc
	v_cndmask_b32_e64 v60, v60, -v60, vcc
	v_cndmask_b32_e64 v65, v65, -v65, vcc
	v_cndmask_b32_e64 v64, v64, -v64, vcc
	v_pk_fma_f32 v[38:39], v[46:47], v[38:39], v[48:49]
	v_pk_fma_f32 v[46:47], v[42:43], v[54:55], v[56:57]
	v_pk_fma_f32 v[48:49], v[52:53], v[58:59], v[60:61]
	v_pk_fma_f32 v[52:53], v[44:45], v[62:63], v[64:65]
	v_cvt_pk_bf16_f32 v42, v38, v39
	v_cvt_pk_bf16_f32 v43, v46, v47
	v_cvt_pk_bf16_f32 v44, v48, v49
	v_cvt_pk_bf16_f32 v45, v52, v53
	global_store_dwordx4 v[50:51], v[42:45], off offset:128
	global_load_dwordx4 v[42:45], v[32:33], off offset:1536
	v_cvt_f64_u32_e32 v[32:33], v21
	v_mul_f64 v[38:39], v[8:9], v[32:33]
	v_rndne_f64_e32 v[38:39], v[38:39]
	v_mul_f64 v[46:47], v[10:11], v[32:33]
	v_fma_f64 v[38:39], v[8:9], v[32:33], -v[38:39]
	v_rndne_f64_e32 v[46:47], v[46:47]
	v_cvt_f32_f64_e32 v21, v[38:39]
	v_fma_f64 v[46:47], v[10:11], v[32:33], -v[46:47]
	v_cos_f32_e32 v38, v21
	v_sin_f32_e32 v40, v21
	v_cvt_f32_f64_e32 v21, v[46:47]
	v_mul_f64 v[46:47], v[14:15], v[32:33]
	v_rndne_f64_e32 v[46:47], v[46:47]
	v_mul_f64 v[50:51], v[22:23], v[32:33]
	v_fma_f64 v[46:47], v[14:15], v[32:33], -v[46:47]
	v_rndne_f64_e32 v[50:51], v[50:51]
	v_cos_f32_e32 v39, v21
	v_sin_f32_e32 v41, v21
	v_cvt_f32_f64_e32 v21, v[46:47]
	v_fma_f64 v[50:51], v[22:23], v[32:33], -v[50:51]
	v_cos_f32_e32 v46, v21
	v_sin_f32_e32 v48, v21
	v_cvt_f32_f64_e32 v21, v[50:51]
	v_mul_f64 v[50:51], v[26:27], v[32:33]
	v_rndne_f64_e32 v[50:51], v[50:51]
	v_mul_f64 v[54:55], v[28:29], v[32:33]
	v_fma_f64 v[50:51], v[26:27], v[32:33], -v[50:51]
	v_rndne_f64_e32 v[54:55], v[54:55]
	v_cos_f32_e32 v47, v21
	v_sin_f32_e32 v49, v21
	v_cvt_f32_f64_e32 v21, v[50:51]
	v_fma_f64 v[54:55], v[28:29], v[32:33], -v[54:55]
	v_cos_f32_e32 v50, v21
	v_sin_f32_e32 v52, v21
	v_cvt_f32_f64_e32 v21, v[54:55]
	v_mul_f64 v[54:55], v[30:31], v[32:33]
	v_rndne_f64_e32 v[54:55], v[54:55]
	v_mul_f64 v[58:59], v[12:13], v[32:33]
	v_fma_f64 v[54:55], v[30:31], v[32:33], -v[54:55]
	v_rndne_f64_e32 v[58:59], v[58:59]
	v_cos_f32_e32 v51, v21
	v_sin_f32_e32 v53, v21
	v_cvt_f32_f64_e32 v21, v[54:55]
	v_fma_f64 v[32:33], v[12:13], v[32:33], -v[58:59]
	v_cos_f32_e32 v54, v21
	v_sin_f32_e32 v56, v21
	v_cvt_f32_f64_e32 v21, v[32:33]
	v_cos_f32_e32 v55, v21
	v_sin_f32_e32 v57, v21
	s_waitcnt vmcnt(0)
	v_lshlrev_b32_e32 v32, 16, v42
	v_and_b32_e32 v33, 0xffff0000, v42
	v_lshlrev_b32_e32 v42, 16, v43
	v_and_b32_e32 v43, 0xffff0000, v43
	v_lshlrev_b32_e32 v58, 16, v44
	v_and_b32_e32 v59, 0xffff0000, v44
	v_lshlrev_b32_e32 v44, 16, v45
	v_and_b32_e32 v45, 0xffff0000, v45
	v_pk_mul_f32 v[32:33], v[36:37], v[32:33] op_sel_hi:[0,1]
	v_pk_mul_f32 v[42:43], v[36:37], v[42:43] op_sel_hi:[0,1]
	v_pk_mul_f32 v[58:59], v[36:37], v[58:59] op_sel_hi:[0,1]
	v_pk_mul_f32 v[36:37], v[36:37], v[44:45] op_sel_hi:[0,1]
	v_pk_mul_f32 v[32:33], v[4:5], v[32:33]
	v_pk_mul_f32 v[42:43], v[6:7], v[42:43]
	v_pk_mul_f32 v[44:45], v[0:1], v[58:59]
	v_pk_mul_f32 v[36:37], v[2:3], v[36:37]
	ds_bpermute_b32 v58, v141, v32
	ds_bpermute_b32 v59, v141, v33
	ds_bpermute_b32 v60, v141, v42
	ds_bpermute_b32 v61, v141, v43
	ds_bpermute_b32 v62, v141, v44
	ds_bpermute_b32 v63, v141, v45
	ds_bpermute_b32 v64, v141, v36
	ds_bpermute_b32 v65, v141, v37
	s_waitcnt lgkmcnt(6)
	v_pk_mul_f32 v[40:41], v[40:41], v[58:59]
	s_waitcnt lgkmcnt(4)
; __device__ __forceinline__ unsigned cvtpk(float lo, float hi) { f32x2_t v = {lo, hi}; bf16x2_t b = __builtin_convertvector(v, bf16x2_t); return __builtin_bit_cast(unsigned, b); }
; __device__ __forceinline__ float bflo(unsigned w) { return __uint_as_float(w << 16); }
; __device__ __forceinline__ float bfhi(unsigned w) { return __uint_as_float(w & 0xffff0000u); }
; #define PG8_BAR __builtin_amdgcn_s_barrier()
; template <class Epi>
; __device__ __forceinline__ void gemm_phase(LAS unsigned char* lds, const Gemm g, const StaticOrder& S, const Epi& E, int wave_s) {
;     ...
;         if (wr == 0) PG8_BAR;
;         E(acc, cur, wr, wc, fr, fq);
;         if (!has_next) break;
; #pragma unroll
;         for (int a = 0; a < 2; ++a)
; #pragma unroll
;             for (int b = 0; b < 2; ++b)
; #pragma unroll
;                 for (int m = 0; m < 4; ++m)
; #pragma unroll
;                     for (int n = 0; n < 2; ++n) acc[a][b][m][n] = (f32x4){0.f, 0.f, 0.f, 0.f};
;         cur = nxt; cA = nA; cB = nB; ++ui;
;         if (wr == 1) PG8_BAR;
;     __device__ __forceinline__ void operator()(const f32x4 (&acc)[2][2][4][2], const Unit& u, int wr, int wc, int fr, int fq) const {
;     ...
; #pragma unroll
;         for (int ai = 0; ai < 2; ++ai)
; #pragma unroll
;             for (int m = 0; m < 4; ++m) {
;                 const int row = row0 + ai * HALF + m * 16; const int pos = row & (SEQ - 1);
;                 const float rh = rhs[ai * 4 + m];
;                 const u32x4 kw = *(const u32x4*)(T1 + (size_t)row * 1024 + 768 + 8 * fq);
;                 const float kr[8] = {bflo(kw.x), bfhi(kw.x), bflo(kw.y), bfhi(kw.y), bflo(kw.z), bfhi(kw.z), bflo(kw.w), bfhi(kw.w)};
;                 float ro[8];
; #pragma unroll
;                 for (int j = 0; j < 8; ++j) {
;                     const float x = kr[j] * rh * (j < 4 ? gr0[j & 3] : gr1[j & 3]);
;                     const float px = __shfl_xor(x, 32);
;                     float cs, sn; rope_cs(pos, 2 * (8 * (fq & 1) + j), cs, sn);
;                     ro[j] = (fq < 2) ? (x * cs - px * sn) : (px * sn + x * cs);
;                 }
;                 u32x4 w; w.x = cvtpk(ro[0], ro[1]); w.y = cvtpk(ro[2], ro[3]); w.z = cvtpk(ro[4], ro[5]); w.w = cvtpk(ro[6], ro[7]);
;                 *(u32x4*)(O + (size_t)row * 1536 + head * 96 + 64 + 8 * fq) = w;
;                 asm volatile("" ::: "memory");
	v_pk_mul_f32 v[48:49], v[48:49], v[60:61]
	s_waitcnt lgkmcnt(2)
	v_pk_mul_f32 v[52:53], v[52:53], v[62:63]
	v_cndmask_b32_e64 v41, v41, -v41, vcc
	s_waitcnt lgkmcnt(0)
	v_pk_mul_f32 v[56:57], v[56:57], v[64:65]
	v_cndmask_b32_e64 v40, v40, -v40, vcc
	v_cndmask_b32_e64 v49, v49, -v49, vcc
	v_cndmask_b32_e64 v48, v48, -v48, vcc
	v_cndmask_b32_e64 v53, v53, -v53, vcc
	v_cndmask_b32_e64 v52, v52, -v52, vcc
	v_cndmask_b32_e64 v57, v57, -v57, vcc
	v_cndmask_b32_e64 v56, v56, -v56, vcc
	v_pk_fma_f32 v[32:33], v[38:39], v[32:33], v[40:41]
	v_pk_fma_f32 v[38:39], v[42:43], v[46:47], v[48:49]
	v_pk_fma_f32 v[40:41], v[44:45], v[50:51], v[52:53]
	v_pk_fma_f32 v[42:43], v[36:37], v[54:55], v[56:57]
	v_cvt_pk_bf16_f32 v36, v32, v33
	v_cvt_pk_bf16_f32 v37, v38, v39
	v_cvt_pk_bf16_f32 v38, v40, v41
	v_cvt_pk_bf16_f32 v39, v42, v43
	global_store_dwordx4 v[34:35], v[36:39], off offset:128
	global_load_dwordx4 v[32:35], v[16:17], off offset:1536
	v_and_b32_e32 v16, 0xfff, v24
	v_cvt_f64_u32_e32 v[16:17], v16
	v_mul_f64 v[24:25], v[8:9], v[16:17]
	v_mul_f64 v[36:37], v[10:11], v[16:17]
	v_rndne_f64_e32 v[24:25], v[24:25]
	v_rndne_f64_e32 v[36:37], v[36:37]
	v_fma_f64 v[8:9], v[8:9], v[16:17], -v[24:25]
	v_fma_f64 v[10:11], v[10:11], v[16:17], -v[36:37]
	v_cvt_f32_f64_e32 v9, v[8:9]
	v_cvt_f32_f64_e32 v10, v[10:11]
	v_mul_f64 v[36:37], v[22:23], v[16:17]
	v_cos_f32_e32 v8, v9
	v_sin_f32_e32 v24, v9
	v_cos_f32_e32 v9, v10
	v_sin_f32_e32 v25, v10
	v_mul_f64 v[10:11], v[14:15], v[16:17]
	v_rndne_f64_e32 v[36:37], v[36:37]
	v_rndne_f64_e32 v[10:11], v[10:11]
	v_fma_f64 v[22:23], v[22:23], v[16:17], -v[36:37]
	v_fma_f64 v[10:11], v[14:15], v[16:17], -v[10:11]
	v_cvt_f32_f64_e32 v15, v[22:23]
	v_mul_f64 v[22:23], v[26:27], v[16:17]
	v_rndne_f64_e32 v[22:23], v[22:23]
	v_mul_f64 v[36:37], v[28:29], v[16:17]
	v_fma_f64 v[22:23], v[26:27], v[16:17], -v[22:23]
	v_rndne_f64_e32 v[36:37], v[36:37]
	v_cvt_f32_f64_e32 v21, v[22:23]
	v_fma_f64 v[28:29], v[28:29], v[16:17], -v[36:37]
	v_mul_f64 v[36:37], v[12:13], v[16:17]
	v_cos_f32_e32 v22, v21
	v_sin_f32_e32 v26, v21
	v_cvt_f32_f64_e32 v21, v[28:29]
	v_mul_f64 v[28:29], v[30:31], v[16:17]
	v_rndne_f64_e32 v[36:37], v[36:37]
	v_rndne_f64_e32 v[28:29], v[28:29]
	v_fma_f64 v[12:13], v[12:13], v[16:17], -v[36:37]
	v_fma_f64 v[28:29], v[30:31], v[16:17], -v[28:29]
	v_cvt_f32_f64_e32 v12, v[12:13]
	v_cos_f32_e32 v23, v21
	v_sin_f32_e32 v27, v21
	v_cvt_f32_f64_e32 v21, v[28:29]
	v_cos_f32_e32 v29, v12
	v_sin_f32_e32 v31, v12
	v_cos_f32_e32 v28, v21
	v_sin_f32_e32 v30, v21
	v_cvt_f32_f64_e32 v11, v[10:11]
	v_cos_f32_e32 v10, v11
	v_sin_f32_e32 v14, v11
	v_cos_f32_e32 v11, v15
	v_sin_f32_e32 v15, v15
	s_waitcnt vmcnt(0)
	v_lshlrev_b32_e32 v12, 16, v32
	v_and_b32_e32 v13, 0xffff0000, v32
	v_lshlrev_b32_e32 v16, 16, v33
	v_and_b32_e32 v17, 0xffff0000, v33
	v_lshlrev_b32_e32 v32, 16, v34
	v_and_b32_e32 v33, 0xffff0000, v34
	v_lshlrev_b32_e32 v34, 16, v35
	v_and_b32_e32 v35, 0xffff0000, v35
	v_pk_mul_f32 v[12:13], v[20:21], v[12:13] op_sel_hi:[0,1]
	v_pk_mul_f32 v[16:17], v[20:21], v[16:17] op_sel_hi:[0,1]
	v_pk_mul_f32 v[32:33], v[20:21], v[32:33] op_sel_hi:[0,1]
	v_pk_mul_f32 v[20:21], v[20:21], v[34:35] op_sel_hi:[0,1]
	v_pk_mul_f32 v[4:5], v[4:5], v[12:13]
	v_pk_mul_f32 v[6:7], v[6:7], v[16:17]
	v_pk_mul_f32 v[0:1], v[0:1], v[32:33]
	v_pk_mul_f32 v[2:3], v[2:3], v[20:21]
	ds_bpermute_b32 v12, v141, v4
	ds_bpermute_b32 v13, v141, v5
	ds_bpermute_b32 v16, v141, v6
	ds_bpermute_b32 v17, v141, v7
	ds_bpermute_b32 v20, v141, v0
	ds_bpermute_b32 v21, v141, v1
	ds_bpermute_b32 v32, v141, v2
	ds_bpermute_b32 v33, v141, v3
	s_waitcnt lgkmcnt(6)
	v_pk_mul_f32 v[12:13], v[24:25], v[12:13]
	s_waitcnt lgkmcnt(4)
	v_pk_mul_f32 v[14:15], v[14:15], v[16:17]
	s_waitcnt lgkmcnt(2)
	v_pk_mul_f32 v[16:17], v[26:27], v[20:21]
	v_cndmask_b32_e64 v13, v13, -v13, vcc
	s_waitcnt lgkmcnt(0)
	v_pk_mul_f32 v[20:21], v[30:31], v[32:33]
	v_cndmask_b32_e64 v12, v12, -v12, vcc
	v_cndmask_b32_e64 v15, v15, -v15, vcc
	v_cndmask_b32_e64 v14, v14, -v14, vcc
	v_cndmask_b32_e64 v17, v17, -v17, vcc
	v_cndmask_b32_e64 v16, v16, -v16, vcc
	v_cndmask_b32_e64 v21, v21, -v21, vcc
	v_cndmask_b32_e64 v20, v20, -v20, vcc
	v_pk_fma_f32 v[4:5], v[8:9], v[4:5], v[12:13]
	v_pk_fma_f32 v[6:7], v[6:7], v[10:11], v[14:15]
	v_pk_fma_f32 v[8:9], v[0:1], v[22:23], v[16:17]
	v_pk_fma_f32 v[10:11], v[2:3], v[28:29], v[20:21]
	v_cvt_pk_bf16_f32 v0, v4, v5
	v_cvt_pk_bf16_f32 v1, v6, v7
	v_cvt_pk_bf16_f32 v2, v8, v9
	v_cvt_pk_bf16_f32 v3, v10, v11
	global_store_dwordx4 v[18:19], v[0:3], off offset:128
	s_andn2_b64 vcc, exec, s[6:7]
	s_mov_b64 s[6:7], -1
	s_cbranch_vccnz .LBB0_1540
	s_andn2_b64 vcc, exec, s[20:21]
	s_cbranch_vccnz .LBB0_1539
	s_barrier
	s_branch .LBB0_1539
